# static s_setprio 1 for waves 0-3 set once at kernel entry, every per-segment priority flip in the GEMM K-loops removed
# speedup vs baseline: 1.0129x; 1.0041x over previous
; #define LAS __attribute__((address_space(3)))
; DI int otid(int wv) { int t; asm volatile("v_mbcnt_lo_u32_b32 %0, -1, 0\n\tv_mbcnt_hi_u32_b32 %0, -1, %0" : "=v"(t)); return wv * 64 + t; }
; __global__ void __launch_bounds__(NTHREADS, 2) fwd_megakernel(Args A) {
;     extern __shared__ __attribute__((aligned(16))) unsigned char lds_raw[];
;     LAS unsigned char* lds = (LAS unsigned char*)lds_raw;
;     cg::grid_group grid = cg::this_grid();
;     const int wv = __builtin_amdgcn_readfirstlane(threadIdx.x >> 6);
;     volatile LAS unsigned* bst = (volatile LAS unsigned*)(lds + 152576);
;     if (otid(wv) < 2) bst[otid(wv)] = 0u;
_Z14fwd_megakernel4Args:
	s_mov_b32 s92, s2
	s_add_u32 s2, s0, 0xa8
	s_addc_u32 s3, s1, 0
	s_load_dwordx8 s[52:59], s[0:1], 0x80
	v_writelane_b32 v247, s2, 0
	s_load_dwordx2 s[94:95], s[0:1], 0xa8
	v_and_b32_e32 v33, 0x3ff, v0
	v_writelane_b32 v247, s3, 1
	s_load_dword s2, s[0:1], 0xb0
	v_mbcnt_lo_u32_b32 v1, -1, 0
	v_mbcnt_hi_u32_b32 v1, -1, v1
	s_waitcnt lgkmcnt(0)
	v_writelane_b32 v247, s2, 2
	v_readfirstlane_b32 s2, v33
	s_and_b32 s90, s2, 0xffffffc0
	s_cmp_ge_u32 s90, 0x100
	s_cbranch_scc1 .Lprio_done
	s_setprio 1
.Lprio_done:
	v_add_u32_e32 v1, s90, v1
	v_cmp_gt_i32_e32 vcc, 2, v1
	s_and_saveexec_b64 s[4:5], vcc
	s_cbranch_execz .LBB0_2
	s_lshl_b32 s3, s90, 2
	v_mbcnt_lo_u32_b32 v1, -1, 0
	v_mbcnt_hi_u32_b32 v1, -1, v1
	s_add_i32 s3, s3, 0
	v_lshl_add_u32 v1, v1, 2, s3
	v_add_u32_e32 v1, 0x25400, v1
	v_mov_b32_e32 v2, 0
	ds_write_b32 v1, v2

; #define PG8_STAGE(bufoff, gbase, voff) do { _Pragma("unroll") for (int _i = 0; _i < 2; ++_i) \
;         __builtin_amdgcn_global_load_lds((const unsigned*)((const char*)(gbase) + (voff)[_i]), (LAS unsigned*)(lds + (bufoff) + ldsw + _i * 8192), 16, 0, 0); } while (0)
; #define PG8_LDA(dst, b, h) do { _Pragma("unroll") for (int m = 0; m < 4; ++m) _Pragma("unroll") for (int k = 0; k < 2; ++k) dst[m][k] = *(const LAS bf16x8*)(lds + PG8_SA(b, h) + aoff + m * 2048 + k * 1024); } while (0)
; #define PG8_LDB(dst, b, h) do { _Pragma("unroll") for (int n = 0; n < 2; ++n) _Pragma("unroll") for (int k = 0; k < 2; ++k) dst[n][k] = *(const LAS bf16x8*)(lds + PG8_SB(b, h) + boff + n * 2048 + k * 1024); } while (0)
; #define PG8_MMA(ai, bj, At, Bt) do { __builtin_amdgcn_s_setprio(1); _Pragma("unroll") for (int m = 0; m < 4; ++m) _Pragma("unroll") for (int n = 0; n < 2; ++n) _Pragma("unroll") for (int k = 0; k < 2; ++k) \
;         acc[ai][bj][m][n] = __builtin_amdgcn_mfma_f32_16x16x32_bf16(Bt[n][k], At[m][k], acc[ai][bj][m][n], 0, 0, 0); __builtin_amdgcn_s_setprio(0); } while (0)
; #define PG8_WAIT_V(n) asm volatile("s_waitcnt vmcnt(" #n ")" ::: "memory")
; #define PG8_WAIT_L(n) asm volatile("s_waitcnt lgkmcnt(" #n ")" ::: "memory")
; #define PG8_BAR __builtin_amdgcn_s_barrier()
; #define PG8_SCHED __builtin_amdgcn_sched_barrier(0)
; template <class Desc, class Epi>
; DI void gemm_phase(LAS unsigned char* lds, const Desc& D, const Epi& E, int wv) {
;     ...
;         for (int t = 0; t < nt; t += 2) {
;             const bool last = (t == nt - 2);
;             const char* a1 = cA + (size_t)(t + 1) * kstep;
;             const char* a2 = last ? nA : cA + (size_t)(t + 2) * kstep; const char* b2 = last ? nB : cB + (size_t)(t + 2) * kstep;
;             const char* a3 = a2 + kstep; const char* b3 = b2 + kstep;
;             PG8_LDB(B0, 0, 0); PG8_LDB(B1, 0, 1); PG8_SCHED; PG8_LDA(At, 0, 0); PG8_STAGE(PG8_SA(1, 1), a1 + hstepA, voffA);
;             PG8_WAIT_V(8); PG8_WAIT_L(0); PG8_BAR; PG8_MMA(0, 0, At, B0); PG8_MMA(0, 1, At, B1); PG8_BAR; PG8_SCHED;
;             PG8_LDA(At, 0, 1); PG8_STAGE(PG8_SB(0, 0), b2, voffB); PG8_STAGE(PG8_SB(0, 1), b2 + hstepB, voffB); PG8_STAGE(PG8_SA(0, 0), a2, voffA);
;             PG8_WAIT_V(8); PG8_WAIT_L(0); PG8_BAR; PG8_MMA(1, 0, At, B0); PG8_MMA(1, 1, At, B1); PG8_BAR; PG8_SCHED;
.LBB0_292:
	ds_read_b128 v[152:155], v149
	ds_read_b128 v[156:159], v149 offset:1024
	ds_read_b128 v[160:163], v149 offset:2048
	ds_read_b128 v[164:167], v149 offset:3072
	ds_read_b128 v[168:171], v150
	ds_read_b128 v[172:175], v150 offset:1024
	ds_read_b128 v[176:179], v150 offset:2048
	ds_read_b128 v[180:183], v150 offset:3072
	s_add_u32 s66, s64, 0xfff80080
	s_addc_u32 s67, s65, -1
	s_cmp_eq_u32 s63, 28
	s_cselect_b32 s69, s39, s67
	s_cselect_b32 s68, s38, s66
	s_cselect_b32 s67, s47, s61
	s_cselect_b32 s66, s46, s53
	v_lshl_add_u64 v[146:147], s[64:65], 0, v[138:139]
	s_add_i32 m0, s31, 0xc000
	ds_read_b128 v[184:187], v151
	ds_read_b128 v[188:191], v151 offset:1024
	ds_read_b128 v[192:195], v151 offset:2048
	ds_read_b128 v[196:199], v151 offset:3072
	ds_read_b128 v[200:203], v151 offset:4096
	ds_read_b128 v[204:207], v151 offset:5120
	ds_read_b128 v[208:211], v151 offset:6144
	ds_read_b128 v[212:215], v151 offset:7168
	global_load_lds_dwordx4 v[146:147], off
	s_add_i32 m0, s31, 0xe000
	v_lshl_add_u64 v[146:147], s[64:65], 0, v[140:141]
	global_load_lds_dwordx4 v[146:147], off
	s_waitcnt vmcnt(8) lgkmcnt(0)
	s_barrier
	v_mfma_f32_16x16x32_bf16 v[124:127], v[152:155], v[184:187], v[124:127]
	v_mfma_f32_16x16x32_bf16 v[120:123], v[160:163], v[184:187], v[120:123]
	v_mfma_f32_16x16x32_bf16 v[108:111], v[152:155], v[192:195], v[108:111]
	v_mfma_f32_16x16x32_bf16 v[104:107], v[160:163], v[192:195], v[104:107]
	v_mfma_f32_16x16x32_bf16 v[92:95], v[152:155], v[200:203], v[92:95]
	v_mfma_f32_16x16x32_bf16 v[88:91], v[160:163], v[200:203], v[88:91]
	v_mfma_f32_16x16x32_bf16 v[76:79], v[152:155], v[208:211], v[76:79]
	v_mfma_f32_16x16x32_bf16 v[72:75], v[160:163], v[208:211], v[72:75]
	v_mfma_f32_16x16x32_bf16 v[124:127], v[156:159], v[188:191], v[124:127]
	v_mfma_f32_16x16x32_bf16 v[120:123], v[164:167], v[188:191], v[120:123]
	v_mfma_f32_16x16x32_bf16 v[108:111], v[156:159], v[196:199], v[108:111]
	v_mfma_f32_16x16x32_bf16 v[104:107], v[164:167], v[196:199], v[104:107]
	v_mfma_f32_16x16x32_bf16 v[92:95], v[156:159], v[204:207], v[92:95]
	v_mfma_f32_16x16x32_bf16 v[88:91], v[164:167], v[204:207], v[88:91]
	v_mfma_f32_16x16x32_bf16 v[76:79], v[156:159], v[212:215], v[76:79]
	v_mfma_f32_16x16x32_bf16 v[72:75], v[164:167], v[212:215], v[72:75]
	v_mfma_f32_16x16x32_bf16 v[116:119], v[168:171], v[184:187], v[116:119]
	v_mfma_f32_16x16x32_bf16 v[112:115], v[176:179], v[184:187], v[112:115]
	v_mfma_f32_16x16x32_bf16 v[100:103], v[168:171], v[192:195], v[100:103]
	v_mfma_f32_16x16x32_bf16 v[96:99], v[176:179], v[192:195], v[96:99]
	v_mfma_f32_16x16x32_bf16 v[84:87], v[168:171], v[200:203], v[84:87]
	v_mfma_f32_16x16x32_bf16 v[80:83], v[176:179], v[200:203], v[80:83]
	v_mfma_f32_16x16x32_bf16 v[68:71], v[168:171], v[208:211], v[68:71]
	v_mfma_f32_16x16x32_bf16 v[64:67], v[176:179], v[208:211], v[64:67]
	v_mfma_f32_16x16x32_bf16 v[116:119], v[172:175], v[188:191], v[116:119]
	v_mfma_f32_16x16x32_bf16 v[112:115], v[180:183], v[188:191], v[112:115]
	v_mfma_f32_16x16x32_bf16 v[100:103], v[172:175], v[196:199], v[100:103]
	v_mfma_f32_16x16x32_bf16 v[96:99], v[180:183], v[196:199], v[96:99]
	v_mfma_f32_16x16x32_bf16 v[84:87], v[172:175], v[204:207], v[84:87]
	v_mfma_f32_16x16x32_bf16 v[80:83], v[180:183], v[204:207], v[80:83]
	v_mfma_f32_16x16x32_bf16 v[68:71], v[172:175], v[212:215], v[68:71]
	v_mfma_f32_16x16x32_bf16 v[64:67], v[180:183], v[212:215], v[64:67]
	s_barrier
	s_add_i32 s76, s51, s28
	v_lshl_add_u64 v[146:147], s[66:67], 0, v[132:133]
	s_mov_b32 m0, s76
	ds_read_b128 v[184:187], v151 offset:16384
	ds_read_b128 v[188:191], v151 offset:17408
	ds_read_b128 v[192:195], v151 offset:18432
	ds_read_b128 v[196:199], v151 offset:19456
	ds_read_b128 v[200:203], v151 offset:20480
	ds_read_b128 v[204:207], v151 offset:21504
	ds_read_b128 v[208:211], v151 offset:22528
	ds_read_b128 v[212:215], v151 offset:23552
	global_load_lds_dwordx4 v[146:147], off
	s_add_i32 m0, s76, 0x2000
	s_add_u32 s76, s66, 0x80000
	v_lshl_add_u64 v[216:217], s[66:67], 0, v[128:129]
	s_addc_u32 s77, s67, 0
	s_add_i32 s78, s70, s28
	global_load_lds_dwordx4 v[216:217], off
	v_lshl_add_u64 v[218:219], s[76:77], 0, v[132:133]
	s_mov_b32 m0, s78
	v_lshl_add_u64 v[220:221], s[68:69], 0, v[130:131]
	global_load_lds_dwordx4 v[218:219], off
	s_add_i32 m0, s78, 0x2000
	v_lshl_add_u64 v[218:219], s[76:77], 0, v[128:129]
	global_load_lds_dwordx4 v[218:219], off
	s_mov_b32 m0, s31
	v_lshl_add_u64 v[218:219], s[68:69], 0, v[134:135]
	global_load_lds_dwordx4 v[218:219], off
	s_mov_b32 m0, s34
	s_nop 0
	global_load_lds_dwordx4 v[220:221], off
	s_waitcnt vmcnt(8) lgkmcnt(0)
	s_barrier
; #define PG8_STAGE(bufoff, gbase, voff) do { _Pragma("unroll") for (int _i = 0; _i < 2; ++_i) \
;         __builtin_amdgcn_global_load_lds((const unsigned*)((const char*)(gbase) + (voff)[_i]), (LAS unsigned*)(lds + (bufoff) + ldsw + _i * 8192), 16, 0, 0); } while (0)
; #define PG8_LDA(dst, b, h) do { _Pragma("unroll") for (int m = 0; m < 4; ++m) _Pragma("unroll") for (int k = 0; k < 2; ++k) dst[m][k] = *(const LAS bf16x8*)(lds + PG8_SA(b, h) + aoff + m * 2048 + k * 1024); } while (0)
; #define PG8_LDB(dst, b, h) do { _Pragma("unroll") for (int n = 0; n < 2; ++n) _Pragma("unroll") for (int k = 0; k < 2; ++k) dst[n][k] = *(const LAS bf16x8*)(lds + PG8_SB(b, h) + boff + n * 2048 + k * 1024); } while (0)
; #define PG8_MMA(ai, bj, At, Bt) do { __builtin_amdgcn_s_setprio(1); _Pragma("unroll") for (int m = 0; m < 4; ++m) _Pragma("unroll") for (int n = 0; n < 2; ++n) _Pragma("unroll") for (int k = 0; k < 2; ++k) \
;         acc[ai][bj][m][n] = __builtin_amdgcn_mfma_f32_16x16x32_bf16(Bt[n][k], At[m][k], acc[ai][bj][m][n], 0, 0, 0); __builtin_amdgcn_s_setprio(0); } while (0)
; #define PG8_WAIT_V(n) asm volatile("s_waitcnt vmcnt(" #n ")" ::: "memory")
; #define PG8_WAIT_L(n) asm volatile("s_waitcnt lgkmcnt(" #n ")" ::: "memory")
; #define PG8_BAR __builtin_amdgcn_s_barrier()
; #define PG8_SCHED __builtin_amdgcn_sched_barrier(0)
; template <class Desc, class Epi>
; DI void gemm_phase(LAS unsigned char* lds, const Desc& D, const Epi& E, int wv) {
;     ...
;             PG8_WAIT_V(8); PG8_WAIT_L(0); PG8_BAR; PG8_MMA(1, 0, At, B0); PG8_MMA(1, 1, At, B1); PG8_BAR; PG8_SCHED;
;             PG8_LDB(B0, 1, 0); PG8_LDB(B1, 1, 1); PG8_SCHED; PG8_LDA(At, 1, 0); PG8_STAGE(PG8_SA(0, 1), a2 + hstepA, voffA);
;             PG8_WAIT_V(8); PG8_WAIT_L(0); PG8_BAR; PG8_MMA(0, 0, At, B0); PG8_MMA(0, 1, At, B1); PG8_BAR; PG8_SCHED;
	v_mfma_f32_16x16x32_bf16 v[60:63], v[152:155], v[184:187], v[60:63]
	v_mfma_f32_16x16x32_bf16 v[56:59], v[160:163], v[184:187], v[56:59]
	v_mfma_f32_16x16x32_bf16 v[44:47], v[152:155], v[192:195], v[44:47]
	v_mfma_f32_16x16x32_bf16 v[40:43], v[160:163], v[192:195], v[40:43]
	v_mfma_f32_16x16x32_bf16 v[28:31], v[152:155], v[200:203], v[28:31]
	v_mfma_f32_16x16x32_bf16 v[24:27], v[160:163], v[200:203], v[24:27]
	v_mfma_f32_16x16x32_bf16 v[12:15], v[152:155], v[208:211], v[12:15]
	v_mfma_f32_16x16x32_bf16 v[8:11], v[160:163], v[208:211], v[8:11]
	v_mfma_f32_16x16x32_bf16 v[60:63], v[156:159], v[188:191], v[60:63]
	v_mfma_f32_16x16x32_bf16 v[56:59], v[164:167], v[188:191], v[56:59]
	v_mfma_f32_16x16x32_bf16 v[44:47], v[156:159], v[196:199], v[44:47]
	v_mfma_f32_16x16x32_bf16 v[40:43], v[164:167], v[196:199], v[40:43]
	v_mfma_f32_16x16x32_bf16 v[28:31], v[156:159], v[204:207], v[28:31]
	v_mfma_f32_16x16x32_bf16 v[24:27], v[164:167], v[204:207], v[24:27]
	v_mfma_f32_16x16x32_bf16 v[12:15], v[156:159], v[212:215], v[12:15]
	v_mfma_f32_16x16x32_bf16 v[8:11], v[164:167], v[212:215], v[8:11]
	v_mfma_f32_16x16x32_bf16 v[52:55], v[168:171], v[184:187], v[52:55]
	v_mfma_f32_16x16x32_bf16 v[48:51], v[176:179], v[184:187], v[48:51]
	v_mfma_f32_16x16x32_bf16 v[36:39], v[168:171], v[192:195], v[36:39]
	v_mfma_f32_16x16x32_bf16 v[32:35], v[176:179], v[192:195], v[32:35]
	v_mfma_f32_16x16x32_bf16 v[20:23], v[168:171], v[200:203], v[20:23]
	v_mfma_f32_16x16x32_bf16 v[16:19], v[176:179], v[200:203], v[16:19]
	v_mfma_f32_16x16x32_bf16 v[4:7], v[168:171], v[208:211], v[4:7]
	v_mfma_f32_16x16x32_bf16 v[0:3], v[176:179], v[208:211], v[0:3]
	v_mfma_f32_16x16x32_bf16 v[52:55], v[172:175], v[188:191], v[52:55]
	v_mfma_f32_16x16x32_bf16 v[48:51], v[180:183], v[188:191], v[48:51]
	v_mfma_f32_16x16x32_bf16 v[36:39], v[172:175], v[196:199], v[36:39]
	v_mfma_f32_16x16x32_bf16 v[32:35], v[180:183], v[196:199], v[32:35]
	v_mfma_f32_16x16x32_bf16 v[20:23], v[172:175], v[204:207], v[20:23]
	v_mfma_f32_16x16x32_bf16 v[16:19], v[180:183], v[204:207], v[16:19]
	v_mfma_f32_16x16x32_bf16 v[4:7], v[172:175], v[212:215], v[4:7]
	v_mfma_f32_16x16x32_bf16 v[0:3], v[180:183], v[212:215], v[0:3]
	s_barrier
	s_add_i32 s76, 0, 0x18000
	v_add_u32_e32 v136, s76, v148
	s_add_i32 s77, 0, 0x1c000
	ds_read_b128 v[152:155], v136
	ds_read_b128 v[156:159], v136 offset:1024
	ds_read_b128 v[160:163], v136 offset:2048
	ds_read_b128 v[164:167], v136 offset:3072
	v_add_u32_e32 v136, s77, v148
	ds_read_b128 v[168:171], v136
	ds_read_b128 v[172:175], v136 offset:1024
	ds_read_b128 v[176:179], v136 offset:2048
	ds_read_b128 v[180:183], v136 offset:3072
	s_add_u32 s68, s68, 0x80000
	s_addc_u32 s69, s69, 0
	s_mov_b32 m0, s35
	v_lshl_add_u64 v[222:223], s[68:69], 0, v[134:135]
	ds_read_b128 v[184:187], v151 offset:32768
	ds_read_b128 v[188:191], v151 offset:33792
	ds_read_b128 v[192:195], v151 offset:34816
	ds_read_b128 v[196:199], v151 offset:35840
	ds_read_b128 v[200:203], v151 offset:36864
	ds_read_b128 v[204:207], v151 offset:37888
	ds_read_b128 v[208:211], v151 offset:38912
	ds_read_b128 v[212:215], v151 offset:39936
	global_load_lds_dwordx4 v[222:223], off
	s_mov_b32 m0, s40
	v_lshl_add_u64 v[222:223], s[68:69], 0, v[130:131]
	global_load_lds_dwordx4 v[222:223], off
	s_waitcnt vmcnt(8) lgkmcnt(0)
	s_barrier
	v_mfma_f32_16x16x32_bf16 v[124:127], v[152:155], v[184:187], v[124:127]
	v_mfma_f32_16x16x32_bf16 v[120:123], v[160:163], v[184:187], v[120:123]
	v_mfma_f32_16x16x32_bf16 v[108:111], v[152:155], v[192:195], v[108:111]
	v_mfma_f32_16x16x32_bf16 v[104:107], v[160:163], v[192:195], v[104:107]
	v_mfma_f32_16x16x32_bf16 v[92:95], v[152:155], v[200:203], v[92:95]
	v_mfma_f32_16x16x32_bf16 v[88:91], v[160:163], v[200:203], v[88:91]
	v_mfma_f32_16x16x32_bf16 v[76:79], v[152:155], v[208:211], v[76:79]
	v_mfma_f32_16x16x32_bf16 v[72:75], v[160:163], v[208:211], v[72:75]
	v_mfma_f32_16x16x32_bf16 v[124:127], v[156:159], v[188:191], v[124:127]
	v_mfma_f32_16x16x32_bf16 v[120:123], v[164:167], v[188:191], v[120:123]
	v_mfma_f32_16x16x32_bf16 v[108:111], v[156:159], v[196:199], v[108:111]
	v_mfma_f32_16x16x32_bf16 v[104:107], v[164:167], v[196:199], v[104:107]
	v_mfma_f32_16x16x32_bf16 v[92:95], v[156:159], v[204:207], v[92:95]
	v_mfma_f32_16x16x32_bf16 v[88:91], v[164:167], v[204:207], v[88:91]
	v_mfma_f32_16x16x32_bf16 v[76:79], v[156:159], v[212:215], v[76:79]
	v_mfma_f32_16x16x32_bf16 v[72:75], v[164:167], v[212:215], v[72:75]
	v_mfma_f32_16x16x32_bf16 v[116:119], v[168:171], v[184:187], v[116:119]
	v_mfma_f32_16x16x32_bf16 v[112:115], v[176:179], v[184:187], v[112:115]
	v_mfma_f32_16x16x32_bf16 v[100:103], v[168:171], v[192:195], v[100:103]
	v_mfma_f32_16x16x32_bf16 v[96:99], v[176:179], v[192:195], v[96:99]
	v_mfma_f32_16x16x32_bf16 v[84:87], v[168:171], v[200:203], v[84:87]
	v_mfma_f32_16x16x32_bf16 v[80:83], v[176:179], v[200:203], v[80:83]
	v_mfma_f32_16x16x32_bf16 v[68:71], v[168:171], v[208:211], v[68:71]
	v_mfma_f32_16x16x32_bf16 v[64:67], v[176:179], v[208:211], v[64:67]
	v_mfma_f32_16x16x32_bf16 v[116:119], v[172:175], v[188:191], v[116:119]
	v_mfma_f32_16x16x32_bf16 v[112:115], v[180:183], v[188:191], v[112:115]
	v_mfma_f32_16x16x32_bf16 v[100:103], v[172:175], v[196:199], v[100:103]
	v_mfma_f32_16x16x32_bf16 v[96:99], v[180:183], v[196:199], v[96:99]
	v_mfma_f32_16x16x32_bf16 v[84:87], v[172:175], v[204:207], v[84:87]
	v_mfma_f32_16x16x32_bf16 v[80:83], v[180:183], v[204:207], v[80:83]
	v_mfma_f32_16x16x32_bf16 v[68:71], v[172:175], v[212:215], v[68:71]
	v_mfma_f32_16x16x32_bf16 v[64:67], v[180:183], v[212:215], v[64:67]
	s_barrier
; #define PG8_STAGE(bufoff, gbase, voff) do { _Pragma("unroll") for (int _i = 0; _i < 2; ++_i) \
;         __builtin_amdgcn_global_load_lds((const unsigned*)((const char*)(gbase) + (voff)[_i]), (LAS unsigned*)(lds + (bufoff) + ldsw + _i * 8192), 16, 0, 0); } while (0)
; #define PG8_LDA(dst, b, h) do { _Pragma("unroll") for (int m = 0; m < 4; ++m) _Pragma("unroll") for (int k = 0; k < 2; ++k) dst[m][k] = *(const LAS bf16x8*)(lds + PG8_SA(b, h) + aoff + m * 2048 + k * 1024); } while (0)
; #define PG8_MMA(ai, bj, At, Bt) do { __builtin_amdgcn_s_setprio(1); _Pragma("unroll") for (int m = 0; m < 4; ++m) _Pragma("unroll") for (int n = 0; n < 2; ++n) _Pragma("unroll") for (int k = 0; k < 2; ++k) \
;         acc[ai][bj][m][n] = __builtin_amdgcn_mfma_f32_16x16x32_bf16(Bt[n][k], At[m][k], acc[ai][bj][m][n], 0, 0, 0); __builtin_amdgcn_s_setprio(0); } while (0)
; #define PG8_WAIT_V(n) asm volatile("s_waitcnt vmcnt(" #n ")" ::: "memory")
; #define PG8_WAIT_L(n) asm volatile("s_waitcnt lgkmcnt(" #n ")" ::: "memory")
; #define PG8_BAR __builtin_amdgcn_s_barrier()
; #define PG8_SCHED __builtin_amdgcn_sched_barrier(0)
; template <class Desc, class Epi>
; DI void gemm_phase(LAS unsigned char* lds, const Desc& D, const Epi& E, int wv) {
;     ...
;             PG8_LDA(At, 1, 1); PG8_STAGE(PG8_SB(1, 0), b3, voffB); PG8_STAGE(PG8_SB(1, 1), b3 + hstepB, voffB); PG8_STAGE(PG8_SA(1, 0), a3, voffA);
;             PG8_WAIT_V(8); PG8_WAIT_L(0); PG8_BAR; PG8_MMA(1, 0, At, B0); PG8_MMA(1, 1, At, B1); PG8_BAR; PG8_SCHED;
;         }
;         if (wr == 0) PG8_BAR;
	s_add_i32 s68, s76, s28
	v_lshl_add_u64 v[146:147], v[146:147], 0, s[8:9]
	s_mov_b32 m0, s68
	ds_read_b128 v[184:187], v151 offset:49152
	ds_read_b128 v[188:191], v151 offset:50176
	ds_read_b128 v[192:195], v151 offset:51200
	ds_read_b128 v[196:199], v151 offset:52224
	ds_read_b128 v[200:203], v151 offset:53248
	ds_read_b128 v[204:207], v151 offset:54272
	ds_read_b128 v[208:211], v151 offset:55296
	ds_read_b128 v[212:215], v151 offset:56320
	global_load_lds_dwordx4 v[146:147], off
	s_add_i32 m0, s68, 0x2000
	s_add_u32 s66, s66, 0x80080
	v_lshl_add_u64 v[146:147], v[216:217], 0, s[8:9]
	s_addc_u32 s67, s67, 0
	s_add_i32 s68, s77, s28
	global_load_lds_dwordx4 v[146:147], off
	s_mov_b32 m0, s68
	v_lshl_add_u64 v[146:147], s[66:67], 0, v[132:133]
	global_load_lds_dwordx4 v[146:147], off
	s_add_i32 m0, s68, 0x2000
	v_lshl_add_u64 v[146:147], s[66:67], 0, v[128:129]
	global_load_lds_dwordx4 v[146:147], off
	s_mov_b32 m0, s48
	v_lshl_add_u64 v[146:147], v[218:219], 0, s[8:9]
	global_load_lds_dwordx4 v[146:147], off
	s_mov_b32 m0, s49
	v_lshl_add_u64 v[146:147], v[220:221], 0, s[8:9]
	global_load_lds_dwordx4 v[146:147], off
	s_waitcnt vmcnt(8) lgkmcnt(0)
	s_barrier
	v_mfma_f32_16x16x32_bf16 v[60:63], v[152:155], v[184:187], v[60:63]
	v_mfma_f32_16x16x32_bf16 v[56:59], v[160:163], v[184:187], v[56:59]
	v_mfma_f32_16x16x32_bf16 v[44:47], v[152:155], v[192:195], v[44:47]
	v_mfma_f32_16x16x32_bf16 v[40:43], v[160:163], v[192:195], v[40:43]
	v_mfma_f32_16x16x32_bf16 v[28:31], v[152:155], v[200:203], v[28:31]
	v_mfma_f32_16x16x32_bf16 v[24:27], v[160:163], v[200:203], v[24:27]
	v_mfma_f32_16x16x32_bf16 v[12:15], v[152:155], v[208:211], v[12:15]
	v_mfma_f32_16x16x32_bf16 v[8:11], v[160:163], v[208:211], v[8:11]
	v_mfma_f32_16x16x32_bf16 v[60:63], v[156:159], v[188:191], v[60:63]
	v_mfma_f32_16x16x32_bf16 v[56:59], v[164:167], v[188:191], v[56:59]
	v_mfma_f32_16x16x32_bf16 v[44:47], v[156:159], v[196:199], v[44:47]
	v_mfma_f32_16x16x32_bf16 v[40:43], v[164:167], v[196:199], v[40:43]
	v_mfma_f32_16x16x32_bf16 v[28:31], v[156:159], v[204:207], v[28:31]
	v_mfma_f32_16x16x32_bf16 v[24:27], v[164:167], v[204:207], v[24:27]
	v_mfma_f32_16x16x32_bf16 v[12:15], v[156:159], v[212:215], v[12:15]
	v_mfma_f32_16x16x32_bf16 v[8:11], v[164:167], v[212:215], v[8:11]
	v_mfma_f32_16x16x32_bf16 v[52:55], v[168:171], v[184:187], v[52:55]
	v_mfma_f32_16x16x32_bf16 v[48:51], v[176:179], v[184:187], v[48:51]
	v_mfma_f32_16x16x32_bf16 v[36:39], v[168:171], v[192:195], v[36:39]
	v_mfma_f32_16x16x32_bf16 v[32:35], v[176:179], v[192:195], v[32:35]
	v_mfma_f32_16x16x32_bf16 v[20:23], v[168:171], v[200:203], v[20:23]
	v_mfma_f32_16x16x32_bf16 v[16:19], v[176:179], v[200:203], v[16:19]
	v_mfma_f32_16x16x32_bf16 v[4:7], v[168:171], v[208:211], v[4:7]
	v_mfma_f32_16x16x32_bf16 v[0:3], v[176:179], v[208:211], v[0:3]
	v_mfma_f32_16x16x32_bf16 v[52:55], v[172:175], v[188:191], v[52:55]
	v_mfma_f32_16x16x32_bf16 v[48:51], v[180:183], v[188:191], v[48:51]
	v_mfma_f32_16x16x32_bf16 v[36:39], v[172:175], v[196:199], v[36:39]
	v_mfma_f32_16x16x32_bf16 v[32:35], v[180:183], v[196:199], v[32:35]
	v_mfma_f32_16x16x32_bf16 v[20:23], v[172:175], v[204:207], v[20:23]
	v_mfma_f32_16x16x32_bf16 v[16:19], v[180:183], v[204:207], v[16:19]
	v_mfma_f32_16x16x32_bf16 v[4:7], v[172:175], v[212:215], v[4:7]
	v_mfma_f32_16x16x32_bf16 v[0:3], v[180:183], v[212:215], v[0:3]
	s_barrier
	s_add_i32 s63, s63, 2
	s_add_u32 s64, s64, 0x100
	s_addc_u32 s65, s65, 0
	s_add_u32 s53, s53, 0x100
	s_addc_u32 s61, s61, 0
	s_cmp_gt_u32 s63, 29
	s_cbranch_scc0 .LBB0_292
	s_and_b64 vcc, exec, s[14:15]
	s_cbranch_vccz .LBB0_295
	s_barrier

; #define PG8_STAGE(bufoff, gbase, voff) do { _Pragma("unroll") for (int _i = 0; _i < 2; ++_i) \
;         __builtin_amdgcn_global_load_lds((const unsigned*)((const char*)(gbase) + (voff)[_i]), (LAS unsigned*)(lds + (bufoff) + ldsw + _i * 8192), 16, 0, 0); } while (0)
; #define PG8_LDA(dst, b, h) do { _Pragma("unroll") for (int m = 0; m < 4; ++m) _Pragma("unroll") for (int k = 0; k < 2; ++k) dst[m][k] = *(const LAS bf16x8*)(lds + PG8_SA(b, h) + aoff + m * 2048 + k * 1024); } while (0)
; #define PG8_LDB(dst, b, h) do { _Pragma("unroll") for (int n = 0; n < 2; ++n) _Pragma("unroll") for (int k = 0; k < 2; ++k) dst[n][k] = *(const LAS bf16x8*)(lds + PG8_SB(b, h) + boff + n * 2048 + k * 1024); } while (0)
; #define PG8_MMA(ai, bj, At, Bt) do { __builtin_amdgcn_s_setprio(1); _Pragma("unroll") for (int m = 0; m < 4; ++m) _Pragma("unroll") for (int n = 0; n < 2; ++n) _Pragma("unroll") for (int k = 0; k < 2; ++k) \
;         acc[ai][bj][m][n] = __builtin_amdgcn_mfma_f32_16x16x32_bf16(Bt[n][k], At[m][k], acc[ai][bj][m][n], 0, 0, 0); __builtin_amdgcn_s_setprio(0); } while (0)
; #define PG8_WAIT_V(n) asm volatile("s_waitcnt vmcnt(" #n ")" ::: "memory")
; #define PG8_WAIT_L(n) asm volatile("s_waitcnt lgkmcnt(" #n ")" ::: "memory")
; #define PG8_BAR __builtin_amdgcn_s_barrier()
; #define PG8_SCHED __builtin_amdgcn_sched_barrier(0)
; template <class Desc, class Epi>
; DI void gemm_phase(LAS unsigned char* lds, const Desc& D, const Epi& E, int wv) {
;     ...
;         for (int t = 0; t < nt; t += 2) {
;             const bool last = (t == nt - 2);
;             const char* a1 = cA + (size_t)(t + 1) * kstep;
;             const char* a2 = last ? nA : cA + (size_t)(t + 2) * kstep; const char* b2 = last ? nB : cB + (size_t)(t + 2) * kstep;
;             const char* a3 = a2 + kstep; const char* b3 = b2 + kstep;
;             PG8_LDB(B0, 0, 0); PG8_LDB(B1, 0, 1); PG8_SCHED; PG8_LDA(At, 0, 0); PG8_STAGE(PG8_SA(1, 1), a1 + hstepA, voffA);
;             PG8_WAIT_V(8); PG8_WAIT_L(0); PG8_BAR; PG8_MMA(0, 0, At, B0); PG8_MMA(0, 1, At, B1); PG8_BAR; PG8_SCHED;
;             PG8_LDA(At, 0, 1); PG8_STAGE(PG8_SB(0, 0), b2, voffB); PG8_STAGE(PG8_SB(0, 1), b2 + hstepB, voffB); PG8_STAGE(PG8_SA(0, 0), a2, voffA);
;             PG8_WAIT_V(8); PG8_WAIT_L(0); PG8_BAR; PG8_MMA(1, 0, At, B0); PG8_MMA(1, 1, At, B1); PG8_BAR; PG8_SCHED;
.LBB0_339:
	ds_read_b128 v[142:145], v151
	ds_read_b128 v[146:149], v151 offset:1024
	ds_read_b128 v[158:161], v151 offset:2048
	ds_read_b128 v[162:165], v151 offset:3072
	ds_read_b128 v[166:169], v152
	ds_read_b128 v[170:173], v152 offset:1024
	ds_read_b128 v[174:177], v152 offset:2048
	ds_read_b128 v[178:181], v152 offset:3072
	s_add_u32 s8, s6, 0xfffe0080
	s_addc_u32 s9, s7, -1
	s_cmp_eq_u32 s67, 4
	s_cselect_b32 s65, s61, s9
	s_cselect_b32 s64, s60, s8
	s_cselect_b32 s9, s63, s66
	s_cselect_b32 s8, s62, s53
	v_lshl_add_u64 v[214:215], s[6:7], 0, v[138:139]
	s_add_i32 m0, s3, 0xc000
	ds_read_b128 v[182:185], v153
	ds_read_b128 v[186:189], v153 offset:1024
	ds_read_b128 v[190:193], v153 offset:2048
	ds_read_b128 v[194:197], v153 offset:3072
	ds_read_b128 v[198:201], v153 offset:4096
	ds_read_b128 v[202:205], v153 offset:5120
	ds_read_b128 v[206:209], v153 offset:6144
	ds_read_b128 v[210:213], v153 offset:7168
	global_load_lds_dwordx4 v[214:215], off
	s_add_i32 m0, s3, 0xe000
	v_lshl_add_u64 v[214:215], s[6:7], 0, v[140:141]
	global_load_lds_dwordx4 v[214:215], off
	s_waitcnt vmcnt(8) lgkmcnt(0)
	s_barrier
	v_mfma_f32_16x16x32_bf16 v[124:127], v[142:145], v[182:185], v[124:127]
	v_mfma_f32_16x16x32_bf16 v[120:123], v[158:161], v[182:185], v[120:123]
	v_mfma_f32_16x16x32_bf16 v[108:111], v[142:145], v[190:193], v[108:111]
	v_mfma_f32_16x16x32_bf16 v[104:107], v[158:161], v[190:193], v[104:107]
	v_mfma_f32_16x16x32_bf16 v[92:95], v[142:145], v[198:201], v[92:95]
	v_mfma_f32_16x16x32_bf16 v[88:91], v[158:161], v[198:201], v[88:91]
	v_mfma_f32_16x16x32_bf16 v[76:79], v[142:145], v[206:209], v[76:79]
	v_mfma_f32_16x16x32_bf16 v[72:75], v[158:161], v[206:209], v[72:75]
	v_mfma_f32_16x16x32_bf16 v[124:127], v[146:149], v[186:189], v[124:127]
	v_mfma_f32_16x16x32_bf16 v[120:123], v[162:165], v[186:189], v[120:123]
	v_mfma_f32_16x16x32_bf16 v[108:111], v[146:149], v[194:197], v[108:111]
	v_mfma_f32_16x16x32_bf16 v[104:107], v[162:165], v[194:197], v[104:107]
	v_mfma_f32_16x16x32_bf16 v[92:95], v[146:149], v[202:205], v[92:95]
	v_mfma_f32_16x16x32_bf16 v[88:91], v[162:165], v[202:205], v[88:91]
	v_mfma_f32_16x16x32_bf16 v[76:79], v[146:149], v[210:213], v[76:79]
	v_mfma_f32_16x16x32_bf16 v[72:75], v[162:165], v[210:213], v[72:75]
	v_mfma_f32_16x16x32_bf16 v[116:119], v[166:169], v[182:185], v[116:119]
	v_mfma_f32_16x16x32_bf16 v[112:115], v[174:177], v[182:185], v[112:115]
	v_mfma_f32_16x16x32_bf16 v[100:103], v[166:169], v[190:193], v[100:103]
	v_mfma_f32_16x16x32_bf16 v[96:99], v[174:177], v[190:193], v[96:99]
	v_mfma_f32_16x16x32_bf16 v[84:87], v[166:169], v[198:201], v[84:87]
	v_mfma_f32_16x16x32_bf16 v[80:83], v[174:177], v[198:201], v[80:83]
	v_mfma_f32_16x16x32_bf16 v[68:71], v[166:169], v[206:209], v[68:71]
	v_mfma_f32_16x16x32_bf16 v[64:67], v[174:177], v[206:209], v[64:67]
	v_mfma_f32_16x16x32_bf16 v[116:119], v[170:173], v[186:189], v[116:119]
	v_mfma_f32_16x16x32_bf16 v[112:115], v[178:181], v[186:189], v[112:115]
	v_mfma_f32_16x16x32_bf16 v[100:103], v[170:173], v[194:197], v[100:103]
	v_mfma_f32_16x16x32_bf16 v[96:99], v[178:181], v[194:197], v[96:99]
	v_mfma_f32_16x16x32_bf16 v[84:87], v[170:173], v[202:205], v[84:87]
	v_mfma_f32_16x16x32_bf16 v[80:83], v[178:181], v[202:205], v[80:83]
	v_mfma_f32_16x16x32_bf16 v[68:71], v[170:173], v[210:213], v[68:71]
	v_mfma_f32_16x16x32_bf16 v[64:67], v[178:181], v[210:213], v[64:67]
	s_barrier
	s_add_i32 s68, s41, s2
	v_lshl_add_u64 v[214:215], s[8:9], 0, v[130:131]
	s_mov_b32 m0, s68
	ds_read_b128 v[182:185], v153 offset:16384
	ds_read_b128 v[186:189], v153 offset:17408
	ds_read_b128 v[190:193], v153 offset:18432
	ds_read_b128 v[194:197], v153 offset:19456
	ds_read_b128 v[198:201], v153 offset:20480
	ds_read_b128 v[202:205], v153 offset:21504
	ds_read_b128 v[206:209], v153 offset:22528
	ds_read_b128 v[210:213], v153 offset:23552
	global_load_lds_dwordx4 v[214:215], off
	s_add_i32 m0, s68, 0x2000
	s_add_u32 s68, s8, 0x80000
	v_lshl_add_u64 v[216:217], s[8:9], 0, v[134:135]
	s_addc_u32 s69, s9, 0
	s_add_i32 s70, s42, s2
	global_load_lds_dwordx4 v[216:217], off
	v_lshl_add_u64 v[218:219], s[68:69], 0, v[130:131]
	s_mov_b32 m0, s70
	v_lshl_add_u64 v[220:221], s[64:65], 0, v[132:133]
	global_load_lds_dwordx4 v[218:219], off
	s_add_i32 m0, s70, 0x2000
	v_lshl_add_u64 v[218:219], s[68:69], 0, v[134:135]
	global_load_lds_dwordx4 v[218:219], off
	s_mov_b32 m0, s3
	v_lshl_add_u64 v[218:219], s[64:65], 0, v[128:129]
	global_load_lds_dwordx4 v[218:219], off
	s_mov_b32 m0, s28
	s_nop 0
	global_load_lds_dwordx4 v[220:221], off
	s_waitcnt vmcnt(8) lgkmcnt(0)
	s_barrier
; #define PG8_STAGE(bufoff, gbase, voff) do { _Pragma("unroll") for (int _i = 0; _i < 2; ++_i) \
;         __builtin_amdgcn_global_load_lds((const unsigned*)((const char*)(gbase) + (voff)[_i]), (LAS unsigned*)(lds + (bufoff) + ldsw + _i * 8192), 16, 0, 0); } while (0)
; #define PG8_LDA(dst, b, h) do { _Pragma("unroll") for (int m = 0; m < 4; ++m) _Pragma("unroll") for (int k = 0; k < 2; ++k) dst[m][k] = *(const LAS bf16x8*)(lds + PG8_SA(b, h) + aoff + m * 2048 + k * 1024); } while (0)
; #define PG8_LDB(dst, b, h) do { _Pragma("unroll") for (int n = 0; n < 2; ++n) _Pragma("unroll") for (int k = 0; k < 2; ++k) dst[n][k] = *(const LAS bf16x8*)(lds + PG8_SB(b, h) + boff + n * 2048 + k * 1024); } while (0)
; #define PG8_MMA(ai, bj, At, Bt) do { __builtin_amdgcn_s_setprio(1); _Pragma("unroll") for (int m = 0; m < 4; ++m) _Pragma("unroll") for (int n = 0; n < 2; ++n) _Pragma("unroll") for (int k = 0; k < 2; ++k) \
;         acc[ai][bj][m][n] = __builtin_amdgcn_mfma_f32_16x16x32_bf16(Bt[n][k], At[m][k], acc[ai][bj][m][n], 0, 0, 0); __builtin_amdgcn_s_setprio(0); } while (0)
; #define PG8_WAIT_V(n) asm volatile("s_waitcnt vmcnt(" #n ")" ::: "memory")
; #define PG8_WAIT_L(n) asm volatile("s_waitcnt lgkmcnt(" #n ")" ::: "memory")
; #define PG8_BAR __builtin_amdgcn_s_barrier()
; #define PG8_SCHED __builtin_amdgcn_sched_barrier(0)
; template <class Desc, class Epi>
; DI void gemm_phase(LAS unsigned char* lds, const Desc& D, const Epi& E, int wv) {
;     ...
;             PG8_WAIT_V(8); PG8_WAIT_L(0); PG8_BAR; PG8_MMA(1, 0, At, B0); PG8_MMA(1, 1, At, B1); PG8_BAR; PG8_SCHED;
;             PG8_LDB(B0, 1, 0); PG8_LDB(B1, 1, 1); PG8_SCHED; PG8_LDA(At, 1, 0); PG8_STAGE(PG8_SA(0, 1), a2 + hstepA, voffA);
;             PG8_WAIT_V(8); PG8_WAIT_L(0); PG8_BAR; PG8_MMA(0, 0, At, B0); PG8_MMA(0, 1, At, B1); PG8_BAR; PG8_SCHED;
	v_mfma_f32_16x16x32_bf16 v[60:63], v[142:145], v[182:185], v[60:63]
	v_mfma_f32_16x16x32_bf16 v[56:59], v[158:161], v[182:185], v[56:59]
	v_mfma_f32_16x16x32_bf16 v[44:47], v[142:145], v[190:193], v[44:47]
	v_mfma_f32_16x16x32_bf16 v[40:43], v[158:161], v[190:193], v[40:43]
	v_mfma_f32_16x16x32_bf16 v[28:31], v[142:145], v[198:201], v[28:31]
	v_mfma_f32_16x16x32_bf16 v[24:27], v[158:161], v[198:201], v[24:27]
	v_mfma_f32_16x16x32_bf16 v[12:15], v[142:145], v[206:209], v[12:15]
	v_mfma_f32_16x16x32_bf16 v[8:11], v[158:161], v[206:209], v[8:11]
	v_mfma_f32_16x16x32_bf16 v[60:63], v[146:149], v[186:189], v[60:63]
	v_mfma_f32_16x16x32_bf16 v[56:59], v[162:165], v[186:189], v[56:59]
	v_mfma_f32_16x16x32_bf16 v[44:47], v[146:149], v[194:197], v[44:47]
	v_mfma_f32_16x16x32_bf16 v[40:43], v[162:165], v[194:197], v[40:43]
	v_mfma_f32_16x16x32_bf16 v[28:31], v[146:149], v[202:205], v[28:31]
	v_mfma_f32_16x16x32_bf16 v[24:27], v[162:165], v[202:205], v[24:27]
	v_mfma_f32_16x16x32_bf16 v[12:15], v[146:149], v[210:213], v[12:15]
	v_mfma_f32_16x16x32_bf16 v[8:11], v[162:165], v[210:213], v[8:11]
	v_mfma_f32_16x16x32_bf16 v[52:55], v[166:169], v[182:185], v[52:55]
	v_mfma_f32_16x16x32_bf16 v[48:51], v[174:177], v[182:185], v[48:51]
	v_mfma_f32_16x16x32_bf16 v[36:39], v[166:169], v[190:193], v[36:39]
	v_mfma_f32_16x16x32_bf16 v[32:35], v[174:177], v[190:193], v[32:35]
	v_mfma_f32_16x16x32_bf16 v[20:23], v[166:169], v[198:201], v[20:23]
	v_mfma_f32_16x16x32_bf16 v[16:19], v[174:177], v[198:201], v[16:19]
	v_mfma_f32_16x16x32_bf16 v[4:7], v[166:169], v[206:209], v[4:7]
	v_mfma_f32_16x16x32_bf16 v[0:3], v[174:177], v[206:209], v[0:3]
	v_mfma_f32_16x16x32_bf16 v[52:55], v[170:173], v[186:189], v[52:55]
	v_mfma_f32_16x16x32_bf16 v[48:51], v[178:181], v[186:189], v[48:51]
	v_mfma_f32_16x16x32_bf16 v[36:39], v[170:173], v[194:197], v[36:39]
	v_mfma_f32_16x16x32_bf16 v[32:35], v[178:181], v[194:197], v[32:35]
	v_mfma_f32_16x16x32_bf16 v[20:23], v[170:173], v[202:205], v[20:23]
	v_mfma_f32_16x16x32_bf16 v[16:19], v[178:181], v[202:205], v[16:19]
	v_mfma_f32_16x16x32_bf16 v[4:7], v[170:173], v[210:213], v[4:7]
	v_mfma_f32_16x16x32_bf16 v[0:3], v[178:181], v[210:213], v[0:3]
	s_barrier
	s_add_i32 s68, 0, 0x18000
	v_add_u32_e32 v136, s68, v150
	s_add_i32 s69, 0, 0x1c000
	ds_read_b128 v[142:145], v136
	ds_read_b128 v[146:149], v136 offset:1024
	ds_read_b128 v[158:161], v136 offset:2048
	ds_read_b128 v[162:165], v136 offset:3072
	v_add_u32_e32 v136, s69, v150
	ds_read_b128 v[166:169], v136
	ds_read_b128 v[170:173], v136 offset:1024
	ds_read_b128 v[174:177], v136 offset:2048
	ds_read_b128 v[178:181], v136 offset:3072
	s_add_u32 s64, s64, 0x20000
	s_addc_u32 s65, s65, 0
	s_mov_b32 m0, s29
	v_lshl_add_u64 v[222:223], s[64:65], 0, v[128:129]
	ds_read_b128 v[182:185], v153 offset:32768
	ds_read_b128 v[186:189], v153 offset:33792
	ds_read_b128 v[190:193], v153 offset:34816
	ds_read_b128 v[194:197], v153 offset:35840
	ds_read_b128 v[198:201], v153 offset:36864
	ds_read_b128 v[202:205], v153 offset:37888
	ds_read_b128 v[206:209], v153 offset:38912
	ds_read_b128 v[210:213], v153 offset:39936
	global_load_lds_dwordx4 v[222:223], off
	s_mov_b32 m0, s30
	v_lshl_add_u64 v[222:223], s[64:65], 0, v[132:133]
	global_load_lds_dwordx4 v[222:223], off
	s_waitcnt vmcnt(8) lgkmcnt(0)
	s_barrier
	v_mfma_f32_16x16x32_bf16 v[124:127], v[142:145], v[182:185], v[124:127]
	v_mfma_f32_16x16x32_bf16 v[120:123], v[158:161], v[182:185], v[120:123]
	v_mfma_f32_16x16x32_bf16 v[108:111], v[142:145], v[190:193], v[108:111]
	v_mfma_f32_16x16x32_bf16 v[104:107], v[158:161], v[190:193], v[104:107]
	v_mfma_f32_16x16x32_bf16 v[92:95], v[142:145], v[198:201], v[92:95]
	v_mfma_f32_16x16x32_bf16 v[88:91], v[158:161], v[198:201], v[88:91]
	v_mfma_f32_16x16x32_bf16 v[76:79], v[142:145], v[206:209], v[76:79]
	v_mfma_f32_16x16x32_bf16 v[72:75], v[158:161], v[206:209], v[72:75]
	v_mfma_f32_16x16x32_bf16 v[124:127], v[146:149], v[186:189], v[124:127]
	v_mfma_f32_16x16x32_bf16 v[120:123], v[162:165], v[186:189], v[120:123]
	v_mfma_f32_16x16x32_bf16 v[108:111], v[146:149], v[194:197], v[108:111]
	v_mfma_f32_16x16x32_bf16 v[104:107], v[162:165], v[194:197], v[104:107]
	v_mfma_f32_16x16x32_bf16 v[92:95], v[146:149], v[202:205], v[92:95]
	v_mfma_f32_16x16x32_bf16 v[88:91], v[162:165], v[202:205], v[88:91]
	v_mfma_f32_16x16x32_bf16 v[76:79], v[146:149], v[210:213], v[76:79]
	v_mfma_f32_16x16x32_bf16 v[72:75], v[162:165], v[210:213], v[72:75]
	v_mfma_f32_16x16x32_bf16 v[116:119], v[166:169], v[182:185], v[116:119]
	v_mfma_f32_16x16x32_bf16 v[112:115], v[174:177], v[182:185], v[112:115]
	v_mfma_f32_16x16x32_bf16 v[100:103], v[166:169], v[190:193], v[100:103]
	v_mfma_f32_16x16x32_bf16 v[96:99], v[174:177], v[190:193], v[96:99]
	v_mfma_f32_16x16x32_bf16 v[84:87], v[166:169], v[198:201], v[84:87]
	v_mfma_f32_16x16x32_bf16 v[80:83], v[174:177], v[198:201], v[80:83]
	v_mfma_f32_16x16x32_bf16 v[68:71], v[166:169], v[206:209], v[68:71]
	v_mfma_f32_16x16x32_bf16 v[64:67], v[174:177], v[206:209], v[64:67]
	v_mfma_f32_16x16x32_bf16 v[116:119], v[170:173], v[186:189], v[116:119]
	v_mfma_f32_16x16x32_bf16 v[112:115], v[178:181], v[186:189], v[112:115]
	v_mfma_f32_16x16x32_bf16 v[100:103], v[170:173], v[194:197], v[100:103]
	v_mfma_f32_16x16x32_bf16 v[96:99], v[178:181], v[194:197], v[96:99]
	v_mfma_f32_16x16x32_bf16 v[84:87], v[170:173], v[202:205], v[84:87]
	v_mfma_f32_16x16x32_bf16 v[80:83], v[178:181], v[202:205], v[80:83]
	v_mfma_f32_16x16x32_bf16 v[68:71], v[170:173], v[210:213], v[68:71]
	v_mfma_f32_16x16x32_bf16 v[64:67], v[178:181], v[210:213], v[64:67]
	s_barrier
; #define PG8_STAGE(bufoff, gbase, voff) do { _Pragma("unroll") for (int _i = 0; _i < 2; ++_i) \
;         __builtin_amdgcn_global_load_lds((const unsigned*)((const char*)(gbase) + (voff)[_i]), (LAS unsigned*)(lds + (bufoff) + ldsw + _i * 8192), 16, 0, 0); } while (0)
; #define PG8_LDA(dst, b, h) do { _Pragma("unroll") for (int m = 0; m < 4; ++m) _Pragma("unroll") for (int k = 0; k < 2; ++k) dst[m][k] = *(const LAS bf16x8*)(lds + PG8_SA(b, h) + aoff + m * 2048 + k * 1024); } while (0)
; #define PG8_MMA(ai, bj, At, Bt) do { __builtin_amdgcn_s_setprio(1); _Pragma("unroll") for (int m = 0; m < 4; ++m) _Pragma("unroll") for (int n = 0; n < 2; ++n) _Pragma("unroll") for (int k = 0; k < 2; ++k) \
;         acc[ai][bj][m][n] = __builtin_amdgcn_mfma_f32_16x16x32_bf16(Bt[n][k], At[m][k], acc[ai][bj][m][n], 0, 0, 0); __builtin_amdgcn_s_setprio(0); } while (0)
; #define PG8_WAIT_V(n) asm volatile("s_waitcnt vmcnt(" #n ")" ::: "memory")
; #define PG8_WAIT_L(n) asm volatile("s_waitcnt lgkmcnt(" #n ")" ::: "memory")
; #define PG8_BAR __builtin_amdgcn_s_barrier()
; #define PG8_SCHED __builtin_amdgcn_sched_barrier(0)
; template <class Desc, class Epi>
; DI void gemm_phase(LAS unsigned char* lds, const Desc& D, const Epi& E, int wv) {
;     ...
;             PG8_LDA(At, 1, 1); PG8_STAGE(PG8_SB(1, 0), b3, voffB); PG8_STAGE(PG8_SB(1, 1), b3 + hstepB, voffB); PG8_STAGE(PG8_SA(1, 0), a3, voffA);
;             PG8_WAIT_V(8); PG8_WAIT_L(0); PG8_BAR; PG8_MMA(1, 0, At, B0); PG8_MMA(1, 1, At, B1); PG8_BAR; PG8_SCHED;
;         }
;         if (wr == 0) PG8_BAR;
	s_add_i32 s64, s68, s2
	v_lshl_add_u64 v[214:215], v[214:215], 0, s[20:21]
	s_mov_b32 m0, s64
	ds_read_b128 v[182:185], v153 offset:49152
	ds_read_b128 v[186:189], v153 offset:50176
	ds_read_b128 v[190:193], v153 offset:51200
	ds_read_b128 v[194:197], v153 offset:52224
	ds_read_b128 v[198:201], v153 offset:53248
	ds_read_b128 v[202:205], v153 offset:54272
	ds_read_b128 v[206:209], v153 offset:55296
	ds_read_b128 v[210:213], v153 offset:56320
	global_load_lds_dwordx4 v[214:215], off
	s_add_i32 m0, s64, 0x2000
	s_add_u32 s8, s8, 0x80080
	v_lshl_add_u64 v[214:215], v[216:217], 0, s[20:21]
	s_addc_u32 s9, s9, 0
	s_add_i32 s64, s69, s2
	global_load_lds_dwordx4 v[214:215], off
	s_mov_b32 m0, s64
	v_lshl_add_u64 v[214:215], s[8:9], 0, v[130:131]
	global_load_lds_dwordx4 v[214:215], off
	s_add_i32 m0, s64, 0x2000
	v_lshl_add_u64 v[214:215], s[8:9], 0, v[134:135]
	global_load_lds_dwordx4 v[214:215], off
	s_mov_b32 m0, s35
	v_lshl_add_u64 v[214:215], v[218:219], 0, s[20:21]
	global_load_lds_dwordx4 v[214:215], off
	s_mov_b32 m0, s40
	v_lshl_add_u64 v[214:215], v[220:221], 0, s[20:21]
	global_load_lds_dwordx4 v[214:215], off
	s_waitcnt vmcnt(8) lgkmcnt(0)
	s_barrier
	v_mfma_f32_16x16x32_bf16 v[60:63], v[142:145], v[182:185], v[60:63]
	v_mfma_f32_16x16x32_bf16 v[56:59], v[158:161], v[182:185], v[56:59]
	v_mfma_f32_16x16x32_bf16 v[44:47], v[142:145], v[190:193], v[44:47]
	v_mfma_f32_16x16x32_bf16 v[40:43], v[158:161], v[190:193], v[40:43]
	v_mfma_f32_16x16x32_bf16 v[28:31], v[142:145], v[198:201], v[28:31]
	v_mfma_f32_16x16x32_bf16 v[24:27], v[158:161], v[198:201], v[24:27]
	v_mfma_f32_16x16x32_bf16 v[12:15], v[142:145], v[206:209], v[12:15]
	v_mfma_f32_16x16x32_bf16 v[8:11], v[158:161], v[206:209], v[8:11]
	v_mfma_f32_16x16x32_bf16 v[60:63], v[146:149], v[186:189], v[60:63]
	v_mfma_f32_16x16x32_bf16 v[56:59], v[162:165], v[186:189], v[56:59]
	v_mfma_f32_16x16x32_bf16 v[44:47], v[146:149], v[194:197], v[44:47]
	v_mfma_f32_16x16x32_bf16 v[40:43], v[162:165], v[194:197], v[40:43]
	v_mfma_f32_16x16x32_bf16 v[28:31], v[146:149], v[202:205], v[28:31]
	v_mfma_f32_16x16x32_bf16 v[24:27], v[162:165], v[202:205], v[24:27]
	v_mfma_f32_16x16x32_bf16 v[12:15], v[146:149], v[210:213], v[12:15]
	v_mfma_f32_16x16x32_bf16 v[8:11], v[162:165], v[210:213], v[8:11]
	v_mfma_f32_16x16x32_bf16 v[52:55], v[166:169], v[182:185], v[52:55]
	v_mfma_f32_16x16x32_bf16 v[48:51], v[174:177], v[182:185], v[48:51]
	v_mfma_f32_16x16x32_bf16 v[36:39], v[166:169], v[190:193], v[36:39]
	v_mfma_f32_16x16x32_bf16 v[32:35], v[174:177], v[190:193], v[32:35]
	v_mfma_f32_16x16x32_bf16 v[20:23], v[166:169], v[198:201], v[20:23]
	v_mfma_f32_16x16x32_bf16 v[16:19], v[174:177], v[198:201], v[16:19]
	v_mfma_f32_16x16x32_bf16 v[4:7], v[166:169], v[206:209], v[4:7]
	v_mfma_f32_16x16x32_bf16 v[0:3], v[174:177], v[206:209], v[0:3]
	v_mfma_f32_16x16x32_bf16 v[52:55], v[170:173], v[186:189], v[52:55]
	v_mfma_f32_16x16x32_bf16 v[48:51], v[178:181], v[186:189], v[48:51]
	v_mfma_f32_16x16x32_bf16 v[36:39], v[170:173], v[194:197], v[36:39]
	v_mfma_f32_16x16x32_bf16 v[32:35], v[178:181], v[194:197], v[32:35]
	v_mfma_f32_16x16x32_bf16 v[20:23], v[170:173], v[202:205], v[20:23]
	v_mfma_f32_16x16x32_bf16 v[16:19], v[178:181], v[202:205], v[16:19]
	v_mfma_f32_16x16x32_bf16 v[4:7], v[170:173], v[210:213], v[4:7]
	v_mfma_f32_16x16x32_bf16 v[0:3], v[178:181], v[210:213], v[0:3]
	s_barrier
	s_add_i32 s67, s67, 2
	s_add_u32 s6, s6, 0x100
	s_addc_u32 s7, s7, 0
	s_add_u32 s53, s53, 0x100
	s_addc_u32 s66, s66, 0
	s_cmp_gt_u32 s67, 5
	s_cbranch_scc0 .LBB0_339
	s_and_b64 vcc, exec, s[22:23]
	s_cbranch_vccz .LBB0_342
	s_barrier

; #define PG8_STAGE(bufoff, gbase, voff) do { _Pragma("unroll") for (int _i = 0; _i < 2; ++_i) \
;         __builtin_amdgcn_global_load_lds((const unsigned*)((const char*)(gbase) + (voff)[_i]), (LAS unsigned*)(lds + (bufoff) + ldsw + _i * 8192), 16, 0, 0); } while (0)
; #define PG8_LDA(dst, b, h) do { _Pragma("unroll") for (int m = 0; m < 4; ++m) _Pragma("unroll") for (int k = 0; k < 2; ++k) dst[m][k] = *(const LAS bf16x8*)(lds + PG8_SA(b, h) + aoff + m * 2048 + k * 1024); } while (0)
; #define PG8_LDB(dst, b, h) do { _Pragma("unroll") for (int n = 0; n < 2; ++n) _Pragma("unroll") for (int k = 0; k < 2; ++k) dst[n][k] = *(const LAS bf16x8*)(lds + PG8_SB(b, h) + boff + n * 2048 + k * 1024); } while (0)
; #define PG8_MMA(ai, bj, At, Bt) do { __builtin_amdgcn_s_setprio(1); _Pragma("unroll") for (int m = 0; m < 4; ++m) _Pragma("unroll") for (int n = 0; n < 2; ++n) _Pragma("unroll") for (int k = 0; k < 2; ++k) \
;         acc[ai][bj][m][n] = __builtin_amdgcn_mfma_f32_16x16x32_bf16(Bt[n][k], At[m][k], acc[ai][bj][m][n], 0, 0, 0); __builtin_amdgcn_s_setprio(0); } while (0)
; #define PG8_WAIT_V(n) asm volatile("s_waitcnt vmcnt(" #n ")" ::: "memory")
; #define PG8_WAIT_L(n) asm volatile("s_waitcnt lgkmcnt(" #n ")" ::: "memory")
; #define PG8_BAR __builtin_amdgcn_s_barrier()
; #define PG8_SCHED __builtin_amdgcn_sched_barrier(0)
; template <class Desc, class Epi>
; DI void gemm_phase(LAS unsigned char* lds, const Desc& D, const Epi& E, int wv) {
;     ...
;         for (int t = 0; t < nt; t += 2) {
;             const bool last = (t == nt - 2);
;             const char* a1 = cA + (size_t)(t + 1) * kstep;
;             const char* a2 = last ? nA : cA + (size_t)(t + 2) * kstep; const char* b2 = last ? nB : cB + (size_t)(t + 2) * kstep;
;             const char* a3 = a2 + kstep; const char* b3 = b2 + kstep;
;             PG8_LDB(B0, 0, 0); PG8_LDB(B1, 0, 1); PG8_SCHED; PG8_LDA(At, 0, 0); PG8_STAGE(PG8_SA(1, 1), a1 + hstepA, voffA);
;             PG8_WAIT_V(8); PG8_WAIT_L(0); PG8_BAR; PG8_MMA(0, 0, At, B0); PG8_MMA(0, 1, At, B1); PG8_BAR; PG8_SCHED;
;             PG8_LDA(At, 0, 1); PG8_STAGE(PG8_SB(0, 0), b2, voffB); PG8_STAGE(PG8_SB(0, 1), b2 + hstepB, voffB); PG8_STAGE(PG8_SA(0, 0), a2, voffA);
.LBB0_581:
	ds_read_b128 v[128:131], v185
	ds_read_b128 v[132:135], v185 offset:1024
	ds_read_b128 v[150:153], v185 offset:2048
	ds_read_b128 v[154:157], v185 offset:3072
	ds_read_b128 v[158:161], v186
	ds_read_b128 v[162:165], v186 offset:1024
	ds_read_b128 v[166:169], v186 offset:2048
	ds_read_b128 v[170:173], v186 offset:3072
	s_add_u32 s49, s66, 0xfff00080
	s_addc_u32 s50, s67, -1
	s_cmp_eq_u32 s48, 28
	s_cselect_b32 s71, s19, s50
	s_cselect_b32 s70, s18, s49
	s_cselect_b32 s69, s21, s47
	s_cselect_b32 s68, s20, s1
	v_lshl_add_u64 v[182:183], s[66:67], 0, v[146:147]
	s_add_i32 m0, s3, 0xc000
	ds_read_b128 v[174:177], v187
	ds_read_b128 v[178:181], v187 offset:1024
	ds_read_b128 v[190:193], v187 offset:2048
	ds_read_b128 v[194:197], v187 offset:3072
	ds_read_b128 v[198:201], v187 offset:4096
	ds_read_b128 v[202:205], v187 offset:5120
	ds_read_b128 v[206:209], v187 offset:6144
	ds_read_b128 v[210:213], v187 offset:7168
	global_load_lds_dwordx4 v[182:183], off
	s_add_i32 m0, s3, 0xe000
	v_lshl_add_u64 v[182:183], s[66:67], 0, v[148:149]
	global_load_lds_dwordx4 v[182:183], off
	s_waitcnt vmcnt(8) lgkmcnt(0)
	s_barrier
	v_mfma_f32_16x16x32_bf16 v[124:127], v[128:131], v[174:177], v[124:127]
	v_mfma_f32_16x16x32_bf16 v[120:123], v[150:153], v[174:177], v[120:123]
	v_mfma_f32_16x16x32_bf16 v[108:111], v[128:131], v[190:193], v[108:111]
	v_mfma_f32_16x16x32_bf16 v[104:107], v[150:153], v[190:193], v[104:107]
	v_mfma_f32_16x16x32_bf16 v[92:95], v[128:131], v[198:201], v[92:95]
	v_mfma_f32_16x16x32_bf16 v[88:91], v[150:153], v[198:201], v[88:91]
	v_mfma_f32_16x16x32_bf16 v[76:79], v[128:131], v[206:209], v[76:79]
	v_mfma_f32_16x16x32_bf16 v[72:75], v[150:153], v[206:209], v[72:75]
	v_mfma_f32_16x16x32_bf16 v[124:127], v[132:135], v[178:181], v[124:127]
	v_mfma_f32_16x16x32_bf16 v[120:123], v[154:157], v[178:181], v[120:123]
	v_mfma_f32_16x16x32_bf16 v[108:111], v[132:135], v[194:197], v[108:111]
	v_mfma_f32_16x16x32_bf16 v[104:107], v[154:157], v[194:197], v[104:107]
	v_mfma_f32_16x16x32_bf16 v[92:95], v[132:135], v[202:205], v[92:95]
	v_mfma_f32_16x16x32_bf16 v[88:91], v[154:157], v[202:205], v[88:91]
	v_mfma_f32_16x16x32_bf16 v[76:79], v[132:135], v[210:213], v[76:79]
	v_mfma_f32_16x16x32_bf16 v[72:75], v[154:157], v[210:213], v[72:75]
	v_mfma_f32_16x16x32_bf16 v[116:119], v[158:161], v[174:177], v[116:119]
	v_mfma_f32_16x16x32_bf16 v[112:115], v[166:169], v[174:177], v[112:115]
	v_mfma_f32_16x16x32_bf16 v[100:103], v[158:161], v[190:193], v[100:103]
	v_mfma_f32_16x16x32_bf16 v[96:99], v[166:169], v[190:193], v[96:99]
	v_mfma_f32_16x16x32_bf16 v[84:87], v[158:161], v[198:201], v[84:87]
	v_mfma_f32_16x16x32_bf16 v[80:83], v[166:169], v[198:201], v[80:83]
	v_mfma_f32_16x16x32_bf16 v[68:71], v[158:161], v[206:209], v[68:71]
	v_mfma_f32_16x16x32_bf16 v[64:67], v[166:169], v[206:209], v[64:67]
	v_mfma_f32_16x16x32_bf16 v[116:119], v[162:165], v[178:181], v[116:119]
	v_mfma_f32_16x16x32_bf16 v[112:115], v[170:173], v[178:181], v[112:115]
	v_mfma_f32_16x16x32_bf16 v[100:103], v[162:165], v[194:197], v[100:103]
	v_mfma_f32_16x16x32_bf16 v[96:99], v[170:173], v[194:197], v[96:99]
	v_mfma_f32_16x16x32_bf16 v[84:87], v[162:165], v[202:205], v[84:87]
	v_mfma_f32_16x16x32_bf16 v[80:83], v[170:173], v[202:205], v[80:83]
	v_mfma_f32_16x16x32_bf16 v[68:71], v[162:165], v[210:213], v[68:71]
	v_mfma_f32_16x16x32_bf16 v[64:67], v[170:173], v[210:213], v[64:67]
	s_barrier
	s_add_i32 s49, s42, s2
	v_lshl_add_u64 v[182:183], s[68:69], 0, v[140:141]
	s_mov_b32 m0, s49
	ds_read_b128 v[174:177], v187 offset:16384
	ds_read_b128 v[178:181], v187 offset:17408
	ds_read_b128 v[190:193], v187 offset:18432
	ds_read_b128 v[194:197], v187 offset:19456
	ds_read_b128 v[198:201], v187 offset:20480
	ds_read_b128 v[202:205], v187 offset:21504
	ds_read_b128 v[206:209], v187 offset:22528
	ds_read_b128 v[210:213], v187 offset:23552
	global_load_lds_dwordx4 v[182:183], off
	s_add_i32 m0, s49, 0x2000
	s_add_u32 s50, s68, 0x100000
	v_lshl_add_u64 v[214:215], s[68:69], 0, v[136:137]
	s_addc_u32 s51, s69, 0
	s_add_i32 s49, s43, s2
	global_load_lds_dwordx4 v[214:215], off
	v_lshl_add_u64 v[216:217], s[50:51], 0, v[140:141]
	s_mov_b32 m0, s49
	v_lshl_add_u64 v[218:219], s[70:71], 0, v[138:139]
	global_load_lds_dwordx4 v[216:217], off
	s_add_i32 m0, s49, 0x2000
	v_lshl_add_u64 v[216:217], s[50:51], 0, v[136:137]
	global_load_lds_dwordx4 v[216:217], off
	s_mov_b32 m0, s3
	v_lshl_add_u64 v[216:217], s[70:71], 0, v[142:143]
	global_load_lds_dwordx4 v[216:217], off
	s_mov_b32 m0, s28
	s_nop 0
	global_load_lds_dwordx4 v[218:219], off
	s_waitcnt vmcnt(8) lgkmcnt(0)
	s_barrier
; #define PG8_STAGE(bufoff, gbase, voff) do { _Pragma("unroll") for (int _i = 0; _i < 2; ++_i) \
;         __builtin_amdgcn_global_load_lds((const unsigned*)((const char*)(gbase) + (voff)[_i]), (LAS unsigned*)(lds + (bufoff) + ldsw + _i * 8192), 16, 0, 0); } while (0)
; #define PG8_LDA(dst, b, h) do { _Pragma("unroll") for (int m = 0; m < 4; ++m) _Pragma("unroll") for (int k = 0; k < 2; ++k) dst[m][k] = *(const LAS bf16x8*)(lds + PG8_SA(b, h) + aoff + m * 2048 + k * 1024); } while (0)
; #define PG8_LDB(dst, b, h) do { _Pragma("unroll") for (int n = 0; n < 2; ++n) _Pragma("unroll") for (int k = 0; k < 2; ++k) dst[n][k] = *(const LAS bf16x8*)(lds + PG8_SB(b, h) + boff + n * 2048 + k * 1024); } while (0)
; #define PG8_MMA(ai, bj, At, Bt) do { __builtin_amdgcn_s_setprio(1); _Pragma("unroll") for (int m = 0; m < 4; ++m) _Pragma("unroll") for (int n = 0; n < 2; ++n) _Pragma("unroll") for (int k = 0; k < 2; ++k) \
;         acc[ai][bj][m][n] = __builtin_amdgcn_mfma_f32_16x16x32_bf16(Bt[n][k], At[m][k], acc[ai][bj][m][n], 0, 0, 0); __builtin_amdgcn_s_setprio(0); } while (0)
; #define PG8_WAIT_V(n) asm volatile("s_waitcnt vmcnt(" #n ")" ::: "memory")
; #define PG8_WAIT_L(n) asm volatile("s_waitcnt lgkmcnt(" #n ")" ::: "memory")
; #define PG8_BAR __builtin_amdgcn_s_barrier()
; #define PG8_SCHED __builtin_amdgcn_sched_barrier(0)
; template <class Desc, class Epi>
; DI void gemm_phase(LAS unsigned char* lds, const Desc& D, const Epi& E, int wv) {
;     ...
;             PG8_WAIT_V(8); PG8_WAIT_L(0); PG8_BAR; PG8_MMA(1, 0, At, B0); PG8_MMA(1, 1, At, B1); PG8_BAR; PG8_SCHED;
;             PG8_LDB(B0, 1, 0); PG8_LDB(B1, 1, 1); PG8_SCHED; PG8_LDA(At, 1, 0); PG8_STAGE(PG8_SA(0, 1), a2 + hstepA, voffA);
;             PG8_WAIT_V(8); PG8_WAIT_L(0); PG8_BAR; PG8_MMA(0, 0, At, B0); PG8_MMA(0, 1, At, B1); PG8_BAR; PG8_SCHED;
;             PG8_LDA(At, 1, 1); PG8_STAGE(PG8_SB(1, 0), b3, voffB); PG8_STAGE(PG8_SB(1, 1), b3 + hstepB, voffB); PG8_STAGE(PG8_SA(1, 0), a3, voffA);
	v_mfma_f32_16x16x32_bf16 v[60:63], v[128:131], v[174:177], v[60:63]
	v_mfma_f32_16x16x32_bf16 v[56:59], v[150:153], v[174:177], v[56:59]
	v_mfma_f32_16x16x32_bf16 v[44:47], v[128:131], v[190:193], v[44:47]
	v_mfma_f32_16x16x32_bf16 v[40:43], v[150:153], v[190:193], v[40:43]
	v_mfma_f32_16x16x32_bf16 v[28:31], v[128:131], v[198:201], v[28:31]
	v_mfma_f32_16x16x32_bf16 v[24:27], v[150:153], v[198:201], v[24:27]
	v_mfma_f32_16x16x32_bf16 v[12:15], v[128:131], v[206:209], v[12:15]
	v_mfma_f32_16x16x32_bf16 v[8:11], v[150:153], v[206:209], v[8:11]
	v_mfma_f32_16x16x32_bf16 v[60:63], v[132:135], v[178:181], v[60:63]
	v_mfma_f32_16x16x32_bf16 v[56:59], v[154:157], v[178:181], v[56:59]
	v_mfma_f32_16x16x32_bf16 v[44:47], v[132:135], v[194:197], v[44:47]
	v_mfma_f32_16x16x32_bf16 v[40:43], v[154:157], v[194:197], v[40:43]
	v_mfma_f32_16x16x32_bf16 v[28:31], v[132:135], v[202:205], v[28:31]
	v_mfma_f32_16x16x32_bf16 v[24:27], v[154:157], v[202:205], v[24:27]
	v_mfma_f32_16x16x32_bf16 v[12:15], v[132:135], v[210:213], v[12:15]
	v_mfma_f32_16x16x32_bf16 v[8:11], v[154:157], v[210:213], v[8:11]
	v_mfma_f32_16x16x32_bf16 v[52:55], v[158:161], v[174:177], v[52:55]
	v_mfma_f32_16x16x32_bf16 v[48:51], v[166:169], v[174:177], v[48:51]
	v_mfma_f32_16x16x32_bf16 v[36:39], v[158:161], v[190:193], v[36:39]
	v_mfma_f32_16x16x32_bf16 v[32:35], v[166:169], v[190:193], v[32:35]
	v_mfma_f32_16x16x32_bf16 v[20:23], v[158:161], v[198:201], v[20:23]
	v_mfma_f32_16x16x32_bf16 v[16:19], v[166:169], v[198:201], v[16:19]
	v_mfma_f32_16x16x32_bf16 v[4:7], v[158:161], v[206:209], v[4:7]
	v_mfma_f32_16x16x32_bf16 v[0:3], v[166:169], v[206:209], v[0:3]
	v_mfma_f32_16x16x32_bf16 v[52:55], v[162:165], v[178:181], v[52:55]
	v_mfma_f32_16x16x32_bf16 v[48:51], v[170:173], v[178:181], v[48:51]
	v_mfma_f32_16x16x32_bf16 v[36:39], v[162:165], v[194:197], v[36:39]
	v_mfma_f32_16x16x32_bf16 v[32:35], v[170:173], v[194:197], v[32:35]
	v_mfma_f32_16x16x32_bf16 v[20:23], v[162:165], v[202:205], v[20:23]
	v_mfma_f32_16x16x32_bf16 v[16:19], v[170:173], v[202:205], v[16:19]
	v_mfma_f32_16x16x32_bf16 v[4:7], v[162:165], v[210:213], v[4:7]
	v_mfma_f32_16x16x32_bf16 v[0:3], v[170:173], v[210:213], v[0:3]
	s_barrier
	s_add_i32 s49, 0, 0x18000
	v_add_u32_e32 v144, s49, v184
	s_add_i32 s52, 0, 0x1c000
	ds_read_b128 v[128:131], v144
	ds_read_b128 v[132:135], v144 offset:1024
	ds_read_b128 v[150:153], v144 offset:2048
	ds_read_b128 v[154:157], v144 offset:3072
	v_add_u32_e32 v144, s52, v184
	ds_read_b128 v[158:161], v144
	ds_read_b128 v[162:165], v144 offset:1024
	ds_read_b128 v[166:169], v144 offset:2048
	ds_read_b128 v[170:173], v144 offset:3072
	s_add_u32 s50, s70, 0x100000
	s_addc_u32 s51, s71, 0
	s_mov_b32 m0, s29
	v_lshl_add_u64 v[220:221], s[50:51], 0, v[142:143]
	ds_read_b128 v[174:177], v187 offset:32768
	ds_read_b128 v[178:181], v187 offset:33792
	ds_read_b128 v[190:193], v187 offset:34816
	ds_read_b128 v[194:197], v187 offset:35840
	ds_read_b128 v[198:201], v187 offset:36864
	ds_read_b128 v[202:205], v187 offset:37888
	ds_read_b128 v[206:209], v187 offset:38912
	ds_read_b128 v[210:213], v187 offset:39936
	global_load_lds_dwordx4 v[220:221], off
	s_mov_b32 m0, s30
	v_lshl_add_u64 v[220:221], s[50:51], 0, v[138:139]
	global_load_lds_dwordx4 v[220:221], off
	s_waitcnt vmcnt(8) lgkmcnt(0)
	s_barrier
	v_mfma_f32_16x16x32_bf16 v[124:127], v[128:131], v[174:177], v[124:127]
	v_mfma_f32_16x16x32_bf16 v[120:123], v[150:153], v[174:177], v[120:123]
	v_mfma_f32_16x16x32_bf16 v[108:111], v[128:131], v[190:193], v[108:111]
	v_mfma_f32_16x16x32_bf16 v[104:107], v[150:153], v[190:193], v[104:107]
	v_mfma_f32_16x16x32_bf16 v[92:95], v[128:131], v[198:201], v[92:95]
	v_mfma_f32_16x16x32_bf16 v[88:91], v[150:153], v[198:201], v[88:91]
	v_mfma_f32_16x16x32_bf16 v[76:79], v[128:131], v[206:209], v[76:79]
	v_mfma_f32_16x16x32_bf16 v[72:75], v[150:153], v[206:209], v[72:75]
	v_mfma_f32_16x16x32_bf16 v[124:127], v[132:135], v[178:181], v[124:127]
	v_mfma_f32_16x16x32_bf16 v[120:123], v[154:157], v[178:181], v[120:123]
	v_mfma_f32_16x16x32_bf16 v[108:111], v[132:135], v[194:197], v[108:111]
	v_mfma_f32_16x16x32_bf16 v[104:107], v[154:157], v[194:197], v[104:107]
	v_mfma_f32_16x16x32_bf16 v[92:95], v[132:135], v[202:205], v[92:95]
	v_mfma_f32_16x16x32_bf16 v[88:91], v[154:157], v[202:205], v[88:91]
	v_mfma_f32_16x16x32_bf16 v[76:79], v[132:135], v[210:213], v[76:79]
	v_mfma_f32_16x16x32_bf16 v[72:75], v[154:157], v[210:213], v[72:75]
	v_mfma_f32_16x16x32_bf16 v[116:119], v[158:161], v[174:177], v[116:119]
	v_mfma_f32_16x16x32_bf16 v[112:115], v[166:169], v[174:177], v[112:115]
	v_mfma_f32_16x16x32_bf16 v[100:103], v[158:161], v[190:193], v[100:103]
	v_mfma_f32_16x16x32_bf16 v[96:99], v[166:169], v[190:193], v[96:99]
	v_mfma_f32_16x16x32_bf16 v[84:87], v[158:161], v[198:201], v[84:87]
	v_mfma_f32_16x16x32_bf16 v[80:83], v[166:169], v[198:201], v[80:83]
	v_mfma_f32_16x16x32_bf16 v[68:71], v[158:161], v[206:209], v[68:71]
	v_mfma_f32_16x16x32_bf16 v[64:67], v[166:169], v[206:209], v[64:67]
	v_mfma_f32_16x16x32_bf16 v[116:119], v[162:165], v[178:181], v[116:119]
	v_mfma_f32_16x16x32_bf16 v[112:115], v[170:173], v[178:181], v[112:115]
	v_mfma_f32_16x16x32_bf16 v[100:103], v[162:165], v[194:197], v[100:103]
	v_mfma_f32_16x16x32_bf16 v[96:99], v[170:173], v[194:197], v[96:99]
	v_mfma_f32_16x16x32_bf16 v[84:87], v[162:165], v[202:205], v[84:87]
	v_mfma_f32_16x16x32_bf16 v[80:83], v[170:173], v[202:205], v[80:83]
	v_mfma_f32_16x16x32_bf16 v[68:71], v[162:165], v[210:213], v[68:71]
	v_mfma_f32_16x16x32_bf16 v[64:67], v[170:173], v[210:213], v[64:67]
	s_barrier
; #define PG8_STAGE(bufoff, gbase, voff) do { _Pragma("unroll") for (int _i = 0; _i < 2; ++_i) \
;         __builtin_amdgcn_global_load_lds((const unsigned*)((const char*)(gbase) + (voff)[_i]), (LAS unsigned*)(lds + (bufoff) + ldsw + _i * 8192), 16, 0, 0); } while (0)
; #define PG8_LDA(dst, b, h) do { _Pragma("unroll") for (int m = 0; m < 4; ++m) _Pragma("unroll") for (int k = 0; k < 2; ++k) dst[m][k] = *(const LAS bf16x8*)(lds + PG8_SA(b, h) + aoff + m * 2048 + k * 1024); } while (0)
; #define PG8_MMA(ai, bj, At, Bt) do { __builtin_amdgcn_s_setprio(1); _Pragma("unroll") for (int m = 0; m < 4; ++m) _Pragma("unroll") for (int n = 0; n < 2; ++n) _Pragma("unroll") for (int k = 0; k < 2; ++k) \
;         acc[ai][bj][m][n] = __builtin_amdgcn_mfma_f32_16x16x32_bf16(Bt[n][k], At[m][k], acc[ai][bj][m][n], 0, 0, 0); __builtin_amdgcn_s_setprio(0); } while (0)
; #define PG8_WAIT_V(n) asm volatile("s_waitcnt vmcnt(" #n ")" ::: "memory")
; #define PG8_WAIT_L(n) asm volatile("s_waitcnt lgkmcnt(" #n ")" ::: "memory")
; #define PG8_BAR __builtin_amdgcn_s_barrier()
; #define PG8_SCHED __builtin_amdgcn_sched_barrier(0)
; template <class Desc, class Epi>
; DI void gemm_phase(LAS unsigned char* lds, const Desc& D, const Epi& E, int wv) {
;     ...
;             PG8_LDA(At, 1, 1); PG8_STAGE(PG8_SB(1, 0), b3, voffB); PG8_STAGE(PG8_SB(1, 1), b3 + hstepB, voffB); PG8_STAGE(PG8_SA(1, 0), a3, voffA);
;             PG8_WAIT_V(8); PG8_WAIT_L(0); PG8_BAR; PG8_MMA(1, 0, At, B0); PG8_MMA(1, 1, At, B1); PG8_BAR; PG8_SCHED;
;         }
;         if (wr == 0) PG8_BAR;
	s_add_i32 s49, s49, s2
	v_lshl_add_u64 v[182:183], v[182:183], 0, s[8:9]
	s_mov_b32 m0, s49
	ds_read_b128 v[174:177], v187 offset:49152
	ds_read_b128 v[178:181], v187 offset:50176
	ds_read_b128 v[190:193], v187 offset:51200
	ds_read_b128 v[194:197], v187 offset:52224
	ds_read_b128 v[198:201], v187 offset:53248
	ds_read_b128 v[202:205], v187 offset:54272
	ds_read_b128 v[206:209], v187 offset:55296
	ds_read_b128 v[210:213], v187 offset:56320
	global_load_lds_dwordx4 v[182:183], off
	s_add_i32 m0, s49, 0x2000
	s_add_u32 s50, s68, 0x100080
	v_lshl_add_u64 v[182:183], v[214:215], 0, s[8:9]
	s_addc_u32 s51, s69, 0
	s_add_i32 s49, s52, s2
	global_load_lds_dwordx4 v[182:183], off
	s_mov_b32 m0, s49
	v_lshl_add_u64 v[182:183], s[50:51], 0, v[140:141]
	global_load_lds_dwordx4 v[182:183], off
	s_add_i32 m0, s49, 0x2000
	v_lshl_add_u64 v[182:183], s[50:51], 0, v[136:137]
	global_load_lds_dwordx4 v[182:183], off
	s_mov_b32 m0, s35
	v_lshl_add_u64 v[182:183], v[216:217], 0, s[8:9]
	global_load_lds_dwordx4 v[182:183], off
	s_mov_b32 m0, s40
	v_lshl_add_u64 v[182:183], v[218:219], 0, s[8:9]
	global_load_lds_dwordx4 v[182:183], off
	s_waitcnt vmcnt(8) lgkmcnt(0)
	s_barrier
	v_mfma_f32_16x16x32_bf16 v[60:63], v[128:131], v[174:177], v[60:63]
	v_mfma_f32_16x16x32_bf16 v[56:59], v[150:153], v[174:177], v[56:59]
	v_mfma_f32_16x16x32_bf16 v[44:47], v[128:131], v[190:193], v[44:47]
	v_mfma_f32_16x16x32_bf16 v[40:43], v[150:153], v[190:193], v[40:43]
	v_mfma_f32_16x16x32_bf16 v[28:31], v[128:131], v[198:201], v[28:31]
	v_mfma_f32_16x16x32_bf16 v[24:27], v[150:153], v[198:201], v[24:27]
	v_mfma_f32_16x16x32_bf16 v[12:15], v[128:131], v[206:209], v[12:15]
	v_mfma_f32_16x16x32_bf16 v[8:11], v[150:153], v[206:209], v[8:11]
	v_mfma_f32_16x16x32_bf16 v[60:63], v[132:135], v[178:181], v[60:63]
	v_mfma_f32_16x16x32_bf16 v[56:59], v[154:157], v[178:181], v[56:59]
	v_mfma_f32_16x16x32_bf16 v[44:47], v[132:135], v[194:197], v[44:47]
	v_mfma_f32_16x16x32_bf16 v[40:43], v[154:157], v[194:197], v[40:43]
	v_mfma_f32_16x16x32_bf16 v[28:31], v[132:135], v[202:205], v[28:31]
	v_mfma_f32_16x16x32_bf16 v[24:27], v[154:157], v[202:205], v[24:27]
	v_mfma_f32_16x16x32_bf16 v[12:15], v[132:135], v[210:213], v[12:15]
	v_mfma_f32_16x16x32_bf16 v[8:11], v[154:157], v[210:213], v[8:11]
	v_mfma_f32_16x16x32_bf16 v[52:55], v[158:161], v[174:177], v[52:55]
	v_mfma_f32_16x16x32_bf16 v[48:51], v[166:169], v[174:177], v[48:51]
	v_mfma_f32_16x16x32_bf16 v[36:39], v[158:161], v[190:193], v[36:39]
	v_mfma_f32_16x16x32_bf16 v[32:35], v[166:169], v[190:193], v[32:35]
	v_mfma_f32_16x16x32_bf16 v[20:23], v[158:161], v[198:201], v[20:23]
	v_mfma_f32_16x16x32_bf16 v[16:19], v[166:169], v[198:201], v[16:19]
	v_mfma_f32_16x16x32_bf16 v[4:7], v[158:161], v[206:209], v[4:7]
	v_mfma_f32_16x16x32_bf16 v[0:3], v[166:169], v[206:209], v[0:3]
	v_mfma_f32_16x16x32_bf16 v[52:55], v[162:165], v[178:181], v[52:55]
	v_mfma_f32_16x16x32_bf16 v[48:51], v[170:173], v[178:181], v[48:51]
	v_mfma_f32_16x16x32_bf16 v[36:39], v[162:165], v[194:197], v[36:39]
	v_mfma_f32_16x16x32_bf16 v[32:35], v[170:173], v[194:197], v[32:35]
	v_mfma_f32_16x16x32_bf16 v[20:23], v[162:165], v[202:205], v[20:23]
	v_mfma_f32_16x16x32_bf16 v[16:19], v[170:173], v[202:205], v[16:19]
	v_mfma_f32_16x16x32_bf16 v[4:7], v[162:165], v[210:213], v[4:7]
	v_mfma_f32_16x16x32_bf16 v[0:3], v[170:173], v[210:213], v[0:3]
	s_barrier
	s_add_i32 s48, s48, 2
	s_add_u32 s66, s66, 0x100
	s_addc_u32 s67, s67, 0
	s_add_u32 s1, s1, 0x100
	s_addc_u32 s47, s47, 0
	s_cmp_gt_u32 s48, 29
	s_cbranch_scc0 .LBB0_581
	s_and_b64 vcc, exec, s[14:15]
	s_cbranch_vccz .LBB0_584
	s_barrier

; #define PG8_STAGE(bufoff, gbase, voff) do { _Pragma("unroll") for (int _i = 0; _i < 2; ++_i) \
;         __builtin_amdgcn_global_load_lds((const unsigned*)((const char*)(gbase) + (voff)[_i]), (LAS unsigned*)(lds + (bufoff) + ldsw + _i * 8192), 16, 0, 0); } while (0)
; #define PG8_LDA(dst, b, h) do { _Pragma("unroll") for (int m = 0; m < 4; ++m) _Pragma("unroll") for (int k = 0; k < 2; ++k) dst[m][k] = *(const LAS bf16x8*)(lds + PG8_SA(b, h) + aoff + m * 2048 + k * 1024); } while (0)
; #define PG8_LDB(dst, b, h) do { _Pragma("unroll") for (int n = 0; n < 2; ++n) _Pragma("unroll") for (int k = 0; k < 2; ++k) dst[n][k] = *(const LAS bf16x8*)(lds + PG8_SB(b, h) + boff + n * 2048 + k * 1024); } while (0)
; #define PG8_MMA(ai, bj, At, Bt) do { __builtin_amdgcn_s_setprio(1); _Pragma("unroll") for (int m = 0; m < 4; ++m) _Pragma("unroll") for (int n = 0; n < 2; ++n) _Pragma("unroll") for (int k = 0; k < 2; ++k) \
;         acc[ai][bj][m][n] = __builtin_amdgcn_mfma_f32_16x16x32_bf16(Bt[n][k], At[m][k], acc[ai][bj][m][n], 0, 0, 0); __builtin_amdgcn_s_setprio(0); } while (0)
; #define PG8_WAIT_V(n) asm volatile("s_waitcnt vmcnt(" #n ")" ::: "memory")
; #define PG8_WAIT_L(n) asm volatile("s_waitcnt lgkmcnt(" #n ")" ::: "memory")
; #define PG8_BAR __builtin_amdgcn_s_barrier()
; #define PG8_SCHED __builtin_amdgcn_sched_barrier(0)
; template <class Desc, class Epi>
; DI void gemm_phase(LAS unsigned char* lds, const Desc& D, const Epi& E, int wv) {
;     ...
;         for (int t = 0; t < nt; t += 2) {
;             const bool last = (t == nt - 2);
;             const char* a1 = cA + (size_t)(t + 1) * kstep;
;             const char* a2 = last ? nA : cA + (size_t)(t + 2) * kstep; const char* b2 = last ? nB : cB + (size_t)(t + 2) * kstep;
;             const char* a3 = a2 + kstep; const char* b3 = b2 + kstep;
;             PG8_LDB(B0, 0, 0); PG8_LDB(B1, 0, 1); PG8_SCHED; PG8_LDA(At, 0, 0); PG8_STAGE(PG8_SA(1, 1), a1 + hstepA, voffA);
;             PG8_WAIT_V(8); PG8_WAIT_L(0); PG8_BAR; PG8_MMA(0, 0, At, B0); PG8_MMA(0, 1, At, B1); PG8_BAR; PG8_SCHED;
;             PG8_LDA(At, 0, 1); PG8_STAGE(PG8_SB(0, 0), b2, voffB); PG8_STAGE(PG8_SB(0, 1), b2 + hstepB, voffB); PG8_STAGE(PG8_SA(0, 0), a2, voffA);
.LBB0_763:
	ds_read_b128 v[150:153], v147
	ds_read_b128 v[154:157], v147 offset:1024
	ds_read_b128 v[158:161], v147 offset:2048
	ds_read_b128 v[162:165], v147 offset:3072
	ds_read_b128 v[166:169], v148
	ds_read_b128 v[170:173], v148 offset:1024
	ds_read_b128 v[174:177], v148 offset:2048
	ds_read_b128 v[178:181], v148 offset:3072
	s_add_u32 s64, s62, 0x100
	s_addc_u32 s65, s63, 0
	s_add_u32 s50, s21, s62
	s_addc_u32 s51, s23, s63
	s_cmp_eq_u32 s49, 4
	s_cselect_b32 s53, 0, s64
	s_cselect_b32 s52, 0, s65
	s_cselect_b32 s66, s18, s50
	s_cselect_b32 s67, s19, s51
	s_add_u32 s68, s4, s53
	s_addc_u32 s69, s5, s52
	v_lshl_add_u64 v[144:145], v[136:137], 0, s[62:63]
	s_add_i32 m0, s3, 0xc000
	ds_read_b128 v[182:185], v149
	ds_read_b128 v[186:189], v149 offset:1024
	ds_read_b128 v[190:193], v149 offset:2048
	ds_read_b128 v[194:197], v149 offset:3072
	ds_read_b128 v[198:201], v149 offset:4096
	ds_read_b128 v[202:205], v149 offset:5120
	ds_read_b128 v[206:209], v149 offset:6144
	ds_read_b128 v[210:213], v149 offset:7168
	global_load_lds_dwordx4 v[144:145], off
	s_add_i32 m0, s3, 0xe000
	v_lshl_add_u64 v[144:145], v[138:139], 0, s[62:63]
	global_load_lds_dwordx4 v[144:145], off
	s_waitcnt vmcnt(8) lgkmcnt(0)
	s_barrier
	v_mfma_f32_16x16x32_bf16 v[124:127], v[150:153], v[182:185], v[124:127]
	v_mfma_f32_16x16x32_bf16 v[120:123], v[158:161], v[182:185], v[120:123]
	v_mfma_f32_16x16x32_bf16 v[108:111], v[150:153], v[190:193], v[108:111]
	v_mfma_f32_16x16x32_bf16 v[104:107], v[158:161], v[190:193], v[104:107]
	v_mfma_f32_16x16x32_bf16 v[92:95], v[150:153], v[198:201], v[92:95]
	v_mfma_f32_16x16x32_bf16 v[88:91], v[158:161], v[198:201], v[88:91]
	v_mfma_f32_16x16x32_bf16 v[76:79], v[150:153], v[206:209], v[76:79]
	v_mfma_f32_16x16x32_bf16 v[72:75], v[158:161], v[206:209], v[72:75]
	v_mfma_f32_16x16x32_bf16 v[124:127], v[154:157], v[186:189], v[124:127]
	v_mfma_f32_16x16x32_bf16 v[120:123], v[162:165], v[186:189], v[120:123]
	v_mfma_f32_16x16x32_bf16 v[108:111], v[154:157], v[194:197], v[108:111]
	v_mfma_f32_16x16x32_bf16 v[104:107], v[162:165], v[194:197], v[104:107]
	v_mfma_f32_16x16x32_bf16 v[92:95], v[154:157], v[202:205], v[92:95]
	v_mfma_f32_16x16x32_bf16 v[88:91], v[162:165], v[202:205], v[88:91]
	v_mfma_f32_16x16x32_bf16 v[76:79], v[154:157], v[210:213], v[76:79]
	v_mfma_f32_16x16x32_bf16 v[72:75], v[162:165], v[210:213], v[72:75]
	v_mfma_f32_16x16x32_bf16 v[116:119], v[166:169], v[182:185], v[116:119]
	v_mfma_f32_16x16x32_bf16 v[112:115], v[174:177], v[182:185], v[112:115]
	v_mfma_f32_16x16x32_bf16 v[100:103], v[166:169], v[190:193], v[100:103]
	v_mfma_f32_16x16x32_bf16 v[96:99], v[174:177], v[190:193], v[96:99]
	v_mfma_f32_16x16x32_bf16 v[84:87], v[166:169], v[198:201], v[84:87]
	v_mfma_f32_16x16x32_bf16 v[80:83], v[174:177], v[198:201], v[80:83]
	v_mfma_f32_16x16x32_bf16 v[68:71], v[166:169], v[206:209], v[68:71]
	v_mfma_f32_16x16x32_bf16 v[64:67], v[174:177], v[206:209], v[64:67]
	v_mfma_f32_16x16x32_bf16 v[116:119], v[170:173], v[186:189], v[116:119]
	v_mfma_f32_16x16x32_bf16 v[112:115], v[178:181], v[186:189], v[112:115]
	v_mfma_f32_16x16x32_bf16 v[100:103], v[170:173], v[194:197], v[100:103]
	v_mfma_f32_16x16x32_bf16 v[96:99], v[178:181], v[194:197], v[96:99]
	v_mfma_f32_16x16x32_bf16 v[84:87], v[170:173], v[202:205], v[84:87]
	v_mfma_f32_16x16x32_bf16 v[80:83], v[178:181], v[202:205], v[80:83]
	v_mfma_f32_16x16x32_bf16 v[68:71], v[170:173], v[210:213], v[68:71]
	v_mfma_f32_16x16x32_bf16 v[64:67], v[178:181], v[210:213], v[64:67]
	s_barrier
	s_add_i32 s50, s43, s2
	v_lshl_add_u64 v[144:145], s[66:67], 0, v[130:131]
	s_mov_b32 m0, s50
	ds_read_b128 v[182:185], v149 offset:16384
	ds_read_b128 v[186:189], v149 offset:17408
	ds_read_b128 v[190:193], v149 offset:18432
	ds_read_b128 v[194:197], v149 offset:19456
	ds_read_b128 v[198:201], v149 offset:20480
	ds_read_b128 v[202:205], v149 offset:21504
	ds_read_b128 v[206:209], v149 offset:22528
	ds_read_b128 v[210:213], v149 offset:23552
	global_load_lds_dwordx4 v[144:145], off
	s_add_i32 m0, s50, 0x2000
	s_add_u32 s50, s66, 0x20000
	v_lshl_add_u64 v[214:215], s[66:67], 0, v[134:135]
	s_addc_u32 s51, s67, 0
	s_add_i32 s52, s46, s2
	global_load_lds_dwordx4 v[214:215], off
	v_lshl_add_u64 v[216:217], s[50:51], 0, v[130:131]
	s_mov_b32 m0, s52
	v_lshl_add_u64 v[218:219], s[68:69], 0, v[132:133]
	global_load_lds_dwordx4 v[216:217], off
	s_add_i32 m0, s52, 0x2000
	v_lshl_add_u64 v[216:217], s[50:51], 0, v[134:135]
	global_load_lds_dwordx4 v[216:217], off
	s_mov_b32 m0, s3
	v_lshl_add_u64 v[216:217], s[68:69], 0, v[128:129]
	global_load_lds_dwordx4 v[216:217], off
	s_mov_b32 m0, s28
	s_nop 0
	global_load_lds_dwordx4 v[218:219], off
	s_waitcnt vmcnt(8) lgkmcnt(0)
	s_barrier
; #define PG8_STAGE(bufoff, gbase, voff) do { _Pragma("unroll") for (int _i = 0; _i < 2; ++_i) \
;         __builtin_amdgcn_global_load_lds((const unsigned*)((const char*)(gbase) + (voff)[_i]), (LAS unsigned*)(lds + (bufoff) + ldsw + _i * 8192), 16, 0, 0); } while (0)
; #define PG8_LDA(dst, b, h) do { _Pragma("unroll") for (int m = 0; m < 4; ++m) _Pragma("unroll") for (int k = 0; k < 2; ++k) dst[m][k] = *(const LAS bf16x8*)(lds + PG8_SA(b, h) + aoff + m * 2048 + k * 1024); } while (0)
; #define PG8_LDB(dst, b, h) do { _Pragma("unroll") for (int n = 0; n < 2; ++n) _Pragma("unroll") for (int k = 0; k < 2; ++k) dst[n][k] = *(const LAS bf16x8*)(lds + PG8_SB(b, h) + boff + n * 2048 + k * 1024); } while (0)
; #define PG8_MMA(ai, bj, At, Bt) do { __builtin_amdgcn_s_setprio(1); _Pragma("unroll") for (int m = 0; m < 4; ++m) _Pragma("unroll") for (int n = 0; n < 2; ++n) _Pragma("unroll") for (int k = 0; k < 2; ++k) \
;         acc[ai][bj][m][n] = __builtin_amdgcn_mfma_f32_16x16x32_bf16(Bt[n][k], At[m][k], acc[ai][bj][m][n], 0, 0, 0); __builtin_amdgcn_s_setprio(0); } while (0)
; #define PG8_WAIT_V(n) asm volatile("s_waitcnt vmcnt(" #n ")" ::: "memory")
; #define PG8_WAIT_L(n) asm volatile("s_waitcnt lgkmcnt(" #n ")" ::: "memory")
; #define PG8_BAR __builtin_amdgcn_s_barrier()
; #define PG8_SCHED __builtin_amdgcn_sched_barrier(0)
; template <class Desc, class Epi>
; DI void gemm_phase(LAS unsigned char* lds, const Desc& D, const Epi& E, int wv) {
;     ...
;             PG8_WAIT_V(8); PG8_WAIT_L(0); PG8_BAR; PG8_MMA(1, 0, At, B0); PG8_MMA(1, 1, At, B1); PG8_BAR; PG8_SCHED;
;             PG8_LDB(B0, 1, 0); PG8_LDB(B1, 1, 1); PG8_SCHED; PG8_LDA(At, 1, 0); PG8_STAGE(PG8_SA(0, 1), a2 + hstepA, voffA);
;             PG8_WAIT_V(8); PG8_WAIT_L(0); PG8_BAR; PG8_MMA(0, 0, At, B0); PG8_MMA(0, 1, At, B1); PG8_BAR; PG8_SCHED;
;             PG8_LDA(At, 1, 1); PG8_STAGE(PG8_SB(1, 0), b3, voffB); PG8_STAGE(PG8_SB(1, 1), b3 + hstepB, voffB); PG8_STAGE(PG8_SA(1, 0), a3, voffA);
	v_mfma_f32_16x16x32_bf16 v[60:63], v[150:153], v[182:185], v[60:63]
	v_mfma_f32_16x16x32_bf16 v[56:59], v[158:161], v[182:185], v[56:59]
	v_mfma_f32_16x16x32_bf16 v[44:47], v[150:153], v[190:193], v[44:47]
	v_mfma_f32_16x16x32_bf16 v[40:43], v[158:161], v[190:193], v[40:43]
	v_mfma_f32_16x16x32_bf16 v[28:31], v[150:153], v[198:201], v[28:31]
	v_mfma_f32_16x16x32_bf16 v[24:27], v[158:161], v[198:201], v[24:27]
	v_mfma_f32_16x16x32_bf16 v[12:15], v[150:153], v[206:209], v[12:15]
	v_mfma_f32_16x16x32_bf16 v[8:11], v[158:161], v[206:209], v[8:11]
	v_mfma_f32_16x16x32_bf16 v[60:63], v[154:157], v[186:189], v[60:63]
	v_mfma_f32_16x16x32_bf16 v[56:59], v[162:165], v[186:189], v[56:59]
	v_mfma_f32_16x16x32_bf16 v[44:47], v[154:157], v[194:197], v[44:47]
	v_mfma_f32_16x16x32_bf16 v[40:43], v[162:165], v[194:197], v[40:43]
	v_mfma_f32_16x16x32_bf16 v[28:31], v[154:157], v[202:205], v[28:31]
	v_mfma_f32_16x16x32_bf16 v[24:27], v[162:165], v[202:205], v[24:27]
	v_mfma_f32_16x16x32_bf16 v[12:15], v[154:157], v[210:213], v[12:15]
	v_mfma_f32_16x16x32_bf16 v[8:11], v[162:165], v[210:213], v[8:11]
	v_mfma_f32_16x16x32_bf16 v[52:55], v[166:169], v[182:185], v[52:55]
	v_mfma_f32_16x16x32_bf16 v[48:51], v[174:177], v[182:185], v[48:51]
	v_mfma_f32_16x16x32_bf16 v[36:39], v[166:169], v[190:193], v[36:39]
	v_mfma_f32_16x16x32_bf16 v[32:35], v[174:177], v[190:193], v[32:35]
	v_mfma_f32_16x16x32_bf16 v[20:23], v[166:169], v[198:201], v[20:23]
	v_mfma_f32_16x16x32_bf16 v[16:19], v[174:177], v[198:201], v[16:19]
	v_mfma_f32_16x16x32_bf16 v[4:7], v[166:169], v[206:209], v[4:7]
	v_mfma_f32_16x16x32_bf16 v[0:3], v[174:177], v[206:209], v[0:3]
	v_mfma_f32_16x16x32_bf16 v[52:55], v[170:173], v[186:189], v[52:55]
	v_mfma_f32_16x16x32_bf16 v[48:51], v[178:181], v[186:189], v[48:51]
	v_mfma_f32_16x16x32_bf16 v[36:39], v[170:173], v[194:197], v[36:39]
	v_mfma_f32_16x16x32_bf16 v[32:35], v[178:181], v[194:197], v[32:35]
	v_mfma_f32_16x16x32_bf16 v[20:23], v[170:173], v[202:205], v[20:23]
	v_mfma_f32_16x16x32_bf16 v[16:19], v[178:181], v[202:205], v[16:19]
	v_mfma_f32_16x16x32_bf16 v[4:7], v[170:173], v[210:213], v[4:7]
	v_mfma_f32_16x16x32_bf16 v[0:3], v[178:181], v[210:213], v[0:3]
	s_barrier
	s_add_i32 s52, 0, 0x18000
	s_add_i32 s53, 0, 0x1c000
	v_add_u32_e32 v162, s52, v146
	v_add_u32_e32 v178, s53, v146
	ds_read_b128 v[150:153], v162
	ds_read_b128 v[154:157], v162 offset:1024
	ds_read_b128 v[158:161], v162 offset:2048
	ds_read_b128 v[162:165], v162 offset:3072
	ds_read_b128 v[166:169], v178
	ds_read_b128 v[170:173], v178 offset:1024
	ds_read_b128 v[174:177], v178 offset:2048
	ds_read_b128 v[178:181], v178 offset:3072
	s_add_u32 s50, s68, 0x20000
	s_addc_u32 s51, s69, 0
	s_mov_b32 m0, s29
	v_lshl_add_u64 v[220:221], s[50:51], 0, v[128:129]
	ds_read_b128 v[182:185], v149 offset:32768
	ds_read_b128 v[186:189], v149 offset:33792
	ds_read_b128 v[190:193], v149 offset:34816
	ds_read_b128 v[194:197], v149 offset:35840
	ds_read_b128 v[198:201], v149 offset:36864
	ds_read_b128 v[202:205], v149 offset:37888
	ds_read_b128 v[206:209], v149 offset:38912
	ds_read_b128 v[210:213], v149 offset:39936
	global_load_lds_dwordx4 v[220:221], off
	s_mov_b32 m0, s30
	v_lshl_add_u64 v[220:221], s[50:51], 0, v[132:133]
	global_load_lds_dwordx4 v[220:221], off
	s_waitcnt vmcnt(8) lgkmcnt(0)
	s_barrier
	v_mfma_f32_16x16x32_bf16 v[124:127], v[150:153], v[182:185], v[124:127]
	v_mfma_f32_16x16x32_bf16 v[120:123], v[158:161], v[182:185], v[120:123]
	v_mfma_f32_16x16x32_bf16 v[108:111], v[150:153], v[190:193], v[108:111]
	v_mfma_f32_16x16x32_bf16 v[104:107], v[158:161], v[190:193], v[104:107]
	v_mfma_f32_16x16x32_bf16 v[92:95], v[150:153], v[198:201], v[92:95]
	v_mfma_f32_16x16x32_bf16 v[88:91], v[158:161], v[198:201], v[88:91]
	v_mfma_f32_16x16x32_bf16 v[76:79], v[150:153], v[206:209], v[76:79]
	v_mfma_f32_16x16x32_bf16 v[72:75], v[158:161], v[206:209], v[72:75]
	v_mfma_f32_16x16x32_bf16 v[124:127], v[154:157], v[186:189], v[124:127]
	v_mfma_f32_16x16x32_bf16 v[120:123], v[162:165], v[186:189], v[120:123]
	v_mfma_f32_16x16x32_bf16 v[108:111], v[154:157], v[194:197], v[108:111]
	v_mfma_f32_16x16x32_bf16 v[104:107], v[162:165], v[194:197], v[104:107]
	v_mfma_f32_16x16x32_bf16 v[92:95], v[154:157], v[202:205], v[92:95]
	v_mfma_f32_16x16x32_bf16 v[88:91], v[162:165], v[202:205], v[88:91]
	v_mfma_f32_16x16x32_bf16 v[76:79], v[154:157], v[210:213], v[76:79]
	v_mfma_f32_16x16x32_bf16 v[72:75], v[162:165], v[210:213], v[72:75]
	v_mfma_f32_16x16x32_bf16 v[116:119], v[166:169], v[182:185], v[116:119]
	v_mfma_f32_16x16x32_bf16 v[112:115], v[174:177], v[182:185], v[112:115]
	v_mfma_f32_16x16x32_bf16 v[100:103], v[166:169], v[190:193], v[100:103]
	v_mfma_f32_16x16x32_bf16 v[96:99], v[174:177], v[190:193], v[96:99]
	v_mfma_f32_16x16x32_bf16 v[84:87], v[166:169], v[198:201], v[84:87]
	v_mfma_f32_16x16x32_bf16 v[80:83], v[174:177], v[198:201], v[80:83]
	v_mfma_f32_16x16x32_bf16 v[68:71], v[166:169], v[206:209], v[68:71]
	v_mfma_f32_16x16x32_bf16 v[64:67], v[174:177], v[206:209], v[64:67]
	v_mfma_f32_16x16x32_bf16 v[116:119], v[170:173], v[186:189], v[116:119]
	v_mfma_f32_16x16x32_bf16 v[112:115], v[178:181], v[186:189], v[112:115]
	v_mfma_f32_16x16x32_bf16 v[100:103], v[170:173], v[194:197], v[100:103]
	v_mfma_f32_16x16x32_bf16 v[96:99], v[178:181], v[194:197], v[96:99]
	v_mfma_f32_16x16x32_bf16 v[84:87], v[170:173], v[202:205], v[84:87]
	v_mfma_f32_16x16x32_bf16 v[80:83], v[178:181], v[202:205], v[80:83]
	v_mfma_f32_16x16x32_bf16 v[68:71], v[170:173], v[210:213], v[68:71]
	v_mfma_f32_16x16x32_bf16 v[64:67], v[178:181], v[210:213], v[64:67]
	s_barrier
; #define PG8_STAGE(bufoff, gbase, voff) do { _Pragma("unroll") for (int _i = 0; _i < 2; ++_i) \
;         __builtin_amdgcn_global_load_lds((const unsigned*)((const char*)(gbase) + (voff)[_i]), (LAS unsigned*)(lds + (bufoff) + ldsw + _i * 8192), 16, 0, 0); } while (0)
; #define PG8_LDA(dst, b, h) do { _Pragma("unroll") for (int m = 0; m < 4; ++m) _Pragma("unroll") for (int k = 0; k < 2; ++k) dst[m][k] = *(const LAS bf16x8*)(lds + PG8_SA(b, h) + aoff + m * 2048 + k * 1024); } while (0)
; #define PG8_MMA(ai, bj, At, Bt) do { __builtin_amdgcn_s_setprio(1); _Pragma("unroll") for (int m = 0; m < 4; ++m) _Pragma("unroll") for (int n = 0; n < 2; ++n) _Pragma("unroll") for (int k = 0; k < 2; ++k) \
;         acc[ai][bj][m][n] = __builtin_amdgcn_mfma_f32_16x16x32_bf16(Bt[n][k], At[m][k], acc[ai][bj][m][n], 0, 0, 0); __builtin_amdgcn_s_setprio(0); } while (0)
; #define PG8_WAIT_V(n) asm volatile("s_waitcnt vmcnt(" #n ")" ::: "memory")
; #define PG8_WAIT_L(n) asm volatile("s_waitcnt lgkmcnt(" #n ")" ::: "memory")
; #define PG8_BAR __builtin_amdgcn_s_barrier()
; #define PG8_SCHED __builtin_amdgcn_sched_barrier(0)
; template <class Desc, class Epi>
; DI void gemm_phase(LAS unsigned char* lds, const Desc& D, const Epi& E, int wv) {
;     ...
;             PG8_LDA(At, 1, 1); PG8_STAGE(PG8_SB(1, 0), b3, voffB); PG8_STAGE(PG8_SB(1, 1), b3 + hstepB, voffB); PG8_STAGE(PG8_SA(1, 0), a3, voffA);
;             PG8_WAIT_V(8); PG8_WAIT_L(0); PG8_BAR; PG8_MMA(1, 0, At, B0); PG8_MMA(1, 1, At, B1); PG8_BAR; PG8_SCHED;
;         }
;         if (wr == 0) PG8_BAR;
	s_add_i32 s50, s52, s2
	v_lshl_add_u64 v[144:145], v[144:145], 0, s[8:9]
	s_mov_b32 m0, s50
	ds_read_b128 v[182:185], v149 offset:49152
	ds_read_b128 v[186:189], v149 offset:50176
	ds_read_b128 v[190:193], v149 offset:51200
	ds_read_b128 v[194:197], v149 offset:52224
	ds_read_b128 v[198:201], v149 offset:53248
	ds_read_b128 v[202:205], v149 offset:54272
	ds_read_b128 v[206:209], v149 offset:55296
	ds_read_b128 v[210:213], v149 offset:56320
	global_load_lds_dwordx4 v[144:145], off
	s_add_i32 m0, s50, 0x2000
	s_add_u32 s50, s66, 0x20080
	v_lshl_add_u64 v[144:145], v[214:215], 0, s[8:9]
	s_addc_u32 s51, s67, 0
	s_add_i32 s52, s53, s2
	global_load_lds_dwordx4 v[144:145], off
	s_mov_b32 m0, s52
	v_lshl_add_u64 v[144:145], s[50:51], 0, v[130:131]
	global_load_lds_dwordx4 v[144:145], off
	s_add_i32 m0, s52, 0x2000
	v_lshl_add_u64 v[144:145], s[50:51], 0, v[134:135]
	global_load_lds_dwordx4 v[144:145], off
	s_mov_b32 m0, s40
	v_lshl_add_u64 v[144:145], v[216:217], 0, s[8:9]
	global_load_lds_dwordx4 v[144:145], off
	s_mov_b32 m0, s41
	v_lshl_add_u64 v[144:145], v[218:219], 0, s[8:9]
	global_load_lds_dwordx4 v[144:145], off
	s_waitcnt vmcnt(8) lgkmcnt(0)
	s_barrier
	v_mfma_f32_16x16x32_bf16 v[60:63], v[150:153], v[182:185], v[60:63]
	v_mfma_f32_16x16x32_bf16 v[56:59], v[158:161], v[182:185], v[56:59]
	v_mfma_f32_16x16x32_bf16 v[44:47], v[150:153], v[190:193], v[44:47]
	v_mfma_f32_16x16x32_bf16 v[40:43], v[158:161], v[190:193], v[40:43]
	v_mfma_f32_16x16x32_bf16 v[28:31], v[150:153], v[198:201], v[28:31]
	v_mfma_f32_16x16x32_bf16 v[24:27], v[158:161], v[198:201], v[24:27]
	v_mfma_f32_16x16x32_bf16 v[12:15], v[150:153], v[206:209], v[12:15]
	v_mfma_f32_16x16x32_bf16 v[8:11], v[158:161], v[206:209], v[8:11]
	v_mfma_f32_16x16x32_bf16 v[60:63], v[154:157], v[186:189], v[60:63]
	v_mfma_f32_16x16x32_bf16 v[56:59], v[162:165], v[186:189], v[56:59]
	v_mfma_f32_16x16x32_bf16 v[44:47], v[154:157], v[194:197], v[44:47]
	v_mfma_f32_16x16x32_bf16 v[40:43], v[162:165], v[194:197], v[40:43]
	v_mfma_f32_16x16x32_bf16 v[28:31], v[154:157], v[202:205], v[28:31]
	v_mfma_f32_16x16x32_bf16 v[24:27], v[162:165], v[202:205], v[24:27]
	v_mfma_f32_16x16x32_bf16 v[12:15], v[154:157], v[210:213], v[12:15]
	v_mfma_f32_16x16x32_bf16 v[8:11], v[162:165], v[210:213], v[8:11]
	v_mfma_f32_16x16x32_bf16 v[52:55], v[166:169], v[182:185], v[52:55]
	v_mfma_f32_16x16x32_bf16 v[48:51], v[174:177], v[182:185], v[48:51]
	v_mfma_f32_16x16x32_bf16 v[36:39], v[166:169], v[190:193], v[36:39]
	v_mfma_f32_16x16x32_bf16 v[32:35], v[174:177], v[190:193], v[32:35]
	v_mfma_f32_16x16x32_bf16 v[20:23], v[166:169], v[198:201], v[20:23]
	v_mfma_f32_16x16x32_bf16 v[16:19], v[174:177], v[198:201], v[16:19]
	v_mfma_f32_16x16x32_bf16 v[4:7], v[166:169], v[206:209], v[4:7]
	v_mfma_f32_16x16x32_bf16 v[0:3], v[174:177], v[206:209], v[0:3]
	v_mfma_f32_16x16x32_bf16 v[52:55], v[170:173], v[186:189], v[52:55]
	v_mfma_f32_16x16x32_bf16 v[48:51], v[178:181], v[186:189], v[48:51]
	v_mfma_f32_16x16x32_bf16 v[36:39], v[170:173], v[194:197], v[36:39]
	v_mfma_f32_16x16x32_bf16 v[32:35], v[178:181], v[194:197], v[32:35]
	v_mfma_f32_16x16x32_bf16 v[20:23], v[170:173], v[202:205], v[20:23]
	v_mfma_f32_16x16x32_bf16 v[16:19], v[178:181], v[202:205], v[16:19]
	v_mfma_f32_16x16x32_bf16 v[4:7], v[170:173], v[210:213], v[4:7]
	v_mfma_f32_16x16x32_bf16 v[0:3], v[178:181], v[210:213], v[0:3]
	s_barrier
	s_add_i32 s49, s49, 2
	s_cmp_gt_u32 s49, 5
	s_mov_b64 s[62:63], s[64:65]
	s_cbranch_scc0 .LBB0_763
	s_and_b64 vcc, exec, s[14:15]
	s_cbranch_vccz .LBB0_766
	s_barrier

; #define PG8_STAGE(bufoff, gbase, voff) do { _Pragma("unroll") for (int _i = 0; _i < 2; ++_i) \
;         __builtin_amdgcn_global_load_lds((const unsigned*)((const char*)(gbase) + (voff)[_i]), (LAS unsigned*)(lds + (bufoff) + ldsw + _i * 8192), 16, 0, 0); } while (0)
; #define PG8_LDA(dst, b, h) do { _Pragma("unroll") for (int m = 0; m < 4; ++m) _Pragma("unroll") for (int k = 0; k < 2; ++k) dst[m][k] = *(const LAS bf16x8*)(lds + PG8_SA(b, h) + aoff + m * 2048 + k * 1024); } while (0)
; #define PG8_LDB(dst, b, h) do { _Pragma("unroll") for (int n = 0; n < 2; ++n) _Pragma("unroll") for (int k = 0; k < 2; ++k) dst[n][k] = *(const LAS bf16x8*)(lds + PG8_SB(b, h) + boff + n * 2048 + k * 1024); } while (0)
; #define PG8_MMA(ai, bj, At, Bt) do { __builtin_amdgcn_s_setprio(1); _Pragma("unroll") for (int m = 0; m < 4; ++m) _Pragma("unroll") for (int n = 0; n < 2; ++n) _Pragma("unroll") for (int k = 0; k < 2; ++k) \
;         acc[ai][bj][m][n] = __builtin_amdgcn_mfma_f32_16x16x32_bf16(Bt[n][k], At[m][k], acc[ai][bj][m][n], 0, 0, 0); __builtin_amdgcn_s_setprio(0); } while (0)
; #define PG8_WAIT_V(n) asm volatile("s_waitcnt vmcnt(" #n ")" ::: "memory")
; #define PG8_WAIT_L(n) asm volatile("s_waitcnt lgkmcnt(" #n ")" ::: "memory")
; #define PG8_BAR __builtin_amdgcn_s_barrier()
; #define PG8_SCHED __builtin_amdgcn_sched_barrier(0)
; template <class Desc, class Epi>
; DI void gemm_phase(LAS unsigned char* lds, const Desc& D, const Epi& E, int wv) {
;     ...
;         for (int t = 0; t < nt; t += 2) {
;             const bool last = (t == nt - 2);
;             const char* a1 = cA + (size_t)(t + 1) * kstep;
;             const char* a2 = last ? nA : cA + (size_t)(t + 2) * kstep; const char* b2 = last ? nB : cB + (size_t)(t + 2) * kstep;
;             const char* a3 = a2 + kstep; const char* b3 = b2 + kstep;
;             PG8_LDB(B0, 0, 0); PG8_LDB(B1, 0, 1); PG8_SCHED; PG8_LDA(At, 0, 0); PG8_STAGE(PG8_SA(1, 1), a1 + hstepA, voffA);
;             PG8_WAIT_V(8); PG8_WAIT_L(0); PG8_BAR; PG8_MMA(0, 0, At, B0); PG8_MMA(0, 1, At, B1); PG8_BAR; PG8_SCHED;
;             PG8_LDA(At, 0, 1); PG8_STAGE(PG8_SB(0, 0), b2, voffB); PG8_STAGE(PG8_SB(0, 1), b2 + hstepB, voffB); PG8_STAGE(PG8_SA(0, 0), a2, voffA);
.LBB0_831:
	ds_read_b128 v[128:131], v169
	ds_read_b128 v[132:135], v169 offset:1024
	ds_read_b128 v[136:139], v169 offset:2048
	ds_read_b128 v[140:143], v169 offset:3072
	ds_read_b128 v[160:163], v170
	ds_read_b128 v[164:167], v170 offset:1024
	ds_read_b128 v[172:175], v170 offset:2048
	ds_read_b128 v[176:179], v170 offset:3072
	s_add_u32 s51, s6, 0xfff80080
	s_addc_u32 s52, s7, -1
	s_cmp_eq_u32 s50, 28
	s_cselect_b32 s69, s19, s52
	s_cselect_b32 s68, s18, s51
	s_cselect_b32 s67, s21, s49
	s_cselect_b32 s66, s20, s23
	v_lshl_add_u64 v[212:213], s[6:7], 0, v[152:153]
	s_add_i32 m0, s28, 0xc000
	ds_read_b128 v[180:183], v171
	ds_read_b128 v[184:187], v171 offset:1024
	ds_read_b128 v[188:191], v171 offset:2048
	ds_read_b128 v[192:195], v171 offset:3072
	ds_read_b128 v[196:199], v171 offset:4096
	ds_read_b128 v[200:203], v171 offset:5120
	ds_read_b128 v[204:207], v171 offset:6144
	ds_read_b128 v[208:211], v171 offset:7168
	global_load_lds_dwordx4 v[212:213], off
	s_add_i32 m0, s28, 0xe000
	v_lshl_add_u64 v[212:213], s[6:7], 0, v[154:155]
	global_load_lds_dwordx4 v[212:213], off
	s_waitcnt vmcnt(8) lgkmcnt(0)
	s_barrier
	v_mfma_f32_16x16x32_bf16 v[124:127], v[128:131], v[180:183], v[124:127]
	v_mfma_f32_16x16x32_bf16 v[120:123], v[136:139], v[180:183], v[120:123]
	v_mfma_f32_16x16x32_bf16 v[112:115], v[128:131], v[188:191], v[112:115]
	v_mfma_f32_16x16x32_bf16 v[108:111], v[136:139], v[188:191], v[108:111]
	v_mfma_f32_16x16x32_bf16 v[100:103], v[128:131], v[196:199], v[100:103]
	v_mfma_f32_16x16x32_bf16 v[92:95], v[136:139], v[196:199], v[92:95]
	v_mfma_f32_16x16x32_bf16 v[84:87], v[128:131], v[204:207], v[84:87]
	v_mfma_f32_16x16x32_bf16 v[76:79], v[136:139], v[204:207], v[76:79]
	v_mfma_f32_16x16x32_bf16 v[124:127], v[132:135], v[184:187], v[124:127]
	v_mfma_f32_16x16x32_bf16 v[120:123], v[140:143], v[184:187], v[120:123]
	v_mfma_f32_16x16x32_bf16 v[112:115], v[132:135], v[192:195], v[112:115]
	v_mfma_f32_16x16x32_bf16 v[108:111], v[140:143], v[192:195], v[108:111]
	v_mfma_f32_16x16x32_bf16 v[100:103], v[132:135], v[200:203], v[100:103]
	v_mfma_f32_16x16x32_bf16 v[92:95], v[140:143], v[200:203], v[92:95]
	v_mfma_f32_16x16x32_bf16 v[84:87], v[132:135], v[208:211], v[84:87]
	v_mfma_f32_16x16x32_bf16 v[76:79], v[140:143], v[208:211], v[76:79]
	v_mfma_f32_16x16x32_bf16 v[116:119], v[160:163], v[180:183], v[116:119]
	v_mfma_f32_16x16x32_bf16 v[104:107], v[172:175], v[180:183], v[104:107]
	v_mfma_f32_16x16x32_bf16 v[96:99], v[160:163], v[188:191], v[96:99]
	v_mfma_f32_16x16x32_bf16 v[88:91], v[172:175], v[188:191], v[88:91]
	v_mfma_f32_16x16x32_bf16 v[80:83], v[160:163], v[196:199], v[80:83]
	v_mfma_f32_16x16x32_bf16 v[72:75], v[172:175], v[196:199], v[72:75]
	v_mfma_f32_16x16x32_bf16 v[68:71], v[160:163], v[204:207], v[68:71]
	v_mfma_f32_16x16x32_bf16 v[64:67], v[172:175], v[204:207], v[64:67]
	v_mfma_f32_16x16x32_bf16 v[116:119], v[164:167], v[184:187], v[116:119]
	v_mfma_f32_16x16x32_bf16 v[104:107], v[176:179], v[184:187], v[104:107]
	v_mfma_f32_16x16x32_bf16 v[96:99], v[164:167], v[192:195], v[96:99]
	v_mfma_f32_16x16x32_bf16 v[88:91], v[176:179], v[192:195], v[88:91]
	v_mfma_f32_16x16x32_bf16 v[80:83], v[164:167], v[200:203], v[80:83]
	v_mfma_f32_16x16x32_bf16 v[72:75], v[176:179], v[200:203], v[72:75]
	v_mfma_f32_16x16x32_bf16 v[68:71], v[164:167], v[208:211], v[68:71]
	v_mfma_f32_16x16x32_bf16 v[64:67], v[176:179], v[208:211], v[64:67]
	s_barrier
	s_add_i32 s51, s46, s2
	v_lshl_add_u64 v[212:213], s[66:67], 0, v[148:149]
	s_mov_b32 m0, s51
	ds_read_b128 v[180:183], v171 offset:16384
	ds_read_b128 v[184:187], v171 offset:17408
	ds_read_b128 v[188:191], v171 offset:18432
	ds_read_b128 v[192:195], v171 offset:19456
	ds_read_b128 v[196:199], v171 offset:20480
	ds_read_b128 v[200:203], v171 offset:21504
	ds_read_b128 v[204:207], v171 offset:22528
	ds_read_b128 v[208:211], v171 offset:23552
	global_load_lds_dwordx4 v[212:213], off
	s_add_i32 m0, s51, 0x2000
	s_add_u32 s52, s66, 0x80000
	v_lshl_add_u64 v[214:215], s[66:67], 0, v[144:145]
	s_addc_u32 s53, s67, 0
	s_add_i32 s51, s47, s2
	global_load_lds_dwordx4 v[214:215], off
	v_lshl_add_u64 v[216:217], s[52:53], 0, v[148:149]
	s_mov_b32 m0, s51
	v_lshl_add_u64 v[218:219], s[68:69], 0, v[146:147]
	global_load_lds_dwordx4 v[216:217], off
	s_add_i32 m0, s51, 0x2000
	v_lshl_add_u64 v[216:217], s[52:53], 0, v[144:145]
	global_load_lds_dwordx4 v[216:217], off
	s_mov_b32 m0, s28
	v_lshl_add_u64 v[216:217], s[68:69], 0, v[150:151]
	global_load_lds_dwordx4 v[216:217], off
	s_mov_b32 m0, s29
	s_nop 0
	global_load_lds_dwordx4 v[218:219], off
	s_waitcnt vmcnt(8) lgkmcnt(0)
	s_barrier
; #define PG8_STAGE(bufoff, gbase, voff) do { _Pragma("unroll") for (int _i = 0; _i < 2; ++_i) \
;         __builtin_amdgcn_global_load_lds((const unsigned*)((const char*)(gbase) + (voff)[_i]), (LAS unsigned*)(lds + (bufoff) + ldsw + _i * 8192), 16, 0, 0); } while (0)
; #define PG8_LDA(dst, b, h) do { _Pragma("unroll") for (int m = 0; m < 4; ++m) _Pragma("unroll") for (int k = 0; k < 2; ++k) dst[m][k] = *(const LAS bf16x8*)(lds + PG8_SA(b, h) + aoff + m * 2048 + k * 1024); } while (0)
; #define PG8_LDB(dst, b, h) do { _Pragma("unroll") for (int n = 0; n < 2; ++n) _Pragma("unroll") for (int k = 0; k < 2; ++k) dst[n][k] = *(const LAS bf16x8*)(lds + PG8_SB(b, h) + boff + n * 2048 + k * 1024); } while (0)
; #define PG8_MMA(ai, bj, At, Bt) do { __builtin_amdgcn_s_setprio(1); _Pragma("unroll") for (int m = 0; m < 4; ++m) _Pragma("unroll") for (int n = 0; n < 2; ++n) _Pragma("unroll") for (int k = 0; k < 2; ++k) \
;         acc[ai][bj][m][n] = __builtin_amdgcn_mfma_f32_16x16x32_bf16(Bt[n][k], At[m][k], acc[ai][bj][m][n], 0, 0, 0); __builtin_amdgcn_s_setprio(0); } while (0)
; #define PG8_WAIT_V(n) asm volatile("s_waitcnt vmcnt(" #n ")" ::: "memory")
; #define PG8_WAIT_L(n) asm volatile("s_waitcnt lgkmcnt(" #n ")" ::: "memory")
; #define PG8_BAR __builtin_amdgcn_s_barrier()
; #define PG8_SCHED __builtin_amdgcn_sched_barrier(0)
; template <class Desc, class Epi>
; DI void gemm_phase(LAS unsigned char* lds, const Desc& D, const Epi& E, int wv) {
;     ...
;             PG8_WAIT_V(8); PG8_WAIT_L(0); PG8_BAR; PG8_MMA(1, 0, At, B0); PG8_MMA(1, 1, At, B1); PG8_BAR; PG8_SCHED;
;             PG8_LDB(B0, 1, 0); PG8_LDB(B1, 1, 1); PG8_SCHED; PG8_LDA(At, 1, 0); PG8_STAGE(PG8_SA(0, 1), a2 + hstepA, voffA);
;             PG8_WAIT_V(8); PG8_WAIT_L(0); PG8_BAR; PG8_MMA(0, 0, At, B0); PG8_MMA(0, 1, At, B1); PG8_BAR; PG8_SCHED;
;             PG8_LDA(At, 1, 1); PG8_STAGE(PG8_SB(1, 0), b3, voffB); PG8_STAGE(PG8_SB(1, 1), b3 + hstepB, voffB); PG8_STAGE(PG8_SA(1, 0), a3, voffA);
	v_mfma_f32_16x16x32_bf16 v[60:63], v[128:131], v[180:183], v[60:63]
	v_mfma_f32_16x16x32_bf16 v[56:59], v[136:139], v[180:183], v[56:59]
	v_mfma_f32_16x16x32_bf16 v[52:55], v[128:131], v[188:191], v[52:55]
	v_mfma_f32_16x16x32_bf16 v[44:47], v[136:139], v[188:191], v[44:47]
	v_mfma_f32_16x16x32_bf16 v[36:39], v[128:131], v[196:199], v[36:39]
	v_mfma_f32_16x16x32_bf16 v[28:31], v[136:139], v[196:199], v[28:31]
	v_mfma_f32_16x16x32_bf16 v[20:23], v[128:131], v[204:207], v[20:23]
	v_mfma_f32_16x16x32_bf16 v[12:15], v[136:139], v[204:207], v[12:15]
	v_mfma_f32_16x16x32_bf16 v[60:63], v[132:135], v[184:187], v[60:63]
	v_mfma_f32_16x16x32_bf16 v[56:59], v[140:143], v[184:187], v[56:59]
	v_mfma_f32_16x16x32_bf16 v[52:55], v[132:135], v[192:195], v[52:55]
	v_mfma_f32_16x16x32_bf16 v[44:47], v[140:143], v[192:195], v[44:47]
	v_mfma_f32_16x16x32_bf16 v[36:39], v[132:135], v[200:203], v[36:39]
	v_mfma_f32_16x16x32_bf16 v[28:31], v[140:143], v[200:203], v[28:31]
	v_mfma_f32_16x16x32_bf16 v[20:23], v[132:135], v[208:211], v[20:23]
	v_mfma_f32_16x16x32_bf16 v[12:15], v[140:143], v[208:211], v[12:15]
	v_mfma_f32_16x16x32_bf16 v[48:51], v[160:163], v[180:183], v[48:51]
	v_mfma_f32_16x16x32_bf16 v[40:43], v[172:175], v[180:183], v[40:43]
	v_mfma_f32_16x16x32_bf16 v[32:35], v[160:163], v[188:191], v[32:35]
	v_mfma_f32_16x16x32_bf16 v[24:27], v[172:175], v[188:191], v[24:27]
	v_mfma_f32_16x16x32_bf16 v[16:19], v[160:163], v[196:199], v[16:19]
	v_mfma_f32_16x16x32_bf16 v[8:11], v[172:175], v[196:199], v[8:11]
	v_mfma_f32_16x16x32_bf16 v[4:7], v[160:163], v[204:207], v[4:7]
	v_mfma_f32_16x16x32_bf16 v[0:3], v[172:175], v[204:207], v[0:3]
	v_mfma_f32_16x16x32_bf16 v[48:51], v[164:167], v[184:187], v[48:51]
	v_mfma_f32_16x16x32_bf16 v[40:43], v[176:179], v[184:187], v[40:43]
	v_mfma_f32_16x16x32_bf16 v[32:35], v[164:167], v[192:195], v[32:35]
	v_mfma_f32_16x16x32_bf16 v[24:27], v[176:179], v[192:195], v[24:27]
	v_mfma_f32_16x16x32_bf16 v[16:19], v[164:167], v[200:203], v[16:19]
	v_mfma_f32_16x16x32_bf16 v[8:11], v[176:179], v[200:203], v[8:11]
	v_mfma_f32_16x16x32_bf16 v[4:7], v[164:167], v[208:211], v[4:7]
	v_mfma_f32_16x16x32_bf16 v[0:3], v[176:179], v[208:211], v[0:3]
	s_barrier
	s_add_i32 s51, 0, 0x18000
	s_add_i32 s60, 0, 0x1c000
	v_add_u32_e32 v140, s51, v168
	v_add_u32_e32 v176, s60, v168
	ds_read_b128 v[128:131], v140
	ds_read_b128 v[132:135], v140 offset:1024
	ds_read_b128 v[136:139], v140 offset:2048
	ds_read_b128 v[140:143], v140 offset:3072
	ds_read_b128 v[160:163], v176
	ds_read_b128 v[164:167], v176 offset:1024
	ds_read_b128 v[172:175], v176 offset:2048
	ds_read_b128 v[176:179], v176 offset:3072
	s_add_u32 s52, s68, 0x80000
	s_addc_u32 s53, s69, 0
	s_mov_b32 m0, s30
	v_lshl_add_u64 v[220:221], s[52:53], 0, v[150:151]
	ds_read_b128 v[180:183], v171 offset:32768
	ds_read_b128 v[184:187], v171 offset:33792
	ds_read_b128 v[188:191], v171 offset:34816
	ds_read_b128 v[192:195], v171 offset:35840
	ds_read_b128 v[196:199], v171 offset:36864
	ds_read_b128 v[200:203], v171 offset:37888
	ds_read_b128 v[204:207], v171 offset:38912
	ds_read_b128 v[208:211], v171 offset:39936
	global_load_lds_dwordx4 v[220:221], off
	s_mov_b32 m0, s31
	v_lshl_add_u64 v[220:221], s[52:53], 0, v[146:147]
	global_load_lds_dwordx4 v[220:221], off
	s_waitcnt vmcnt(8) lgkmcnt(0)
	s_barrier
	v_mfma_f32_16x16x32_bf16 v[124:127], v[128:131], v[180:183], v[124:127]
	v_mfma_f32_16x16x32_bf16 v[120:123], v[136:139], v[180:183], v[120:123]
	v_mfma_f32_16x16x32_bf16 v[112:115], v[128:131], v[188:191], v[112:115]
	v_mfma_f32_16x16x32_bf16 v[108:111], v[136:139], v[188:191], v[108:111]
	v_mfma_f32_16x16x32_bf16 v[100:103], v[128:131], v[196:199], v[100:103]
	v_mfma_f32_16x16x32_bf16 v[92:95], v[136:139], v[196:199], v[92:95]
	v_mfma_f32_16x16x32_bf16 v[84:87], v[128:131], v[204:207], v[84:87]
	v_mfma_f32_16x16x32_bf16 v[76:79], v[136:139], v[204:207], v[76:79]
	v_mfma_f32_16x16x32_bf16 v[124:127], v[132:135], v[184:187], v[124:127]
	v_mfma_f32_16x16x32_bf16 v[120:123], v[140:143], v[184:187], v[120:123]
	v_mfma_f32_16x16x32_bf16 v[112:115], v[132:135], v[192:195], v[112:115]
	v_mfma_f32_16x16x32_bf16 v[108:111], v[140:143], v[192:195], v[108:111]
	v_mfma_f32_16x16x32_bf16 v[100:103], v[132:135], v[200:203], v[100:103]
	v_mfma_f32_16x16x32_bf16 v[92:95], v[140:143], v[200:203], v[92:95]
	v_mfma_f32_16x16x32_bf16 v[84:87], v[132:135], v[208:211], v[84:87]
	v_mfma_f32_16x16x32_bf16 v[76:79], v[140:143], v[208:211], v[76:79]
	v_mfma_f32_16x16x32_bf16 v[116:119], v[160:163], v[180:183], v[116:119]
	v_mfma_f32_16x16x32_bf16 v[104:107], v[172:175], v[180:183], v[104:107]
	v_mfma_f32_16x16x32_bf16 v[96:99], v[160:163], v[188:191], v[96:99]
	v_mfma_f32_16x16x32_bf16 v[88:91], v[172:175], v[188:191], v[88:91]
	v_mfma_f32_16x16x32_bf16 v[80:83], v[160:163], v[196:199], v[80:83]
	v_mfma_f32_16x16x32_bf16 v[72:75], v[172:175], v[196:199], v[72:75]
	v_mfma_f32_16x16x32_bf16 v[68:71], v[160:163], v[204:207], v[68:71]
	v_mfma_f32_16x16x32_bf16 v[64:67], v[172:175], v[204:207], v[64:67]
	v_mfma_f32_16x16x32_bf16 v[116:119], v[164:167], v[184:187], v[116:119]
	v_mfma_f32_16x16x32_bf16 v[104:107], v[176:179], v[184:187], v[104:107]
	v_mfma_f32_16x16x32_bf16 v[96:99], v[164:167], v[192:195], v[96:99]
	v_mfma_f32_16x16x32_bf16 v[88:91], v[176:179], v[192:195], v[88:91]
	v_mfma_f32_16x16x32_bf16 v[80:83], v[164:167], v[200:203], v[80:83]
	v_mfma_f32_16x16x32_bf16 v[72:75], v[176:179], v[200:203], v[72:75]
	v_mfma_f32_16x16x32_bf16 v[68:71], v[164:167], v[208:211], v[68:71]
	v_mfma_f32_16x16x32_bf16 v[64:67], v[176:179], v[208:211], v[64:67]
	s_barrier
; #define PG8_STAGE(bufoff, gbase, voff) do { _Pragma("unroll") for (int _i = 0; _i < 2; ++_i) \
;         __builtin_amdgcn_global_load_lds((const unsigned*)((const char*)(gbase) + (voff)[_i]), (LAS unsigned*)(lds + (bufoff) + ldsw + _i * 8192), 16, 0, 0); } while (0)
; #define PG8_LDA(dst, b, h) do { _Pragma("unroll") for (int m = 0; m < 4; ++m) _Pragma("unroll") for (int k = 0; k < 2; ++k) dst[m][k] = *(const LAS bf16x8*)(lds + PG8_SA(b, h) + aoff + m * 2048 + k * 1024); } while (0)
; #define PG8_MMA(ai, bj, At, Bt) do { __builtin_amdgcn_s_setprio(1); _Pragma("unroll") for (int m = 0; m < 4; ++m) _Pragma("unroll") for (int n = 0; n < 2; ++n) _Pragma("unroll") for (int k = 0; k < 2; ++k) \
;         acc[ai][bj][m][n] = __builtin_amdgcn_mfma_f32_16x16x32_bf16(Bt[n][k], At[m][k], acc[ai][bj][m][n], 0, 0, 0); __builtin_amdgcn_s_setprio(0); } while (0)
; #define PG8_WAIT_V(n) asm volatile("s_waitcnt vmcnt(" #n ")" ::: "memory")
; #define PG8_WAIT_L(n) asm volatile("s_waitcnt lgkmcnt(" #n ")" ::: "memory")
; #define PG8_BAR __builtin_amdgcn_s_barrier()
; #define PG8_SCHED __builtin_amdgcn_sched_barrier(0)
; template <class Desc, class Epi>
; DI void gemm_phase(LAS unsigned char* lds, const Desc& D, const Epi& E, int wv) {
;     ...
;             PG8_LDA(At, 1, 1); PG8_STAGE(PG8_SB(1, 0), b3, voffB); PG8_STAGE(PG8_SB(1, 1), b3 + hstepB, voffB); PG8_STAGE(PG8_SA(1, 0), a3, voffA);
;             PG8_WAIT_V(8); PG8_WAIT_L(0); PG8_BAR; PG8_MMA(1, 0, At, B0); PG8_MMA(1, 1, At, B1); PG8_BAR; PG8_SCHED;
;         }
;         if (wr == 0) PG8_BAR;
	s_add_i32 s51, s51, s2
	v_lshl_add_u64 v[212:213], v[212:213], 0, s[10:11]
	s_mov_b32 m0, s51
	ds_read_b128 v[180:183], v171 offset:49152
	ds_read_b128 v[184:187], v171 offset:50176
	ds_read_b128 v[188:191], v171 offset:51200
	ds_read_b128 v[192:195], v171 offset:52224
	ds_read_b128 v[196:199], v171 offset:53248
	ds_read_b128 v[200:203], v171 offset:54272
	ds_read_b128 v[204:207], v171 offset:55296
	ds_read_b128 v[208:211], v171 offset:56320
	global_load_lds_dwordx4 v[212:213], off
	s_add_i32 m0, s51, 0x2000
	s_add_u32 s52, s66, 0x80080
	v_lshl_add_u64 v[212:213], v[214:215], 0, s[10:11]
	s_addc_u32 s53, s67, 0
	s_add_i32 s51, s60, s2
	global_load_lds_dwordx4 v[212:213], off
	s_mov_b32 m0, s51
	v_lshl_add_u64 v[212:213], s[52:53], 0, v[148:149]
	global_load_lds_dwordx4 v[212:213], off
	s_add_i32 m0, s51, 0x2000
	v_lshl_add_u64 v[212:213], s[52:53], 0, v[144:145]
	global_load_lds_dwordx4 v[212:213], off
	s_mov_b32 m0, s41
	v_lshl_add_u64 v[212:213], v[216:217], 0, s[10:11]
	global_load_lds_dwordx4 v[212:213], off
	s_mov_b32 m0, s42
	v_lshl_add_u64 v[212:213], v[218:219], 0, s[10:11]
	global_load_lds_dwordx4 v[212:213], off
	s_waitcnt vmcnt(8) lgkmcnt(0)
	s_barrier
	v_mfma_f32_16x16x32_bf16 v[60:63], v[128:131], v[180:183], v[60:63]
	v_mfma_f32_16x16x32_bf16 v[56:59], v[136:139], v[180:183], v[56:59]
	v_mfma_f32_16x16x32_bf16 v[52:55], v[128:131], v[188:191], v[52:55]
	v_mfma_f32_16x16x32_bf16 v[44:47], v[136:139], v[188:191], v[44:47]
	v_mfma_f32_16x16x32_bf16 v[36:39], v[128:131], v[196:199], v[36:39]
	v_mfma_f32_16x16x32_bf16 v[28:31], v[136:139], v[196:199], v[28:31]
	v_mfma_f32_16x16x32_bf16 v[20:23], v[128:131], v[204:207], v[20:23]
	v_mfma_f32_16x16x32_bf16 v[12:15], v[136:139], v[204:207], v[12:15]
	v_mfma_f32_16x16x32_bf16 v[60:63], v[132:135], v[184:187], v[60:63]
	v_mfma_f32_16x16x32_bf16 v[56:59], v[140:143], v[184:187], v[56:59]
	v_mfma_f32_16x16x32_bf16 v[52:55], v[132:135], v[192:195], v[52:55]
	v_mfma_f32_16x16x32_bf16 v[44:47], v[140:143], v[192:195], v[44:47]
	v_mfma_f32_16x16x32_bf16 v[36:39], v[132:135], v[200:203], v[36:39]
	v_mfma_f32_16x16x32_bf16 v[28:31], v[140:143], v[200:203], v[28:31]
	v_mfma_f32_16x16x32_bf16 v[20:23], v[132:135], v[208:211], v[20:23]
	v_mfma_f32_16x16x32_bf16 v[12:15], v[140:143], v[208:211], v[12:15]
	v_mfma_f32_16x16x32_bf16 v[48:51], v[160:163], v[180:183], v[48:51]
	v_mfma_f32_16x16x32_bf16 v[40:43], v[172:175], v[180:183], v[40:43]
	v_mfma_f32_16x16x32_bf16 v[32:35], v[160:163], v[188:191], v[32:35]
	v_mfma_f32_16x16x32_bf16 v[24:27], v[172:175], v[188:191], v[24:27]
	v_mfma_f32_16x16x32_bf16 v[16:19], v[160:163], v[196:199], v[16:19]
	v_mfma_f32_16x16x32_bf16 v[8:11], v[172:175], v[196:199], v[8:11]
	v_mfma_f32_16x16x32_bf16 v[4:7], v[160:163], v[204:207], v[4:7]
	v_mfma_f32_16x16x32_bf16 v[0:3], v[172:175], v[204:207], v[0:3]
	v_mfma_f32_16x16x32_bf16 v[48:51], v[164:167], v[184:187], v[48:51]
	v_mfma_f32_16x16x32_bf16 v[40:43], v[176:179], v[184:187], v[40:43]
	v_mfma_f32_16x16x32_bf16 v[32:35], v[164:167], v[192:195], v[32:35]
	v_mfma_f32_16x16x32_bf16 v[24:27], v[176:179], v[192:195], v[24:27]
	v_mfma_f32_16x16x32_bf16 v[16:19], v[164:167], v[200:203], v[16:19]
	v_mfma_f32_16x16x32_bf16 v[8:11], v[176:179], v[200:203], v[8:11]
	v_mfma_f32_16x16x32_bf16 v[4:7], v[164:167], v[208:211], v[4:7]
	v_mfma_f32_16x16x32_bf16 v[0:3], v[176:179], v[208:211], v[0:3]
	s_barrier
	s_add_i32 s50, s50, 2
	s_add_u32 s6, s6, 0x100
	s_addc_u32 s7, s7, 0
	s_add_u32 s23, s23, 0x100
	s_addc_u32 s49, s49, 0
	s_cmp_gt_u32 s50, 29
	s_cbranch_scc0 .LBB0_831
	s_and_b64 vcc, exec, s[14:15]
	s_cbranch_vccz .LBB0_834
	s_barrier

; #define PG8_STAGE(bufoff, gbase, voff) do { _Pragma("unroll") for (int _i = 0; _i < 2; ++_i) \
;         __builtin_amdgcn_global_load_lds((const unsigned*)((const char*)(gbase) + (voff)[_i]), (LAS unsigned*)(lds + (bufoff) + ldsw + _i * 8192), 16, 0, 0); } while (0)
; #define PG8_LDA(dst, b, h) do { _Pragma("unroll") for (int m = 0; m < 4; ++m) _Pragma("unroll") for (int k = 0; k < 2; ++k) dst[m][k] = *(const LAS bf16x8*)(lds + PG8_SA(b, h) + aoff + m * 2048 + k * 1024); } while (0)
; #define PG8_LDB(dst, b, h) do { _Pragma("unroll") for (int n = 0; n < 2; ++n) _Pragma("unroll") for (int k = 0; k < 2; ++k) dst[n][k] = *(const LAS bf16x8*)(lds + PG8_SB(b, h) + boff + n * 2048 + k * 1024); } while (0)
; #define PG8_MMA(ai, bj, At, Bt) do { __builtin_amdgcn_s_setprio(1); _Pragma("unroll") for (int m = 0; m < 4; ++m) _Pragma("unroll") for (int n = 0; n < 2; ++n) _Pragma("unroll") for (int k = 0; k < 2; ++k) \
;         acc[ai][bj][m][n] = __builtin_amdgcn_mfma_f32_16x16x32_bf16(Bt[n][k], At[m][k], acc[ai][bj][m][n], 0, 0, 0); __builtin_amdgcn_s_setprio(0); } while (0)
; #define PG8_WAIT_V(n) asm volatile("s_waitcnt vmcnt(" #n ")" ::: "memory")
; #define PG8_WAIT_L(n) asm volatile("s_waitcnt lgkmcnt(" #n ")" ::: "memory")
; #define PG8_BAR __builtin_amdgcn_s_barrier()
; #define PG8_SCHED __builtin_amdgcn_sched_barrier(0)
; template <class Desc, class Epi>
; DI void gemm_phase(LAS unsigned char* lds, const Desc& D, const Epi& E, int wv) {
;     ...
;         for (int t = 0; t < nt; t += 2) {
;             const bool last = (t == nt - 2);
;             const char* a1 = cA + (size_t)(t + 1) * kstep;
;             const char* a2 = last ? nA : cA + (size_t)(t + 2) * kstep; const char* b2 = last ? nB : cB + (size_t)(t + 2) * kstep;
;             const char* a3 = a2 + kstep; const char* b3 = b2 + kstep;
;             PG8_LDB(B0, 0, 0); PG8_LDB(B1, 0, 1); PG8_SCHED; PG8_LDA(At, 0, 0); PG8_STAGE(PG8_SA(1, 1), a1 + hstepA, voffA);
;             PG8_WAIT_V(8); PG8_WAIT_L(0); PG8_BAR; PG8_MMA(0, 0, At, B0); PG8_MMA(0, 1, At, B1); PG8_BAR; PG8_SCHED;
;             PG8_LDA(At, 0, 1); PG8_STAGE(PG8_SB(0, 0), b2, voffB); PG8_STAGE(PG8_SB(0, 1), b2 + hstepB, voffB); PG8_STAGE(PG8_SA(0, 0), a2, voffA);
.LBB0_962:
	ds_read_b128 v[146:149], v157
	ds_read_b128 v[150:153], v157 offset:1024
	ds_read_b128 v[160:163], v157 offset:2048
	ds_read_b128 v[164:167], v157 offset:3072
	ds_read_b128 v[168:171], v158
	ds_read_b128 v[172:175], v158 offset:1024
	ds_read_b128 v[176:179], v158 offset:2048
	ds_read_b128 v[180:183], v158 offset:3072
	s_add_u32 s60, s70, 0xfff80080
	s_addc_u32 s63, s71, -1
	s_cmp_eq_u32 s53, 28
	s_cselect_b32 s75, s65, s63
	s_cselect_b32 s74, s64, s60
	s_cselect_b32 s73, s69, s10
	s_cselect_b32 s72, s68, s9
	v_lshl_add_u64 v[154:155], s[70:71], 0, v[138:139]
	s_add_i32 m0, s3, 0xc000
	ds_read_b128 v[184:187], v159
	ds_read_b128 v[188:191], v159 offset:1024
	ds_read_b128 v[192:195], v159 offset:2048
	ds_read_b128 v[196:199], v159 offset:3072
	ds_read_b128 v[200:203], v159 offset:4096
	ds_read_b128 v[204:207], v159 offset:5120
	ds_read_b128 v[208:211], v159 offset:6144
	ds_read_b128 v[212:215], v159 offset:7168
	global_load_lds_dwordx4 v[154:155], off
	s_add_i32 m0, s3, 0xe000
	v_lshl_add_u64 v[154:155], s[70:71], 0, v[140:141]
	global_load_lds_dwordx4 v[154:155], off
	s_waitcnt vmcnt(8) lgkmcnt(0)
	s_barrier
	v_mfma_f32_16x16x32_bf16 v[124:127], v[146:149], v[184:187], v[124:127]
	v_mfma_f32_16x16x32_bf16 v[120:123], v[160:163], v[184:187], v[120:123]
	v_mfma_f32_16x16x32_bf16 v[108:111], v[146:149], v[192:195], v[108:111]
	v_mfma_f32_16x16x32_bf16 v[104:107], v[160:163], v[192:195], v[104:107]
	v_mfma_f32_16x16x32_bf16 v[92:95], v[146:149], v[200:203], v[92:95]
	v_mfma_f32_16x16x32_bf16 v[88:91], v[160:163], v[200:203], v[88:91]
	v_mfma_f32_16x16x32_bf16 v[76:79], v[146:149], v[208:211], v[76:79]
	v_mfma_f32_16x16x32_bf16 v[72:75], v[160:163], v[208:211], v[72:75]
	v_mfma_f32_16x16x32_bf16 v[124:127], v[150:153], v[188:191], v[124:127]
	v_mfma_f32_16x16x32_bf16 v[120:123], v[164:167], v[188:191], v[120:123]
	v_mfma_f32_16x16x32_bf16 v[108:111], v[150:153], v[196:199], v[108:111]
	v_mfma_f32_16x16x32_bf16 v[104:107], v[164:167], v[196:199], v[104:107]
	v_mfma_f32_16x16x32_bf16 v[92:95], v[150:153], v[204:207], v[92:95]
	v_mfma_f32_16x16x32_bf16 v[88:91], v[164:167], v[204:207], v[88:91]
	v_mfma_f32_16x16x32_bf16 v[76:79], v[150:153], v[212:215], v[76:79]
	v_mfma_f32_16x16x32_bf16 v[72:75], v[164:167], v[212:215], v[72:75]
	v_mfma_f32_16x16x32_bf16 v[116:119], v[168:171], v[184:187], v[116:119]
	v_mfma_f32_16x16x32_bf16 v[112:115], v[176:179], v[184:187], v[112:115]
	v_mfma_f32_16x16x32_bf16 v[100:103], v[168:171], v[192:195], v[100:103]
	v_mfma_f32_16x16x32_bf16 v[96:99], v[176:179], v[192:195], v[96:99]
	v_mfma_f32_16x16x32_bf16 v[84:87], v[168:171], v[200:203], v[84:87]
	v_mfma_f32_16x16x32_bf16 v[80:83], v[176:179], v[200:203], v[80:83]
	v_mfma_f32_16x16x32_bf16 v[68:71], v[168:171], v[208:211], v[68:71]
	v_mfma_f32_16x16x32_bf16 v[64:67], v[176:179], v[208:211], v[64:67]
	v_mfma_f32_16x16x32_bf16 v[116:119], v[172:175], v[188:191], v[116:119]
	v_mfma_f32_16x16x32_bf16 v[112:115], v[180:183], v[188:191], v[112:115]
	v_mfma_f32_16x16x32_bf16 v[100:103], v[172:175], v[196:199], v[100:103]
	v_mfma_f32_16x16x32_bf16 v[96:99], v[180:183], v[196:199], v[96:99]
	v_mfma_f32_16x16x32_bf16 v[84:87], v[172:175], v[204:207], v[84:87]
	v_mfma_f32_16x16x32_bf16 v[80:83], v[180:183], v[204:207], v[80:83]
	v_mfma_f32_16x16x32_bf16 v[68:71], v[172:175], v[212:215], v[68:71]
	v_mfma_f32_16x16x32_bf16 v[64:67], v[180:183], v[212:215], v[64:67]
	s_barrier
	s_add_i32 s60, s46, s2
	v_lshl_add_u64 v[154:155], s[72:73], 0, v[130:131]
	s_mov_b32 m0, s60
	ds_read_b128 v[184:187], v159 offset:16384
	ds_read_b128 v[188:191], v159 offset:17408
	ds_read_b128 v[192:195], v159 offset:18432
	ds_read_b128 v[196:199], v159 offset:19456
	ds_read_b128 v[200:203], v159 offset:20480
	ds_read_b128 v[204:207], v159 offset:21504
	ds_read_b128 v[208:211], v159 offset:22528
	ds_read_b128 v[212:215], v159 offset:23552
	global_load_lds_dwordx4 v[154:155], off
	s_add_i32 m0, s60, 0x2000
	s_add_u32 s76, s72, 0x80000
	v_lshl_add_u64 v[216:217], s[72:73], 0, v[134:135]
	s_addc_u32 s77, s73, 0
	s_add_i32 s60, s47, s2
	global_load_lds_dwordx4 v[216:217], off
	v_lshl_add_u64 v[218:219], s[76:77], 0, v[130:131]
	s_mov_b32 m0, s60
	v_lshl_add_u64 v[220:221], s[74:75], 0, v[132:133]
	global_load_lds_dwordx4 v[218:219], off
	s_add_i32 m0, s60, 0x2000
	v_lshl_add_u64 v[218:219], s[76:77], 0, v[134:135]
	global_load_lds_dwordx4 v[218:219], off
	s_mov_b32 m0, s3
	v_lshl_add_u64 v[218:219], s[74:75], 0, v[128:129]
	global_load_lds_dwordx4 v[218:219], off
	s_mov_b32 m0, s28
	s_nop 0
	global_load_lds_dwordx4 v[220:221], off
	s_waitcnt vmcnt(8) lgkmcnt(0)
	s_barrier
; #define PG8_STAGE(bufoff, gbase, voff) do { _Pragma("unroll") for (int _i = 0; _i < 2; ++_i) \
;         __builtin_amdgcn_global_load_lds((const unsigned*)((const char*)(gbase) + (voff)[_i]), (LAS unsigned*)(lds + (bufoff) + ldsw + _i * 8192), 16, 0, 0); } while (0)
; #define PG8_LDA(dst, b, h) do { _Pragma("unroll") for (int m = 0; m < 4; ++m) _Pragma("unroll") for (int k = 0; k < 2; ++k) dst[m][k] = *(const LAS bf16x8*)(lds + PG8_SA(b, h) + aoff + m * 2048 + k * 1024); } while (0)
; #define PG8_LDB(dst, b, h) do { _Pragma("unroll") for (int n = 0; n < 2; ++n) _Pragma("unroll") for (int k = 0; k < 2; ++k) dst[n][k] = *(const LAS bf16x8*)(lds + PG8_SB(b, h) + boff + n * 2048 + k * 1024); } while (0)
; #define PG8_MMA(ai, bj, At, Bt) do { __builtin_amdgcn_s_setprio(1); _Pragma("unroll") for (int m = 0; m < 4; ++m) _Pragma("unroll") for (int n = 0; n < 2; ++n) _Pragma("unroll") for (int k = 0; k < 2; ++k) \
;         acc[ai][bj][m][n] = __builtin_amdgcn_mfma_f32_16x16x32_bf16(Bt[n][k], At[m][k], acc[ai][bj][m][n], 0, 0, 0); __builtin_amdgcn_s_setprio(0); } while (0)
; #define PG8_WAIT_V(n) asm volatile("s_waitcnt vmcnt(" #n ")" ::: "memory")
; #define PG8_WAIT_L(n) asm volatile("s_waitcnt lgkmcnt(" #n ")" ::: "memory")
; #define PG8_BAR __builtin_amdgcn_s_barrier()
; #define PG8_SCHED __builtin_amdgcn_sched_barrier(0)
; template <class Desc, class Epi>
; DI void gemm_phase(LAS unsigned char* lds, const Desc& D, const Epi& E, int wv) {
;     ...
;             PG8_WAIT_V(8); PG8_WAIT_L(0); PG8_BAR; PG8_MMA(1, 0, At, B0); PG8_MMA(1, 1, At, B1); PG8_BAR; PG8_SCHED;
;             PG8_LDB(B0, 1, 0); PG8_LDB(B1, 1, 1); PG8_SCHED; PG8_LDA(At, 1, 0); PG8_STAGE(PG8_SA(0, 1), a2 + hstepA, voffA);
;             PG8_WAIT_V(8); PG8_WAIT_L(0); PG8_BAR; PG8_MMA(0, 0, At, B0); PG8_MMA(0, 1, At, B1); PG8_BAR; PG8_SCHED;
;             PG8_LDA(At, 1, 1); PG8_STAGE(PG8_SB(1, 0), b3, voffB); PG8_STAGE(PG8_SB(1, 1), b3 + hstepB, voffB); PG8_STAGE(PG8_SA(1, 0), a3, voffA);
	v_mfma_f32_16x16x32_bf16 v[60:63], v[146:149], v[184:187], v[60:63]
	v_mfma_f32_16x16x32_bf16 v[56:59], v[160:163], v[184:187], v[56:59]
	v_mfma_f32_16x16x32_bf16 v[44:47], v[146:149], v[192:195], v[44:47]
	v_mfma_f32_16x16x32_bf16 v[40:43], v[160:163], v[192:195], v[40:43]
	v_mfma_f32_16x16x32_bf16 v[28:31], v[146:149], v[200:203], v[28:31]
	v_mfma_f32_16x16x32_bf16 v[24:27], v[160:163], v[200:203], v[24:27]
	v_mfma_f32_16x16x32_bf16 v[12:15], v[146:149], v[208:211], v[12:15]
	v_mfma_f32_16x16x32_bf16 v[8:11], v[160:163], v[208:211], v[8:11]
	v_mfma_f32_16x16x32_bf16 v[60:63], v[150:153], v[188:191], v[60:63]
	v_mfma_f32_16x16x32_bf16 v[56:59], v[164:167], v[188:191], v[56:59]
	v_mfma_f32_16x16x32_bf16 v[44:47], v[150:153], v[196:199], v[44:47]
	v_mfma_f32_16x16x32_bf16 v[40:43], v[164:167], v[196:199], v[40:43]
	v_mfma_f32_16x16x32_bf16 v[28:31], v[150:153], v[204:207], v[28:31]
	v_mfma_f32_16x16x32_bf16 v[24:27], v[164:167], v[204:207], v[24:27]
	v_mfma_f32_16x16x32_bf16 v[12:15], v[150:153], v[212:215], v[12:15]
	v_mfma_f32_16x16x32_bf16 v[8:11], v[164:167], v[212:215], v[8:11]
	v_mfma_f32_16x16x32_bf16 v[52:55], v[168:171], v[184:187], v[52:55]
	v_mfma_f32_16x16x32_bf16 v[48:51], v[176:179], v[184:187], v[48:51]
	v_mfma_f32_16x16x32_bf16 v[36:39], v[168:171], v[192:195], v[36:39]
	v_mfma_f32_16x16x32_bf16 v[32:35], v[176:179], v[192:195], v[32:35]
	v_mfma_f32_16x16x32_bf16 v[20:23], v[168:171], v[200:203], v[20:23]
	v_mfma_f32_16x16x32_bf16 v[16:19], v[176:179], v[200:203], v[16:19]
	v_mfma_f32_16x16x32_bf16 v[4:7], v[168:171], v[208:211], v[4:7]
	v_mfma_f32_16x16x32_bf16 v[0:3], v[176:179], v[208:211], v[0:3]
	v_mfma_f32_16x16x32_bf16 v[52:55], v[172:175], v[188:191], v[52:55]
	v_mfma_f32_16x16x32_bf16 v[48:51], v[180:183], v[188:191], v[48:51]
	v_mfma_f32_16x16x32_bf16 v[36:39], v[172:175], v[196:199], v[36:39]
	v_mfma_f32_16x16x32_bf16 v[32:35], v[180:183], v[196:199], v[32:35]
	v_mfma_f32_16x16x32_bf16 v[20:23], v[172:175], v[204:207], v[20:23]
	v_mfma_f32_16x16x32_bf16 v[16:19], v[180:183], v[204:207], v[16:19]
	v_mfma_f32_16x16x32_bf16 v[4:7], v[172:175], v[212:215], v[4:7]
	v_mfma_f32_16x16x32_bf16 v[0:3], v[180:183], v[212:215], v[0:3]
	s_barrier
	s_add_i32 s60, 0, 0x18000
	v_add_u32_e32 v136, s60, v156
	s_add_i32 s63, 0, 0x1c000
	ds_read_b128 v[146:149], v136
	ds_read_b128 v[150:153], v136 offset:1024
	ds_read_b128 v[160:163], v136 offset:2048
	ds_read_b128 v[164:167], v136 offset:3072
	v_add_u32_e32 v136, s63, v156
	ds_read_b128 v[168:171], v136
	ds_read_b128 v[172:175], v136 offset:1024
	ds_read_b128 v[176:179], v136 offset:2048
	ds_read_b128 v[180:183], v136 offset:3072
	s_add_u32 s74, s74, 0x80000
	s_addc_u32 s75, s75, 0
	s_mov_b32 m0, s29
	v_lshl_add_u64 v[222:223], s[74:75], 0, v[128:129]
	ds_read_b128 v[184:187], v159 offset:32768
	ds_read_b128 v[188:191], v159 offset:33792
	ds_read_b128 v[192:195], v159 offset:34816
	ds_read_b128 v[196:199], v159 offset:35840
	ds_read_b128 v[200:203], v159 offset:36864
	ds_read_b128 v[204:207], v159 offset:37888
	ds_read_b128 v[208:211], v159 offset:38912
	ds_read_b128 v[212:215], v159 offset:39936
	global_load_lds_dwordx4 v[222:223], off
	s_mov_b32 m0, s30
	v_lshl_add_u64 v[222:223], s[74:75], 0, v[132:133]
	global_load_lds_dwordx4 v[222:223], off
	s_waitcnt vmcnt(8) lgkmcnt(0)
	s_barrier
	v_mfma_f32_16x16x32_bf16 v[124:127], v[146:149], v[184:187], v[124:127]
	v_mfma_f32_16x16x32_bf16 v[120:123], v[160:163], v[184:187], v[120:123]
	v_mfma_f32_16x16x32_bf16 v[108:111], v[146:149], v[192:195], v[108:111]
	v_mfma_f32_16x16x32_bf16 v[104:107], v[160:163], v[192:195], v[104:107]
	v_mfma_f32_16x16x32_bf16 v[92:95], v[146:149], v[200:203], v[92:95]
	v_mfma_f32_16x16x32_bf16 v[88:91], v[160:163], v[200:203], v[88:91]
	v_mfma_f32_16x16x32_bf16 v[76:79], v[146:149], v[208:211], v[76:79]
	v_mfma_f32_16x16x32_bf16 v[72:75], v[160:163], v[208:211], v[72:75]
	v_mfma_f32_16x16x32_bf16 v[124:127], v[150:153], v[188:191], v[124:127]
	v_mfma_f32_16x16x32_bf16 v[120:123], v[164:167], v[188:191], v[120:123]
	v_mfma_f32_16x16x32_bf16 v[108:111], v[150:153], v[196:199], v[108:111]
	v_mfma_f32_16x16x32_bf16 v[104:107], v[164:167], v[196:199], v[104:107]
	v_mfma_f32_16x16x32_bf16 v[92:95], v[150:153], v[204:207], v[92:95]
	v_mfma_f32_16x16x32_bf16 v[88:91], v[164:167], v[204:207], v[88:91]
	v_mfma_f32_16x16x32_bf16 v[76:79], v[150:153], v[212:215], v[76:79]
	v_mfma_f32_16x16x32_bf16 v[72:75], v[164:167], v[212:215], v[72:75]
	v_mfma_f32_16x16x32_bf16 v[116:119], v[168:171], v[184:187], v[116:119]
	v_mfma_f32_16x16x32_bf16 v[112:115], v[176:179], v[184:187], v[112:115]
	v_mfma_f32_16x16x32_bf16 v[100:103], v[168:171], v[192:195], v[100:103]
	v_mfma_f32_16x16x32_bf16 v[96:99], v[176:179], v[192:195], v[96:99]
	v_mfma_f32_16x16x32_bf16 v[84:87], v[168:171], v[200:203], v[84:87]
	v_mfma_f32_16x16x32_bf16 v[80:83], v[176:179], v[200:203], v[80:83]
	v_mfma_f32_16x16x32_bf16 v[68:71], v[168:171], v[208:211], v[68:71]
	v_mfma_f32_16x16x32_bf16 v[64:67], v[176:179], v[208:211], v[64:67]
	v_mfma_f32_16x16x32_bf16 v[116:119], v[172:175], v[188:191], v[116:119]
	v_mfma_f32_16x16x32_bf16 v[112:115], v[180:183], v[188:191], v[112:115]
	v_mfma_f32_16x16x32_bf16 v[100:103], v[172:175], v[196:199], v[100:103]
	v_mfma_f32_16x16x32_bf16 v[96:99], v[180:183], v[196:199], v[96:99]
	v_mfma_f32_16x16x32_bf16 v[84:87], v[172:175], v[204:207], v[84:87]
	v_mfma_f32_16x16x32_bf16 v[80:83], v[180:183], v[204:207], v[80:83]
	v_mfma_f32_16x16x32_bf16 v[68:71], v[172:175], v[212:215], v[68:71]
	v_mfma_f32_16x16x32_bf16 v[64:67], v[180:183], v[212:215], v[64:67]
	s_barrier
; #define PG8_STAGE(bufoff, gbase, voff) do { _Pragma("unroll") for (int _i = 0; _i < 2; ++_i) \
;         __builtin_amdgcn_global_load_lds((const unsigned*)((const char*)(gbase) + (voff)[_i]), (LAS unsigned*)(lds + (bufoff) + ldsw + _i * 8192), 16, 0, 0); } while (0)
; #define PG8_LDA(dst, b, h) do { _Pragma("unroll") for (int m = 0; m < 4; ++m) _Pragma("unroll") for (int k = 0; k < 2; ++k) dst[m][k] = *(const LAS bf16x8*)(lds + PG8_SA(b, h) + aoff + m * 2048 + k * 1024); } while (0)
; #define PG8_MMA(ai, bj, At, Bt) do { __builtin_amdgcn_s_setprio(1); _Pragma("unroll") for (int m = 0; m < 4; ++m) _Pragma("unroll") for (int n = 0; n < 2; ++n) _Pragma("unroll") for (int k = 0; k < 2; ++k) \
;         acc[ai][bj][m][n] = __builtin_amdgcn_mfma_f32_16x16x32_bf16(Bt[n][k], At[m][k], acc[ai][bj][m][n], 0, 0, 0); __builtin_amdgcn_s_setprio(0); } while (0)
; #define PG8_WAIT_V(n) asm volatile("s_waitcnt vmcnt(" #n ")" ::: "memory")
; #define PG8_WAIT_L(n) asm volatile("s_waitcnt lgkmcnt(" #n ")" ::: "memory")
; #define PG8_BAR __builtin_amdgcn_s_barrier()
; #define PG8_SCHED __builtin_amdgcn_sched_barrier(0)
; template <class Desc, class Epi>
; DI void gemm_phase(LAS unsigned char* lds, const Desc& D, const Epi& E, int wv) {
;     ...
;             PG8_LDA(At, 1, 1); PG8_STAGE(PG8_SB(1, 0), b3, voffB); PG8_STAGE(PG8_SB(1, 1), b3 + hstepB, voffB); PG8_STAGE(PG8_SA(1, 0), a3, voffA);
;             PG8_WAIT_V(8); PG8_WAIT_L(0); PG8_BAR; PG8_MMA(1, 0, At, B0); PG8_MMA(1, 1, At, B1); PG8_BAR; PG8_SCHED;
;         }
;         if (wr == 0) PG8_BAR;
	s_add_i32 s60, s60, s2
	v_lshl_add_u64 v[154:155], v[154:155], 0, s[14:15]
	s_mov_b32 m0, s60
	ds_read_b128 v[184:187], v159 offset:49152
	ds_read_b128 v[188:191], v159 offset:50176
	ds_read_b128 v[192:195], v159 offset:51200
	ds_read_b128 v[196:199], v159 offset:52224
	ds_read_b128 v[200:203], v159 offset:53248
	ds_read_b128 v[204:207], v159 offset:54272
	ds_read_b128 v[208:211], v159 offset:55296
	ds_read_b128 v[212:215], v159 offset:56320
	global_load_lds_dwordx4 v[154:155], off
	s_add_i32 m0, s60, 0x2000
	s_add_u32 s72, s72, 0x80080
	v_lshl_add_u64 v[154:155], v[216:217], 0, s[14:15]
	s_addc_u32 s73, s73, 0
	s_add_i32 s60, s63, s2
	global_load_lds_dwordx4 v[154:155], off
	s_mov_b32 m0, s60
	v_lshl_add_u64 v[154:155], s[72:73], 0, v[130:131]
	global_load_lds_dwordx4 v[154:155], off
	s_add_i32 m0, s60, 0x2000
	v_lshl_add_u64 v[154:155], s[72:73], 0, v[134:135]
	global_load_lds_dwordx4 v[154:155], off
	s_mov_b32 m0, s41
	v_lshl_add_u64 v[154:155], v[218:219], 0, s[14:15]
	global_load_lds_dwordx4 v[154:155], off
	s_mov_b32 m0, s42
	v_lshl_add_u64 v[154:155], v[220:221], 0, s[14:15]
	global_load_lds_dwordx4 v[154:155], off
	s_waitcnt vmcnt(8) lgkmcnt(0)
	s_barrier
	v_mfma_f32_16x16x32_bf16 v[60:63], v[146:149], v[184:187], v[60:63]
	v_mfma_f32_16x16x32_bf16 v[56:59], v[160:163], v[184:187], v[56:59]
	v_mfma_f32_16x16x32_bf16 v[44:47], v[146:149], v[192:195], v[44:47]
	v_mfma_f32_16x16x32_bf16 v[40:43], v[160:163], v[192:195], v[40:43]
	v_mfma_f32_16x16x32_bf16 v[28:31], v[146:149], v[200:203], v[28:31]
	v_mfma_f32_16x16x32_bf16 v[24:27], v[160:163], v[200:203], v[24:27]
	v_mfma_f32_16x16x32_bf16 v[12:15], v[146:149], v[208:211], v[12:15]
	v_mfma_f32_16x16x32_bf16 v[8:11], v[160:163], v[208:211], v[8:11]
	v_mfma_f32_16x16x32_bf16 v[60:63], v[150:153], v[188:191], v[60:63]
	v_mfma_f32_16x16x32_bf16 v[56:59], v[164:167], v[188:191], v[56:59]
	v_mfma_f32_16x16x32_bf16 v[44:47], v[150:153], v[196:199], v[44:47]
	v_mfma_f32_16x16x32_bf16 v[40:43], v[164:167], v[196:199], v[40:43]
	v_mfma_f32_16x16x32_bf16 v[28:31], v[150:153], v[204:207], v[28:31]
	v_mfma_f32_16x16x32_bf16 v[24:27], v[164:167], v[204:207], v[24:27]
	v_mfma_f32_16x16x32_bf16 v[12:15], v[150:153], v[212:215], v[12:15]
	v_mfma_f32_16x16x32_bf16 v[8:11], v[164:167], v[212:215], v[8:11]
	v_mfma_f32_16x16x32_bf16 v[52:55], v[168:171], v[184:187], v[52:55]
	v_mfma_f32_16x16x32_bf16 v[48:51], v[176:179], v[184:187], v[48:51]
	v_mfma_f32_16x16x32_bf16 v[36:39], v[168:171], v[192:195], v[36:39]
	v_mfma_f32_16x16x32_bf16 v[32:35], v[176:179], v[192:195], v[32:35]
	v_mfma_f32_16x16x32_bf16 v[20:23], v[168:171], v[200:203], v[20:23]
	v_mfma_f32_16x16x32_bf16 v[16:19], v[176:179], v[200:203], v[16:19]
	v_mfma_f32_16x16x32_bf16 v[4:7], v[168:171], v[208:211], v[4:7]
	v_mfma_f32_16x16x32_bf16 v[0:3], v[176:179], v[208:211], v[0:3]
	v_mfma_f32_16x16x32_bf16 v[52:55], v[172:175], v[188:191], v[52:55]
	v_mfma_f32_16x16x32_bf16 v[48:51], v[180:183], v[188:191], v[48:51]
	v_mfma_f32_16x16x32_bf16 v[36:39], v[172:175], v[196:199], v[36:39]
	v_mfma_f32_16x16x32_bf16 v[32:35], v[180:183], v[196:199], v[32:35]
	v_mfma_f32_16x16x32_bf16 v[20:23], v[172:175], v[204:207], v[20:23]
	v_mfma_f32_16x16x32_bf16 v[16:19], v[180:183], v[204:207], v[16:19]
	v_mfma_f32_16x16x32_bf16 v[4:7], v[172:175], v[212:215], v[4:7]
	v_mfma_f32_16x16x32_bf16 v[0:3], v[180:183], v[212:215], v[0:3]
	s_barrier
	s_add_i32 s53, s53, 2
	s_add_u32 s70, s70, 0x100
	s_addc_u32 s71, s71, 0
	s_add_u32 s9, s9, 0x100
	s_addc_u32 s10, s10, 0
	s_cmp_gt_u32 s53, 29
	s_cbranch_scc0 .LBB0_962
	s_and_b64 vcc, exec, s[20:21]
	s_cbranch_vccz .LBB0_965
	s_barrier

; #define PG8_STAGE(bufoff, gbase, voff) do { _Pragma("unroll") for (int _i = 0; _i < 2; ++_i) \
;         __builtin_amdgcn_global_load_lds((const unsigned*)((const char*)(gbase) + (voff)[_i]), (LAS unsigned*)(lds + (bufoff) + ldsw + _i * 8192), 16, 0, 0); } while (0)
; #define PG8_LDA(dst, b, h) do { _Pragma("unroll") for (int m = 0; m < 4; ++m) _Pragma("unroll") for (int k = 0; k < 2; ++k) dst[m][k] = *(const LAS bf16x8*)(lds + PG8_SA(b, h) + aoff + m * 2048 + k * 1024); } while (0)
; #define PG8_LDB(dst, b, h) do { _Pragma("unroll") for (int n = 0; n < 2; ++n) _Pragma("unroll") for (int k = 0; k < 2; ++k) dst[n][k] = *(const LAS bf16x8*)(lds + PG8_SB(b, h) + boff + n * 2048 + k * 1024); } while (0)
; #define PG8_MMA(ai, bj, At, Bt) do { __builtin_amdgcn_s_setprio(1); _Pragma("unroll") for (int m = 0; m < 4; ++m) _Pragma("unroll") for (int n = 0; n < 2; ++n) _Pragma("unroll") for (int k = 0; k < 2; ++k) \
;         acc[ai][bj][m][n] = __builtin_amdgcn_mfma_f32_16x16x32_bf16(Bt[n][k], At[m][k], acc[ai][bj][m][n], 0, 0, 0); __builtin_amdgcn_s_setprio(0); } while (0)
; #define PG8_WAIT_V(n) asm volatile("s_waitcnt vmcnt(" #n ")" ::: "memory")
; #define PG8_WAIT_L(n) asm volatile("s_waitcnt lgkmcnt(" #n ")" ::: "memory")
; #define PG8_BAR __builtin_amdgcn_s_barrier()
; #define PG8_SCHED __builtin_amdgcn_sched_barrier(0)
; template <class Desc, class Epi>
; DI void gemm_phase(LAS unsigned char* lds, const Desc& D, const Epi& E, int wv) {
;     ...
;         for (int t = 0; t < nt; t += 2) {
;             const bool last = (t == nt - 2);
;             const char* a1 = cA + (size_t)(t + 1) * kstep;
;             const char* a2 = last ? nA : cA + (size_t)(t + 2) * kstep; const char* b2 = last ? nB : cB + (size_t)(t + 2) * kstep;
;             const char* a3 = a2 + kstep; const char* b3 = b2 + kstep;
;             PG8_LDB(B0, 0, 0); PG8_LDB(B1, 0, 1); PG8_SCHED; PG8_LDA(At, 0, 0); PG8_STAGE(PG8_SA(1, 1), a1 + hstepA, voffA);
;             PG8_WAIT_V(8); PG8_WAIT_L(0); PG8_BAR; PG8_MMA(0, 0, At, B0); PG8_MMA(0, 1, At, B1); PG8_BAR; PG8_SCHED;
;             PG8_LDA(At, 0, 1); PG8_STAGE(PG8_SB(0, 0), b2, voffB); PG8_STAGE(PG8_SB(0, 1), b2 + hstepB, voffB); PG8_STAGE(PG8_SA(0, 0), a2, voffA);
.LBB0_1313:
	ds_read_b128 v[146:149], v157
	ds_read_b128 v[150:153], v157 offset:1024
	ds_read_b128 v[160:163], v157 offset:2048
	ds_read_b128 v[164:167], v157 offset:3072
	ds_read_b128 v[168:171], v158
	ds_read_b128 v[172:175], v158 offset:1024
	ds_read_b128 v[176:179], v158 offset:2048
	ds_read_b128 v[180:183], v158 offset:3072
	s_add_u32 s40, s22, 0xfff80080
	s_addc_u32 s41, s23, -1
	s_cmp_eq_u32 s50, 28
	s_cselect_b32 s63, s15, s41
	s_cselect_b32 s62, s14, s40
	s_cselect_b32 s41, s17, s21
	s_cselect_b32 s40, s16, s19
	v_lshl_add_u64 v[154:155], s[22:23], 0, v[138:139]
	s_add_i32 m0, s28, 0xc000
	ds_read_b128 v[184:187], v159
	ds_read_b128 v[188:191], v159 offset:1024
	ds_read_b128 v[192:195], v159 offset:2048
	ds_read_b128 v[196:199], v159 offset:3072
	ds_read_b128 v[200:203], v159 offset:4096
	ds_read_b128 v[204:207], v159 offset:5120
	ds_read_b128 v[208:211], v159 offset:6144
	ds_read_b128 v[212:215], v159 offset:7168
	global_load_lds_dwordx4 v[154:155], off
	s_add_i32 m0, s28, 0xe000
	v_lshl_add_u64 v[154:155], s[22:23], 0, v[140:141]
	global_load_lds_dwordx4 v[154:155], off
	s_waitcnt vmcnt(8) lgkmcnt(0)
	s_barrier
	v_mfma_f32_16x16x32_bf16 v[124:127], v[146:149], v[184:187], v[124:127]
	v_mfma_f32_16x16x32_bf16 v[120:123], v[160:163], v[184:187], v[120:123]
	v_mfma_f32_16x16x32_bf16 v[108:111], v[146:149], v[192:195], v[108:111]
	v_mfma_f32_16x16x32_bf16 v[104:107], v[160:163], v[192:195], v[104:107]
	v_mfma_f32_16x16x32_bf16 v[92:95], v[146:149], v[200:203], v[92:95]
	v_mfma_f32_16x16x32_bf16 v[88:91], v[160:163], v[200:203], v[88:91]
	v_mfma_f32_16x16x32_bf16 v[76:79], v[146:149], v[208:211], v[76:79]
	v_mfma_f32_16x16x32_bf16 v[72:75], v[160:163], v[208:211], v[72:75]
	v_mfma_f32_16x16x32_bf16 v[124:127], v[150:153], v[188:191], v[124:127]
	v_mfma_f32_16x16x32_bf16 v[120:123], v[164:167], v[188:191], v[120:123]
	v_mfma_f32_16x16x32_bf16 v[108:111], v[150:153], v[196:199], v[108:111]
	v_mfma_f32_16x16x32_bf16 v[104:107], v[164:167], v[196:199], v[104:107]
	v_mfma_f32_16x16x32_bf16 v[92:95], v[150:153], v[204:207], v[92:95]
	v_mfma_f32_16x16x32_bf16 v[88:91], v[164:167], v[204:207], v[88:91]
	v_mfma_f32_16x16x32_bf16 v[76:79], v[150:153], v[212:215], v[76:79]
	v_mfma_f32_16x16x32_bf16 v[72:75], v[164:167], v[212:215], v[72:75]
	v_mfma_f32_16x16x32_bf16 v[116:119], v[168:171], v[184:187], v[116:119]
	v_mfma_f32_16x16x32_bf16 v[112:115], v[176:179], v[184:187], v[112:115]
	v_mfma_f32_16x16x32_bf16 v[100:103], v[168:171], v[192:195], v[100:103]
	v_mfma_f32_16x16x32_bf16 v[96:99], v[176:179], v[192:195], v[96:99]
	v_mfma_f32_16x16x32_bf16 v[84:87], v[168:171], v[200:203], v[84:87]
	v_mfma_f32_16x16x32_bf16 v[80:83], v[176:179], v[200:203], v[80:83]
	v_mfma_f32_16x16x32_bf16 v[68:71], v[168:171], v[208:211], v[68:71]
	v_mfma_f32_16x16x32_bf16 v[64:67], v[176:179], v[208:211], v[64:67]
	v_mfma_f32_16x16x32_bf16 v[116:119], v[172:175], v[188:191], v[116:119]
	v_mfma_f32_16x16x32_bf16 v[112:115], v[180:183], v[188:191], v[112:115]
	v_mfma_f32_16x16x32_bf16 v[100:103], v[172:175], v[196:199], v[100:103]
	v_mfma_f32_16x16x32_bf16 v[96:99], v[180:183], v[196:199], v[96:99]
	v_mfma_f32_16x16x32_bf16 v[84:87], v[172:175], v[204:207], v[84:87]
	v_mfma_f32_16x16x32_bf16 v[80:83], v[180:183], v[204:207], v[80:83]
	v_mfma_f32_16x16x32_bf16 v[68:71], v[172:175], v[212:215], v[68:71]
	v_mfma_f32_16x16x32_bf16 v[64:67], v[180:183], v[212:215], v[64:67]
	s_barrier
	s_add_i32 s51, s48, s2
	v_lshl_add_u64 v[154:155], s[40:41], 0, v[132:133]
	s_mov_b32 m0, s51
	ds_read_b128 v[184:187], v159 offset:16384
	ds_read_b128 v[188:191], v159 offset:17408
	ds_read_b128 v[192:195], v159 offset:18432
	ds_read_b128 v[196:199], v159 offset:19456
	ds_read_b128 v[200:203], v159 offset:20480
	ds_read_b128 v[204:207], v159 offset:21504
	ds_read_b128 v[208:211], v159 offset:22528
	ds_read_b128 v[212:215], v159 offset:23552
	global_load_lds_dwordx4 v[154:155], off
	s_add_i32 m0, s51, 0x2000
	s_add_u32 s52, s40, 0x80000
	v_lshl_add_u64 v[216:217], s[40:41], 0, v[128:129]
	s_addc_u32 s53, s41, 0
	s_add_i32 s51, s49, s2
	global_load_lds_dwordx4 v[216:217], off
	v_lshl_add_u64 v[218:219], s[52:53], 0, v[132:133]
	s_mov_b32 m0, s51
	v_lshl_add_u64 v[220:221], s[62:63], 0, v[130:131]
	global_load_lds_dwordx4 v[218:219], off
	s_add_i32 m0, s51, 0x2000
	v_lshl_add_u64 v[218:219], s[52:53], 0, v[128:129]
	global_load_lds_dwordx4 v[218:219], off
	s_mov_b32 m0, s28
	v_lshl_add_u64 v[218:219], s[62:63], 0, v[134:135]
	global_load_lds_dwordx4 v[218:219], off
	s_mov_b32 m0, s29
	s_nop 0
	global_load_lds_dwordx4 v[220:221], off
	s_waitcnt vmcnt(8) lgkmcnt(0)
	s_barrier
; #define PG8_STAGE(bufoff, gbase, voff) do { _Pragma("unroll") for (int _i = 0; _i < 2; ++_i) \
;         __builtin_amdgcn_global_load_lds((const unsigned*)((const char*)(gbase) + (voff)[_i]), (LAS unsigned*)(lds + (bufoff) + ldsw + _i * 8192), 16, 0, 0); } while (0)
; #define PG8_LDA(dst, b, h) do { _Pragma("unroll") for (int m = 0; m < 4; ++m) _Pragma("unroll") for (int k = 0; k < 2; ++k) dst[m][k] = *(const LAS bf16x8*)(lds + PG8_SA(b, h) + aoff + m * 2048 + k * 1024); } while (0)
; #define PG8_LDB(dst, b, h) do { _Pragma("unroll") for (int n = 0; n < 2; ++n) _Pragma("unroll") for (int k = 0; k < 2; ++k) dst[n][k] = *(const LAS bf16x8*)(lds + PG8_SB(b, h) + boff + n * 2048 + k * 1024); } while (0)
; #define PG8_MMA(ai, bj, At, Bt) do { __builtin_amdgcn_s_setprio(1); _Pragma("unroll") for (int m = 0; m < 4; ++m) _Pragma("unroll") for (int n = 0; n < 2; ++n) _Pragma("unroll") for (int k = 0; k < 2; ++k) \
;         acc[ai][bj][m][n] = __builtin_amdgcn_mfma_f32_16x16x32_bf16(Bt[n][k], At[m][k], acc[ai][bj][m][n], 0, 0, 0); __builtin_amdgcn_s_setprio(0); } while (0)
; #define PG8_WAIT_V(n) asm volatile("s_waitcnt vmcnt(" #n ")" ::: "memory")
; #define PG8_WAIT_L(n) asm volatile("s_waitcnt lgkmcnt(" #n ")" ::: "memory")
; #define PG8_BAR __builtin_amdgcn_s_barrier()
; #define PG8_SCHED __builtin_amdgcn_sched_barrier(0)
; template <class Desc, class Epi>
; DI void gemm_phase(LAS unsigned char* lds, const Desc& D, const Epi& E, int wv) {
;     ...
;             PG8_WAIT_V(8); PG8_WAIT_L(0); PG8_BAR; PG8_MMA(1, 0, At, B0); PG8_MMA(1, 1, At, B1); PG8_BAR; PG8_SCHED;
;             PG8_LDB(B0, 1, 0); PG8_LDB(B1, 1, 1); PG8_SCHED; PG8_LDA(At, 1, 0); PG8_STAGE(PG8_SA(0, 1), a2 + hstepA, voffA);
;             PG8_WAIT_V(8); PG8_WAIT_L(0); PG8_BAR; PG8_MMA(0, 0, At, B0); PG8_MMA(0, 1, At, B1); PG8_BAR; PG8_SCHED;
;             PG8_LDA(At, 1, 1); PG8_STAGE(PG8_SB(1, 0), b3, voffB); PG8_STAGE(PG8_SB(1, 1), b3 + hstepB, voffB); PG8_STAGE(PG8_SA(1, 0), a3, voffA);
	v_mfma_f32_16x16x32_bf16 v[60:63], v[146:149], v[184:187], v[60:63]
	v_mfma_f32_16x16x32_bf16 v[56:59], v[160:163], v[184:187], v[56:59]
	v_mfma_f32_16x16x32_bf16 v[44:47], v[146:149], v[192:195], v[44:47]
	v_mfma_f32_16x16x32_bf16 v[40:43], v[160:163], v[192:195], v[40:43]
	v_mfma_f32_16x16x32_bf16 v[28:31], v[146:149], v[200:203], v[28:31]
	v_mfma_f32_16x16x32_bf16 v[24:27], v[160:163], v[200:203], v[24:27]
	v_mfma_f32_16x16x32_bf16 v[12:15], v[146:149], v[208:211], v[12:15]
	v_mfma_f32_16x16x32_bf16 v[8:11], v[160:163], v[208:211], v[8:11]
	v_mfma_f32_16x16x32_bf16 v[60:63], v[150:153], v[188:191], v[60:63]
	v_mfma_f32_16x16x32_bf16 v[56:59], v[164:167], v[188:191], v[56:59]
	v_mfma_f32_16x16x32_bf16 v[44:47], v[150:153], v[196:199], v[44:47]
	v_mfma_f32_16x16x32_bf16 v[40:43], v[164:167], v[196:199], v[40:43]
	v_mfma_f32_16x16x32_bf16 v[28:31], v[150:153], v[204:207], v[28:31]
	v_mfma_f32_16x16x32_bf16 v[24:27], v[164:167], v[204:207], v[24:27]
	v_mfma_f32_16x16x32_bf16 v[12:15], v[150:153], v[212:215], v[12:15]
	v_mfma_f32_16x16x32_bf16 v[8:11], v[164:167], v[212:215], v[8:11]
	v_mfma_f32_16x16x32_bf16 v[52:55], v[168:171], v[184:187], v[52:55]
	v_mfma_f32_16x16x32_bf16 v[48:51], v[176:179], v[184:187], v[48:51]
	v_mfma_f32_16x16x32_bf16 v[36:39], v[168:171], v[192:195], v[36:39]
	v_mfma_f32_16x16x32_bf16 v[32:35], v[176:179], v[192:195], v[32:35]
	v_mfma_f32_16x16x32_bf16 v[20:23], v[168:171], v[200:203], v[20:23]
	v_mfma_f32_16x16x32_bf16 v[16:19], v[176:179], v[200:203], v[16:19]
	v_mfma_f32_16x16x32_bf16 v[4:7], v[168:171], v[208:211], v[4:7]
	v_mfma_f32_16x16x32_bf16 v[0:3], v[176:179], v[208:211], v[0:3]
	v_mfma_f32_16x16x32_bf16 v[52:55], v[172:175], v[188:191], v[52:55]
	v_mfma_f32_16x16x32_bf16 v[48:51], v[180:183], v[188:191], v[48:51]
	v_mfma_f32_16x16x32_bf16 v[36:39], v[172:175], v[196:199], v[36:39]
	v_mfma_f32_16x16x32_bf16 v[32:35], v[180:183], v[196:199], v[32:35]
	v_mfma_f32_16x16x32_bf16 v[20:23], v[172:175], v[204:207], v[20:23]
	v_mfma_f32_16x16x32_bf16 v[16:19], v[180:183], v[204:207], v[16:19]
	v_mfma_f32_16x16x32_bf16 v[4:7], v[172:175], v[212:215], v[4:7]
	v_mfma_f32_16x16x32_bf16 v[0:3], v[180:183], v[212:215], v[0:3]
	s_barrier
	s_add_i32 s51, 0, 0x18000
	v_add_u32_e32 v136, s51, v156
	s_add_i32 s60, 0, 0x1c000
	ds_read_b128 v[146:149], v136
	ds_read_b128 v[150:153], v136 offset:1024
	ds_read_b128 v[160:163], v136 offset:2048
	ds_read_b128 v[164:167], v136 offset:3072
	v_add_u32_e32 v136, s60, v156
	ds_read_b128 v[168:171], v136
	ds_read_b128 v[172:175], v136 offset:1024
	ds_read_b128 v[176:179], v136 offset:2048
	ds_read_b128 v[180:183], v136 offset:3072
	s_add_u32 s52, s62, 0x80000
	s_addc_u32 s53, s63, 0
	s_mov_b32 m0, s30
	v_lshl_add_u64 v[222:223], s[52:53], 0, v[134:135]
	ds_read_b128 v[184:187], v159 offset:32768
	ds_read_b128 v[188:191], v159 offset:33792
	ds_read_b128 v[192:195], v159 offset:34816
	ds_read_b128 v[196:199], v159 offset:35840
	ds_read_b128 v[200:203], v159 offset:36864
	ds_read_b128 v[204:207], v159 offset:37888
	ds_read_b128 v[208:211], v159 offset:38912
	ds_read_b128 v[212:215], v159 offset:39936
	global_load_lds_dwordx4 v[222:223], off
	s_mov_b32 m0, s31
	v_lshl_add_u64 v[222:223], s[52:53], 0, v[130:131]
	global_load_lds_dwordx4 v[222:223], off
	s_waitcnt vmcnt(8) lgkmcnt(0)
	s_barrier
	v_mfma_f32_16x16x32_bf16 v[124:127], v[146:149], v[184:187], v[124:127]
	v_mfma_f32_16x16x32_bf16 v[120:123], v[160:163], v[184:187], v[120:123]
	v_mfma_f32_16x16x32_bf16 v[108:111], v[146:149], v[192:195], v[108:111]
	v_mfma_f32_16x16x32_bf16 v[104:107], v[160:163], v[192:195], v[104:107]
	v_mfma_f32_16x16x32_bf16 v[92:95], v[146:149], v[200:203], v[92:95]
	v_mfma_f32_16x16x32_bf16 v[88:91], v[160:163], v[200:203], v[88:91]
	v_mfma_f32_16x16x32_bf16 v[76:79], v[146:149], v[208:211], v[76:79]
	v_mfma_f32_16x16x32_bf16 v[72:75], v[160:163], v[208:211], v[72:75]
	v_mfma_f32_16x16x32_bf16 v[124:127], v[150:153], v[188:191], v[124:127]
	v_mfma_f32_16x16x32_bf16 v[120:123], v[164:167], v[188:191], v[120:123]
	v_mfma_f32_16x16x32_bf16 v[108:111], v[150:153], v[196:199], v[108:111]
	v_mfma_f32_16x16x32_bf16 v[104:107], v[164:167], v[196:199], v[104:107]
	v_mfma_f32_16x16x32_bf16 v[92:95], v[150:153], v[204:207], v[92:95]
	v_mfma_f32_16x16x32_bf16 v[88:91], v[164:167], v[204:207], v[88:91]
	v_mfma_f32_16x16x32_bf16 v[76:79], v[150:153], v[212:215], v[76:79]
	v_mfma_f32_16x16x32_bf16 v[72:75], v[164:167], v[212:215], v[72:75]
	v_mfma_f32_16x16x32_bf16 v[116:119], v[168:171], v[184:187], v[116:119]
	v_mfma_f32_16x16x32_bf16 v[112:115], v[176:179], v[184:187], v[112:115]
	v_mfma_f32_16x16x32_bf16 v[100:103], v[168:171], v[192:195], v[100:103]
	v_mfma_f32_16x16x32_bf16 v[96:99], v[176:179], v[192:195], v[96:99]
	v_mfma_f32_16x16x32_bf16 v[84:87], v[168:171], v[200:203], v[84:87]
	v_mfma_f32_16x16x32_bf16 v[80:83], v[176:179], v[200:203], v[80:83]
	v_mfma_f32_16x16x32_bf16 v[68:71], v[168:171], v[208:211], v[68:71]
	v_mfma_f32_16x16x32_bf16 v[64:67], v[176:179], v[208:211], v[64:67]
	v_mfma_f32_16x16x32_bf16 v[116:119], v[172:175], v[188:191], v[116:119]
	v_mfma_f32_16x16x32_bf16 v[112:115], v[180:183], v[188:191], v[112:115]
	v_mfma_f32_16x16x32_bf16 v[100:103], v[172:175], v[196:199], v[100:103]
	v_mfma_f32_16x16x32_bf16 v[96:99], v[180:183], v[196:199], v[96:99]
	v_mfma_f32_16x16x32_bf16 v[84:87], v[172:175], v[204:207], v[84:87]
	v_mfma_f32_16x16x32_bf16 v[80:83], v[180:183], v[204:207], v[80:83]
	v_mfma_f32_16x16x32_bf16 v[68:71], v[172:175], v[212:215], v[68:71]
	v_mfma_f32_16x16x32_bf16 v[64:67], v[180:183], v[212:215], v[64:67]
	s_barrier
; #define PG8_STAGE(bufoff, gbase, voff) do { _Pragma("unroll") for (int _i = 0; _i < 2; ++_i) \
;         __builtin_amdgcn_global_load_lds((const unsigned*)((const char*)(gbase) + (voff)[_i]), (LAS unsigned*)(lds + (bufoff) + ldsw + _i * 8192), 16, 0, 0); } while (0)
; #define PG8_LDA(dst, b, h) do { _Pragma("unroll") for (int m = 0; m < 4; ++m) _Pragma("unroll") for (int k = 0; k < 2; ++k) dst[m][k] = *(const LAS bf16x8*)(lds + PG8_SA(b, h) + aoff + m * 2048 + k * 1024); } while (0)
; #define PG8_MMA(ai, bj, At, Bt) do { __builtin_amdgcn_s_setprio(1); _Pragma("unroll") for (int m = 0; m < 4; ++m) _Pragma("unroll") for (int n = 0; n < 2; ++n) _Pragma("unroll") for (int k = 0; k < 2; ++k) \
;         acc[ai][bj][m][n] = __builtin_amdgcn_mfma_f32_16x16x32_bf16(Bt[n][k], At[m][k], acc[ai][bj][m][n], 0, 0, 0); __builtin_amdgcn_s_setprio(0); } while (0)
; #define PG8_WAIT_V(n) asm volatile("s_waitcnt vmcnt(" #n ")" ::: "memory")
; #define PG8_WAIT_L(n) asm volatile("s_waitcnt lgkmcnt(" #n ")" ::: "memory")
; #define PG8_BAR __builtin_amdgcn_s_barrier()
; #define PG8_SCHED __builtin_amdgcn_sched_barrier(0)
; template <class Desc, class Epi>
; DI void gemm_phase(LAS unsigned char* lds, const Desc& D, const Epi& E, int wv) {
;     ...
;             PG8_LDA(At, 1, 1); PG8_STAGE(PG8_SB(1, 0), b3, voffB); PG8_STAGE(PG8_SB(1, 1), b3 + hstepB, voffB); PG8_STAGE(PG8_SA(1, 0), a3, voffA);
;             PG8_WAIT_V(8); PG8_WAIT_L(0); PG8_BAR; PG8_MMA(1, 0, At, B0); PG8_MMA(1, 1, At, B1); PG8_BAR; PG8_SCHED;
;         }
;         if (wr == 0) PG8_BAR;
	s_add_i32 s51, s51, s2
	v_lshl_add_u64 v[154:155], v[154:155], 0, s[10:11]
	s_mov_b32 m0, s51
	ds_read_b128 v[184:187], v159 offset:49152
	ds_read_b128 v[188:191], v159 offset:50176
	ds_read_b128 v[192:195], v159 offset:51200
	ds_read_b128 v[196:199], v159 offset:52224
	ds_read_b128 v[200:203], v159 offset:53248
	ds_read_b128 v[204:207], v159 offset:54272
	ds_read_b128 v[208:211], v159 offset:55296
	ds_read_b128 v[212:215], v159 offset:56320
	global_load_lds_dwordx4 v[154:155], off
	s_add_i32 m0, s51, 0x2000
	s_add_u32 s40, s40, 0x80080
	v_lshl_add_u64 v[154:155], v[216:217], 0, s[10:11]
	s_addc_u32 s41, s41, 0
	s_add_i32 s51, s60, s2
	global_load_lds_dwordx4 v[154:155], off
	s_mov_b32 m0, s51
	v_lshl_add_u64 v[154:155], s[40:41], 0, v[132:133]
	global_load_lds_dwordx4 v[154:155], off
	s_add_i32 m0, s51, 0x2000
	v_lshl_add_u64 v[154:155], s[40:41], 0, v[128:129]
	global_load_lds_dwordx4 v[154:155], off
	s_mov_b32 m0, s43
	v_lshl_add_u64 v[154:155], v[218:219], 0, s[10:11]
	global_load_lds_dwordx4 v[154:155], off
	s_mov_b32 m0, s46
	v_lshl_add_u64 v[154:155], v[220:221], 0, s[10:11]
	global_load_lds_dwordx4 v[154:155], off
	s_waitcnt vmcnt(8) lgkmcnt(0)
	s_barrier
	v_mfma_f32_16x16x32_bf16 v[60:63], v[146:149], v[184:187], v[60:63]
	v_mfma_f32_16x16x32_bf16 v[56:59], v[160:163], v[184:187], v[56:59]
	v_mfma_f32_16x16x32_bf16 v[44:47], v[146:149], v[192:195], v[44:47]
	v_mfma_f32_16x16x32_bf16 v[40:43], v[160:163], v[192:195], v[40:43]
	v_mfma_f32_16x16x32_bf16 v[28:31], v[146:149], v[200:203], v[28:31]
	v_mfma_f32_16x16x32_bf16 v[24:27], v[160:163], v[200:203], v[24:27]
	v_mfma_f32_16x16x32_bf16 v[12:15], v[146:149], v[208:211], v[12:15]
	v_mfma_f32_16x16x32_bf16 v[8:11], v[160:163], v[208:211], v[8:11]
	v_mfma_f32_16x16x32_bf16 v[60:63], v[150:153], v[188:191], v[60:63]
	v_mfma_f32_16x16x32_bf16 v[56:59], v[164:167], v[188:191], v[56:59]
	v_mfma_f32_16x16x32_bf16 v[44:47], v[150:153], v[196:199], v[44:47]
	v_mfma_f32_16x16x32_bf16 v[40:43], v[164:167], v[196:199], v[40:43]
	v_mfma_f32_16x16x32_bf16 v[28:31], v[150:153], v[204:207], v[28:31]
	v_mfma_f32_16x16x32_bf16 v[24:27], v[164:167], v[204:207], v[24:27]
	v_mfma_f32_16x16x32_bf16 v[12:15], v[150:153], v[212:215], v[12:15]
	v_mfma_f32_16x16x32_bf16 v[8:11], v[164:167], v[212:215], v[8:11]
	v_mfma_f32_16x16x32_bf16 v[52:55], v[168:171], v[184:187], v[52:55]
	v_mfma_f32_16x16x32_bf16 v[48:51], v[176:179], v[184:187], v[48:51]
	v_mfma_f32_16x16x32_bf16 v[36:39], v[168:171], v[192:195], v[36:39]
	v_mfma_f32_16x16x32_bf16 v[32:35], v[176:179], v[192:195], v[32:35]
	v_mfma_f32_16x16x32_bf16 v[20:23], v[168:171], v[200:203], v[20:23]
	v_mfma_f32_16x16x32_bf16 v[16:19], v[176:179], v[200:203], v[16:19]
	v_mfma_f32_16x16x32_bf16 v[4:7], v[168:171], v[208:211], v[4:7]
	v_mfma_f32_16x16x32_bf16 v[0:3], v[176:179], v[208:211], v[0:3]
	v_mfma_f32_16x16x32_bf16 v[52:55], v[172:175], v[188:191], v[52:55]
	v_mfma_f32_16x16x32_bf16 v[48:51], v[180:183], v[188:191], v[48:51]
	v_mfma_f32_16x16x32_bf16 v[36:39], v[172:175], v[196:199], v[36:39]
	v_mfma_f32_16x16x32_bf16 v[32:35], v[180:183], v[196:199], v[32:35]
	v_mfma_f32_16x16x32_bf16 v[20:23], v[172:175], v[204:207], v[20:23]
	v_mfma_f32_16x16x32_bf16 v[16:19], v[180:183], v[204:207], v[16:19]
	v_mfma_f32_16x16x32_bf16 v[4:7], v[172:175], v[212:215], v[4:7]
	v_mfma_f32_16x16x32_bf16 v[0:3], v[180:183], v[212:215], v[0:3]
	s_barrier
	s_add_i32 s50, s50, 2
	s_add_u32 s22, s22, 0x100
	s_addc_u32 s23, s23, 0
	s_add_u32 s19, s19, 0x100
	s_addc_u32 s21, s21, 0
	s_cmp_gt_u32 s50, 29
	s_cbranch_scc0 .LBB0_1313
	s_and_b64 vcc, exec, s[12:13]
	s_cbranch_vccz .LBB0_1316
	s_barrier

; #define PG8_STAGE(bufoff, gbase, voff) do { _Pragma("unroll") for (int _i = 0; _i < 2; ++_i) \
;         __builtin_amdgcn_global_load_lds((const unsigned*)((const char*)(gbase) + (voff)[_i]), (LAS unsigned*)(lds + (bufoff) + ldsw + _i * 8192), 16, 0, 0); } while (0)
; #define PG8_LDA(dst, b, h) do { _Pragma("unroll") for (int m = 0; m < 4; ++m) _Pragma("unroll") for (int k = 0; k < 2; ++k) dst[m][k] = *(const LAS bf16x8*)(lds + PG8_SA(b, h) + aoff + m * 2048 + k * 1024); } while (0)
; #define PG8_LDB(dst, b, h) do { _Pragma("unroll") for (int n = 0; n < 2; ++n) _Pragma("unroll") for (int k = 0; k < 2; ++k) dst[n][k] = *(const LAS bf16x8*)(lds + PG8_SB(b, h) + boff + n * 2048 + k * 1024); } while (0)
; #define PG8_MMA(ai, bj, At, Bt) do { __builtin_amdgcn_s_setprio(1); _Pragma("unroll") for (int m = 0; m < 4; ++m) _Pragma("unroll") for (int n = 0; n < 2; ++n) _Pragma("unroll") for (int k = 0; k < 2; ++k) \
;         acc[ai][bj][m][n] = __builtin_amdgcn_mfma_f32_16x16x32_bf16(Bt[n][k], At[m][k], acc[ai][bj][m][n], 0, 0, 0); __builtin_amdgcn_s_setprio(0); } while (0)
; #define PG8_WAIT_V(n) asm volatile("s_waitcnt vmcnt(" #n ")" ::: "memory")
; #define PG8_WAIT_L(n) asm volatile("s_waitcnt lgkmcnt(" #n ")" ::: "memory")
; #define PG8_BAR __builtin_amdgcn_s_barrier()
; #define PG8_SCHED __builtin_amdgcn_sched_barrier(0)
; template <class Desc, class Epi>
; DI void gemm_phase(LAS unsigned char* lds, const Desc& D, const Epi& E, int wv) {
;     ...
;         for (int t = 0; t < nt; t += 2) {
;             const bool last = (t == nt - 2);
;             const char* a1 = cA + (size_t)(t + 1) * kstep;
;             const char* a2 = last ? nA : cA + (size_t)(t + 2) * kstep; const char* b2 = last ? nB : cB + (size_t)(t + 2) * kstep;
;             const char* a3 = a2 + kstep; const char* b3 = b2 + kstep;
;             PG8_LDB(B0, 0, 0); PG8_LDB(B1, 0, 1); PG8_SCHED; PG8_LDA(At, 0, 0); PG8_STAGE(PG8_SA(1, 1), a1 + hstepA, voffA);
;             PG8_WAIT_V(8); PG8_WAIT_L(0); PG8_BAR; PG8_MMA(0, 0, At, B0); PG8_MMA(0, 1, At, B1); PG8_BAR; PG8_SCHED;
;             PG8_LDA(At, 0, 1); PG8_STAGE(PG8_SB(0, 0), b2, voffB); PG8_STAGE(PG8_SB(0, 1), b2 + hstepB, voffB); PG8_STAGE(PG8_SA(0, 0), a2, voffA);
.LBB0_1501:
	ds_read_b128 v[128:131], v230
	ds_read_b128 v[132:135], v230 offset:1024
	ds_read_b128 v[136:139], v230 offset:2048
	ds_read_b128 v[140:143], v230 offset:3072
	ds_read_b128 v[144:147], v231
	ds_read_b128 v[148:151], v231 offset:1024
	ds_read_b128 v[152:155], v231 offset:2048
	ds_read_b128 v[156:159], v231 offset:3072
	s_add_u32 s22, s20, 0xfff80080
	s_addc_u32 s23, s21, -1
	s_cmp_eq_u32 s64, 28
	s_cselect_b32 s41, s11, s23
	s_cselect_b32 s40, s10, s22
	s_cselect_b32 s23, s13, s17
	s_cselect_b32 s22, s12, s15
	v_lshl_add_u64 v[192:193], s[20:21], 0, v[216:217]
	s_add_i32 m0, s30, 0xc000
	ds_read_b128 v[160:163], v232
	ds_read_b128 v[164:167], v232 offset:1024
	ds_read_b128 v[168:171], v232 offset:2048
	ds_read_b128 v[172:175], v232 offset:3072
	ds_read_b128 v[176:179], v232 offset:4096
	ds_read_b128 v[180:183], v232 offset:5120
	ds_read_b128 v[184:187], v232 offset:6144
	ds_read_b128 v[188:191], v232 offset:7168
	global_load_lds_dwordx4 v[192:193], off
	s_add_i32 m0, s30, 0xe000
	v_lshl_add_u64 v[192:193], s[20:21], 0, v[218:219]
	global_load_lds_dwordx4 v[192:193], off
	s_waitcnt vmcnt(8) lgkmcnt(0)
	s_barrier
	v_mfma_f32_16x16x32_bf16 v[124:127], v[128:131], v[160:163], v[124:127]
	v_mfma_f32_16x16x32_bf16 v[120:123], v[136:139], v[160:163], v[120:123]
	v_mfma_f32_16x16x32_bf16 v[112:115], v[128:131], v[168:171], v[112:115]
	v_mfma_f32_16x16x32_bf16 v[104:107], v[136:139], v[168:171], v[104:107]
	v_mfma_f32_16x16x32_bf16 v[96:99], v[128:131], v[176:179], v[96:99]
	v_mfma_f32_16x16x32_bf16 v[88:91], v[136:139], v[176:179], v[88:91]
	v_mfma_f32_16x16x32_bf16 v[80:83], v[128:131], v[184:187], v[80:83]
	v_mfma_f32_16x16x32_bf16 v[72:75], v[136:139], v[184:187], v[72:75]
	v_mfma_f32_16x16x32_bf16 v[124:127], v[132:135], v[164:167], v[124:127]
	v_mfma_f32_16x16x32_bf16 v[120:123], v[140:143], v[164:167], v[120:123]
	v_mfma_f32_16x16x32_bf16 v[112:115], v[132:135], v[172:175], v[112:115]
	v_mfma_f32_16x16x32_bf16 v[104:107], v[140:143], v[172:175], v[104:107]
	v_mfma_f32_16x16x32_bf16 v[96:99], v[132:135], v[180:183], v[96:99]
	v_mfma_f32_16x16x32_bf16 v[88:91], v[140:143], v[180:183], v[88:91]
	v_mfma_f32_16x16x32_bf16 v[80:83], v[132:135], v[188:191], v[80:83]
	v_mfma_f32_16x16x32_bf16 v[72:75], v[140:143], v[188:191], v[72:75]
	v_mfma_f32_16x16x32_bf16 v[116:119], v[144:147], v[160:163], v[116:119]
	v_mfma_f32_16x16x32_bf16 v[108:111], v[152:155], v[160:163], v[108:111]
	v_mfma_f32_16x16x32_bf16 v[100:103], v[144:147], v[168:171], v[100:103]
	v_mfma_f32_16x16x32_bf16 v[92:95], v[152:155], v[168:171], v[92:95]
	v_mfma_f32_16x16x32_bf16 v[84:87], v[144:147], v[176:179], v[84:87]
	v_mfma_f32_16x16x32_bf16 v[76:79], v[152:155], v[176:179], v[76:79]
	v_mfma_f32_16x16x32_bf16 v[68:71], v[144:147], v[184:187], v[68:71]
	v_mfma_f32_16x16x32_bf16 v[64:67], v[152:155], v[184:187], v[64:67]
	v_mfma_f32_16x16x32_bf16 v[116:119], v[148:151], v[164:167], v[116:119]
	v_mfma_f32_16x16x32_bf16 v[108:111], v[156:159], v[164:167], v[108:111]
	v_mfma_f32_16x16x32_bf16 v[100:103], v[148:151], v[172:175], v[100:103]
	v_mfma_f32_16x16x32_bf16 v[92:95], v[156:159], v[172:175], v[92:95]
	v_mfma_f32_16x16x32_bf16 v[84:87], v[148:151], v[180:183], v[84:87]
	v_mfma_f32_16x16x32_bf16 v[76:79], v[156:159], v[180:183], v[76:79]
	v_mfma_f32_16x16x32_bf16 v[68:71], v[148:151], v[188:191], v[68:71]
	v_mfma_f32_16x16x32_bf16 v[64:67], v[156:159], v[188:191], v[64:67]
	s_barrier
	s_add_i32 s65, s51, s28
	v_lshl_add_u64 v[192:193], s[22:23], 0, v[212:213]
	s_mov_b32 m0, s65
	ds_read_b128 v[160:163], v232 offset:16384
	ds_read_b128 v[164:167], v232 offset:17408
	ds_read_b128 v[168:171], v232 offset:18432
	ds_read_b128 v[172:175], v232 offset:19456
	ds_read_b128 v[176:179], v232 offset:20480
	ds_read_b128 v[180:183], v232 offset:21504
	ds_read_b128 v[184:187], v232 offset:22528
	ds_read_b128 v[188:191], v232 offset:23552
	global_load_lds_dwordx4 v[192:193], off
	s_add_i32 m0, s65, 0x2000
	s_add_u32 s66, s22, 0x80000
	v_lshl_add_u64 v[194:195], s[22:23], 0, v[208:209]
	s_addc_u32 s67, s23, 0
	s_add_i32 s65, s52, s28
	global_load_lds_dwordx4 v[194:195], off
	v_lshl_add_u64 v[196:197], s[66:67], 0, v[212:213]
	s_mov_b32 m0, s65
	v_lshl_add_u64 v[198:199], s[40:41], 0, v[210:211]
	global_load_lds_dwordx4 v[196:197], off
	s_add_i32 m0, s65, 0x2000
	v_lshl_add_u64 v[196:197], s[66:67], 0, v[208:209]
	global_load_lds_dwordx4 v[196:197], off
	s_mov_b32 m0, s30
	v_lshl_add_u64 v[196:197], s[40:41], 0, v[214:215]
	global_load_lds_dwordx4 v[196:197], off
	s_mov_b32 m0, s31
	s_nop 0
	global_load_lds_dwordx4 v[198:199], off
	s_waitcnt vmcnt(8) lgkmcnt(0)
	s_barrier
; #define PG8_STAGE(bufoff, gbase, voff) do { _Pragma("unroll") for (int _i = 0; _i < 2; ++_i) \
;         __builtin_amdgcn_global_load_lds((const unsigned*)((const char*)(gbase) + (voff)[_i]), (LAS unsigned*)(lds + (bufoff) + ldsw + _i * 8192), 16, 0, 0); } while (0)
; #define PG8_LDA(dst, b, h) do { _Pragma("unroll") for (int m = 0; m < 4; ++m) _Pragma("unroll") for (int k = 0; k < 2; ++k) dst[m][k] = *(const LAS bf16x8*)(lds + PG8_SA(b, h) + aoff + m * 2048 + k * 1024); } while (0)
; #define PG8_LDB(dst, b, h) do { _Pragma("unroll") for (int n = 0; n < 2; ++n) _Pragma("unroll") for (int k = 0; k < 2; ++k) dst[n][k] = *(const LAS bf16x8*)(lds + PG8_SB(b, h) + boff + n * 2048 + k * 1024); } while (0)
; #define PG8_MMA(ai, bj, At, Bt) do { __builtin_amdgcn_s_setprio(1); _Pragma("unroll") for (int m = 0; m < 4; ++m) _Pragma("unroll") for (int n = 0; n < 2; ++n) _Pragma("unroll") for (int k = 0; k < 2; ++k) \
;         acc[ai][bj][m][n] = __builtin_amdgcn_mfma_f32_16x16x32_bf16(Bt[n][k], At[m][k], acc[ai][bj][m][n], 0, 0, 0); __builtin_amdgcn_s_setprio(0); } while (0)
; #define PG8_WAIT_V(n) asm volatile("s_waitcnt vmcnt(" #n ")" ::: "memory")
; #define PG8_WAIT_L(n) asm volatile("s_waitcnt lgkmcnt(" #n ")" ::: "memory")
; #define PG8_BAR __builtin_amdgcn_s_barrier()
; #define PG8_SCHED __builtin_amdgcn_sched_barrier(0)
; template <class Desc, class Epi>
; DI void gemm_phase(LAS unsigned char* lds, const Desc& D, const Epi& E, int wv) {
;     ...
;             PG8_WAIT_V(8); PG8_WAIT_L(0); PG8_BAR; PG8_MMA(1, 0, At, B0); PG8_MMA(1, 1, At, B1); PG8_BAR; PG8_SCHED;
;             PG8_LDB(B0, 1, 0); PG8_LDB(B1, 1, 1); PG8_SCHED; PG8_LDA(At, 1, 0); PG8_STAGE(PG8_SA(0, 1), a2 + hstepA, voffA);
;             PG8_WAIT_V(8); PG8_WAIT_L(0); PG8_BAR; PG8_MMA(0, 0, At, B0); PG8_MMA(0, 1, At, B1); PG8_BAR; PG8_SCHED;
;             PG8_LDA(At, 1, 1); PG8_STAGE(PG8_SB(1, 0), b3, voffB); PG8_STAGE(PG8_SB(1, 1), b3 + hstepB, voffB); PG8_STAGE(PG8_SA(1, 0), a3, voffA);
	v_mfma_f32_16x16x32_bf16 v[60:63], v[128:131], v[160:163], v[60:63]
	v_mfma_f32_16x16x32_bf16 v[56:59], v[136:139], v[160:163], v[56:59]
	v_mfma_f32_16x16x32_bf16 v[48:51], v[128:131], v[168:171], v[48:51]
	v_mfma_f32_16x16x32_bf16 v[40:43], v[136:139], v[168:171], v[40:43]
	v_mfma_f32_16x16x32_bf16 v[32:35], v[128:131], v[176:179], v[32:35]
	v_mfma_f32_16x16x32_bf16 v[24:27], v[136:139], v[176:179], v[24:27]
	v_mfma_f32_16x16x32_bf16 v[16:19], v[128:131], v[184:187], v[16:19]
	v_mfma_f32_16x16x32_bf16 v[8:11], v[136:139], v[184:187], v[8:11]
	v_mfma_f32_16x16x32_bf16 v[60:63], v[132:135], v[164:167], v[60:63]
	v_mfma_f32_16x16x32_bf16 v[56:59], v[140:143], v[164:167], v[56:59]
	v_mfma_f32_16x16x32_bf16 v[48:51], v[132:135], v[172:175], v[48:51]
	v_mfma_f32_16x16x32_bf16 v[40:43], v[140:143], v[172:175], v[40:43]
	v_mfma_f32_16x16x32_bf16 v[32:35], v[132:135], v[180:183], v[32:35]
	v_mfma_f32_16x16x32_bf16 v[24:27], v[140:143], v[180:183], v[24:27]
	v_mfma_f32_16x16x32_bf16 v[16:19], v[132:135], v[188:191], v[16:19]
	v_mfma_f32_16x16x32_bf16 v[8:11], v[140:143], v[188:191], v[8:11]
	v_mfma_f32_16x16x32_bf16 v[52:55], v[144:147], v[160:163], v[52:55]
	v_mfma_f32_16x16x32_bf16 v[44:47], v[152:155], v[160:163], v[44:47]
	v_mfma_f32_16x16x32_bf16 v[36:39], v[144:147], v[168:171], v[36:39]
	v_mfma_f32_16x16x32_bf16 v[28:31], v[152:155], v[168:171], v[28:31]
	v_mfma_f32_16x16x32_bf16 v[20:23], v[144:147], v[176:179], v[20:23]
	v_mfma_f32_16x16x32_bf16 v[12:15], v[152:155], v[176:179], v[12:15]
	v_mfma_f32_16x16x32_bf16 v[4:7], v[144:147], v[184:187], v[4:7]
	v_mfma_f32_16x16x32_bf16 v[0:3], v[152:155], v[184:187], v[0:3]
	v_mfma_f32_16x16x32_bf16 v[52:55], v[148:151], v[164:167], v[52:55]
	v_mfma_f32_16x16x32_bf16 v[44:47], v[156:159], v[164:167], v[44:47]
	v_mfma_f32_16x16x32_bf16 v[36:39], v[148:151], v[172:175], v[36:39]
	v_mfma_f32_16x16x32_bf16 v[28:31], v[156:159], v[172:175], v[28:31]
	v_mfma_f32_16x16x32_bf16 v[20:23], v[148:151], v[180:183], v[20:23]
	v_mfma_f32_16x16x32_bf16 v[12:15], v[156:159], v[180:183], v[12:15]
	v_mfma_f32_16x16x32_bf16 v[4:7], v[148:151], v[188:191], v[4:7]
	v_mfma_f32_16x16x32_bf16 v[0:3], v[156:159], v[188:191], v[0:3]
	s_barrier
	s_add_i32 s65, 0, 0x18000
	s_add_i32 s66, 0, 0x1c000
	v_add_u32_e32 v140, s65, v229
	v_add_u32_e32 v156, s66, v229
	ds_read_b128 v[128:131], v140
	ds_read_b128 v[132:135], v140 offset:1024
	ds_read_b128 v[136:139], v140 offset:2048
	ds_read_b128 v[140:143], v140 offset:3072
	ds_read_b128 v[144:147], v156
	ds_read_b128 v[148:151], v156 offset:1024
	ds_read_b128 v[152:155], v156 offset:2048
	ds_read_b128 v[156:159], v156 offset:3072
	s_add_u32 s40, s40, 0x80000
	s_addc_u32 s41, s41, 0
	s_mov_b32 m0, s34
	v_lshl_add_u64 v[200:201], s[40:41], 0, v[214:215]
	ds_read_b128 v[160:163], v232 offset:32768
	ds_read_b128 v[164:167], v232 offset:33792
	ds_read_b128 v[168:171], v232 offset:34816
	ds_read_b128 v[172:175], v232 offset:35840
	ds_read_b128 v[176:179], v232 offset:36864
	ds_read_b128 v[180:183], v232 offset:37888
	ds_read_b128 v[184:187], v232 offset:38912
	ds_read_b128 v[188:191], v232 offset:39936
	global_load_lds_dwordx4 v[200:201], off
	s_mov_b32 m0, s35
	v_lshl_add_u64 v[200:201], s[40:41], 0, v[210:211]
	global_load_lds_dwordx4 v[200:201], off
	s_waitcnt vmcnt(8) lgkmcnt(0)
	s_barrier
	v_mfma_f32_16x16x32_bf16 v[124:127], v[128:131], v[160:163], v[124:127]
	v_mfma_f32_16x16x32_bf16 v[120:123], v[136:139], v[160:163], v[120:123]
	v_mfma_f32_16x16x32_bf16 v[112:115], v[128:131], v[168:171], v[112:115]
	v_mfma_f32_16x16x32_bf16 v[104:107], v[136:139], v[168:171], v[104:107]
	v_mfma_f32_16x16x32_bf16 v[96:99], v[128:131], v[176:179], v[96:99]
	v_mfma_f32_16x16x32_bf16 v[88:91], v[136:139], v[176:179], v[88:91]
	v_mfma_f32_16x16x32_bf16 v[80:83], v[128:131], v[184:187], v[80:83]
	v_mfma_f32_16x16x32_bf16 v[72:75], v[136:139], v[184:187], v[72:75]
	v_mfma_f32_16x16x32_bf16 v[124:127], v[132:135], v[164:167], v[124:127]
	v_mfma_f32_16x16x32_bf16 v[120:123], v[140:143], v[164:167], v[120:123]
	v_mfma_f32_16x16x32_bf16 v[112:115], v[132:135], v[172:175], v[112:115]
	v_mfma_f32_16x16x32_bf16 v[104:107], v[140:143], v[172:175], v[104:107]
	v_mfma_f32_16x16x32_bf16 v[96:99], v[132:135], v[180:183], v[96:99]
	v_mfma_f32_16x16x32_bf16 v[88:91], v[140:143], v[180:183], v[88:91]
	v_mfma_f32_16x16x32_bf16 v[80:83], v[132:135], v[188:191], v[80:83]
	v_mfma_f32_16x16x32_bf16 v[72:75], v[140:143], v[188:191], v[72:75]
	v_mfma_f32_16x16x32_bf16 v[116:119], v[144:147], v[160:163], v[116:119]
	v_mfma_f32_16x16x32_bf16 v[108:111], v[152:155], v[160:163], v[108:111]
	v_mfma_f32_16x16x32_bf16 v[100:103], v[144:147], v[168:171], v[100:103]
	v_mfma_f32_16x16x32_bf16 v[92:95], v[152:155], v[168:171], v[92:95]
	v_mfma_f32_16x16x32_bf16 v[84:87], v[144:147], v[176:179], v[84:87]
	v_mfma_f32_16x16x32_bf16 v[76:79], v[152:155], v[176:179], v[76:79]
	v_mfma_f32_16x16x32_bf16 v[68:71], v[144:147], v[184:187], v[68:71]
	v_mfma_f32_16x16x32_bf16 v[64:67], v[152:155], v[184:187], v[64:67]
	v_mfma_f32_16x16x32_bf16 v[116:119], v[148:151], v[164:167], v[116:119]
	v_mfma_f32_16x16x32_bf16 v[108:111], v[156:159], v[164:167], v[108:111]
	v_mfma_f32_16x16x32_bf16 v[100:103], v[148:151], v[172:175], v[100:103]
	v_mfma_f32_16x16x32_bf16 v[92:95], v[156:159], v[172:175], v[92:95]
	v_mfma_f32_16x16x32_bf16 v[84:87], v[148:151], v[180:183], v[84:87]
	v_mfma_f32_16x16x32_bf16 v[76:79], v[156:159], v[180:183], v[76:79]
	v_mfma_f32_16x16x32_bf16 v[68:71], v[148:151], v[188:191], v[68:71]
	v_mfma_f32_16x16x32_bf16 v[64:67], v[156:159], v[188:191], v[64:67]
	s_barrier
; #define PG8_STAGE(bufoff, gbase, voff) do { _Pragma("unroll") for (int _i = 0; _i < 2; ++_i) \
;         __builtin_amdgcn_global_load_lds((const unsigned*)((const char*)(gbase) + (voff)[_i]), (LAS unsigned*)(lds + (bufoff) + ldsw + _i * 8192), 16, 0, 0); } while (0)
; #define PG8_LDA(dst, b, h) do { _Pragma("unroll") for (int m = 0; m < 4; ++m) _Pragma("unroll") for (int k = 0; k < 2; ++k) dst[m][k] = *(const LAS bf16x8*)(lds + PG8_SA(b, h) + aoff + m * 2048 + k * 1024); } while (0)
; #define PG8_MMA(ai, bj, At, Bt) do { __builtin_amdgcn_s_setprio(1); _Pragma("unroll") for (int m = 0; m < 4; ++m) _Pragma("unroll") for (int n = 0; n < 2; ++n) _Pragma("unroll") for (int k = 0; k < 2; ++k) \
;         acc[ai][bj][m][n] = __builtin_amdgcn_mfma_f32_16x16x32_bf16(Bt[n][k], At[m][k], acc[ai][bj][m][n], 0, 0, 0); __builtin_amdgcn_s_setprio(0); } while (0)
; #define PG8_WAIT_V(n) asm volatile("s_waitcnt vmcnt(" #n ")" ::: "memory")
; #define PG8_WAIT_L(n) asm volatile("s_waitcnt lgkmcnt(" #n ")" ::: "memory")
; #define PG8_BAR __builtin_amdgcn_s_barrier()
; #define PG8_SCHED __builtin_amdgcn_sched_barrier(0)
; template <class Desc, class Epi>
; DI void gemm_phase(LAS unsigned char* lds, const Desc& D, const Epi& E, int wv) {
;     ...
;             PG8_LDA(At, 1, 1); PG8_STAGE(PG8_SB(1, 0), b3, voffB); PG8_STAGE(PG8_SB(1, 1), b3 + hstepB, voffB); PG8_STAGE(PG8_SA(1, 0), a3, voffA);
;             PG8_WAIT_V(8); PG8_WAIT_L(0); PG8_BAR; PG8_MMA(1, 0, At, B0); PG8_MMA(1, 1, At, B1); PG8_BAR; PG8_SCHED;
;         }
;         if (wr == 0) PG8_BAR;
	s_add_i32 s40, s65, s28
	v_lshl_add_u64 v[192:193], v[192:193], 0, s[6:7]
	s_mov_b32 m0, s40
	ds_read_b128 v[160:163], v232 offset:49152
	ds_read_b128 v[164:167], v232 offset:50176
	ds_read_b128 v[168:171], v232 offset:51200
	ds_read_b128 v[172:175], v232 offset:52224
	ds_read_b128 v[176:179], v232 offset:53248
	ds_read_b128 v[180:183], v232 offset:54272
	ds_read_b128 v[184:187], v232 offset:55296
	ds_read_b128 v[188:191], v232 offset:56320
	global_load_lds_dwordx4 v[192:193], off
	s_add_i32 m0, s40, 0x2000
	s_add_u32 s22, s22, 0x80080
	v_lshl_add_u64 v[192:193], v[194:195], 0, s[6:7]
	s_addc_u32 s23, s23, 0
	s_add_i32 s40, s66, s28
	global_load_lds_dwordx4 v[192:193], off
	s_mov_b32 m0, s40
	v_lshl_add_u64 v[192:193], s[22:23], 0, v[212:213]
	global_load_lds_dwordx4 v[192:193], off
	s_add_i32 m0, s40, 0x2000
	v_lshl_add_u64 v[192:193], s[22:23], 0, v[208:209]
	global_load_lds_dwordx4 v[192:193], off
	s_mov_b32 m0, s47
	v_lshl_add_u64 v[192:193], v[196:197], 0, s[6:7]
	global_load_lds_dwordx4 v[192:193], off
	s_mov_b32 m0, s48
	v_lshl_add_u64 v[192:193], v[198:199], 0, s[6:7]
	global_load_lds_dwordx4 v[192:193], off
	s_waitcnt vmcnt(8) lgkmcnt(0)
	s_barrier
	v_mfma_f32_16x16x32_bf16 v[60:63], v[128:131], v[160:163], v[60:63]
	v_mfma_f32_16x16x32_bf16 v[56:59], v[136:139], v[160:163], v[56:59]
	v_mfma_f32_16x16x32_bf16 v[48:51], v[128:131], v[168:171], v[48:51]
	v_mfma_f32_16x16x32_bf16 v[40:43], v[136:139], v[168:171], v[40:43]
	v_mfma_f32_16x16x32_bf16 v[32:35], v[128:131], v[176:179], v[32:35]
	v_mfma_f32_16x16x32_bf16 v[24:27], v[136:139], v[176:179], v[24:27]
	v_mfma_f32_16x16x32_bf16 v[16:19], v[128:131], v[184:187], v[16:19]
	v_mfma_f32_16x16x32_bf16 v[8:11], v[136:139], v[184:187], v[8:11]
	v_mfma_f32_16x16x32_bf16 v[60:63], v[132:135], v[164:167], v[60:63]
	v_mfma_f32_16x16x32_bf16 v[56:59], v[140:143], v[164:167], v[56:59]
	v_mfma_f32_16x16x32_bf16 v[48:51], v[132:135], v[172:175], v[48:51]
	v_mfma_f32_16x16x32_bf16 v[40:43], v[140:143], v[172:175], v[40:43]
	v_mfma_f32_16x16x32_bf16 v[32:35], v[132:135], v[180:183], v[32:35]
	v_mfma_f32_16x16x32_bf16 v[24:27], v[140:143], v[180:183], v[24:27]
	v_mfma_f32_16x16x32_bf16 v[16:19], v[132:135], v[188:191], v[16:19]
	v_mfma_f32_16x16x32_bf16 v[8:11], v[140:143], v[188:191], v[8:11]
	v_mfma_f32_16x16x32_bf16 v[52:55], v[144:147], v[160:163], v[52:55]
	v_mfma_f32_16x16x32_bf16 v[44:47], v[152:155], v[160:163], v[44:47]
	v_mfma_f32_16x16x32_bf16 v[36:39], v[144:147], v[168:171], v[36:39]
	v_mfma_f32_16x16x32_bf16 v[28:31], v[152:155], v[168:171], v[28:31]
	v_mfma_f32_16x16x32_bf16 v[20:23], v[144:147], v[176:179], v[20:23]
	v_mfma_f32_16x16x32_bf16 v[12:15], v[152:155], v[176:179], v[12:15]
	v_mfma_f32_16x16x32_bf16 v[4:7], v[144:147], v[184:187], v[4:7]
	v_mfma_f32_16x16x32_bf16 v[0:3], v[152:155], v[184:187], v[0:3]
	v_mfma_f32_16x16x32_bf16 v[52:55], v[148:151], v[164:167], v[52:55]
	v_mfma_f32_16x16x32_bf16 v[44:47], v[156:159], v[164:167], v[44:47]
	v_mfma_f32_16x16x32_bf16 v[36:39], v[148:151], v[172:175], v[36:39]
	v_mfma_f32_16x16x32_bf16 v[28:31], v[156:159], v[172:175], v[28:31]
	v_mfma_f32_16x16x32_bf16 v[20:23], v[148:151], v[180:183], v[20:23]
	v_mfma_f32_16x16x32_bf16 v[12:15], v[156:159], v[180:183], v[12:15]
	v_mfma_f32_16x16x32_bf16 v[4:7], v[148:151], v[188:191], v[4:7]
	v_mfma_f32_16x16x32_bf16 v[0:3], v[156:159], v[188:191], v[0:3]
	s_barrier
	s_add_i32 s64, s64, 2
	s_add_u32 s20, s20, 0x100
	s_addc_u32 s21, s21, 0
	s_add_u32 s15, s15, 0x100
	s_addc_u32 s17, s17, 0
	s_cmp_gt_u32 s64, 29
	s_cbranch_scc0 .LBB0_1501
	s_and_b64 vcc, exec, s[8:9]
	s_cbranch_vccz .LBB0_1504
	s_barrier

; #define PG8_STAGE(bufoff, gbase, voff) do { _Pragma("unroll") for (int _i = 0; _i < 2; ++_i) \
;         __builtin_amdgcn_global_load_lds((const unsigned*)((const char*)(gbase) + (voff)[_i]), (LAS unsigned*)(lds + (bufoff) + ldsw + _i * 8192), 16, 0, 0); } while (0)
; #define PG8_LDA(dst, b, h) do { _Pragma("unroll") for (int m = 0; m < 4; ++m) _Pragma("unroll") for (int k = 0; k < 2; ++k) dst[m][k] = *(const LAS bf16x8*)(lds + PG8_SA(b, h) + aoff + m * 2048 + k * 1024); } while (0)
; #define PG8_LDB(dst, b, h) do { _Pragma("unroll") for (int n = 0; n < 2; ++n) _Pragma("unroll") for (int k = 0; k < 2; ++k) dst[n][k] = *(const LAS bf16x8*)(lds + PG8_SB(b, h) + boff + n * 2048 + k * 1024); } while (0)
; #define PG8_MMA(ai, bj, At, Bt) do { __builtin_amdgcn_s_setprio(1); _Pragma("unroll") for (int m = 0; m < 4; ++m) _Pragma("unroll") for (int n = 0; n < 2; ++n) _Pragma("unroll") for (int k = 0; k < 2; ++k) \
;         acc[ai][bj][m][n] = __builtin_amdgcn_mfma_f32_16x16x32_bf16(Bt[n][k], At[m][k], acc[ai][bj][m][n], 0, 0, 0); __builtin_amdgcn_s_setprio(0); } while (0)
; #define PG8_WAIT_V(n) asm volatile("s_waitcnt vmcnt(" #n ")" ::: "memory")
; #define PG8_WAIT_L(n) asm volatile("s_waitcnt lgkmcnt(" #n ")" ::: "memory")
; #define PG8_BAR __builtin_amdgcn_s_barrier()
; #define PG8_SCHED __builtin_amdgcn_sched_barrier(0)
; template <class Desc, class Epi>
; DI void gemm_phase(LAS unsigned char* lds, const Desc& D, const Epi& E, int wv) {
;     ...
;         for (int t = 0; t < nt; t += 2) {
;             const bool last = (t == nt - 2);
;             const char* a1 = cA + (size_t)(t + 1) * kstep;
;             const char* a2 = last ? nA : cA + (size_t)(t + 2) * kstep; const char* b2 = last ? nB : cB + (size_t)(t + 2) * kstep;
;             const char* a3 = a2 + kstep; const char* b3 = b2 + kstep;
;             PG8_LDB(B0, 0, 0); PG8_LDB(B1, 0, 1); PG8_SCHED; PG8_LDA(At, 0, 0); PG8_STAGE(PG8_SA(1, 1), a1 + hstepA, voffA);
;             PG8_WAIT_V(8); PG8_WAIT_L(0); PG8_BAR; PG8_MMA(0, 0, At, B0); PG8_MMA(0, 1, At, B1); PG8_BAR; PG8_SCHED;
;             PG8_LDA(At, 0, 1); PG8_STAGE(PG8_SB(0, 0), b2, voffB); PG8_STAGE(PG8_SB(0, 1), b2 + hstepB, voffB); PG8_STAGE(PG8_SA(0, 0), a2, voffA);
.LBB0_1632:
	ds_read_b128 v[146:149], v155
	ds_read_b128 v[150:153], v155 offset:1024
	ds_read_b128 v[158:161], v155 offset:2048
	ds_read_b128 v[162:165], v155 offset:3072
	ds_read_b128 v[166:169], v156
	ds_read_b128 v[170:173], v156 offset:1024
	ds_read_b128 v[174:177], v156 offset:2048
	ds_read_b128 v[178:181], v156 offset:3072
	s_add_u32 s17, s62, 0xfff80080
	s_addc_u32 s19, s63, -1
	s_cmp_eq_u32 s8, 28
	s_cselect_b32 s67, s21, s19
	s_cselect_b32 s66, s20, s17
	s_cselect_b32 s65, s23, s7
	s_cselect_b32 s64, s22, s5
	v_lshl_add_u64 v[214:215], s[62:63], 0, v[138:139]
	s_add_i32 m0, s29, 0xc000
	ds_read_b128 v[182:185], v157
	ds_read_b128 v[186:189], v157 offset:1024
	ds_read_b128 v[190:193], v157 offset:2048
	ds_read_b128 v[194:197], v157 offset:3072
	ds_read_b128 v[198:201], v157 offset:4096
	ds_read_b128 v[202:205], v157 offset:5120
	ds_read_b128 v[206:209], v157 offset:6144
	ds_read_b128 v[210:213], v157 offset:7168
	global_load_lds_dwordx4 v[214:215], off
	s_add_i32 m0, s29, 0xe000
	v_lshl_add_u64 v[214:215], s[62:63], 0, v[140:141]
	global_load_lds_dwordx4 v[214:215], off
	s_waitcnt vmcnt(8) lgkmcnt(0)
	s_barrier
	v_mfma_f32_16x16x32_bf16 v[124:127], v[146:149], v[182:185], v[124:127]
	v_mfma_f32_16x16x32_bf16 v[120:123], v[158:161], v[182:185], v[120:123]
	v_mfma_f32_16x16x32_bf16 v[108:111], v[146:149], v[190:193], v[108:111]
	v_mfma_f32_16x16x32_bf16 v[104:107], v[158:161], v[190:193], v[104:107]
	v_mfma_f32_16x16x32_bf16 v[92:95], v[146:149], v[198:201], v[92:95]
	v_mfma_f32_16x16x32_bf16 v[88:91], v[158:161], v[198:201], v[88:91]
	v_mfma_f32_16x16x32_bf16 v[76:79], v[146:149], v[206:209], v[76:79]
	v_mfma_f32_16x16x32_bf16 v[72:75], v[158:161], v[206:209], v[72:75]
	v_mfma_f32_16x16x32_bf16 v[124:127], v[150:153], v[186:189], v[124:127]
	v_mfma_f32_16x16x32_bf16 v[120:123], v[162:165], v[186:189], v[120:123]
	v_mfma_f32_16x16x32_bf16 v[108:111], v[150:153], v[194:197], v[108:111]
	v_mfma_f32_16x16x32_bf16 v[104:107], v[162:165], v[194:197], v[104:107]
	v_mfma_f32_16x16x32_bf16 v[92:95], v[150:153], v[202:205], v[92:95]
	v_mfma_f32_16x16x32_bf16 v[88:91], v[162:165], v[202:205], v[88:91]
	v_mfma_f32_16x16x32_bf16 v[76:79], v[150:153], v[210:213], v[76:79]
	v_mfma_f32_16x16x32_bf16 v[72:75], v[162:165], v[210:213], v[72:75]
	v_mfma_f32_16x16x32_bf16 v[116:119], v[166:169], v[182:185], v[116:119]
	v_mfma_f32_16x16x32_bf16 v[112:115], v[174:177], v[182:185], v[112:115]
	v_mfma_f32_16x16x32_bf16 v[100:103], v[166:169], v[190:193], v[100:103]
	v_mfma_f32_16x16x32_bf16 v[96:99], v[174:177], v[190:193], v[96:99]
	v_mfma_f32_16x16x32_bf16 v[84:87], v[166:169], v[198:201], v[84:87]
	v_mfma_f32_16x16x32_bf16 v[80:83], v[174:177], v[198:201], v[80:83]
	v_mfma_f32_16x16x32_bf16 v[68:71], v[166:169], v[206:209], v[68:71]
	v_mfma_f32_16x16x32_bf16 v[64:67], v[174:177], v[206:209], v[64:67]
	v_mfma_f32_16x16x32_bf16 v[116:119], v[170:173], v[186:189], v[116:119]
	v_mfma_f32_16x16x32_bf16 v[112:115], v[178:181], v[186:189], v[112:115]
	v_mfma_f32_16x16x32_bf16 v[100:103], v[170:173], v[194:197], v[100:103]
	v_mfma_f32_16x16x32_bf16 v[96:99], v[178:181], v[194:197], v[96:99]
	v_mfma_f32_16x16x32_bf16 v[84:87], v[170:173], v[202:205], v[84:87]
	v_mfma_f32_16x16x32_bf16 v[80:83], v[178:181], v[202:205], v[80:83]
	v_mfma_f32_16x16x32_bf16 v[68:71], v[170:173], v[210:213], v[68:71]
	v_mfma_f32_16x16x32_bf16 v[64:67], v[178:181], v[210:213], v[64:67]
	s_barrier
	s_add_i32 s17, s50, s28
	v_lshl_add_u64 v[214:215], s[64:65], 0, v[130:131]
	s_mov_b32 m0, s17
	ds_read_b128 v[182:185], v157 offset:16384
	ds_read_b128 v[186:189], v157 offset:17408
	ds_read_b128 v[190:193], v157 offset:18432
	ds_read_b128 v[194:197], v157 offset:19456
	ds_read_b128 v[198:201], v157 offset:20480
	ds_read_b128 v[202:205], v157 offset:21504
	ds_read_b128 v[206:209], v157 offset:22528
	ds_read_b128 v[210:213], v157 offset:23552
	global_load_lds_dwordx4 v[214:215], off
	s_add_i32 m0, s17, 0x2000
	s_add_u32 s68, s64, 0x80000
	v_lshl_add_u64 v[216:217], s[64:65], 0, v[134:135]
	s_addc_u32 s69, s65, 0
	s_add_i32 s17, s51, s28
	global_load_lds_dwordx4 v[216:217], off
	v_lshl_add_u64 v[218:219], s[68:69], 0, v[130:131]
	s_mov_b32 m0, s17
	v_lshl_add_u64 v[220:221], s[66:67], 0, v[132:133]
	global_load_lds_dwordx4 v[218:219], off
	s_add_i32 m0, s17, 0x2000
	v_lshl_add_u64 v[218:219], s[68:69], 0, v[134:135]
	global_load_lds_dwordx4 v[218:219], off
	s_mov_b32 m0, s29
	v_lshl_add_u64 v[218:219], s[66:67], 0, v[128:129]
	global_load_lds_dwordx4 v[218:219], off
	s_mov_b32 m0, s30
	s_nop 0
	global_load_lds_dwordx4 v[220:221], off
	s_waitcnt vmcnt(8) lgkmcnt(0)
	s_barrier
; #define PG8_STAGE(bufoff, gbase, voff) do { _Pragma("unroll") for (int _i = 0; _i < 2; ++_i) \
;         __builtin_amdgcn_global_load_lds((const unsigned*)((const char*)(gbase) + (voff)[_i]), (LAS unsigned*)(lds + (bufoff) + ldsw + _i * 8192), 16, 0, 0); } while (0)
; #define PG8_LDA(dst, b, h) do { _Pragma("unroll") for (int m = 0; m < 4; ++m) _Pragma("unroll") for (int k = 0; k < 2; ++k) dst[m][k] = *(const LAS bf16x8*)(lds + PG8_SA(b, h) + aoff + m * 2048 + k * 1024); } while (0)
; #define PG8_LDB(dst, b, h) do { _Pragma("unroll") for (int n = 0; n < 2; ++n) _Pragma("unroll") for (int k = 0; k < 2; ++k) dst[n][k] = *(const LAS bf16x8*)(lds + PG8_SB(b, h) + boff + n * 2048 + k * 1024); } while (0)
; #define PG8_MMA(ai, bj, At, Bt) do { __builtin_amdgcn_s_setprio(1); _Pragma("unroll") for (int m = 0; m < 4; ++m) _Pragma("unroll") for (int n = 0; n < 2; ++n) _Pragma("unroll") for (int k = 0; k < 2; ++k) \
;         acc[ai][bj][m][n] = __builtin_amdgcn_mfma_f32_16x16x32_bf16(Bt[n][k], At[m][k], acc[ai][bj][m][n], 0, 0, 0); __builtin_amdgcn_s_setprio(0); } while (0)
; #define PG8_WAIT_V(n) asm volatile("s_waitcnt vmcnt(" #n ")" ::: "memory")
; #define PG8_WAIT_L(n) asm volatile("s_waitcnt lgkmcnt(" #n ")" ::: "memory")
; #define PG8_BAR __builtin_amdgcn_s_barrier()
; #define PG8_SCHED __builtin_amdgcn_sched_barrier(0)
; template <class Desc, class Epi>
; DI void gemm_phase(LAS unsigned char* lds, const Desc& D, const Epi& E, int wv) {
;     ...
;             PG8_WAIT_V(8); PG8_WAIT_L(0); PG8_BAR; PG8_MMA(1, 0, At, B0); PG8_MMA(1, 1, At, B1); PG8_BAR; PG8_SCHED;
;             PG8_LDB(B0, 1, 0); PG8_LDB(B1, 1, 1); PG8_SCHED; PG8_LDA(At, 1, 0); PG8_STAGE(PG8_SA(0, 1), a2 + hstepA, voffA);
;             PG8_WAIT_V(8); PG8_WAIT_L(0); PG8_BAR; PG8_MMA(0, 0, At, B0); PG8_MMA(0, 1, At, B1); PG8_BAR; PG8_SCHED;
;             PG8_LDA(At, 1, 1); PG8_STAGE(PG8_SB(1, 0), b3, voffB); PG8_STAGE(PG8_SB(1, 1), b3 + hstepB, voffB); PG8_STAGE(PG8_SA(1, 0), a3, voffA);
	v_mfma_f32_16x16x32_bf16 v[60:63], v[146:149], v[182:185], v[60:63]
	v_mfma_f32_16x16x32_bf16 v[56:59], v[158:161], v[182:185], v[56:59]
	v_mfma_f32_16x16x32_bf16 v[44:47], v[146:149], v[190:193], v[44:47]
	v_mfma_f32_16x16x32_bf16 v[40:43], v[158:161], v[190:193], v[40:43]
	v_mfma_f32_16x16x32_bf16 v[28:31], v[146:149], v[198:201], v[28:31]
	v_mfma_f32_16x16x32_bf16 v[24:27], v[158:161], v[198:201], v[24:27]
	v_mfma_f32_16x16x32_bf16 v[12:15], v[146:149], v[206:209], v[12:15]
	v_mfma_f32_16x16x32_bf16 v[8:11], v[158:161], v[206:209], v[8:11]
	v_mfma_f32_16x16x32_bf16 v[60:63], v[150:153], v[186:189], v[60:63]
	v_mfma_f32_16x16x32_bf16 v[56:59], v[162:165], v[186:189], v[56:59]
	v_mfma_f32_16x16x32_bf16 v[44:47], v[150:153], v[194:197], v[44:47]
	v_mfma_f32_16x16x32_bf16 v[40:43], v[162:165], v[194:197], v[40:43]
	v_mfma_f32_16x16x32_bf16 v[28:31], v[150:153], v[202:205], v[28:31]
	v_mfma_f32_16x16x32_bf16 v[24:27], v[162:165], v[202:205], v[24:27]
	v_mfma_f32_16x16x32_bf16 v[12:15], v[150:153], v[210:213], v[12:15]
	v_mfma_f32_16x16x32_bf16 v[8:11], v[162:165], v[210:213], v[8:11]
	v_mfma_f32_16x16x32_bf16 v[52:55], v[166:169], v[182:185], v[52:55]
	v_mfma_f32_16x16x32_bf16 v[48:51], v[174:177], v[182:185], v[48:51]
	v_mfma_f32_16x16x32_bf16 v[36:39], v[166:169], v[190:193], v[36:39]
	v_mfma_f32_16x16x32_bf16 v[32:35], v[174:177], v[190:193], v[32:35]
	v_mfma_f32_16x16x32_bf16 v[20:23], v[166:169], v[198:201], v[20:23]
	v_mfma_f32_16x16x32_bf16 v[16:19], v[174:177], v[198:201], v[16:19]
	v_mfma_f32_16x16x32_bf16 v[4:7], v[166:169], v[206:209], v[4:7]
	v_mfma_f32_16x16x32_bf16 v[0:3], v[174:177], v[206:209], v[0:3]
	v_mfma_f32_16x16x32_bf16 v[52:55], v[170:173], v[186:189], v[52:55]
	v_mfma_f32_16x16x32_bf16 v[48:51], v[178:181], v[186:189], v[48:51]
	v_mfma_f32_16x16x32_bf16 v[36:39], v[170:173], v[194:197], v[36:39]
	v_mfma_f32_16x16x32_bf16 v[32:35], v[178:181], v[194:197], v[32:35]
	v_mfma_f32_16x16x32_bf16 v[20:23], v[170:173], v[202:205], v[20:23]
	v_mfma_f32_16x16x32_bf16 v[16:19], v[178:181], v[202:205], v[16:19]
	v_mfma_f32_16x16x32_bf16 v[4:7], v[170:173], v[210:213], v[4:7]
	v_mfma_f32_16x16x32_bf16 v[0:3], v[178:181], v[210:213], v[0:3]
	s_barrier
	s_add_i32 s17, 0, 0x18000
	v_add_u32_e32 v136, s17, v154
	s_add_i32 s19, 0, 0x1c000
	ds_read_b128 v[146:149], v136
	ds_read_b128 v[150:153], v136 offset:1024
	ds_read_b128 v[158:161], v136 offset:2048
	ds_read_b128 v[162:165], v136 offset:3072
	v_add_u32_e32 v136, s19, v154
	ds_read_b128 v[166:169], v136
	ds_read_b128 v[170:173], v136 offset:1024
	ds_read_b128 v[174:177], v136 offset:2048
	ds_read_b128 v[178:181], v136 offset:3072
	s_add_u32 s66, s66, 0x80000
	s_addc_u32 s67, s67, 0
	s_mov_b32 m0, s31
	v_lshl_add_u64 v[222:223], s[66:67], 0, v[128:129]
	ds_read_b128 v[182:185], v157 offset:32768
	ds_read_b128 v[186:189], v157 offset:33792
	ds_read_b128 v[190:193], v157 offset:34816
	ds_read_b128 v[194:197], v157 offset:35840
	ds_read_b128 v[198:201], v157 offset:36864
	ds_read_b128 v[202:205], v157 offset:37888
	ds_read_b128 v[206:209], v157 offset:38912
	ds_read_b128 v[210:213], v157 offset:39936
	global_load_lds_dwordx4 v[222:223], off
	s_mov_b32 m0, s34
	v_lshl_add_u64 v[222:223], s[66:67], 0, v[132:133]
	global_load_lds_dwordx4 v[222:223], off
	s_waitcnt vmcnt(8) lgkmcnt(0)
	s_barrier
	v_mfma_f32_16x16x32_bf16 v[124:127], v[146:149], v[182:185], v[124:127]
	v_mfma_f32_16x16x32_bf16 v[120:123], v[158:161], v[182:185], v[120:123]
	v_mfma_f32_16x16x32_bf16 v[108:111], v[146:149], v[190:193], v[108:111]
	v_mfma_f32_16x16x32_bf16 v[104:107], v[158:161], v[190:193], v[104:107]
	v_mfma_f32_16x16x32_bf16 v[92:95], v[146:149], v[198:201], v[92:95]
	v_mfma_f32_16x16x32_bf16 v[88:91], v[158:161], v[198:201], v[88:91]
	v_mfma_f32_16x16x32_bf16 v[76:79], v[146:149], v[206:209], v[76:79]
	v_mfma_f32_16x16x32_bf16 v[72:75], v[158:161], v[206:209], v[72:75]
	v_mfma_f32_16x16x32_bf16 v[124:127], v[150:153], v[186:189], v[124:127]
	v_mfma_f32_16x16x32_bf16 v[120:123], v[162:165], v[186:189], v[120:123]
	v_mfma_f32_16x16x32_bf16 v[108:111], v[150:153], v[194:197], v[108:111]
	v_mfma_f32_16x16x32_bf16 v[104:107], v[162:165], v[194:197], v[104:107]
	v_mfma_f32_16x16x32_bf16 v[92:95], v[150:153], v[202:205], v[92:95]
	v_mfma_f32_16x16x32_bf16 v[88:91], v[162:165], v[202:205], v[88:91]
	v_mfma_f32_16x16x32_bf16 v[76:79], v[150:153], v[210:213], v[76:79]
	v_mfma_f32_16x16x32_bf16 v[72:75], v[162:165], v[210:213], v[72:75]
	v_mfma_f32_16x16x32_bf16 v[116:119], v[166:169], v[182:185], v[116:119]
	v_mfma_f32_16x16x32_bf16 v[112:115], v[174:177], v[182:185], v[112:115]
	v_mfma_f32_16x16x32_bf16 v[100:103], v[166:169], v[190:193], v[100:103]
	v_mfma_f32_16x16x32_bf16 v[96:99], v[174:177], v[190:193], v[96:99]
	v_mfma_f32_16x16x32_bf16 v[84:87], v[166:169], v[198:201], v[84:87]
	v_mfma_f32_16x16x32_bf16 v[80:83], v[174:177], v[198:201], v[80:83]
	v_mfma_f32_16x16x32_bf16 v[68:71], v[166:169], v[206:209], v[68:71]
	v_mfma_f32_16x16x32_bf16 v[64:67], v[174:177], v[206:209], v[64:67]
	v_mfma_f32_16x16x32_bf16 v[116:119], v[170:173], v[186:189], v[116:119]
	v_mfma_f32_16x16x32_bf16 v[112:115], v[178:181], v[186:189], v[112:115]
	v_mfma_f32_16x16x32_bf16 v[100:103], v[170:173], v[194:197], v[100:103]
	v_mfma_f32_16x16x32_bf16 v[96:99], v[178:181], v[194:197], v[96:99]
	v_mfma_f32_16x16x32_bf16 v[84:87], v[170:173], v[202:205], v[84:87]
	v_mfma_f32_16x16x32_bf16 v[80:83], v[178:181], v[202:205], v[80:83]
	v_mfma_f32_16x16x32_bf16 v[68:71], v[170:173], v[210:213], v[68:71]
	v_mfma_f32_16x16x32_bf16 v[64:67], v[178:181], v[210:213], v[64:67]
	s_barrier
; #define PG8_STAGE(bufoff, gbase, voff) do { _Pragma("unroll") for (int _i = 0; _i < 2; ++_i) \
;         __builtin_amdgcn_global_load_lds((const unsigned*)((const char*)(gbase) + (voff)[_i]), (LAS unsigned*)(lds + (bufoff) + ldsw + _i * 8192), 16, 0, 0); } while (0)
; #define PG8_LDA(dst, b, h) do { _Pragma("unroll") for (int m = 0; m < 4; ++m) _Pragma("unroll") for (int k = 0; k < 2; ++k) dst[m][k] = *(const LAS bf16x8*)(lds + PG8_SA(b, h) + aoff + m * 2048 + k * 1024); } while (0)
; #define PG8_MMA(ai, bj, At, Bt) do { __builtin_amdgcn_s_setprio(1); _Pragma("unroll") for (int m = 0; m < 4; ++m) _Pragma("unroll") for (int n = 0; n < 2; ++n) _Pragma("unroll") for (int k = 0; k < 2; ++k) \
;         acc[ai][bj][m][n] = __builtin_amdgcn_mfma_f32_16x16x32_bf16(Bt[n][k], At[m][k], acc[ai][bj][m][n], 0, 0, 0); __builtin_amdgcn_s_setprio(0); } while (0)
; #define PG8_WAIT_V(n) asm volatile("s_waitcnt vmcnt(" #n ")" ::: "memory")
; #define PG8_WAIT_L(n) asm volatile("s_waitcnt lgkmcnt(" #n ")" ::: "memory")
; #define PG8_BAR __builtin_amdgcn_s_barrier()
; #define PG8_SCHED __builtin_amdgcn_sched_barrier(0)
; template <class Desc, class Epi>
; DI void gemm_phase(LAS unsigned char* lds, const Desc& D, const Epi& E, int wv) {
;     ...
;             PG8_LDA(At, 1, 1); PG8_STAGE(PG8_SB(1, 0), b3, voffB); PG8_STAGE(PG8_SB(1, 1), b3 + hstepB, voffB); PG8_STAGE(PG8_SA(1, 0), a3, voffA);
;             PG8_WAIT_V(8); PG8_WAIT_L(0); PG8_BAR; PG8_MMA(1, 0, At, B0); PG8_MMA(1, 1, At, B1); PG8_BAR; PG8_SCHED;
;         }
;         if (wr == 0) PG8_BAR;
	s_add_i32 s17, s17, s28
	v_lshl_add_u64 v[214:215], v[214:215], 0, s[12:13]
	s_mov_b32 m0, s17
	ds_read_b128 v[182:185], v157 offset:49152
	ds_read_b128 v[186:189], v157 offset:50176
	ds_read_b128 v[190:193], v157 offset:51200
	ds_read_b128 v[194:197], v157 offset:52224
	ds_read_b128 v[198:201], v157 offset:53248
	ds_read_b128 v[202:205], v157 offset:54272
	ds_read_b128 v[206:209], v157 offset:55296
	ds_read_b128 v[210:213], v157 offset:56320
	global_load_lds_dwordx4 v[214:215], off
	s_add_i32 m0, s17, 0x2000
	s_add_u32 s64, s64, 0x80080
	v_lshl_add_u64 v[214:215], v[216:217], 0, s[12:13]
	s_addc_u32 s65, s65, 0
	s_add_i32 s17, s19, s28
	global_load_lds_dwordx4 v[214:215], off
	s_mov_b32 m0, s17
	v_lshl_add_u64 v[214:215], s[64:65], 0, v[130:131]
	global_load_lds_dwordx4 v[214:215], off
	s_add_i32 m0, s17, 0x2000
	v_lshl_add_u64 v[214:215], s[64:65], 0, v[134:135]
	global_load_lds_dwordx4 v[214:215], off
	s_mov_b32 m0, s47
	v_lshl_add_u64 v[214:215], v[218:219], 0, s[12:13]
	global_load_lds_dwordx4 v[214:215], off
	s_mov_b32 m0, s48
	v_lshl_add_u64 v[214:215], v[220:221], 0, s[12:13]
	global_load_lds_dwordx4 v[214:215], off
	s_waitcnt vmcnt(8) lgkmcnt(0)
	s_barrier
	v_mfma_f32_16x16x32_bf16 v[60:63], v[146:149], v[182:185], v[60:63]
	v_mfma_f32_16x16x32_bf16 v[56:59], v[158:161], v[182:185], v[56:59]
	v_mfma_f32_16x16x32_bf16 v[44:47], v[146:149], v[190:193], v[44:47]
	v_mfma_f32_16x16x32_bf16 v[40:43], v[158:161], v[190:193], v[40:43]
	v_mfma_f32_16x16x32_bf16 v[28:31], v[146:149], v[198:201], v[28:31]
	v_mfma_f32_16x16x32_bf16 v[24:27], v[158:161], v[198:201], v[24:27]
	v_mfma_f32_16x16x32_bf16 v[12:15], v[146:149], v[206:209], v[12:15]
	v_mfma_f32_16x16x32_bf16 v[8:11], v[158:161], v[206:209], v[8:11]
	v_mfma_f32_16x16x32_bf16 v[60:63], v[150:153], v[186:189], v[60:63]
	v_mfma_f32_16x16x32_bf16 v[56:59], v[162:165], v[186:189], v[56:59]
	v_mfma_f32_16x16x32_bf16 v[44:47], v[150:153], v[194:197], v[44:47]
	v_mfma_f32_16x16x32_bf16 v[40:43], v[162:165], v[194:197], v[40:43]
	v_mfma_f32_16x16x32_bf16 v[28:31], v[150:153], v[202:205], v[28:31]
	v_mfma_f32_16x16x32_bf16 v[24:27], v[162:165], v[202:205], v[24:27]
	v_mfma_f32_16x16x32_bf16 v[12:15], v[150:153], v[210:213], v[12:15]
	v_mfma_f32_16x16x32_bf16 v[8:11], v[162:165], v[210:213], v[8:11]
	v_mfma_f32_16x16x32_bf16 v[52:55], v[166:169], v[182:185], v[52:55]
	v_mfma_f32_16x16x32_bf16 v[48:51], v[174:177], v[182:185], v[48:51]
	v_mfma_f32_16x16x32_bf16 v[36:39], v[166:169], v[190:193], v[36:39]
	v_mfma_f32_16x16x32_bf16 v[32:35], v[174:177], v[190:193], v[32:35]
	v_mfma_f32_16x16x32_bf16 v[20:23], v[166:169], v[198:201], v[20:23]
	v_mfma_f32_16x16x32_bf16 v[16:19], v[174:177], v[198:201], v[16:19]
	v_mfma_f32_16x16x32_bf16 v[4:7], v[166:169], v[206:209], v[4:7]
	v_mfma_f32_16x16x32_bf16 v[0:3], v[174:177], v[206:209], v[0:3]
	v_mfma_f32_16x16x32_bf16 v[52:55], v[170:173], v[186:189], v[52:55]
	v_mfma_f32_16x16x32_bf16 v[48:51], v[178:181], v[186:189], v[48:51]
	v_mfma_f32_16x16x32_bf16 v[36:39], v[170:173], v[194:197], v[36:39]
	v_mfma_f32_16x16x32_bf16 v[32:35], v[178:181], v[194:197], v[32:35]
	v_mfma_f32_16x16x32_bf16 v[20:23], v[170:173], v[202:205], v[20:23]
	v_mfma_f32_16x16x32_bf16 v[16:19], v[178:181], v[202:205], v[16:19]
	v_mfma_f32_16x16x32_bf16 v[4:7], v[170:173], v[210:213], v[4:7]
	v_mfma_f32_16x16x32_bf16 v[0:3], v[178:181], v[210:213], v[0:3]
	s_barrier
	s_add_i32 s8, s8, 2
	s_add_u32 s62, s62, 0x100
	s_addc_u32 s63, s63, 0
	s_add_u32 s5, s5, 0x100
	s_addc_u32 s7, s7, 0
	s_cmp_gt_u32 s8, 29
	s_cbranch_scc0 .LBB0_1632
	s_and_b64 vcc, exec, s[14:15]
	s_cbranch_vccz .LBB0_1635
	s_barrier

; #define PG8_STAGE(bufoff, gbase, voff) do { _Pragma("unroll") for (int _i = 0; _i < 2; ++_i) \
;         __builtin_amdgcn_global_load_lds((const unsigned*)((const char*)(gbase) + (voff)[_i]), (LAS unsigned*)(lds + (bufoff) + ldsw + _i * 8192), 16, 0, 0); } while (0)
; #define PG8_LDA(dst, b, h) do { _Pragma("unroll") for (int m = 0; m < 4; ++m) _Pragma("unroll") for (int k = 0; k < 2; ++k) dst[m][k] = *(const LAS bf16x8*)(lds + PG8_SA(b, h) + aoff + m * 2048 + k * 1024); } while (0)
; #define PG8_LDB(dst, b, h) do { _Pragma("unroll") for (int n = 0; n < 2; ++n) _Pragma("unroll") for (int k = 0; k < 2; ++k) dst[n][k] = *(const LAS bf16x8*)(lds + PG8_SB(b, h) + boff + n * 2048 + k * 1024); } while (0)
; #define PG8_MMA(ai, bj, At, Bt) do { __builtin_amdgcn_s_setprio(1); _Pragma("unroll") for (int m = 0; m < 4; ++m) _Pragma("unroll") for (int n = 0; n < 2; ++n) _Pragma("unroll") for (int k = 0; k < 2; ++k) \
;         acc[ai][bj][m][n] = __builtin_amdgcn_mfma_f32_16x16x32_bf16(Bt[n][k], At[m][k], acc[ai][bj][m][n], 0, 0, 0); __builtin_amdgcn_s_setprio(0); } while (0)
; #define PG8_WAIT_V(n) asm volatile("s_waitcnt vmcnt(" #n ")" ::: "memory")
; #define PG8_WAIT_L(n) asm volatile("s_waitcnt lgkmcnt(" #n ")" ::: "memory")
; #define PG8_BAR __builtin_amdgcn_s_barrier()
; #define PG8_SCHED __builtin_amdgcn_sched_barrier(0)
; template <class Desc, class Epi>
; DI void gemm_phase(LAS unsigned char* lds, const Desc& D, const Epi& E, int wv) {
;     ...
;         for (int t = 0; t < nt; t += 2) {
;             const bool last = (t == nt - 2);
;             const char* a1 = cA + (size_t)(t + 1) * kstep;
;             const char* a2 = last ? nA : cA + (size_t)(t + 2) * kstep; const char* b2 = last ? nB : cB + (size_t)(t + 2) * kstep;
;             const char* a3 = a2 + kstep; const char* b3 = b2 + kstep;
;             PG8_LDB(B0, 0, 0); PG8_LDB(B1, 0, 1); PG8_SCHED; PG8_LDA(At, 0, 0); PG8_STAGE(PG8_SA(1, 1), a1 + hstepA, voffA);
;             PG8_WAIT_V(8); PG8_WAIT_L(0); PG8_BAR; PG8_MMA(0, 0, At, B0); PG8_MMA(0, 1, At, B1); PG8_BAR; PG8_SCHED;
;             PG8_LDA(At, 0, 1); PG8_STAGE(PG8_SB(0, 0), b2, voffB); PG8_STAGE(PG8_SB(0, 1), b2 + hstepB, voffB); PG8_STAGE(PG8_SA(0, 0), a2, voffA);
.LBB0_2088:
	ds_read_b128 v[128:131], v221
	ds_read_b128 v[132:135], v221 offset:1024
	ds_read_b128 v[136:139], v221 offset:2048
	ds_read_b128 v[140:143], v221 offset:3072
	ds_read_b128 v[144:147], v222
	ds_read_b128 v[148:151], v222 offset:1024
	ds_read_b128 v[152:155], v222 offset:2048
	ds_read_b128 v[156:159], v222 offset:3072
	s_add_u32 s42, s40, 0xfff80080
	s_addc_u32 s43, s41, -1
	s_cmp_eq_u32 s66, 28
	s_cselect_b32 s49, s15, s43
	s_cselect_b32 s48, s14, s42
	s_cselect_b32 s43, s17, s21
	s_cselect_b32 s42, s16, s19
	v_lshl_add_u64 v[192:193], s[40:41], 0, v[208:209]
	s_add_i32 m0, s29, 0xc000
	ds_read_b128 v[160:163], v223
	ds_read_b128 v[164:167], v223 offset:1024
	ds_read_b128 v[168:171], v223 offset:2048
	ds_read_b128 v[172:175], v223 offset:3072
	ds_read_b128 v[176:179], v223 offset:4096
	ds_read_b128 v[180:183], v223 offset:5120
	ds_read_b128 v[184:187], v223 offset:6144
	ds_read_b128 v[188:191], v223 offset:7168
	global_load_lds_dwordx4 v[192:193], off
	s_add_i32 m0, s29, 0xe000
	v_lshl_add_u64 v[192:193], s[40:41], 0, v[210:211]
	global_load_lds_dwordx4 v[192:193], off
	s_waitcnt vmcnt(8) lgkmcnt(0)
	s_barrier
	v_mfma_f32_16x16x32_bf16 v[124:127], v[128:131], v[160:163], v[124:127]
	v_mfma_f32_16x16x32_bf16 v[120:123], v[136:139], v[160:163], v[120:123]
	v_mfma_f32_16x16x32_bf16 v[112:115], v[128:131], v[168:171], v[112:115]
	v_mfma_f32_16x16x32_bf16 v[104:107], v[136:139], v[168:171], v[104:107]
	v_mfma_f32_16x16x32_bf16 v[96:99], v[128:131], v[176:179], v[96:99]
	v_mfma_f32_16x16x32_bf16 v[88:91], v[136:139], v[176:179], v[88:91]
	v_mfma_f32_16x16x32_bf16 v[80:83], v[128:131], v[184:187], v[80:83]
	v_mfma_f32_16x16x32_bf16 v[72:75], v[136:139], v[184:187], v[72:75]
	v_mfma_f32_16x16x32_bf16 v[124:127], v[132:135], v[164:167], v[124:127]
	v_mfma_f32_16x16x32_bf16 v[120:123], v[140:143], v[164:167], v[120:123]
	v_mfma_f32_16x16x32_bf16 v[112:115], v[132:135], v[172:175], v[112:115]
	v_mfma_f32_16x16x32_bf16 v[104:107], v[140:143], v[172:175], v[104:107]
	v_mfma_f32_16x16x32_bf16 v[96:99], v[132:135], v[180:183], v[96:99]
	v_mfma_f32_16x16x32_bf16 v[88:91], v[140:143], v[180:183], v[88:91]
	v_mfma_f32_16x16x32_bf16 v[80:83], v[132:135], v[188:191], v[80:83]
	v_mfma_f32_16x16x32_bf16 v[72:75], v[140:143], v[188:191], v[72:75]
	v_mfma_f32_16x16x32_bf16 v[116:119], v[144:147], v[160:163], v[116:119]
	v_mfma_f32_16x16x32_bf16 v[108:111], v[152:155], v[160:163], v[108:111]
	v_mfma_f32_16x16x32_bf16 v[100:103], v[144:147], v[168:171], v[100:103]
	v_mfma_f32_16x16x32_bf16 v[92:95], v[152:155], v[168:171], v[92:95]
	v_mfma_f32_16x16x32_bf16 v[84:87], v[144:147], v[176:179], v[84:87]
	v_mfma_f32_16x16x32_bf16 v[76:79], v[152:155], v[176:179], v[76:79]
	v_mfma_f32_16x16x32_bf16 v[68:71], v[144:147], v[184:187], v[68:71]
	v_mfma_f32_16x16x32_bf16 v[64:67], v[152:155], v[184:187], v[64:67]
	v_mfma_f32_16x16x32_bf16 v[116:119], v[148:151], v[164:167], v[116:119]
	v_mfma_f32_16x16x32_bf16 v[108:111], v[156:159], v[164:167], v[108:111]
	v_mfma_f32_16x16x32_bf16 v[100:103], v[148:151], v[172:175], v[100:103]
	v_mfma_f32_16x16x32_bf16 v[92:95], v[156:159], v[172:175], v[92:95]
	v_mfma_f32_16x16x32_bf16 v[84:87], v[148:151], v[180:183], v[84:87]
	v_mfma_f32_16x16x32_bf16 v[76:79], v[156:159], v[180:183], v[76:79]
	v_mfma_f32_16x16x32_bf16 v[68:71], v[148:151], v[188:191], v[68:71]
	v_mfma_f32_16x16x32_bf16 v[64:67], v[156:159], v[188:191], v[64:67]
	s_barrier
	s_add_i32 s67, s53, s28
	v_lshl_add_u64 v[192:193], s[42:43], 0, v[202:203]
	s_mov_b32 m0, s67
	ds_read_b128 v[160:163], v223 offset:16384
	ds_read_b128 v[164:167], v223 offset:17408
	ds_read_b128 v[168:171], v223 offset:18432
	ds_read_b128 v[172:175], v223 offset:19456
	ds_read_b128 v[176:179], v223 offset:20480
	ds_read_b128 v[180:183], v223 offset:21504
	ds_read_b128 v[184:187], v223 offset:22528
	ds_read_b128 v[188:191], v223 offset:23552
	global_load_lds_dwordx4 v[192:193], off
	s_add_i32 m0, s67, 0x2000
	s_add_u32 s68, s42, 0x80000
	v_lshl_add_u64 v[194:195], s[42:43], 0, v[206:207]
	s_addc_u32 s69, s43, 0
	s_add_i32 s67, s60, s28
	global_load_lds_dwordx4 v[194:195], off
	v_lshl_add_u64 v[196:197], s[68:69], 0, v[202:203]
	s_mov_b32 m0, s67
	v_lshl_add_u64 v[198:199], s[48:49], 0, v[204:205]
	global_load_lds_dwordx4 v[196:197], off
	s_add_i32 m0, s67, 0x2000
	v_lshl_add_u64 v[196:197], s[68:69], 0, v[206:207]
	global_load_lds_dwordx4 v[196:197], off
	s_mov_b32 m0, s29
	v_lshl_add_u64 v[196:197], s[48:49], 0, v[200:201]
	global_load_lds_dwordx4 v[196:197], off
	s_mov_b32 m0, s30
	s_nop 0
	global_load_lds_dwordx4 v[198:199], off
	s_waitcnt vmcnt(8) lgkmcnt(0)
	s_barrier
; #define PG8_STAGE(bufoff, gbase, voff) do { _Pragma("unroll") for (int _i = 0; _i < 2; ++_i) \
;         __builtin_amdgcn_global_load_lds((const unsigned*)((const char*)(gbase) + (voff)[_i]), (LAS unsigned*)(lds + (bufoff) + ldsw + _i * 8192), 16, 0, 0); } while (0)
; #define PG8_LDA(dst, b, h) do { _Pragma("unroll") for (int m = 0; m < 4; ++m) _Pragma("unroll") for (int k = 0; k < 2; ++k) dst[m][k] = *(const LAS bf16x8*)(lds + PG8_SA(b, h) + aoff + m * 2048 + k * 1024); } while (0)
; #define PG8_LDB(dst, b, h) do { _Pragma("unroll") for (int n = 0; n < 2; ++n) _Pragma("unroll") for (int k = 0; k < 2; ++k) dst[n][k] = *(const LAS bf16x8*)(lds + PG8_SB(b, h) + boff + n * 2048 + k * 1024); } while (0)
; #define PG8_MMA(ai, bj, At, Bt) do { __builtin_amdgcn_s_setprio(1); _Pragma("unroll") for (int m = 0; m < 4; ++m) _Pragma("unroll") for (int n = 0; n < 2; ++n) _Pragma("unroll") for (int k = 0; k < 2; ++k) \
;         acc[ai][bj][m][n] = __builtin_amdgcn_mfma_f32_16x16x32_bf16(Bt[n][k], At[m][k], acc[ai][bj][m][n], 0, 0, 0); __builtin_amdgcn_s_setprio(0); } while (0)
; #define PG8_WAIT_V(n) asm volatile("s_waitcnt vmcnt(" #n ")" ::: "memory")
; #define PG8_WAIT_L(n) asm volatile("s_waitcnt lgkmcnt(" #n ")" ::: "memory")
; #define PG8_BAR __builtin_amdgcn_s_barrier()
; #define PG8_SCHED __builtin_amdgcn_sched_barrier(0)
; template <class Desc, class Epi>
; DI void gemm_phase(LAS unsigned char* lds, const Desc& D, const Epi& E, int wv) {
;     ...
;             PG8_WAIT_V(8); PG8_WAIT_L(0); PG8_BAR; PG8_MMA(1, 0, At, B0); PG8_MMA(1, 1, At, B1); PG8_BAR; PG8_SCHED;
;             PG8_LDB(B0, 1, 0); PG8_LDB(B1, 1, 1); PG8_SCHED; PG8_LDA(At, 1, 0); PG8_STAGE(PG8_SA(0, 1), a2 + hstepA, voffA);
;             PG8_WAIT_V(8); PG8_WAIT_L(0); PG8_BAR; PG8_MMA(0, 0, At, B0); PG8_MMA(0, 1, At, B1); PG8_BAR; PG8_SCHED;
;             PG8_LDA(At, 1, 1); PG8_STAGE(PG8_SB(1, 0), b3, voffB); PG8_STAGE(PG8_SB(1, 1), b3 + hstepB, voffB); PG8_STAGE(PG8_SA(1, 0), a3, voffA);
	v_mfma_f32_16x16x32_bf16 v[60:63], v[128:131], v[160:163], v[60:63]
	v_mfma_f32_16x16x32_bf16 v[56:59], v[136:139], v[160:163], v[56:59]
	v_mfma_f32_16x16x32_bf16 v[48:51], v[128:131], v[168:171], v[48:51]
	v_mfma_f32_16x16x32_bf16 v[40:43], v[136:139], v[168:171], v[40:43]
	v_mfma_f32_16x16x32_bf16 v[32:35], v[128:131], v[176:179], v[32:35]
	v_mfma_f32_16x16x32_bf16 v[24:27], v[136:139], v[176:179], v[24:27]
	v_mfma_f32_16x16x32_bf16 v[16:19], v[128:131], v[184:187], v[16:19]
	v_mfma_f32_16x16x32_bf16 v[8:11], v[136:139], v[184:187], v[8:11]
	v_mfma_f32_16x16x32_bf16 v[60:63], v[132:135], v[164:167], v[60:63]
	v_mfma_f32_16x16x32_bf16 v[56:59], v[140:143], v[164:167], v[56:59]
	v_mfma_f32_16x16x32_bf16 v[48:51], v[132:135], v[172:175], v[48:51]
	v_mfma_f32_16x16x32_bf16 v[40:43], v[140:143], v[172:175], v[40:43]
	v_mfma_f32_16x16x32_bf16 v[32:35], v[132:135], v[180:183], v[32:35]
	v_mfma_f32_16x16x32_bf16 v[24:27], v[140:143], v[180:183], v[24:27]
	v_mfma_f32_16x16x32_bf16 v[16:19], v[132:135], v[188:191], v[16:19]
	v_mfma_f32_16x16x32_bf16 v[8:11], v[140:143], v[188:191], v[8:11]
	v_mfma_f32_16x16x32_bf16 v[52:55], v[144:147], v[160:163], v[52:55]
	v_mfma_f32_16x16x32_bf16 v[44:47], v[152:155], v[160:163], v[44:47]
	v_mfma_f32_16x16x32_bf16 v[36:39], v[144:147], v[168:171], v[36:39]
	v_mfma_f32_16x16x32_bf16 v[28:31], v[152:155], v[168:171], v[28:31]
	v_mfma_f32_16x16x32_bf16 v[20:23], v[144:147], v[176:179], v[20:23]
	v_mfma_f32_16x16x32_bf16 v[12:15], v[152:155], v[176:179], v[12:15]
	v_mfma_f32_16x16x32_bf16 v[4:7], v[144:147], v[184:187], v[4:7]
	v_mfma_f32_16x16x32_bf16 v[0:3], v[152:155], v[184:187], v[0:3]
	v_mfma_f32_16x16x32_bf16 v[52:55], v[148:151], v[164:167], v[52:55]
	v_mfma_f32_16x16x32_bf16 v[44:47], v[156:159], v[164:167], v[44:47]
	v_mfma_f32_16x16x32_bf16 v[36:39], v[148:151], v[172:175], v[36:39]
	v_mfma_f32_16x16x32_bf16 v[28:31], v[156:159], v[172:175], v[28:31]
	v_mfma_f32_16x16x32_bf16 v[20:23], v[148:151], v[180:183], v[20:23]
	v_mfma_f32_16x16x32_bf16 v[12:15], v[156:159], v[180:183], v[12:15]
	v_mfma_f32_16x16x32_bf16 v[4:7], v[148:151], v[188:191], v[4:7]
	v_mfma_f32_16x16x32_bf16 v[0:3], v[156:159], v[188:191], v[0:3]
	s_barrier
	s_add_i32 s67, 0, 0x18000
	s_add_i32 s68, 0, 0x1c000
	v_add_u32_e32 v140, s67, v220
	v_add_u32_e32 v156, s68, v220
	ds_read_b128 v[128:131], v140
	ds_read_b128 v[132:135], v140 offset:1024
	ds_read_b128 v[136:139], v140 offset:2048
	ds_read_b128 v[140:143], v140 offset:3072
	ds_read_b128 v[144:147], v156
	ds_read_b128 v[148:151], v156 offset:1024
	ds_read_b128 v[152:155], v156 offset:2048
	ds_read_b128 v[156:159], v156 offset:3072
	s_add_u32 s48, s48, 0x80000
	s_addc_u32 s49, s49, 0
	s_mov_b32 m0, s31
	v_lshl_add_u64 v[216:217], s[48:49], 0, v[200:201]
	ds_read_b128 v[160:163], v223 offset:32768
	ds_read_b128 v[164:167], v223 offset:33792
	ds_read_b128 v[168:171], v223 offset:34816
	ds_read_b128 v[172:175], v223 offset:35840
	ds_read_b128 v[176:179], v223 offset:36864
	ds_read_b128 v[180:183], v223 offset:37888
	ds_read_b128 v[184:187], v223 offset:38912
	ds_read_b128 v[188:191], v223 offset:39936
	global_load_lds_dwordx4 v[216:217], off
	s_mov_b32 m0, s34
	v_lshl_add_u64 v[216:217], s[48:49], 0, v[204:205]
	global_load_lds_dwordx4 v[216:217], off
	s_waitcnt vmcnt(8) lgkmcnt(0)
	s_barrier
	v_mfma_f32_16x16x32_bf16 v[124:127], v[128:131], v[160:163], v[124:127]
	v_mfma_f32_16x16x32_bf16 v[120:123], v[136:139], v[160:163], v[120:123]
	v_mfma_f32_16x16x32_bf16 v[112:115], v[128:131], v[168:171], v[112:115]
	v_mfma_f32_16x16x32_bf16 v[104:107], v[136:139], v[168:171], v[104:107]
	v_mfma_f32_16x16x32_bf16 v[96:99], v[128:131], v[176:179], v[96:99]
	v_mfma_f32_16x16x32_bf16 v[88:91], v[136:139], v[176:179], v[88:91]
	v_mfma_f32_16x16x32_bf16 v[80:83], v[128:131], v[184:187], v[80:83]
	v_mfma_f32_16x16x32_bf16 v[72:75], v[136:139], v[184:187], v[72:75]
	v_mfma_f32_16x16x32_bf16 v[124:127], v[132:135], v[164:167], v[124:127]
	v_mfma_f32_16x16x32_bf16 v[120:123], v[140:143], v[164:167], v[120:123]
	v_mfma_f32_16x16x32_bf16 v[112:115], v[132:135], v[172:175], v[112:115]
	v_mfma_f32_16x16x32_bf16 v[104:107], v[140:143], v[172:175], v[104:107]
	v_mfma_f32_16x16x32_bf16 v[96:99], v[132:135], v[180:183], v[96:99]
	v_mfma_f32_16x16x32_bf16 v[88:91], v[140:143], v[180:183], v[88:91]
	v_mfma_f32_16x16x32_bf16 v[80:83], v[132:135], v[188:191], v[80:83]
	v_mfma_f32_16x16x32_bf16 v[72:75], v[140:143], v[188:191], v[72:75]
	v_mfma_f32_16x16x32_bf16 v[116:119], v[144:147], v[160:163], v[116:119]
	v_mfma_f32_16x16x32_bf16 v[108:111], v[152:155], v[160:163], v[108:111]
	v_mfma_f32_16x16x32_bf16 v[100:103], v[144:147], v[168:171], v[100:103]
	v_mfma_f32_16x16x32_bf16 v[92:95], v[152:155], v[168:171], v[92:95]
	v_mfma_f32_16x16x32_bf16 v[84:87], v[144:147], v[176:179], v[84:87]
	v_mfma_f32_16x16x32_bf16 v[76:79], v[152:155], v[176:179], v[76:79]
	v_mfma_f32_16x16x32_bf16 v[68:71], v[144:147], v[184:187], v[68:71]
	v_mfma_f32_16x16x32_bf16 v[64:67], v[152:155], v[184:187], v[64:67]
	v_mfma_f32_16x16x32_bf16 v[116:119], v[148:151], v[164:167], v[116:119]
	v_mfma_f32_16x16x32_bf16 v[108:111], v[156:159], v[164:167], v[108:111]
	v_mfma_f32_16x16x32_bf16 v[100:103], v[148:151], v[172:175], v[100:103]
	v_mfma_f32_16x16x32_bf16 v[92:95], v[156:159], v[172:175], v[92:95]
	v_mfma_f32_16x16x32_bf16 v[84:87], v[148:151], v[180:183], v[84:87]
	v_mfma_f32_16x16x32_bf16 v[76:79], v[156:159], v[180:183], v[76:79]
	v_mfma_f32_16x16x32_bf16 v[68:71], v[148:151], v[188:191], v[68:71]
	v_mfma_f32_16x16x32_bf16 v[64:67], v[156:159], v[188:191], v[64:67]
	s_barrier
; #define PG8_STAGE(bufoff, gbase, voff) do { _Pragma("unroll") for (int _i = 0; _i < 2; ++_i) \
;         __builtin_amdgcn_global_load_lds((const unsigned*)((const char*)(gbase) + (voff)[_i]), (LAS unsigned*)(lds + (bufoff) + ldsw + _i * 8192), 16, 0, 0); } while (0)
; #define PG8_LDA(dst, b, h) do { _Pragma("unroll") for (int m = 0; m < 4; ++m) _Pragma("unroll") for (int k = 0; k < 2; ++k) dst[m][k] = *(const LAS bf16x8*)(lds + PG8_SA(b, h) + aoff + m * 2048 + k * 1024); } while (0)
; #define PG8_MMA(ai, bj, At, Bt) do { __builtin_amdgcn_s_setprio(1); _Pragma("unroll") for (int m = 0; m < 4; ++m) _Pragma("unroll") for (int n = 0; n < 2; ++n) _Pragma("unroll") for (int k = 0; k < 2; ++k) \
;         acc[ai][bj][m][n] = __builtin_amdgcn_mfma_f32_16x16x32_bf16(Bt[n][k], At[m][k], acc[ai][bj][m][n], 0, 0, 0); __builtin_amdgcn_s_setprio(0); } while (0)
; #define PG8_WAIT_V(n) asm volatile("s_waitcnt vmcnt(" #n ")" ::: "memory")
; #define PG8_WAIT_L(n) asm volatile("s_waitcnt lgkmcnt(" #n ")" ::: "memory")
; #define PG8_BAR __builtin_amdgcn_s_barrier()
; #define PG8_SCHED __builtin_amdgcn_sched_barrier(0)
; template <class Desc, class Epi>
; DI void gemm_phase(LAS unsigned char* lds, const Desc& D, const Epi& E, int wv) {
;     ...
;             PG8_LDA(At, 1, 1); PG8_STAGE(PG8_SB(1, 0), b3, voffB); PG8_STAGE(PG8_SB(1, 1), b3 + hstepB, voffB); PG8_STAGE(PG8_SA(1, 0), a3, voffA);
;             PG8_WAIT_V(8); PG8_WAIT_L(0); PG8_BAR; PG8_MMA(1, 0, At, B0); PG8_MMA(1, 1, At, B1); PG8_BAR; PG8_SCHED;
;         }
;         if (wr == 0) PG8_BAR;
	s_add_i32 s48, s67, s28
	v_lshl_add_u64 v[192:193], v[192:193], 0, s[8:9]
	s_mov_b32 m0, s48
	ds_read_b128 v[160:163], v223 offset:49152
	ds_read_b128 v[164:167], v223 offset:50176
	ds_read_b128 v[168:171], v223 offset:51200
	ds_read_b128 v[172:175], v223 offset:52224
	ds_read_b128 v[176:179], v223 offset:53248
	ds_read_b128 v[180:183], v223 offset:54272
	ds_read_b128 v[184:187], v223 offset:55296
	ds_read_b128 v[188:191], v223 offset:56320
	global_load_lds_dwordx4 v[192:193], off
	s_add_i32 m0, s48, 0x2000
	s_add_u32 s42, s42, 0x80080
	v_lshl_add_u64 v[192:193], v[194:195], 0, s[8:9]
	s_addc_u32 s43, s43, 0
	s_add_i32 s48, s68, s28
	global_load_lds_dwordx4 v[192:193], off
	s_mov_b32 m0, s48
	v_lshl_add_u64 v[192:193], s[42:43], 0, v[202:203]
	global_load_lds_dwordx4 v[192:193], off
	s_add_i32 m0, s48, 0x2000
	v_lshl_add_u64 v[192:193], s[42:43], 0, v[206:207]
	global_load_lds_dwordx4 v[192:193], off
	s_mov_b32 m0, s50
	v_lshl_add_u64 v[192:193], v[196:197], 0, s[8:9]
	global_load_lds_dwordx4 v[192:193], off
	s_mov_b32 m0, s51
	v_lshl_add_u64 v[192:193], v[198:199], 0, s[8:9]
	global_load_lds_dwordx4 v[192:193], off
	s_waitcnt vmcnt(8) lgkmcnt(0)
	s_barrier
	v_mfma_f32_16x16x32_bf16 v[60:63], v[128:131], v[160:163], v[60:63]
	v_mfma_f32_16x16x32_bf16 v[56:59], v[136:139], v[160:163], v[56:59]
	v_mfma_f32_16x16x32_bf16 v[48:51], v[128:131], v[168:171], v[48:51]
	v_mfma_f32_16x16x32_bf16 v[40:43], v[136:139], v[168:171], v[40:43]
	v_mfma_f32_16x16x32_bf16 v[32:35], v[128:131], v[176:179], v[32:35]
	v_mfma_f32_16x16x32_bf16 v[24:27], v[136:139], v[176:179], v[24:27]
	v_mfma_f32_16x16x32_bf16 v[16:19], v[128:131], v[184:187], v[16:19]
	v_mfma_f32_16x16x32_bf16 v[8:11], v[136:139], v[184:187], v[8:11]
	v_mfma_f32_16x16x32_bf16 v[60:63], v[132:135], v[164:167], v[60:63]
	v_mfma_f32_16x16x32_bf16 v[56:59], v[140:143], v[164:167], v[56:59]
	v_mfma_f32_16x16x32_bf16 v[48:51], v[132:135], v[172:175], v[48:51]
	v_mfma_f32_16x16x32_bf16 v[40:43], v[140:143], v[172:175], v[40:43]
	v_mfma_f32_16x16x32_bf16 v[32:35], v[132:135], v[180:183], v[32:35]
	v_mfma_f32_16x16x32_bf16 v[24:27], v[140:143], v[180:183], v[24:27]
	v_mfma_f32_16x16x32_bf16 v[16:19], v[132:135], v[188:191], v[16:19]
	v_mfma_f32_16x16x32_bf16 v[8:11], v[140:143], v[188:191], v[8:11]
	v_mfma_f32_16x16x32_bf16 v[52:55], v[144:147], v[160:163], v[52:55]
	v_mfma_f32_16x16x32_bf16 v[44:47], v[152:155], v[160:163], v[44:47]
	v_mfma_f32_16x16x32_bf16 v[36:39], v[144:147], v[168:171], v[36:39]
	v_mfma_f32_16x16x32_bf16 v[28:31], v[152:155], v[168:171], v[28:31]
	v_mfma_f32_16x16x32_bf16 v[20:23], v[144:147], v[176:179], v[20:23]
	v_mfma_f32_16x16x32_bf16 v[12:15], v[152:155], v[176:179], v[12:15]
	v_mfma_f32_16x16x32_bf16 v[4:7], v[144:147], v[184:187], v[4:7]
	v_mfma_f32_16x16x32_bf16 v[0:3], v[152:155], v[184:187], v[0:3]
	v_mfma_f32_16x16x32_bf16 v[52:55], v[148:151], v[164:167], v[52:55]
	v_mfma_f32_16x16x32_bf16 v[44:47], v[156:159], v[164:167], v[44:47]
	v_mfma_f32_16x16x32_bf16 v[36:39], v[148:151], v[172:175], v[36:39]
	v_mfma_f32_16x16x32_bf16 v[28:31], v[156:159], v[172:175], v[28:31]
	v_mfma_f32_16x16x32_bf16 v[20:23], v[148:151], v[180:183], v[20:23]
	v_mfma_f32_16x16x32_bf16 v[12:15], v[156:159], v[180:183], v[12:15]
	v_mfma_f32_16x16x32_bf16 v[4:7], v[148:151], v[188:191], v[4:7]
	v_mfma_f32_16x16x32_bf16 v[0:3], v[156:159], v[188:191], v[0:3]
	s_barrier
	s_add_i32 s66, s66, 2
	s_add_u32 s40, s40, 0x100
	s_addc_u32 s41, s41, 0
	s_add_u32 s19, s19, 0x100
	s_addc_u32 s21, s21, 0
	s_cmp_gt_u32 s66, 29
	s_cbranch_scc0 .LBB0_2088
	s_and_b64 vcc, exec, s[10:11]
	s_cbranch_vccz .LBB0_2091
	s_barrier

; #define PG8_STAGE(bufoff, gbase, voff) do { _Pragma("unroll") for (int _i = 0; _i < 2; ++_i) \
;         __builtin_amdgcn_global_load_lds((const unsigned*)((const char*)(gbase) + (voff)[_i]), (LAS unsigned*)(lds + (bufoff) + ldsw + _i * 8192), 16, 0, 0); } while (0)
; #define PG8_LDA(dst, b, h) do { _Pragma("unroll") for (int m = 0; m < 4; ++m) _Pragma("unroll") for (int k = 0; k < 2; ++k) dst[m][k] = *(const LAS bf16x8*)(lds + PG8_SA(b, h) + aoff + m * 2048 + k * 1024); } while (0)
; #define PG8_LDB(dst, b, h) do { _Pragma("unroll") for (int n = 0; n < 2; ++n) _Pragma("unroll") for (int k = 0; k < 2; ++k) dst[n][k] = *(const LAS bf16x8*)(lds + PG8_SB(b, h) + boff + n * 2048 + k * 1024); } while (0)
; #define PG8_MMA(ai, bj, At, Bt) do { __builtin_amdgcn_s_setprio(1); _Pragma("unroll") for (int m = 0; m < 4; ++m) _Pragma("unroll") for (int n = 0; n < 2; ++n) _Pragma("unroll") for (int k = 0; k < 2; ++k) \
;         acc[ai][bj][m][n] = __builtin_amdgcn_mfma_f32_16x16x32_bf16(Bt[n][k], At[m][k], acc[ai][bj][m][n], 0, 0, 0); __builtin_amdgcn_s_setprio(0); } while (0)
; #define PG8_WAIT_V(n) asm volatile("s_waitcnt vmcnt(" #n ")" ::: "memory")
; #define PG8_WAIT_L(n) asm volatile("s_waitcnt lgkmcnt(" #n ")" ::: "memory")
; #define PG8_BAR __builtin_amdgcn_s_barrier()
; #define PG8_SCHED __builtin_amdgcn_sched_barrier(0)
; template <class Desc, class Epi>
; DI void gemm_phase(LAS unsigned char* lds, const Desc& D, const Epi& E, int wv) {
;     ...
;         for (int t = 0; t < nt; t += 2) {
;             const bool last = (t == nt - 2);
;             const char* a1 = cA + (size_t)(t + 1) * kstep;
;             const char* a2 = last ? nA : cA + (size_t)(t + 2) * kstep; const char* b2 = last ? nB : cB + (size_t)(t + 2) * kstep;
;             const char* a3 = a2 + kstep; const char* b3 = b2 + kstep;
;             PG8_LDB(B0, 0, 0); PG8_LDB(B1, 0, 1); PG8_SCHED; PG8_LDA(At, 0, 0); PG8_STAGE(PG8_SA(1, 1), a1 + hstepA, voffA);
;             PG8_WAIT_V(8); PG8_WAIT_L(0); PG8_BAR; PG8_MMA(0, 0, At, B0); PG8_MMA(0, 1, At, B1); PG8_BAR; PG8_SCHED;
;             PG8_LDA(At, 0, 1); PG8_STAGE(PG8_SB(0, 0), b2, voffB); PG8_STAGE(PG8_SB(0, 1), b2 + hstepB, voffB); PG8_STAGE(PG8_SA(0, 0), a2, voffA);
.LBB0_2213:
	ds_read_b128 v[152:155], v149
	ds_read_b128 v[156:159], v149 offset:1024
	ds_read_b128 v[160:163], v149 offset:2048
	ds_read_b128 v[164:167], v149 offset:3072
	ds_read_b128 v[168:171], v150
	ds_read_b128 v[172:175], v150 offset:1024
	ds_read_b128 v[176:179], v150 offset:2048
	ds_read_b128 v[180:183], v150 offset:3072
	s_add_u32 s48, s42, 0xfff80080
	s_addc_u32 s49, s43, -1
	s_cmp_eq_u32 s41, 28
	s_cselect_b32 s51, s19, s49
	s_cselect_b32 s50, s18, s48
	s_cselect_b32 s49, s21, s25
	s_cselect_b32 s48, s20, s23
	v_lshl_add_u64 v[146:147], s[42:43], 0, v[138:139]
	s_add_i32 m0, s30, 0xc000
	ds_read_b128 v[184:187], v151
	ds_read_b128 v[188:191], v151 offset:1024
	ds_read_b128 v[192:195], v151 offset:2048
	ds_read_b128 v[196:199], v151 offset:3072
	ds_read_b128 v[200:203], v151 offset:4096
	ds_read_b128 v[204:207], v151 offset:5120
	ds_read_b128 v[208:211], v151 offset:6144
	ds_read_b128 v[212:215], v151 offset:7168
	global_load_lds_dwordx4 v[146:147], off
	s_add_i32 m0, s30, 0xe000
	v_lshl_add_u64 v[146:147], s[42:43], 0, v[140:141]
	global_load_lds_dwordx4 v[146:147], off
	s_waitcnt vmcnt(8) lgkmcnt(0)
	s_barrier
	v_mfma_f32_16x16x32_bf16 v[124:127], v[152:155], v[184:187], v[124:127]
	v_mfma_f32_16x16x32_bf16 v[120:123], v[160:163], v[184:187], v[120:123]
	v_mfma_f32_16x16x32_bf16 v[108:111], v[152:155], v[192:195], v[108:111]
	v_mfma_f32_16x16x32_bf16 v[104:107], v[160:163], v[192:195], v[104:107]
	v_mfma_f32_16x16x32_bf16 v[92:95], v[152:155], v[200:203], v[92:95]
	v_mfma_f32_16x16x32_bf16 v[88:91], v[160:163], v[200:203], v[88:91]
	v_mfma_f32_16x16x32_bf16 v[76:79], v[152:155], v[208:211], v[76:79]
	v_mfma_f32_16x16x32_bf16 v[72:75], v[160:163], v[208:211], v[72:75]
	v_mfma_f32_16x16x32_bf16 v[124:127], v[156:159], v[188:191], v[124:127]
	v_mfma_f32_16x16x32_bf16 v[120:123], v[164:167], v[188:191], v[120:123]
	v_mfma_f32_16x16x32_bf16 v[108:111], v[156:159], v[196:199], v[108:111]
	v_mfma_f32_16x16x32_bf16 v[104:107], v[164:167], v[196:199], v[104:107]
	v_mfma_f32_16x16x32_bf16 v[92:95], v[156:159], v[204:207], v[92:95]
	v_mfma_f32_16x16x32_bf16 v[88:91], v[164:167], v[204:207], v[88:91]
	v_mfma_f32_16x16x32_bf16 v[76:79], v[156:159], v[212:215], v[76:79]
	v_mfma_f32_16x16x32_bf16 v[72:75], v[164:167], v[212:215], v[72:75]
	v_mfma_f32_16x16x32_bf16 v[116:119], v[168:171], v[184:187], v[116:119]
	v_mfma_f32_16x16x32_bf16 v[112:115], v[176:179], v[184:187], v[112:115]
	v_mfma_f32_16x16x32_bf16 v[100:103], v[168:171], v[192:195], v[100:103]
	v_mfma_f32_16x16x32_bf16 v[96:99], v[176:179], v[192:195], v[96:99]
	v_mfma_f32_16x16x32_bf16 v[84:87], v[168:171], v[200:203], v[84:87]
	v_mfma_f32_16x16x32_bf16 v[80:83], v[176:179], v[200:203], v[80:83]
	v_mfma_f32_16x16x32_bf16 v[68:71], v[168:171], v[208:211], v[68:71]
	v_mfma_f32_16x16x32_bf16 v[64:67], v[176:179], v[208:211], v[64:67]
	v_mfma_f32_16x16x32_bf16 v[116:119], v[172:175], v[188:191], v[116:119]
	v_mfma_f32_16x16x32_bf16 v[112:115], v[180:183], v[188:191], v[112:115]
	v_mfma_f32_16x16x32_bf16 v[100:103], v[172:175], v[196:199], v[100:103]
	v_mfma_f32_16x16x32_bf16 v[96:99], v[180:183], v[196:199], v[96:99]
	v_mfma_f32_16x16x32_bf16 v[84:87], v[172:175], v[204:207], v[84:87]
	v_mfma_f32_16x16x32_bf16 v[80:83], v[180:183], v[204:207], v[80:83]
	v_mfma_f32_16x16x32_bf16 v[68:71], v[172:175], v[212:215], v[68:71]
	v_mfma_f32_16x16x32_bf16 v[64:67], v[180:183], v[212:215], v[64:67]
	s_barrier
	s_add_i32 s67, s62, s28
	v_lshl_add_u64 v[146:147], s[48:49], 0, v[132:133]
	s_mov_b32 m0, s67
	ds_read_b128 v[184:187], v151 offset:16384
	ds_read_b128 v[188:191], v151 offset:17408
	ds_read_b128 v[192:195], v151 offset:18432
	ds_read_b128 v[196:199], v151 offset:19456
	ds_read_b128 v[200:203], v151 offset:20480
	ds_read_b128 v[204:207], v151 offset:21504
	ds_read_b128 v[208:211], v151 offset:22528
	ds_read_b128 v[212:215], v151 offset:23552
	global_load_lds_dwordx4 v[146:147], off
	s_add_i32 m0, s67, 0x2000
	s_add_u32 s68, s48, 0x80000
	v_lshl_add_u64 v[216:217], s[48:49], 0, v[128:129]
	s_addc_u32 s69, s49, 0
	s_add_i32 s67, s63, s28
	global_load_lds_dwordx4 v[216:217], off
	v_lshl_add_u64 v[218:219], s[68:69], 0, v[132:133]
	s_mov_b32 m0, s67
	v_lshl_add_u64 v[220:221], s[50:51], 0, v[130:131]
	global_load_lds_dwordx4 v[218:219], off
	s_add_i32 m0, s67, 0x2000
	v_lshl_add_u64 v[218:219], s[68:69], 0, v[128:129]
	global_load_lds_dwordx4 v[218:219], off
	s_mov_b32 m0, s30
	v_lshl_add_u64 v[218:219], s[50:51], 0, v[134:135]
	global_load_lds_dwordx4 v[218:219], off
	s_mov_b32 m0, s31
	s_nop 0
	global_load_lds_dwordx4 v[220:221], off
	s_waitcnt vmcnt(8) lgkmcnt(0)
	s_barrier
; #define PG8_STAGE(bufoff, gbase, voff) do { _Pragma("unroll") for (int _i = 0; _i < 2; ++_i) \
;         __builtin_amdgcn_global_load_lds((const unsigned*)((const char*)(gbase) + (voff)[_i]), (LAS unsigned*)(lds + (bufoff) + ldsw + _i * 8192), 16, 0, 0); } while (0)
; #define PG8_LDA(dst, b, h) do { _Pragma("unroll") for (int m = 0; m < 4; ++m) _Pragma("unroll") for (int k = 0; k < 2; ++k) dst[m][k] = *(const LAS bf16x8*)(lds + PG8_SA(b, h) + aoff + m * 2048 + k * 1024); } while (0)
; #define PG8_LDB(dst, b, h) do { _Pragma("unroll") for (int n = 0; n < 2; ++n) _Pragma("unroll") for (int k = 0; k < 2; ++k) dst[n][k] = *(const LAS bf16x8*)(lds + PG8_SB(b, h) + boff + n * 2048 + k * 1024); } while (0)
; #define PG8_MMA(ai, bj, At, Bt) do { __builtin_amdgcn_s_setprio(1); _Pragma("unroll") for (int m = 0; m < 4; ++m) _Pragma("unroll") for (int n = 0; n < 2; ++n) _Pragma("unroll") for (int k = 0; k < 2; ++k) \
;         acc[ai][bj][m][n] = __builtin_amdgcn_mfma_f32_16x16x32_bf16(Bt[n][k], At[m][k], acc[ai][bj][m][n], 0, 0, 0); __builtin_amdgcn_s_setprio(0); } while (0)
; #define PG8_WAIT_V(n) asm volatile("s_waitcnt vmcnt(" #n ")" ::: "memory")
; #define PG8_WAIT_L(n) asm volatile("s_waitcnt lgkmcnt(" #n ")" ::: "memory")
; #define PG8_BAR __builtin_amdgcn_s_barrier()
; #define PG8_SCHED __builtin_amdgcn_sched_barrier(0)
; template <class Desc, class Epi>
; DI void gemm_phase(LAS unsigned char* lds, const Desc& D, const Epi& E, int wv) {
;     ...
;             PG8_WAIT_V(8); PG8_WAIT_L(0); PG8_BAR; PG8_MMA(1, 0, At, B0); PG8_MMA(1, 1, At, B1); PG8_BAR; PG8_SCHED;
;             PG8_LDB(B0, 1, 0); PG8_LDB(B1, 1, 1); PG8_SCHED; PG8_LDA(At, 1, 0); PG8_STAGE(PG8_SA(0, 1), a2 + hstepA, voffA);
;             PG8_WAIT_V(8); PG8_WAIT_L(0); PG8_BAR; PG8_MMA(0, 0, At, B0); PG8_MMA(0, 1, At, B1); PG8_BAR; PG8_SCHED;
;             PG8_LDA(At, 1, 1); PG8_STAGE(PG8_SB(1, 0), b3, voffB); PG8_STAGE(PG8_SB(1, 1), b3 + hstepB, voffB); PG8_STAGE(PG8_SA(1, 0), a3, voffA);
	v_mfma_f32_16x16x32_bf16 v[60:63], v[152:155], v[184:187], v[60:63]
	v_mfma_f32_16x16x32_bf16 v[56:59], v[160:163], v[184:187], v[56:59]
	v_mfma_f32_16x16x32_bf16 v[44:47], v[152:155], v[192:195], v[44:47]
	v_mfma_f32_16x16x32_bf16 v[40:43], v[160:163], v[192:195], v[40:43]
	v_mfma_f32_16x16x32_bf16 v[28:31], v[152:155], v[200:203], v[28:31]
	v_mfma_f32_16x16x32_bf16 v[24:27], v[160:163], v[200:203], v[24:27]
	v_mfma_f32_16x16x32_bf16 v[12:15], v[152:155], v[208:211], v[12:15]
	v_mfma_f32_16x16x32_bf16 v[8:11], v[160:163], v[208:211], v[8:11]
	v_mfma_f32_16x16x32_bf16 v[60:63], v[156:159], v[188:191], v[60:63]
	v_mfma_f32_16x16x32_bf16 v[56:59], v[164:167], v[188:191], v[56:59]
	v_mfma_f32_16x16x32_bf16 v[44:47], v[156:159], v[196:199], v[44:47]
	v_mfma_f32_16x16x32_bf16 v[40:43], v[164:167], v[196:199], v[40:43]
	v_mfma_f32_16x16x32_bf16 v[28:31], v[156:159], v[204:207], v[28:31]
	v_mfma_f32_16x16x32_bf16 v[24:27], v[164:167], v[204:207], v[24:27]
	v_mfma_f32_16x16x32_bf16 v[12:15], v[156:159], v[212:215], v[12:15]
	v_mfma_f32_16x16x32_bf16 v[8:11], v[164:167], v[212:215], v[8:11]
	v_mfma_f32_16x16x32_bf16 v[52:55], v[168:171], v[184:187], v[52:55]
	v_mfma_f32_16x16x32_bf16 v[48:51], v[176:179], v[184:187], v[48:51]
	v_mfma_f32_16x16x32_bf16 v[36:39], v[168:171], v[192:195], v[36:39]
	v_mfma_f32_16x16x32_bf16 v[32:35], v[176:179], v[192:195], v[32:35]
	v_mfma_f32_16x16x32_bf16 v[20:23], v[168:171], v[200:203], v[20:23]
	v_mfma_f32_16x16x32_bf16 v[16:19], v[176:179], v[200:203], v[16:19]
	v_mfma_f32_16x16x32_bf16 v[4:7], v[168:171], v[208:211], v[4:7]
	v_mfma_f32_16x16x32_bf16 v[0:3], v[176:179], v[208:211], v[0:3]
	v_mfma_f32_16x16x32_bf16 v[52:55], v[172:175], v[188:191], v[52:55]
	v_mfma_f32_16x16x32_bf16 v[48:51], v[180:183], v[188:191], v[48:51]
	v_mfma_f32_16x16x32_bf16 v[36:39], v[172:175], v[196:199], v[36:39]
	v_mfma_f32_16x16x32_bf16 v[32:35], v[180:183], v[196:199], v[32:35]
	v_mfma_f32_16x16x32_bf16 v[20:23], v[172:175], v[204:207], v[20:23]
	v_mfma_f32_16x16x32_bf16 v[16:19], v[180:183], v[204:207], v[16:19]
	v_mfma_f32_16x16x32_bf16 v[4:7], v[172:175], v[212:215], v[4:7]
	v_mfma_f32_16x16x32_bf16 v[0:3], v[180:183], v[212:215], v[0:3]
	s_barrier
	s_add_i32 s67, 0, 0x18000
	v_add_u32_e32 v136, s67, v148
	s_add_i32 s68, 0, 0x1c000
	ds_read_b128 v[152:155], v136
	ds_read_b128 v[156:159], v136 offset:1024
	ds_read_b128 v[160:163], v136 offset:2048
	ds_read_b128 v[164:167], v136 offset:3072
	v_add_u32_e32 v136, s68, v148
	ds_read_b128 v[168:171], v136
	ds_read_b128 v[172:175], v136 offset:1024
	ds_read_b128 v[176:179], v136 offset:2048
	ds_read_b128 v[180:183], v136 offset:3072
	s_add_u32 s50, s50, 0x80000
	s_addc_u32 s51, s51, 0
	s_mov_b32 m0, s34
	v_lshl_add_u64 v[222:223], s[50:51], 0, v[134:135]
	ds_read_b128 v[184:187], v151 offset:32768
	ds_read_b128 v[188:191], v151 offset:33792
	ds_read_b128 v[192:195], v151 offset:34816
	ds_read_b128 v[196:199], v151 offset:35840
	ds_read_b128 v[200:203], v151 offset:36864
	ds_read_b128 v[204:207], v151 offset:37888
	ds_read_b128 v[208:211], v151 offset:38912
	ds_read_b128 v[212:215], v151 offset:39936
	global_load_lds_dwordx4 v[222:223], off
	s_mov_b32 m0, s35
	v_lshl_add_u64 v[222:223], s[50:51], 0, v[130:131]
	global_load_lds_dwordx4 v[222:223], off
	s_waitcnt vmcnt(8) lgkmcnt(0)
	s_barrier
	v_mfma_f32_16x16x32_bf16 v[124:127], v[152:155], v[184:187], v[124:127]
	v_mfma_f32_16x16x32_bf16 v[120:123], v[160:163], v[184:187], v[120:123]
	v_mfma_f32_16x16x32_bf16 v[108:111], v[152:155], v[192:195], v[108:111]
	v_mfma_f32_16x16x32_bf16 v[104:107], v[160:163], v[192:195], v[104:107]
	v_mfma_f32_16x16x32_bf16 v[92:95], v[152:155], v[200:203], v[92:95]
	v_mfma_f32_16x16x32_bf16 v[88:91], v[160:163], v[200:203], v[88:91]
	v_mfma_f32_16x16x32_bf16 v[76:79], v[152:155], v[208:211], v[76:79]
	v_mfma_f32_16x16x32_bf16 v[72:75], v[160:163], v[208:211], v[72:75]
	v_mfma_f32_16x16x32_bf16 v[124:127], v[156:159], v[188:191], v[124:127]
	v_mfma_f32_16x16x32_bf16 v[120:123], v[164:167], v[188:191], v[120:123]
	v_mfma_f32_16x16x32_bf16 v[108:111], v[156:159], v[196:199], v[108:111]
	v_mfma_f32_16x16x32_bf16 v[104:107], v[164:167], v[196:199], v[104:107]
	v_mfma_f32_16x16x32_bf16 v[92:95], v[156:159], v[204:207], v[92:95]
	v_mfma_f32_16x16x32_bf16 v[88:91], v[164:167], v[204:207], v[88:91]
	v_mfma_f32_16x16x32_bf16 v[76:79], v[156:159], v[212:215], v[76:79]
	v_mfma_f32_16x16x32_bf16 v[72:75], v[164:167], v[212:215], v[72:75]
	v_mfma_f32_16x16x32_bf16 v[116:119], v[168:171], v[184:187], v[116:119]
	v_mfma_f32_16x16x32_bf16 v[112:115], v[176:179], v[184:187], v[112:115]
	v_mfma_f32_16x16x32_bf16 v[100:103], v[168:171], v[192:195], v[100:103]
	v_mfma_f32_16x16x32_bf16 v[96:99], v[176:179], v[192:195], v[96:99]
	v_mfma_f32_16x16x32_bf16 v[84:87], v[168:171], v[200:203], v[84:87]
	v_mfma_f32_16x16x32_bf16 v[80:83], v[176:179], v[200:203], v[80:83]
	v_mfma_f32_16x16x32_bf16 v[68:71], v[168:171], v[208:211], v[68:71]
	v_mfma_f32_16x16x32_bf16 v[64:67], v[176:179], v[208:211], v[64:67]
	v_mfma_f32_16x16x32_bf16 v[116:119], v[172:175], v[188:191], v[116:119]
	v_mfma_f32_16x16x32_bf16 v[112:115], v[180:183], v[188:191], v[112:115]
	v_mfma_f32_16x16x32_bf16 v[100:103], v[172:175], v[196:199], v[100:103]
	v_mfma_f32_16x16x32_bf16 v[96:99], v[180:183], v[196:199], v[96:99]
	v_mfma_f32_16x16x32_bf16 v[84:87], v[172:175], v[204:207], v[84:87]
	v_mfma_f32_16x16x32_bf16 v[80:83], v[180:183], v[204:207], v[80:83]
	v_mfma_f32_16x16x32_bf16 v[68:71], v[172:175], v[212:215], v[68:71]
	v_mfma_f32_16x16x32_bf16 v[64:67], v[180:183], v[212:215], v[64:67]
	s_barrier
; #define PG8_STAGE(bufoff, gbase, voff) do { _Pragma("unroll") for (int _i = 0; _i < 2; ++_i) \
;         __builtin_amdgcn_global_load_lds((const unsigned*)((const char*)(gbase) + (voff)[_i]), (LAS unsigned*)(lds + (bufoff) + ldsw + _i * 8192), 16, 0, 0); } while (0)
; #define PG8_LDA(dst, b, h) do { _Pragma("unroll") for (int m = 0; m < 4; ++m) _Pragma("unroll") for (int k = 0; k < 2; ++k) dst[m][k] = *(const LAS bf16x8*)(lds + PG8_SA(b, h) + aoff + m * 2048 + k * 1024); } while (0)
; #define PG8_MMA(ai, bj, At, Bt) do { __builtin_amdgcn_s_setprio(1); _Pragma("unroll") for (int m = 0; m < 4; ++m) _Pragma("unroll") for (int n = 0; n < 2; ++n) _Pragma("unroll") for (int k = 0; k < 2; ++k) \
;         acc[ai][bj][m][n] = __builtin_amdgcn_mfma_f32_16x16x32_bf16(Bt[n][k], At[m][k], acc[ai][bj][m][n], 0, 0, 0); __builtin_amdgcn_s_setprio(0); } while (0)
; #define PG8_WAIT_V(n) asm volatile("s_waitcnt vmcnt(" #n ")" ::: "memory")
; #define PG8_WAIT_L(n) asm volatile("s_waitcnt lgkmcnt(" #n ")" ::: "memory")
; #define PG8_BAR __builtin_amdgcn_s_barrier()
; #define PG8_SCHED __builtin_amdgcn_sched_barrier(0)
; template <class Desc, class Epi>
; DI void gemm_phase(LAS unsigned char* lds, const Desc& D, const Epi& E, int wv) {
;     ...
;             PG8_LDA(At, 1, 1); PG8_STAGE(PG8_SB(1, 0), b3, voffB); PG8_STAGE(PG8_SB(1, 1), b3 + hstepB, voffB); PG8_STAGE(PG8_SA(1, 0), a3, voffA);
;             PG8_WAIT_V(8); PG8_WAIT_L(0); PG8_BAR; PG8_MMA(1, 0, At, B0); PG8_MMA(1, 1, At, B1); PG8_BAR; PG8_SCHED;
;         }
;         if (wr == 0) PG8_BAR;
	s_add_i32 s50, s67, s28
	v_lshl_add_u64 v[146:147], v[146:147], 0, s[8:9]
	s_mov_b32 m0, s50
	ds_read_b128 v[184:187], v151 offset:49152
	ds_read_b128 v[188:191], v151 offset:50176
	ds_read_b128 v[192:195], v151 offset:51200
	ds_read_b128 v[196:199], v151 offset:52224
	ds_read_b128 v[200:203], v151 offset:53248
	ds_read_b128 v[204:207], v151 offset:54272
	ds_read_b128 v[208:211], v151 offset:55296
	ds_read_b128 v[212:215], v151 offset:56320
	global_load_lds_dwordx4 v[146:147], off
	s_add_i32 m0, s50, 0x2000
	s_add_u32 s48, s48, 0x80080
	v_lshl_add_u64 v[146:147], v[216:217], 0, s[8:9]
	s_addc_u32 s49, s49, 0
	s_add_i32 s50, s68, s28
	global_load_lds_dwordx4 v[146:147], off
	s_mov_b32 m0, s50
	v_lshl_add_u64 v[146:147], s[48:49], 0, v[132:133]
	global_load_lds_dwordx4 v[146:147], off
	s_add_i32 m0, s50, 0x2000
	v_lshl_add_u64 v[146:147], s[48:49], 0, v[128:129]
	global_load_lds_dwordx4 v[146:147], off
	s_mov_b32 m0, s53
	v_lshl_add_u64 v[146:147], v[218:219], 0, s[8:9]
	global_load_lds_dwordx4 v[146:147], off
	s_mov_b32 m0, s60
	v_lshl_add_u64 v[146:147], v[220:221], 0, s[8:9]
	global_load_lds_dwordx4 v[146:147], off
	s_waitcnt vmcnt(8) lgkmcnt(0)
	s_barrier
	v_mfma_f32_16x16x32_bf16 v[60:63], v[152:155], v[184:187], v[60:63]
	v_mfma_f32_16x16x32_bf16 v[56:59], v[160:163], v[184:187], v[56:59]
	v_mfma_f32_16x16x32_bf16 v[44:47], v[152:155], v[192:195], v[44:47]
	v_mfma_f32_16x16x32_bf16 v[40:43], v[160:163], v[192:195], v[40:43]
	v_mfma_f32_16x16x32_bf16 v[28:31], v[152:155], v[200:203], v[28:31]
	v_mfma_f32_16x16x32_bf16 v[24:27], v[160:163], v[200:203], v[24:27]
	v_mfma_f32_16x16x32_bf16 v[12:15], v[152:155], v[208:211], v[12:15]
	v_mfma_f32_16x16x32_bf16 v[8:11], v[160:163], v[208:211], v[8:11]
	v_mfma_f32_16x16x32_bf16 v[60:63], v[156:159], v[188:191], v[60:63]
	v_mfma_f32_16x16x32_bf16 v[56:59], v[164:167], v[188:191], v[56:59]
	v_mfma_f32_16x16x32_bf16 v[44:47], v[156:159], v[196:199], v[44:47]
	v_mfma_f32_16x16x32_bf16 v[40:43], v[164:167], v[196:199], v[40:43]
	v_mfma_f32_16x16x32_bf16 v[28:31], v[156:159], v[204:207], v[28:31]
	v_mfma_f32_16x16x32_bf16 v[24:27], v[164:167], v[204:207], v[24:27]
	v_mfma_f32_16x16x32_bf16 v[12:15], v[156:159], v[212:215], v[12:15]
	v_mfma_f32_16x16x32_bf16 v[8:11], v[164:167], v[212:215], v[8:11]
	v_mfma_f32_16x16x32_bf16 v[52:55], v[168:171], v[184:187], v[52:55]
	v_mfma_f32_16x16x32_bf16 v[48:51], v[176:179], v[184:187], v[48:51]
	v_mfma_f32_16x16x32_bf16 v[36:39], v[168:171], v[192:195], v[36:39]
	v_mfma_f32_16x16x32_bf16 v[32:35], v[176:179], v[192:195], v[32:35]
	v_mfma_f32_16x16x32_bf16 v[20:23], v[168:171], v[200:203], v[20:23]
	v_mfma_f32_16x16x32_bf16 v[16:19], v[176:179], v[200:203], v[16:19]
	v_mfma_f32_16x16x32_bf16 v[4:7], v[168:171], v[208:211], v[4:7]
	v_mfma_f32_16x16x32_bf16 v[0:3], v[176:179], v[208:211], v[0:3]
	v_mfma_f32_16x16x32_bf16 v[52:55], v[172:175], v[188:191], v[52:55]
	v_mfma_f32_16x16x32_bf16 v[48:51], v[180:183], v[188:191], v[48:51]
	v_mfma_f32_16x16x32_bf16 v[36:39], v[172:175], v[196:199], v[36:39]
	v_mfma_f32_16x16x32_bf16 v[32:35], v[180:183], v[196:199], v[32:35]
	v_mfma_f32_16x16x32_bf16 v[20:23], v[172:175], v[204:207], v[20:23]
	v_mfma_f32_16x16x32_bf16 v[16:19], v[180:183], v[204:207], v[16:19]
	v_mfma_f32_16x16x32_bf16 v[4:7], v[172:175], v[212:215], v[4:7]
	v_mfma_f32_16x16x32_bf16 v[0:3], v[180:183], v[212:215], v[0:3]
	s_barrier
	s_add_i32 s41, s41, 2
	s_add_u32 s42, s42, 0x100
	s_addc_u32 s43, s43, 0
	s_add_u32 s23, s23, 0x100
	s_addc_u32 s25, s25, 0
	s_cmp_gt_u32 s41, 29
	s_cbranch_scc0 .LBB0_2213
	s_and_b64 vcc, exec, s[12:13]
	s_cbranch_vccz .LBB0_2216
	s_barrier

; #define PG8_STAGE(bufoff, gbase, voff) do { _Pragma("unroll") for (int _i = 0; _i < 2; ++_i) \
;         __builtin_amdgcn_global_load_lds((const unsigned*)((const char*)(gbase) + (voff)[_i]), (LAS unsigned*)(lds + (bufoff) + ldsw + _i * 8192), 16, 0, 0); } while (0)
; #define PG8_LDA(dst, b, h) do { _Pragma("unroll") for (int m = 0; m < 4; ++m) _Pragma("unroll") for (int k = 0; k < 2; ++k) dst[m][k] = *(const LAS bf16x8*)(lds + PG8_SA(b, h) + aoff + m * 2048 + k * 1024); } while (0)
; #define PG8_LDB(dst, b, h) do { _Pragma("unroll") for (int n = 0; n < 2; ++n) _Pragma("unroll") for (int k = 0; k < 2; ++k) dst[n][k] = *(const LAS bf16x8*)(lds + PG8_SB(b, h) + boff + n * 2048 + k * 1024); } while (0)
; #define PG8_MMA(ai, bj, At, Bt) do { __builtin_amdgcn_s_setprio(1); _Pragma("unroll") for (int m = 0; m < 4; ++m) _Pragma("unroll") for (int n = 0; n < 2; ++n) _Pragma("unroll") for (int k = 0; k < 2; ++k) \
;         acc[ai][bj][m][n] = __builtin_amdgcn_mfma_f32_16x16x32_bf16(Bt[n][k], At[m][k], acc[ai][bj][m][n], 0, 0, 0); __builtin_amdgcn_s_setprio(0); } while (0)
; #define PG8_WAIT_V(n) asm volatile("s_waitcnt vmcnt(" #n ")" ::: "memory")
; #define PG8_WAIT_L(n) asm volatile("s_waitcnt lgkmcnt(" #n ")" ::: "memory")
; #define PG8_BAR __builtin_amdgcn_s_barrier()
; #define PG8_SCHED __builtin_amdgcn_sched_barrier(0)
; template <class Desc, class Epi>
; DI void gemm_phase(LAS unsigned char* lds, const Desc& D, const Epi& E, int wv) {
;     ...
;         for (int t = 0; t < nt; t += 2) {
;             const bool last = (t == nt - 2);
;             const char* a1 = cA + (size_t)(t + 1) * kstep;
;             const char* a2 = last ? nA : cA + (size_t)(t + 2) * kstep; const char* b2 = last ? nB : cB + (size_t)(t + 2) * kstep;
;             const char* a3 = a2 + kstep; const char* b3 = b2 + kstep;
;             PG8_LDB(B0, 0, 0); PG8_LDB(B1, 0, 1); PG8_SCHED; PG8_LDA(At, 0, 0); PG8_STAGE(PG8_SA(1, 1), a1 + hstepA, voffA);
;             PG8_WAIT_V(8); PG8_WAIT_L(0); PG8_BAR; PG8_MMA(0, 0, At, B0); PG8_MMA(0, 1, At, B1); PG8_BAR; PG8_SCHED;
;             PG8_LDA(At, 0, 1); PG8_STAGE(PG8_SB(0, 0), b2, voffB); PG8_STAGE(PG8_SB(0, 1), b2 + hstepB, voffB); PG8_STAGE(PG8_SA(0, 0), a2, voffA);
;             PG8_WAIT_V(8); PG8_WAIT_L(0); PG8_BAR; PG8_MMA(1, 0, At, B0); PG8_MMA(1, 1, At, B1); PG8_BAR; PG8_SCHED;
.LBB0_2239:
	ds_read_b128 v[142:145], v151
	ds_read_b128 v[146:149], v151 offset:1024
	ds_read_b128 v[158:161], v151 offset:2048
	ds_read_b128 v[162:165], v151 offset:3072
	ds_read_b128 v[166:169], v152
	ds_read_b128 v[170:173], v152 offset:1024
	ds_read_b128 v[174:177], v152 offset:2048
	ds_read_b128 v[178:181], v152 offset:3072
	s_add_u32 s8, s6, 0xfffe0080
	s_addc_u32 s9, s7, -1
	s_cmp_eq_u32 s50, 4
	s_cselect_b32 s43, s25, s9
	s_cselect_b32 s42, s24, s8
	s_cselect_b32 s9, s41, s49
	s_cselect_b32 s8, s40, s48
	v_lshl_add_u64 v[214:215], s[6:7], 0, v[138:139]
	s_add_i32 m0, s3, 0xc000
	ds_read_b128 v[182:185], v153
	ds_read_b128 v[186:189], v153 offset:1024
	ds_read_b128 v[190:193], v153 offset:2048
	ds_read_b128 v[194:197], v153 offset:3072
	ds_read_b128 v[198:201], v153 offset:4096
	ds_read_b128 v[202:205], v153 offset:5120
	ds_read_b128 v[206:209], v153 offset:6144
	ds_read_b128 v[210:213], v153 offset:7168
	global_load_lds_dwordx4 v[214:215], off
	s_add_i32 m0, s3, 0xe000
	v_lshl_add_u64 v[214:215], s[6:7], 0, v[140:141]
	global_load_lds_dwordx4 v[214:215], off
	s_waitcnt vmcnt(8) lgkmcnt(0)
	s_barrier
	v_mfma_f32_16x16x32_bf16 v[124:127], v[142:145], v[182:185], v[124:127]
	v_mfma_f32_16x16x32_bf16 v[120:123], v[158:161], v[182:185], v[120:123]
	v_mfma_f32_16x16x32_bf16 v[108:111], v[142:145], v[190:193], v[108:111]
	v_mfma_f32_16x16x32_bf16 v[104:107], v[158:161], v[190:193], v[104:107]
	v_mfma_f32_16x16x32_bf16 v[92:95], v[142:145], v[198:201], v[92:95]
	v_mfma_f32_16x16x32_bf16 v[88:91], v[158:161], v[198:201], v[88:91]
	v_mfma_f32_16x16x32_bf16 v[76:79], v[142:145], v[206:209], v[76:79]
	v_mfma_f32_16x16x32_bf16 v[72:75], v[158:161], v[206:209], v[72:75]
	v_mfma_f32_16x16x32_bf16 v[124:127], v[146:149], v[186:189], v[124:127]
	v_mfma_f32_16x16x32_bf16 v[120:123], v[162:165], v[186:189], v[120:123]
	v_mfma_f32_16x16x32_bf16 v[108:111], v[146:149], v[194:197], v[108:111]
	v_mfma_f32_16x16x32_bf16 v[104:107], v[162:165], v[194:197], v[104:107]
	v_mfma_f32_16x16x32_bf16 v[92:95], v[146:149], v[202:205], v[92:95]
	v_mfma_f32_16x16x32_bf16 v[88:91], v[162:165], v[202:205], v[88:91]
	v_mfma_f32_16x16x32_bf16 v[76:79], v[146:149], v[210:213], v[76:79]
	v_mfma_f32_16x16x32_bf16 v[72:75], v[162:165], v[210:213], v[72:75]
	v_mfma_f32_16x16x32_bf16 v[116:119], v[166:169], v[182:185], v[116:119]
	v_mfma_f32_16x16x32_bf16 v[112:115], v[174:177], v[182:185], v[112:115]
	v_mfma_f32_16x16x32_bf16 v[100:103], v[166:169], v[190:193], v[100:103]
	v_mfma_f32_16x16x32_bf16 v[96:99], v[174:177], v[190:193], v[96:99]
	v_mfma_f32_16x16x32_bf16 v[84:87], v[166:169], v[198:201], v[84:87]
	v_mfma_f32_16x16x32_bf16 v[80:83], v[174:177], v[198:201], v[80:83]
	v_mfma_f32_16x16x32_bf16 v[68:71], v[166:169], v[206:209], v[68:71]
	v_mfma_f32_16x16x32_bf16 v[64:67], v[174:177], v[206:209], v[64:67]
	v_mfma_f32_16x16x32_bf16 v[116:119], v[170:173], v[186:189], v[116:119]
	v_mfma_f32_16x16x32_bf16 v[112:115], v[178:181], v[186:189], v[112:115]
	v_mfma_f32_16x16x32_bf16 v[100:103], v[170:173], v[194:197], v[100:103]
	v_mfma_f32_16x16x32_bf16 v[96:99], v[178:181], v[194:197], v[96:99]
	v_mfma_f32_16x16x32_bf16 v[84:87], v[170:173], v[202:205], v[84:87]
	v_mfma_f32_16x16x32_bf16 v[80:83], v[178:181], v[202:205], v[80:83]
	v_mfma_f32_16x16x32_bf16 v[68:71], v[170:173], v[210:213], v[68:71]
	v_mfma_f32_16x16x32_bf16 v[64:67], v[178:181], v[210:213], v[64:67]
	s_barrier
	s_add_i32 s51, s47, s2
	v_lshl_add_u64 v[214:215], s[8:9], 0, v[130:131]
	s_mov_b32 m0, s51
	ds_read_b128 v[182:185], v153 offset:16384
	ds_read_b128 v[186:189], v153 offset:17408
	ds_read_b128 v[190:193], v153 offset:18432
	ds_read_b128 v[194:197], v153 offset:19456
	ds_read_b128 v[198:201], v153 offset:20480
	ds_read_b128 v[202:205], v153 offset:21504
	ds_read_b128 v[206:209], v153 offset:22528
	ds_read_b128 v[210:213], v153 offset:23552
	global_load_lds_dwordx4 v[214:215], off
	s_add_i32 m0, s51, 0x2000
	s_add_u32 s64, s8, 0x80000
	v_lshl_add_u64 v[216:217], s[8:9], 0, v[134:135]
	s_addc_u32 s65, s9, 0
	s_add_i32 s51, s52, s2
	global_load_lds_dwordx4 v[216:217], off
	v_lshl_add_u64 v[218:219], s[64:65], 0, v[130:131]
	s_mov_b32 m0, s51
	v_lshl_add_u64 v[220:221], s[42:43], 0, v[132:133]
	global_load_lds_dwordx4 v[218:219], off
	s_add_i32 m0, s51, 0x2000
	v_lshl_add_u64 v[218:219], s[64:65], 0, v[134:135]
	global_load_lds_dwordx4 v[218:219], off
	s_mov_b32 m0, s3
	v_lshl_add_u64 v[218:219], s[42:43], 0, v[128:129]
	global_load_lds_dwordx4 v[218:219], off
	s_mov_b32 m0, s28
	s_nop 0
	global_load_lds_dwordx4 v[220:221], off
	s_waitcnt vmcnt(8) lgkmcnt(0)
	s_barrier
; #define PG8_STAGE(bufoff, gbase, voff) do { _Pragma("unroll") for (int _i = 0; _i < 2; ++_i) \
;         __builtin_amdgcn_global_load_lds((const unsigned*)((const char*)(gbase) + (voff)[_i]), (LAS unsigned*)(lds + (bufoff) + ldsw + _i * 8192), 16, 0, 0); } while (0)
; #define PG8_LDA(dst, b, h) do { _Pragma("unroll") for (int m = 0; m < 4; ++m) _Pragma("unroll") for (int k = 0; k < 2; ++k) dst[m][k] = *(const LAS bf16x8*)(lds + PG8_SA(b, h) + aoff + m * 2048 + k * 1024); } while (0)
; #define PG8_LDB(dst, b, h) do { _Pragma("unroll") for (int n = 0; n < 2; ++n) _Pragma("unroll") for (int k = 0; k < 2; ++k) dst[n][k] = *(const LAS bf16x8*)(lds + PG8_SB(b, h) + boff + n * 2048 + k * 1024); } while (0)
; #define PG8_MMA(ai, bj, At, Bt) do { __builtin_amdgcn_s_setprio(1); _Pragma("unroll") for (int m = 0; m < 4; ++m) _Pragma("unroll") for (int n = 0; n < 2; ++n) _Pragma("unroll") for (int k = 0; k < 2; ++k) \
;         acc[ai][bj][m][n] = __builtin_amdgcn_mfma_f32_16x16x32_bf16(Bt[n][k], At[m][k], acc[ai][bj][m][n], 0, 0, 0); __builtin_amdgcn_s_setprio(0); } while (0)
; #define PG8_WAIT_V(n) asm volatile("s_waitcnt vmcnt(" #n ")" ::: "memory")
; #define PG8_WAIT_L(n) asm volatile("s_waitcnt lgkmcnt(" #n ")" ::: "memory")
; #define PG8_BAR __builtin_amdgcn_s_barrier()
; #define PG8_SCHED __builtin_amdgcn_sched_barrier(0)
; template <class Desc, class Epi>
; DI void gemm_phase(LAS unsigned char* lds, const Desc& D, const Epi& E, int wv) {
;     ...
;             PG8_WAIT_V(8); PG8_WAIT_L(0); PG8_BAR; PG8_MMA(1, 0, At, B0); PG8_MMA(1, 1, At, B1); PG8_BAR; PG8_SCHED;
;             PG8_LDB(B0, 1, 0); PG8_LDB(B1, 1, 1); PG8_SCHED; PG8_LDA(At, 1, 0); PG8_STAGE(PG8_SA(0, 1), a2 + hstepA, voffA);
;             PG8_WAIT_V(8); PG8_WAIT_L(0); PG8_BAR; PG8_MMA(0, 0, At, B0); PG8_MMA(0, 1, At, B1); PG8_BAR; PG8_SCHED;
	v_mfma_f32_16x16x32_bf16 v[60:63], v[142:145], v[182:185], v[60:63]
	v_mfma_f32_16x16x32_bf16 v[56:59], v[158:161], v[182:185], v[56:59]
	v_mfma_f32_16x16x32_bf16 v[44:47], v[142:145], v[190:193], v[44:47]
	v_mfma_f32_16x16x32_bf16 v[40:43], v[158:161], v[190:193], v[40:43]
	v_mfma_f32_16x16x32_bf16 v[28:31], v[142:145], v[198:201], v[28:31]
	v_mfma_f32_16x16x32_bf16 v[24:27], v[158:161], v[198:201], v[24:27]
	v_mfma_f32_16x16x32_bf16 v[12:15], v[142:145], v[206:209], v[12:15]
	v_mfma_f32_16x16x32_bf16 v[8:11], v[158:161], v[206:209], v[8:11]
	v_mfma_f32_16x16x32_bf16 v[60:63], v[146:149], v[186:189], v[60:63]
	v_mfma_f32_16x16x32_bf16 v[56:59], v[162:165], v[186:189], v[56:59]
	v_mfma_f32_16x16x32_bf16 v[44:47], v[146:149], v[194:197], v[44:47]
	v_mfma_f32_16x16x32_bf16 v[40:43], v[162:165], v[194:197], v[40:43]
	v_mfma_f32_16x16x32_bf16 v[28:31], v[146:149], v[202:205], v[28:31]
	v_mfma_f32_16x16x32_bf16 v[24:27], v[162:165], v[202:205], v[24:27]
	v_mfma_f32_16x16x32_bf16 v[12:15], v[146:149], v[210:213], v[12:15]
	v_mfma_f32_16x16x32_bf16 v[8:11], v[162:165], v[210:213], v[8:11]
	v_mfma_f32_16x16x32_bf16 v[52:55], v[166:169], v[182:185], v[52:55]
	v_mfma_f32_16x16x32_bf16 v[48:51], v[174:177], v[182:185], v[48:51]
	v_mfma_f32_16x16x32_bf16 v[36:39], v[166:169], v[190:193], v[36:39]
	v_mfma_f32_16x16x32_bf16 v[32:35], v[174:177], v[190:193], v[32:35]
	v_mfma_f32_16x16x32_bf16 v[20:23], v[166:169], v[198:201], v[20:23]
	v_mfma_f32_16x16x32_bf16 v[16:19], v[174:177], v[198:201], v[16:19]
	v_mfma_f32_16x16x32_bf16 v[4:7], v[166:169], v[206:209], v[4:7]
	v_mfma_f32_16x16x32_bf16 v[0:3], v[174:177], v[206:209], v[0:3]
	v_mfma_f32_16x16x32_bf16 v[52:55], v[170:173], v[186:189], v[52:55]
	v_mfma_f32_16x16x32_bf16 v[48:51], v[178:181], v[186:189], v[48:51]
	v_mfma_f32_16x16x32_bf16 v[36:39], v[170:173], v[194:197], v[36:39]
	v_mfma_f32_16x16x32_bf16 v[32:35], v[178:181], v[194:197], v[32:35]
	v_mfma_f32_16x16x32_bf16 v[20:23], v[170:173], v[202:205], v[20:23]
	v_mfma_f32_16x16x32_bf16 v[16:19], v[178:181], v[202:205], v[16:19]
	v_mfma_f32_16x16x32_bf16 v[4:7], v[170:173], v[210:213], v[4:7]
	v_mfma_f32_16x16x32_bf16 v[0:3], v[178:181], v[210:213], v[0:3]
	s_barrier
	s_add_i32 s51, 0, 0x18000
	v_add_u32_e32 v136, s51, v150
	s_add_i32 s64, 0, 0x1c000
	ds_read_b128 v[142:145], v136
	ds_read_b128 v[146:149], v136 offset:1024
	ds_read_b128 v[158:161], v136 offset:2048
	ds_read_b128 v[162:165], v136 offset:3072
	v_add_u32_e32 v136, s64, v150
	ds_read_b128 v[166:169], v136
	ds_read_b128 v[170:173], v136 offset:1024
	ds_read_b128 v[174:177], v136 offset:2048
	ds_read_b128 v[178:181], v136 offset:3072
	s_add_u32 s42, s42, 0x20000
	s_addc_u32 s43, s43, 0
	s_mov_b32 m0, s29
	v_lshl_add_u64 v[222:223], s[42:43], 0, v[128:129]
	ds_read_b128 v[182:185], v153 offset:32768
	ds_read_b128 v[186:189], v153 offset:33792
	ds_read_b128 v[190:193], v153 offset:34816
	ds_read_b128 v[194:197], v153 offset:35840
	ds_read_b128 v[198:201], v153 offset:36864
	ds_read_b128 v[202:205], v153 offset:37888
	ds_read_b128 v[206:209], v153 offset:38912
	ds_read_b128 v[210:213], v153 offset:39936
	global_load_lds_dwordx4 v[222:223], off
	s_mov_b32 m0, s30
	v_lshl_add_u64 v[222:223], s[42:43], 0, v[132:133]
	global_load_lds_dwordx4 v[222:223], off
	s_waitcnt vmcnt(8) lgkmcnt(0)
	s_barrier
	v_mfma_f32_16x16x32_bf16 v[124:127], v[142:145], v[182:185], v[124:127]
	v_mfma_f32_16x16x32_bf16 v[120:123], v[158:161], v[182:185], v[120:123]
	v_mfma_f32_16x16x32_bf16 v[108:111], v[142:145], v[190:193], v[108:111]
	v_mfma_f32_16x16x32_bf16 v[104:107], v[158:161], v[190:193], v[104:107]
	v_mfma_f32_16x16x32_bf16 v[92:95], v[142:145], v[198:201], v[92:95]
	v_mfma_f32_16x16x32_bf16 v[88:91], v[158:161], v[198:201], v[88:91]
	v_mfma_f32_16x16x32_bf16 v[76:79], v[142:145], v[206:209], v[76:79]
	v_mfma_f32_16x16x32_bf16 v[72:75], v[158:161], v[206:209], v[72:75]
	v_mfma_f32_16x16x32_bf16 v[124:127], v[146:149], v[186:189], v[124:127]
	v_mfma_f32_16x16x32_bf16 v[120:123], v[162:165], v[186:189], v[120:123]
	v_mfma_f32_16x16x32_bf16 v[108:111], v[146:149], v[194:197], v[108:111]
	v_mfma_f32_16x16x32_bf16 v[104:107], v[162:165], v[194:197], v[104:107]
	v_mfma_f32_16x16x32_bf16 v[92:95], v[146:149], v[202:205], v[92:95]
	v_mfma_f32_16x16x32_bf16 v[88:91], v[162:165], v[202:205], v[88:91]
	v_mfma_f32_16x16x32_bf16 v[76:79], v[146:149], v[210:213], v[76:79]
	v_mfma_f32_16x16x32_bf16 v[72:75], v[162:165], v[210:213], v[72:75]
	v_mfma_f32_16x16x32_bf16 v[116:119], v[166:169], v[182:185], v[116:119]
	v_mfma_f32_16x16x32_bf16 v[112:115], v[174:177], v[182:185], v[112:115]
	v_mfma_f32_16x16x32_bf16 v[100:103], v[166:169], v[190:193], v[100:103]
	v_mfma_f32_16x16x32_bf16 v[96:99], v[174:177], v[190:193], v[96:99]
	v_mfma_f32_16x16x32_bf16 v[84:87], v[166:169], v[198:201], v[84:87]
	v_mfma_f32_16x16x32_bf16 v[80:83], v[174:177], v[198:201], v[80:83]
	v_mfma_f32_16x16x32_bf16 v[68:71], v[166:169], v[206:209], v[68:71]
	v_mfma_f32_16x16x32_bf16 v[64:67], v[174:177], v[206:209], v[64:67]
	v_mfma_f32_16x16x32_bf16 v[116:119], v[170:173], v[186:189], v[116:119]
	v_mfma_f32_16x16x32_bf16 v[112:115], v[178:181], v[186:189], v[112:115]
	v_mfma_f32_16x16x32_bf16 v[100:103], v[170:173], v[194:197], v[100:103]
	v_mfma_f32_16x16x32_bf16 v[96:99], v[178:181], v[194:197], v[96:99]
	v_mfma_f32_16x16x32_bf16 v[84:87], v[170:173], v[202:205], v[84:87]
	v_mfma_f32_16x16x32_bf16 v[80:83], v[178:181], v[202:205], v[80:83]
	v_mfma_f32_16x16x32_bf16 v[68:71], v[170:173], v[210:213], v[68:71]
	v_mfma_f32_16x16x32_bf16 v[64:67], v[178:181], v[210:213], v[64:67]
	s_barrier
; #define PG8_STAGE(bufoff, gbase, voff) do { _Pragma("unroll") for (int _i = 0; _i < 2; ++_i) \
;         __builtin_amdgcn_global_load_lds((const unsigned*)((const char*)(gbase) + (voff)[_i]), (LAS unsigned*)(lds + (bufoff) + ldsw + _i * 8192), 16, 0, 0); } while (0)
; #define PG8_LDA(dst, b, h) do { _Pragma("unroll") for (int m = 0; m < 4; ++m) _Pragma("unroll") for (int k = 0; k < 2; ++k) dst[m][k] = *(const LAS bf16x8*)(lds + PG8_SA(b, h) + aoff + m * 2048 + k * 1024); } while (0)
; #define PG8_MMA(ai, bj, At, Bt) do { __builtin_amdgcn_s_setprio(1); _Pragma("unroll") for (int m = 0; m < 4; ++m) _Pragma("unroll") for (int n = 0; n < 2; ++n) _Pragma("unroll") for (int k = 0; k < 2; ++k) \
;         acc[ai][bj][m][n] = __builtin_amdgcn_mfma_f32_16x16x32_bf16(Bt[n][k], At[m][k], acc[ai][bj][m][n], 0, 0, 0); __builtin_amdgcn_s_setprio(0); } while (0)
; #define PG8_WAIT_V(n) asm volatile("s_waitcnt vmcnt(" #n ")" ::: "memory")
; #define PG8_WAIT_L(n) asm volatile("s_waitcnt lgkmcnt(" #n ")" ::: "memory")
; #define PG8_BAR __builtin_amdgcn_s_barrier()
; #define PG8_SCHED __builtin_amdgcn_sched_barrier(0)
; template <class Desc, class Epi>
; DI void gemm_phase(LAS unsigned char* lds, const Desc& D, const Epi& E, int wv) {
;     ...
;             PG8_LDA(At, 1, 1); PG8_STAGE(PG8_SB(1, 0), b3, voffB); PG8_STAGE(PG8_SB(1, 1), b3 + hstepB, voffB); PG8_STAGE(PG8_SA(1, 0), a3, voffA);
;             PG8_WAIT_V(8); PG8_WAIT_L(0); PG8_BAR; PG8_MMA(1, 0, At, B0); PG8_MMA(1, 1, At, B1); PG8_BAR; PG8_SCHED;
;         }
;         if (wr == 0) PG8_BAR;
	s_add_i32 s42, s51, s2
	v_lshl_add_u64 v[214:215], v[214:215], 0, s[14:15]
	s_mov_b32 m0, s42
	ds_read_b128 v[182:185], v153 offset:49152
	ds_read_b128 v[186:189], v153 offset:50176
	ds_read_b128 v[190:193], v153 offset:51200
	ds_read_b128 v[194:197], v153 offset:52224
	ds_read_b128 v[198:201], v153 offset:53248
	ds_read_b128 v[202:205], v153 offset:54272
	ds_read_b128 v[206:209], v153 offset:55296
	ds_read_b128 v[210:213], v153 offset:56320
	global_load_lds_dwordx4 v[214:215], off
	s_add_i32 m0, s42, 0x2000
	s_add_u32 s8, s8, 0x80080
	v_lshl_add_u64 v[214:215], v[216:217], 0, s[14:15]
	s_addc_u32 s9, s9, 0
	s_add_i32 s42, s64, s2
	global_load_lds_dwordx4 v[214:215], off
	s_mov_b32 m0, s42
	v_lshl_add_u64 v[214:215], s[8:9], 0, v[130:131]
	global_load_lds_dwordx4 v[214:215], off
	s_add_i32 m0, s42, 0x2000
	v_lshl_add_u64 v[214:215], s[8:9], 0, v[134:135]
	global_load_lds_dwordx4 v[214:215], off
	s_mov_b32 m0, s35
	v_lshl_add_u64 v[214:215], v[218:219], 0, s[14:15]
	global_load_lds_dwordx4 v[214:215], off
	s_mov_b32 m0, s46
	v_lshl_add_u64 v[214:215], v[220:221], 0, s[14:15]
	global_load_lds_dwordx4 v[214:215], off
	s_waitcnt vmcnt(8) lgkmcnt(0)
	s_barrier
	v_mfma_f32_16x16x32_bf16 v[60:63], v[142:145], v[182:185], v[60:63]
	v_mfma_f32_16x16x32_bf16 v[56:59], v[158:161], v[182:185], v[56:59]
	v_mfma_f32_16x16x32_bf16 v[44:47], v[142:145], v[190:193], v[44:47]
	v_mfma_f32_16x16x32_bf16 v[40:43], v[158:161], v[190:193], v[40:43]
	v_mfma_f32_16x16x32_bf16 v[28:31], v[142:145], v[198:201], v[28:31]
	v_mfma_f32_16x16x32_bf16 v[24:27], v[158:161], v[198:201], v[24:27]
	v_mfma_f32_16x16x32_bf16 v[12:15], v[142:145], v[206:209], v[12:15]
	v_mfma_f32_16x16x32_bf16 v[8:11], v[158:161], v[206:209], v[8:11]
	v_mfma_f32_16x16x32_bf16 v[60:63], v[146:149], v[186:189], v[60:63]
	v_mfma_f32_16x16x32_bf16 v[56:59], v[162:165], v[186:189], v[56:59]
	v_mfma_f32_16x16x32_bf16 v[44:47], v[146:149], v[194:197], v[44:47]
	v_mfma_f32_16x16x32_bf16 v[40:43], v[162:165], v[194:197], v[40:43]
	v_mfma_f32_16x16x32_bf16 v[28:31], v[146:149], v[202:205], v[28:31]
	v_mfma_f32_16x16x32_bf16 v[24:27], v[162:165], v[202:205], v[24:27]
	v_mfma_f32_16x16x32_bf16 v[12:15], v[146:149], v[210:213], v[12:15]
	v_mfma_f32_16x16x32_bf16 v[8:11], v[162:165], v[210:213], v[8:11]
	v_mfma_f32_16x16x32_bf16 v[52:55], v[166:169], v[182:185], v[52:55]
	v_mfma_f32_16x16x32_bf16 v[48:51], v[174:177], v[182:185], v[48:51]
	v_mfma_f32_16x16x32_bf16 v[36:39], v[166:169], v[190:193], v[36:39]
	v_mfma_f32_16x16x32_bf16 v[32:35], v[174:177], v[190:193], v[32:35]
	v_mfma_f32_16x16x32_bf16 v[20:23], v[166:169], v[198:201], v[20:23]
	v_mfma_f32_16x16x32_bf16 v[16:19], v[174:177], v[198:201], v[16:19]
	v_mfma_f32_16x16x32_bf16 v[4:7], v[166:169], v[206:209], v[4:7]
	v_mfma_f32_16x16x32_bf16 v[0:3], v[174:177], v[206:209], v[0:3]
	v_mfma_f32_16x16x32_bf16 v[52:55], v[170:173], v[186:189], v[52:55]
	v_mfma_f32_16x16x32_bf16 v[48:51], v[178:181], v[186:189], v[48:51]
	v_mfma_f32_16x16x32_bf16 v[36:39], v[170:173], v[194:197], v[36:39]
	v_mfma_f32_16x16x32_bf16 v[32:35], v[178:181], v[194:197], v[32:35]
	v_mfma_f32_16x16x32_bf16 v[20:23], v[170:173], v[202:205], v[20:23]
	v_mfma_f32_16x16x32_bf16 v[16:19], v[178:181], v[202:205], v[16:19]
	v_mfma_f32_16x16x32_bf16 v[4:7], v[170:173], v[210:213], v[4:7]
	v_mfma_f32_16x16x32_bf16 v[0:3], v[178:181], v[210:213], v[0:3]
	s_barrier
	s_add_i32 s50, s50, 2
	s_add_u32 s6, s6, 0x100
	s_addc_u32 s7, s7, 0
	s_add_u32 s48, s48, 0x100
	s_addc_u32 s49, s49, 0
	s_cmp_gt_u32 s50, 5
	s_cbranch_scc0 .LBB0_2239
	s_and_b64 vcc, exec, s[18:19]
	s_cbranch_vccz .LBB0_2242
	s_barrier

; #define PG8_STAGE(bufoff, gbase, voff) do { _Pragma("unroll") for (int _i = 0; _i < 2; ++_i) \
;         __builtin_amdgcn_global_load_lds((const unsigned*)((const char*)(gbase) + (voff)[_i]), (LAS unsigned*)(lds + (bufoff) + ldsw + _i * 8192), 16, 0, 0); } while (0)
; #define PG8_LDA(dst, b, h) do { _Pragma("unroll") for (int m = 0; m < 4; ++m) _Pragma("unroll") for (int k = 0; k < 2; ++k) dst[m][k] = *(const LAS bf16x8*)(lds + PG8_SA(b, h) + aoff + m * 2048 + k * 1024); } while (0)
; #define PG8_LDB(dst, b, h) do { _Pragma("unroll") for (int n = 0; n < 2; ++n) _Pragma("unroll") for (int k = 0; k < 2; ++k) dst[n][k] = *(const LAS bf16x8*)(lds + PG8_SB(b, h) + boff + n * 2048 + k * 1024); } while (0)
; #define PG8_MMA(ai, bj, At, Bt) do { __builtin_amdgcn_s_setprio(1); _Pragma("unroll") for (int m = 0; m < 4; ++m) _Pragma("unroll") for (int n = 0; n < 2; ++n) _Pragma("unroll") for (int k = 0; k < 2; ++k) \
;         acc[ai][bj][m][n] = __builtin_amdgcn_mfma_f32_16x16x32_bf16(Bt[n][k], At[m][k], acc[ai][bj][m][n], 0, 0, 0); __builtin_amdgcn_s_setprio(0); } while (0)
; #define PG8_WAIT_V(n) asm volatile("s_waitcnt vmcnt(" #n ")" ::: "memory")
; #define PG8_WAIT_L(n) asm volatile("s_waitcnt lgkmcnt(" #n ")" ::: "memory")
; #define PG8_BAR __builtin_amdgcn_s_barrier()
; #define PG8_SCHED __builtin_amdgcn_sched_barrier(0)
; template <class Desc, class Epi>
; DI void gemm_phase(LAS unsigned char* lds, const Desc& D, const Epi& E, int wv) {
;     ...
;         for (int t = 0; t < nt; t += 2) {
;             const bool last = (t == nt - 2);
;             const char* a1 = cA + (size_t)(t + 1) * kstep;
;             const char* a2 = last ? nA : cA + (size_t)(t + 2) * kstep; const char* b2 = last ? nB : cB + (size_t)(t + 2) * kstep;
;             const char* a3 = a2 + kstep; const char* b3 = b2 + kstep;
;             PG8_LDB(B0, 0, 0); PG8_LDB(B1, 0, 1); PG8_SCHED; PG8_LDA(At, 0, 0); PG8_STAGE(PG8_SA(1, 1), a1 + hstepA, voffA);
;             PG8_WAIT_V(8); PG8_WAIT_L(0); PG8_BAR; PG8_MMA(0, 0, At, B0); PG8_MMA(0, 1, At, B1); PG8_BAR; PG8_SCHED;
;             PG8_LDA(At, 0, 1); PG8_STAGE(PG8_SB(0, 0), b2, voffB); PG8_STAGE(PG8_SB(0, 1), b2 + hstepB, voffB); PG8_STAGE(PG8_SA(0, 0), a2, voffA);
;             PG8_WAIT_V(8); PG8_WAIT_L(0); PG8_BAR; PG8_MMA(1, 0, At, B0); PG8_MMA(1, 1, At, B1); PG8_BAR; PG8_SCHED;
.LBB0_2480:
	ds_read_b128 v[128:131], v185
	ds_read_b128 v[132:135], v185 offset:1024
	ds_read_b128 v[150:153], v185 offset:2048
	ds_read_b128 v[154:157], v185 offset:3072
	ds_read_b128 v[158:161], v186
	ds_read_b128 v[162:165], v186 offset:1024
	ds_read_b128 v[166:169], v186 offset:2048
	ds_read_b128 v[170:173], v186 offset:3072
	s_add_u32 s42, s40, 0xfff00080
	s_addc_u32 s43, s41, -1
	s_cmp_eq_u32 s48, 28
	s_cselect_b32 s47, s17, s43
	s_cselect_b32 s46, s16, s42
	s_cselect_b32 s43, s19, s23
	s_cselect_b32 s42, s18, s5
	v_lshl_add_u64 v[182:183], s[40:41], 0, v[146:147]
	s_add_i32 m0, s3, 0xc000
	ds_read_b128 v[174:177], v187
	ds_read_b128 v[178:181], v187 offset:1024
	ds_read_b128 v[190:193], v187 offset:2048
	ds_read_b128 v[194:197], v187 offset:3072
	ds_read_b128 v[198:201], v187 offset:4096
	ds_read_b128 v[202:205], v187 offset:5120
	ds_read_b128 v[206:209], v187 offset:6144
	ds_read_b128 v[210:213], v187 offset:7168
	global_load_lds_dwordx4 v[182:183], off
	s_add_i32 m0, s3, 0xe000
	v_lshl_add_u64 v[182:183], s[40:41], 0, v[148:149]
	global_load_lds_dwordx4 v[182:183], off
	s_waitcnt vmcnt(8) lgkmcnt(0)
	s_barrier
	v_mfma_f32_16x16x32_bf16 v[124:127], v[128:131], v[174:177], v[124:127]
	v_mfma_f32_16x16x32_bf16 v[120:123], v[150:153], v[174:177], v[120:123]
	v_mfma_f32_16x16x32_bf16 v[108:111], v[128:131], v[190:193], v[108:111]
	v_mfma_f32_16x16x32_bf16 v[104:107], v[150:153], v[190:193], v[104:107]
	v_mfma_f32_16x16x32_bf16 v[92:95], v[128:131], v[198:201], v[92:95]
	v_mfma_f32_16x16x32_bf16 v[88:91], v[150:153], v[198:201], v[88:91]
	v_mfma_f32_16x16x32_bf16 v[76:79], v[128:131], v[206:209], v[76:79]
	v_mfma_f32_16x16x32_bf16 v[72:75], v[150:153], v[206:209], v[72:75]
	v_mfma_f32_16x16x32_bf16 v[124:127], v[132:135], v[178:181], v[124:127]
	v_mfma_f32_16x16x32_bf16 v[120:123], v[154:157], v[178:181], v[120:123]
	v_mfma_f32_16x16x32_bf16 v[108:111], v[132:135], v[194:197], v[108:111]
	v_mfma_f32_16x16x32_bf16 v[104:107], v[154:157], v[194:197], v[104:107]
	v_mfma_f32_16x16x32_bf16 v[92:95], v[132:135], v[202:205], v[92:95]
	v_mfma_f32_16x16x32_bf16 v[88:91], v[154:157], v[202:205], v[88:91]
	v_mfma_f32_16x16x32_bf16 v[76:79], v[132:135], v[210:213], v[76:79]
	v_mfma_f32_16x16x32_bf16 v[72:75], v[154:157], v[210:213], v[72:75]
	v_mfma_f32_16x16x32_bf16 v[116:119], v[158:161], v[174:177], v[116:119]
	v_mfma_f32_16x16x32_bf16 v[112:115], v[166:169], v[174:177], v[112:115]
	v_mfma_f32_16x16x32_bf16 v[100:103], v[158:161], v[190:193], v[100:103]
	v_mfma_f32_16x16x32_bf16 v[96:99], v[166:169], v[190:193], v[96:99]
	v_mfma_f32_16x16x32_bf16 v[84:87], v[158:161], v[198:201], v[84:87]
	v_mfma_f32_16x16x32_bf16 v[80:83], v[166:169], v[198:201], v[80:83]
	v_mfma_f32_16x16x32_bf16 v[68:71], v[158:161], v[206:209], v[68:71]
	v_mfma_f32_16x16x32_bf16 v[64:67], v[166:169], v[206:209], v[64:67]
	v_mfma_f32_16x16x32_bf16 v[116:119], v[162:165], v[178:181], v[116:119]
	v_mfma_f32_16x16x32_bf16 v[112:115], v[170:173], v[178:181], v[112:115]
	v_mfma_f32_16x16x32_bf16 v[100:103], v[162:165], v[194:197], v[100:103]
	v_mfma_f32_16x16x32_bf16 v[96:99], v[170:173], v[194:197], v[96:99]
	v_mfma_f32_16x16x32_bf16 v[84:87], v[162:165], v[202:205], v[84:87]
	v_mfma_f32_16x16x32_bf16 v[80:83], v[170:173], v[202:205], v[80:83]
	v_mfma_f32_16x16x32_bf16 v[68:71], v[162:165], v[210:213], v[68:71]
	v_mfma_f32_16x16x32_bf16 v[64:67], v[170:173], v[210:213], v[64:67]
	s_barrier
	s_add_i32 s49, s52, s2
	v_lshl_add_u64 v[182:183], s[42:43], 0, v[140:141]
	s_mov_b32 m0, s49
	ds_read_b128 v[174:177], v187 offset:16384
	ds_read_b128 v[178:181], v187 offset:17408
	ds_read_b128 v[190:193], v187 offset:18432
	ds_read_b128 v[194:197], v187 offset:19456
	ds_read_b128 v[198:201], v187 offset:20480
	ds_read_b128 v[202:205], v187 offset:21504
	ds_read_b128 v[206:209], v187 offset:22528
	ds_read_b128 v[210:213], v187 offset:23552
	global_load_lds_dwordx4 v[182:183], off
	s_add_i32 m0, s49, 0x2000
	s_add_u32 s62, s42, 0x100000
	v_lshl_add_u64 v[214:215], s[42:43], 0, v[136:137]
	s_addc_u32 s63, s43, 0
	s_add_i32 s49, s53, s2
	global_load_lds_dwordx4 v[214:215], off
	v_lshl_add_u64 v[216:217], s[62:63], 0, v[140:141]
	s_mov_b32 m0, s49
	v_lshl_add_u64 v[218:219], s[46:47], 0, v[138:139]
	global_load_lds_dwordx4 v[216:217], off
	s_add_i32 m0, s49, 0x2000
	v_lshl_add_u64 v[216:217], s[62:63], 0, v[136:137]
	global_load_lds_dwordx4 v[216:217], off
	s_mov_b32 m0, s3
	v_lshl_add_u64 v[216:217], s[46:47], 0, v[142:143]
	global_load_lds_dwordx4 v[216:217], off
	s_mov_b32 m0, s28
	s_nop 0
	global_load_lds_dwordx4 v[218:219], off
	s_waitcnt vmcnt(8) lgkmcnt(0)
	s_barrier
; #define PG8_STAGE(bufoff, gbase, voff) do { _Pragma("unroll") for (int _i = 0; _i < 2; ++_i) \
;         __builtin_amdgcn_global_load_lds((const unsigned*)((const char*)(gbase) + (voff)[_i]), (LAS unsigned*)(lds + (bufoff) + ldsw + _i * 8192), 16, 0, 0); } while (0)
; #define PG8_LDA(dst, b, h) do { _Pragma("unroll") for (int m = 0; m < 4; ++m) _Pragma("unroll") for (int k = 0; k < 2; ++k) dst[m][k] = *(const LAS bf16x8*)(lds + PG8_SA(b, h) + aoff + m * 2048 + k * 1024); } while (0)
; #define PG8_LDB(dst, b, h) do { _Pragma("unroll") for (int n = 0; n < 2; ++n) _Pragma("unroll") for (int k = 0; k < 2; ++k) dst[n][k] = *(const LAS bf16x8*)(lds + PG8_SB(b, h) + boff + n * 2048 + k * 1024); } while (0)
; #define PG8_MMA(ai, bj, At, Bt) do { __builtin_amdgcn_s_setprio(1); _Pragma("unroll") for (int m = 0; m < 4; ++m) _Pragma("unroll") for (int n = 0; n < 2; ++n) _Pragma("unroll") for (int k = 0; k < 2; ++k) \
;         acc[ai][bj][m][n] = __builtin_amdgcn_mfma_f32_16x16x32_bf16(Bt[n][k], At[m][k], acc[ai][bj][m][n], 0, 0, 0); __builtin_amdgcn_s_setprio(0); } while (0)
; #define PG8_WAIT_V(n) asm volatile("s_waitcnt vmcnt(" #n ")" ::: "memory")
; #define PG8_WAIT_L(n) asm volatile("s_waitcnt lgkmcnt(" #n ")" ::: "memory")
; #define PG8_BAR __builtin_amdgcn_s_barrier()
; #define PG8_SCHED __builtin_amdgcn_sched_barrier(0)
; template <class Desc, class Epi>
; DI void gemm_phase(LAS unsigned char* lds, const Desc& D, const Epi& E, int wv) {
;     ...
;             PG8_WAIT_V(8); PG8_WAIT_L(0); PG8_BAR; PG8_MMA(1, 0, At, B0); PG8_MMA(1, 1, At, B1); PG8_BAR; PG8_SCHED;
;             PG8_LDB(B0, 1, 0); PG8_LDB(B1, 1, 1); PG8_SCHED; PG8_LDA(At, 1, 0); PG8_STAGE(PG8_SA(0, 1), a2 + hstepA, voffA);
;             PG8_WAIT_V(8); PG8_WAIT_L(0); PG8_BAR; PG8_MMA(0, 0, At, B0); PG8_MMA(0, 1, At, B1); PG8_BAR; PG8_SCHED;
	v_mfma_f32_16x16x32_bf16 v[60:63], v[128:131], v[174:177], v[60:63]
	v_mfma_f32_16x16x32_bf16 v[56:59], v[150:153], v[174:177], v[56:59]
	v_mfma_f32_16x16x32_bf16 v[44:47], v[128:131], v[190:193], v[44:47]
	v_mfma_f32_16x16x32_bf16 v[40:43], v[150:153], v[190:193], v[40:43]
	v_mfma_f32_16x16x32_bf16 v[28:31], v[128:131], v[198:201], v[28:31]
	v_mfma_f32_16x16x32_bf16 v[24:27], v[150:153], v[198:201], v[24:27]
	v_mfma_f32_16x16x32_bf16 v[12:15], v[128:131], v[206:209], v[12:15]
	v_mfma_f32_16x16x32_bf16 v[8:11], v[150:153], v[206:209], v[8:11]
	v_mfma_f32_16x16x32_bf16 v[60:63], v[132:135], v[178:181], v[60:63]
	v_mfma_f32_16x16x32_bf16 v[56:59], v[154:157], v[178:181], v[56:59]
	v_mfma_f32_16x16x32_bf16 v[44:47], v[132:135], v[194:197], v[44:47]
	v_mfma_f32_16x16x32_bf16 v[40:43], v[154:157], v[194:197], v[40:43]
	v_mfma_f32_16x16x32_bf16 v[28:31], v[132:135], v[202:205], v[28:31]
	v_mfma_f32_16x16x32_bf16 v[24:27], v[154:157], v[202:205], v[24:27]
	v_mfma_f32_16x16x32_bf16 v[12:15], v[132:135], v[210:213], v[12:15]
	v_mfma_f32_16x16x32_bf16 v[8:11], v[154:157], v[210:213], v[8:11]
	v_mfma_f32_16x16x32_bf16 v[52:55], v[158:161], v[174:177], v[52:55]
	v_mfma_f32_16x16x32_bf16 v[48:51], v[166:169], v[174:177], v[48:51]
	v_mfma_f32_16x16x32_bf16 v[36:39], v[158:161], v[190:193], v[36:39]
	v_mfma_f32_16x16x32_bf16 v[32:35], v[166:169], v[190:193], v[32:35]
	v_mfma_f32_16x16x32_bf16 v[20:23], v[158:161], v[198:201], v[20:23]
	v_mfma_f32_16x16x32_bf16 v[16:19], v[166:169], v[198:201], v[16:19]
	v_mfma_f32_16x16x32_bf16 v[4:7], v[158:161], v[206:209], v[4:7]
	v_mfma_f32_16x16x32_bf16 v[0:3], v[166:169], v[206:209], v[0:3]
	v_mfma_f32_16x16x32_bf16 v[52:55], v[162:165], v[178:181], v[52:55]
	v_mfma_f32_16x16x32_bf16 v[48:51], v[170:173], v[178:181], v[48:51]
	v_mfma_f32_16x16x32_bf16 v[36:39], v[162:165], v[194:197], v[36:39]
	v_mfma_f32_16x16x32_bf16 v[32:35], v[170:173], v[194:197], v[32:35]
	v_mfma_f32_16x16x32_bf16 v[20:23], v[162:165], v[202:205], v[20:23]
	v_mfma_f32_16x16x32_bf16 v[16:19], v[170:173], v[202:205], v[16:19]
	v_mfma_f32_16x16x32_bf16 v[4:7], v[162:165], v[210:213], v[4:7]
	v_mfma_f32_16x16x32_bf16 v[0:3], v[170:173], v[210:213], v[0:3]
	s_barrier
	s_add_i32 s49, 0, 0x18000
	v_add_u32_e32 v144, s49, v184
	s_add_i32 s61, 0, 0x1c000
	ds_read_b128 v[128:131], v144
	ds_read_b128 v[132:135], v144 offset:1024
	ds_read_b128 v[150:153], v144 offset:2048
	ds_read_b128 v[154:157], v144 offset:3072
	v_add_u32_e32 v144, s61, v184
	ds_read_b128 v[158:161], v144
	ds_read_b128 v[162:165], v144 offset:1024
	ds_read_b128 v[166:169], v144 offset:2048
	ds_read_b128 v[170:173], v144 offset:3072
	s_add_u32 s46, s46, 0x100000
	s_addc_u32 s47, s47, 0
	s_mov_b32 m0, s29
	v_lshl_add_u64 v[220:221], s[46:47], 0, v[142:143]
	ds_read_b128 v[174:177], v187 offset:32768
	ds_read_b128 v[178:181], v187 offset:33792
	ds_read_b128 v[190:193], v187 offset:34816
	ds_read_b128 v[194:197], v187 offset:35840
	ds_read_b128 v[198:201], v187 offset:36864
	ds_read_b128 v[202:205], v187 offset:37888
	ds_read_b128 v[206:209], v187 offset:38912
	ds_read_b128 v[210:213], v187 offset:39936
	global_load_lds_dwordx4 v[220:221], off
	s_mov_b32 m0, s30
	v_lshl_add_u64 v[220:221], s[46:47], 0, v[138:139]
	global_load_lds_dwordx4 v[220:221], off
	s_waitcnt vmcnt(8) lgkmcnt(0)
	s_barrier
	v_mfma_f32_16x16x32_bf16 v[124:127], v[128:131], v[174:177], v[124:127]
	v_mfma_f32_16x16x32_bf16 v[120:123], v[150:153], v[174:177], v[120:123]
	v_mfma_f32_16x16x32_bf16 v[108:111], v[128:131], v[190:193], v[108:111]
	v_mfma_f32_16x16x32_bf16 v[104:107], v[150:153], v[190:193], v[104:107]
	v_mfma_f32_16x16x32_bf16 v[92:95], v[128:131], v[198:201], v[92:95]
	v_mfma_f32_16x16x32_bf16 v[88:91], v[150:153], v[198:201], v[88:91]
	v_mfma_f32_16x16x32_bf16 v[76:79], v[128:131], v[206:209], v[76:79]
	v_mfma_f32_16x16x32_bf16 v[72:75], v[150:153], v[206:209], v[72:75]
	v_mfma_f32_16x16x32_bf16 v[124:127], v[132:135], v[178:181], v[124:127]
	v_mfma_f32_16x16x32_bf16 v[120:123], v[154:157], v[178:181], v[120:123]
	v_mfma_f32_16x16x32_bf16 v[108:111], v[132:135], v[194:197], v[108:111]
	v_mfma_f32_16x16x32_bf16 v[104:107], v[154:157], v[194:197], v[104:107]
	v_mfma_f32_16x16x32_bf16 v[92:95], v[132:135], v[202:205], v[92:95]
	v_mfma_f32_16x16x32_bf16 v[88:91], v[154:157], v[202:205], v[88:91]
	v_mfma_f32_16x16x32_bf16 v[76:79], v[132:135], v[210:213], v[76:79]
	v_mfma_f32_16x16x32_bf16 v[72:75], v[154:157], v[210:213], v[72:75]
	v_mfma_f32_16x16x32_bf16 v[116:119], v[158:161], v[174:177], v[116:119]
	v_mfma_f32_16x16x32_bf16 v[112:115], v[166:169], v[174:177], v[112:115]
	v_mfma_f32_16x16x32_bf16 v[100:103], v[158:161], v[190:193], v[100:103]
	v_mfma_f32_16x16x32_bf16 v[96:99], v[166:169], v[190:193], v[96:99]
	v_mfma_f32_16x16x32_bf16 v[84:87], v[158:161], v[198:201], v[84:87]
	v_mfma_f32_16x16x32_bf16 v[80:83], v[166:169], v[198:201], v[80:83]
	v_mfma_f32_16x16x32_bf16 v[68:71], v[158:161], v[206:209], v[68:71]
	v_mfma_f32_16x16x32_bf16 v[64:67], v[166:169], v[206:209], v[64:67]
	v_mfma_f32_16x16x32_bf16 v[116:119], v[162:165], v[178:181], v[116:119]
	v_mfma_f32_16x16x32_bf16 v[112:115], v[170:173], v[178:181], v[112:115]
	v_mfma_f32_16x16x32_bf16 v[100:103], v[162:165], v[194:197], v[100:103]
	v_mfma_f32_16x16x32_bf16 v[96:99], v[170:173], v[194:197], v[96:99]
	v_mfma_f32_16x16x32_bf16 v[84:87], v[162:165], v[202:205], v[84:87]
	v_mfma_f32_16x16x32_bf16 v[80:83], v[170:173], v[202:205], v[80:83]
	v_mfma_f32_16x16x32_bf16 v[68:71], v[162:165], v[210:213], v[68:71]
	v_mfma_f32_16x16x32_bf16 v[64:67], v[170:173], v[210:213], v[64:67]
	s_barrier
; #define PG8_STAGE(bufoff, gbase, voff) do { _Pragma("unroll") for (int _i = 0; _i < 2; ++_i) \
;         __builtin_amdgcn_global_load_lds((const unsigned*)((const char*)(gbase) + (voff)[_i]), (LAS unsigned*)(lds + (bufoff) + ldsw + _i * 8192), 16, 0, 0); } while (0)
; #define PG8_LDA(dst, b, h) do { _Pragma("unroll") for (int m = 0; m < 4; ++m) _Pragma("unroll") for (int k = 0; k < 2; ++k) dst[m][k] = *(const LAS bf16x8*)(lds + PG8_SA(b, h) + aoff + m * 2048 + k * 1024); } while (0)
; #define PG8_MMA(ai, bj, At, Bt) do { __builtin_amdgcn_s_setprio(1); _Pragma("unroll") for (int m = 0; m < 4; ++m) _Pragma("unroll") for (int n = 0; n < 2; ++n) _Pragma("unroll") for (int k = 0; k < 2; ++k) \
;         acc[ai][bj][m][n] = __builtin_amdgcn_mfma_f32_16x16x32_bf16(Bt[n][k], At[m][k], acc[ai][bj][m][n], 0, 0, 0); __builtin_amdgcn_s_setprio(0); } while (0)
; #define PG8_WAIT_V(n) asm volatile("s_waitcnt vmcnt(" #n ")" ::: "memory")
; #define PG8_WAIT_L(n) asm volatile("s_waitcnt lgkmcnt(" #n ")" ::: "memory")
; #define PG8_BAR __builtin_amdgcn_s_barrier()
; #define PG8_SCHED __builtin_amdgcn_sched_barrier(0)
; template <class Desc, class Epi>
; DI void gemm_phase(LAS unsigned char* lds, const Desc& D, const Epi& E, int wv) {
;     ...
;             PG8_LDA(At, 1, 1); PG8_STAGE(PG8_SB(1, 0), b3, voffB); PG8_STAGE(PG8_SB(1, 1), b3 + hstepB, voffB); PG8_STAGE(PG8_SA(1, 0), a3, voffA);
;             PG8_WAIT_V(8); PG8_WAIT_L(0); PG8_BAR; PG8_MMA(1, 0, At, B0); PG8_MMA(1, 1, At, B1); PG8_BAR; PG8_SCHED;
;         }
;         if (wr == 0) PG8_BAR;
	s_add_i32 s46, s49, s2
	v_lshl_add_u64 v[182:183], v[182:183], 0, s[12:13]
	s_mov_b32 m0, s46
	ds_read_b128 v[174:177], v187 offset:49152
	ds_read_b128 v[178:181], v187 offset:50176
	ds_read_b128 v[190:193], v187 offset:51200
	ds_read_b128 v[194:197], v187 offset:52224
	ds_read_b128 v[198:201], v187 offset:53248
	ds_read_b128 v[202:205], v187 offset:54272
	ds_read_b128 v[206:209], v187 offset:55296
	ds_read_b128 v[210:213], v187 offset:56320
	global_load_lds_dwordx4 v[182:183], off
	s_add_i32 m0, s46, 0x2000
	s_add_u32 s42, s42, 0x100080
	v_lshl_add_u64 v[182:183], v[214:215], 0, s[12:13]
	s_addc_u32 s43, s43, 0
	s_add_i32 s46, s61, s2
	global_load_lds_dwordx4 v[182:183], off
	s_mov_b32 m0, s46
	v_lshl_add_u64 v[182:183], s[42:43], 0, v[140:141]
	global_load_lds_dwordx4 v[182:183], off
	s_add_i32 m0, s46, 0x2000
	v_lshl_add_u64 v[182:183], s[42:43], 0, v[136:137]
	global_load_lds_dwordx4 v[182:183], off
	s_mov_b32 m0, s50
	v_lshl_add_u64 v[182:183], v[216:217], 0, s[12:13]
	global_load_lds_dwordx4 v[182:183], off
	s_mov_b32 m0, s51
	v_lshl_add_u64 v[182:183], v[218:219], 0, s[12:13]
	global_load_lds_dwordx4 v[182:183], off
	s_waitcnt vmcnt(8) lgkmcnt(0)
	s_barrier
	v_mfma_f32_16x16x32_bf16 v[60:63], v[128:131], v[174:177], v[60:63]
	v_mfma_f32_16x16x32_bf16 v[56:59], v[150:153], v[174:177], v[56:59]
	v_mfma_f32_16x16x32_bf16 v[44:47], v[128:131], v[190:193], v[44:47]
	v_mfma_f32_16x16x32_bf16 v[40:43], v[150:153], v[190:193], v[40:43]
	v_mfma_f32_16x16x32_bf16 v[28:31], v[128:131], v[198:201], v[28:31]
	v_mfma_f32_16x16x32_bf16 v[24:27], v[150:153], v[198:201], v[24:27]
	v_mfma_f32_16x16x32_bf16 v[12:15], v[128:131], v[206:209], v[12:15]
	v_mfma_f32_16x16x32_bf16 v[8:11], v[150:153], v[206:209], v[8:11]
	v_mfma_f32_16x16x32_bf16 v[60:63], v[132:135], v[178:181], v[60:63]
	v_mfma_f32_16x16x32_bf16 v[56:59], v[154:157], v[178:181], v[56:59]
	v_mfma_f32_16x16x32_bf16 v[44:47], v[132:135], v[194:197], v[44:47]
	v_mfma_f32_16x16x32_bf16 v[40:43], v[154:157], v[194:197], v[40:43]
	v_mfma_f32_16x16x32_bf16 v[28:31], v[132:135], v[202:205], v[28:31]
	v_mfma_f32_16x16x32_bf16 v[24:27], v[154:157], v[202:205], v[24:27]
	v_mfma_f32_16x16x32_bf16 v[12:15], v[132:135], v[210:213], v[12:15]
	v_mfma_f32_16x16x32_bf16 v[8:11], v[154:157], v[210:213], v[8:11]
	v_mfma_f32_16x16x32_bf16 v[52:55], v[158:161], v[174:177], v[52:55]
	v_mfma_f32_16x16x32_bf16 v[48:51], v[166:169], v[174:177], v[48:51]
	v_mfma_f32_16x16x32_bf16 v[36:39], v[158:161], v[190:193], v[36:39]
	v_mfma_f32_16x16x32_bf16 v[32:35], v[166:169], v[190:193], v[32:35]
	v_mfma_f32_16x16x32_bf16 v[20:23], v[158:161], v[198:201], v[20:23]
	v_mfma_f32_16x16x32_bf16 v[16:19], v[166:169], v[198:201], v[16:19]
	v_mfma_f32_16x16x32_bf16 v[4:7], v[158:161], v[206:209], v[4:7]
	v_mfma_f32_16x16x32_bf16 v[0:3], v[166:169], v[206:209], v[0:3]
	v_mfma_f32_16x16x32_bf16 v[52:55], v[162:165], v[178:181], v[52:55]
	v_mfma_f32_16x16x32_bf16 v[48:51], v[170:173], v[178:181], v[48:51]
	v_mfma_f32_16x16x32_bf16 v[36:39], v[162:165], v[194:197], v[36:39]
	v_mfma_f32_16x16x32_bf16 v[32:35], v[170:173], v[194:197], v[32:35]
	v_mfma_f32_16x16x32_bf16 v[20:23], v[162:165], v[202:205], v[20:23]
	v_mfma_f32_16x16x32_bf16 v[16:19], v[170:173], v[202:205], v[16:19]
	v_mfma_f32_16x16x32_bf16 v[4:7], v[162:165], v[210:213], v[4:7]
	v_mfma_f32_16x16x32_bf16 v[0:3], v[170:173], v[210:213], v[0:3]
	s_barrier
	s_add_i32 s48, s48, 2
	s_add_u32 s40, s40, 0x100
	s_addc_u32 s41, s41, 0
	s_add_u32 s5, s5, 0x100
	s_addc_u32 s23, s23, 0
	s_cmp_gt_u32 s48, 29
	s_cbranch_scc0 .LBB0_2480
	s_and_b64 vcc, exec, s[14:15]
	s_cbranch_vccz .LBB0_2483
	s_barrier

; #define PG8_STAGE(bufoff, gbase, voff) do { _Pragma("unroll") for (int _i = 0; _i < 2; ++_i) \
;         __builtin_amdgcn_global_load_lds((const unsigned*)((const char*)(gbase) + (voff)[_i]), (LAS unsigned*)(lds + (bufoff) + ldsw + _i * 8192), 16, 0, 0); } while (0)
; #define PG8_LDA(dst, b, h) do { _Pragma("unroll") for (int m = 0; m < 4; ++m) _Pragma("unroll") for (int k = 0; k < 2; ++k) dst[m][k] = *(const LAS bf16x8*)(lds + PG8_SA(b, h) + aoff + m * 2048 + k * 1024); } while (0)
; #define PG8_LDB(dst, b, h) do { _Pragma("unroll") for (int n = 0; n < 2; ++n) _Pragma("unroll") for (int k = 0; k < 2; ++k) dst[n][k] = *(const LAS bf16x8*)(lds + PG8_SB(b, h) + boff + n * 2048 + k * 1024); } while (0)
; #define PG8_MMA(ai, bj, At, Bt) do { __builtin_amdgcn_s_setprio(1); _Pragma("unroll") for (int m = 0; m < 4; ++m) _Pragma("unroll") for (int n = 0; n < 2; ++n) _Pragma("unroll") for (int k = 0; k < 2; ++k) \
;         acc[ai][bj][m][n] = __builtin_amdgcn_mfma_f32_16x16x32_bf16(Bt[n][k], At[m][k], acc[ai][bj][m][n], 0, 0, 0); __builtin_amdgcn_s_setprio(0); } while (0)
; #define PG8_WAIT_V(n) asm volatile("s_waitcnt vmcnt(" #n ")" ::: "memory")
; #define PG8_WAIT_L(n) asm volatile("s_waitcnt lgkmcnt(" #n ")" ::: "memory")
; #define PG8_BAR __builtin_amdgcn_s_barrier()
; #define PG8_SCHED __builtin_amdgcn_sched_barrier(0)
; template <class Desc, class Epi>
; DI void gemm_phase(LAS unsigned char* lds, const Desc& D, const Epi& E, int wv) {
;     ...
;         for (int t = 0; t < nt; t += 2) {
;             const bool last = (t == nt - 2);
;             const char* a1 = cA + (size_t)(t + 1) * kstep;
;             const char* a2 = last ? nA : cA + (size_t)(t + 2) * kstep; const char* b2 = last ? nB : cB + (size_t)(t + 2) * kstep;
;             const char* a3 = a2 + kstep; const char* b3 = b2 + kstep;
;             PG8_LDB(B0, 0, 0); PG8_LDB(B1, 0, 1); PG8_SCHED; PG8_LDA(At, 0, 0); PG8_STAGE(PG8_SA(1, 1), a1 + hstepA, voffA);
;             PG8_WAIT_V(8); PG8_WAIT_L(0); PG8_BAR; PG8_MMA(0, 0, At, B0); PG8_MMA(0, 1, At, B1); PG8_BAR; PG8_SCHED;
;             PG8_LDA(At, 0, 1); PG8_STAGE(PG8_SB(0, 0), b2, voffB); PG8_STAGE(PG8_SB(0, 1), b2 + hstepB, voffB); PG8_STAGE(PG8_SA(0, 0), a2, voffA);
;             PG8_WAIT_V(8); PG8_WAIT_L(0); PG8_BAR; PG8_MMA(1, 0, At, B0); PG8_MMA(1, 1, At, B1); PG8_BAR; PG8_SCHED;
.LBB0_2706:
	ds_read_b128 v[128:131], v205
	ds_read_b128 v[132:135], v205 offset:1024
	ds_read_b128 v[136:139], v205 offset:2048
	ds_read_b128 v[140:143], v205 offset:3072
	ds_read_b128 v[144:147], v206
	ds_read_b128 v[148:151], v206 offset:1024
	ds_read_b128 v[152:155], v206 offset:2048
	ds_read_b128 v[156:159], v206 offset:3072
	s_add_u32 s34, s24, 0xfff80080
	s_addc_u32 s35, s25, -1
	s_cmp_eq_u32 s66, 28
	s_cselect_b32 s41, s15, s35
	s_cselect_b32 s40, s14, s34
	s_cselect_b32 s35, s17, s21
	s_cselect_b32 s34, s16, s19
	v_lshl_add_u64 v[212:213], s[24:25], 0, v[192:193]
	s_add_i32 m0, s30, 0xc000
	ds_read_b128 v[160:163], v207
	ds_read_b128 v[164:167], v207 offset:1024
	ds_read_b128 v[168:171], v207 offset:2048
	ds_read_b128 v[172:175], v207 offset:3072
	ds_read_b128 v[176:179], v207 offset:4096
	ds_read_b128 v[180:183], v207 offset:5120
	ds_read_b128 v[200:203], v207 offset:6144
	ds_read_b128 v[208:211], v207 offset:7168
	global_load_lds_dwordx4 v[212:213], off
	s_add_i32 m0, s30, 0xe000
	v_lshl_add_u64 v[212:213], s[24:25], 0, v[194:195]
	global_load_lds_dwordx4 v[212:213], off
	s_waitcnt vmcnt(8) lgkmcnt(0)
	s_barrier
	v_mfma_f32_16x16x32_bf16 v[124:127], v[128:131], v[160:163], v[124:127]
	v_mfma_f32_16x16x32_bf16 v[120:123], v[136:139], v[160:163], v[120:123]
	v_mfma_f32_16x16x32_bf16 v[112:115], v[128:131], v[168:171], v[112:115]
	v_mfma_f32_16x16x32_bf16 v[104:107], v[136:139], v[168:171], v[104:107]
	v_mfma_f32_16x16x32_bf16 v[96:99], v[128:131], v[176:179], v[96:99]
	v_mfma_f32_16x16x32_bf16 v[88:91], v[136:139], v[176:179], v[88:91]
	v_mfma_f32_16x16x32_bf16 v[80:83], v[128:131], v[200:203], v[80:83]
	v_mfma_f32_16x16x32_bf16 v[72:75], v[136:139], v[200:203], v[72:75]
	v_mfma_f32_16x16x32_bf16 v[124:127], v[132:135], v[164:167], v[124:127]
	v_mfma_f32_16x16x32_bf16 v[120:123], v[140:143], v[164:167], v[120:123]
	v_mfma_f32_16x16x32_bf16 v[112:115], v[132:135], v[172:175], v[112:115]
	v_mfma_f32_16x16x32_bf16 v[104:107], v[140:143], v[172:175], v[104:107]
	v_mfma_f32_16x16x32_bf16 v[96:99], v[132:135], v[180:183], v[96:99]
	v_mfma_f32_16x16x32_bf16 v[88:91], v[140:143], v[180:183], v[88:91]
	v_mfma_f32_16x16x32_bf16 v[80:83], v[132:135], v[208:211], v[80:83]
	v_mfma_f32_16x16x32_bf16 v[72:75], v[140:143], v[208:211], v[72:75]
	v_mfma_f32_16x16x32_bf16 v[116:119], v[144:147], v[160:163], v[116:119]
	v_mfma_f32_16x16x32_bf16 v[108:111], v[152:155], v[160:163], v[108:111]
	v_mfma_f32_16x16x32_bf16 v[100:103], v[144:147], v[168:171], v[100:103]
	v_mfma_f32_16x16x32_bf16 v[92:95], v[152:155], v[168:171], v[92:95]
	v_mfma_f32_16x16x32_bf16 v[84:87], v[144:147], v[176:179], v[84:87]
	v_mfma_f32_16x16x32_bf16 v[76:79], v[152:155], v[176:179], v[76:79]
	v_mfma_f32_16x16x32_bf16 v[68:71], v[144:147], v[200:203], v[68:71]
	v_mfma_f32_16x16x32_bf16 v[64:67], v[152:155], v[200:203], v[64:67]
	v_mfma_f32_16x16x32_bf16 v[116:119], v[148:151], v[164:167], v[116:119]
	v_mfma_f32_16x16x32_bf16 v[108:111], v[156:159], v[164:167], v[108:111]
	v_mfma_f32_16x16x32_bf16 v[100:103], v[148:151], v[172:175], v[100:103]
	v_mfma_f32_16x16x32_bf16 v[92:95], v[156:159], v[172:175], v[92:95]
	v_mfma_f32_16x16x32_bf16 v[84:87], v[148:151], v[180:183], v[84:87]
	v_mfma_f32_16x16x32_bf16 v[76:79], v[156:159], v[180:183], v[76:79]
	v_mfma_f32_16x16x32_bf16 v[68:71], v[148:151], v[208:211], v[68:71]
	v_mfma_f32_16x16x32_bf16 v[64:67], v[156:159], v[208:211], v[64:67]
	s_barrier
	s_add_i32 s67, s52, s28
	v_lshl_add_u64 v[212:213], s[34:35], 0, v[188:189]
	s_mov_b32 m0, s67
	ds_read_b128 v[160:163], v207 offset:16384
	ds_read_b128 v[164:167], v207 offset:17408
	ds_read_b128 v[168:171], v207 offset:18432
	ds_read_b128 v[172:175], v207 offset:19456
	ds_read_b128 v[176:179], v207 offset:20480
	ds_read_b128 v[180:183], v207 offset:21504
	ds_read_b128 v[200:203], v207 offset:22528
	ds_read_b128 v[208:211], v207 offset:23552
	global_load_lds_dwordx4 v[212:213], off
	s_add_i32 m0, s67, 0x2000
	s_add_u32 s68, s34, 0x80000
	v_lshl_add_u64 v[214:215], s[34:35], 0, v[184:185]
	s_addc_u32 s69, s35, 0
	s_add_i32 s67, s53, s28
	global_load_lds_dwordx4 v[214:215], off
	v_lshl_add_u64 v[216:217], s[68:69], 0, v[188:189]
	s_mov_b32 m0, s67
	v_lshl_add_u64 v[218:219], s[40:41], 0, v[186:187]
	global_load_lds_dwordx4 v[216:217], off
	s_add_i32 m0, s67, 0x2000
	v_lshl_add_u64 v[216:217], s[68:69], 0, v[184:185]
	global_load_lds_dwordx4 v[216:217], off
	s_mov_b32 m0, s30
	v_lshl_add_u64 v[216:217], s[40:41], 0, v[190:191]
	global_load_lds_dwordx4 v[216:217], off
	s_mov_b32 m0, s31
	s_nop 0
	global_load_lds_dwordx4 v[218:219], off
	s_waitcnt vmcnt(8) lgkmcnt(0)
	s_barrier
; #define PG8_STAGE(bufoff, gbase, voff) do { _Pragma("unroll") for (int _i = 0; _i < 2; ++_i) \
;         __builtin_amdgcn_global_load_lds((const unsigned*)((const char*)(gbase) + (voff)[_i]), (LAS unsigned*)(lds + (bufoff) + ldsw + _i * 8192), 16, 0, 0); } while (0)
; #define PG8_LDA(dst, b, h) do { _Pragma("unroll") for (int m = 0; m < 4; ++m) _Pragma("unroll") for (int k = 0; k < 2; ++k) dst[m][k] = *(const LAS bf16x8*)(lds + PG8_SA(b, h) + aoff + m * 2048 + k * 1024); } while (0)
; #define PG8_LDB(dst, b, h) do { _Pragma("unroll") for (int n = 0; n < 2; ++n) _Pragma("unroll") for (int k = 0; k < 2; ++k) dst[n][k] = *(const LAS bf16x8*)(lds + PG8_SB(b, h) + boff + n * 2048 + k * 1024); } while (0)
; #define PG8_MMA(ai, bj, At, Bt) do { __builtin_amdgcn_s_setprio(1); _Pragma("unroll") for (int m = 0; m < 4; ++m) _Pragma("unroll") for (int n = 0; n < 2; ++n) _Pragma("unroll") for (int k = 0; k < 2; ++k) \
;         acc[ai][bj][m][n] = __builtin_amdgcn_mfma_f32_16x16x32_bf16(Bt[n][k], At[m][k], acc[ai][bj][m][n], 0, 0, 0); __builtin_amdgcn_s_setprio(0); } while (0)
; #define PG8_WAIT_V(n) asm volatile("s_waitcnt vmcnt(" #n ")" ::: "memory")
; #define PG8_WAIT_L(n) asm volatile("s_waitcnt lgkmcnt(" #n ")" ::: "memory")
; #define PG8_BAR __builtin_amdgcn_s_barrier()
; #define PG8_SCHED __builtin_amdgcn_sched_barrier(0)
; template <class Desc, class Epi>
; DI void gemm_phase(LAS unsigned char* lds, const Desc& D, const Epi& E, int wv) {
;     ...
;             PG8_WAIT_V(8); PG8_WAIT_L(0); PG8_BAR; PG8_MMA(1, 0, At, B0); PG8_MMA(1, 1, At, B1); PG8_BAR; PG8_SCHED;
;             PG8_LDB(B0, 1, 0); PG8_LDB(B1, 1, 1); PG8_SCHED; PG8_LDA(At, 1, 0); PG8_STAGE(PG8_SA(0, 1), a2 + hstepA, voffA);
;             PG8_WAIT_V(8); PG8_WAIT_L(0); PG8_BAR; PG8_MMA(0, 0, At, B0); PG8_MMA(0, 1, At, B1); PG8_BAR; PG8_SCHED;
	v_mfma_f32_16x16x32_bf16 v[60:63], v[128:131], v[160:163], v[60:63]
	v_mfma_f32_16x16x32_bf16 v[56:59], v[136:139], v[160:163], v[56:59]
	v_mfma_f32_16x16x32_bf16 v[48:51], v[128:131], v[168:171], v[48:51]
	v_mfma_f32_16x16x32_bf16 v[40:43], v[136:139], v[168:171], v[40:43]
	v_mfma_f32_16x16x32_bf16 v[32:35], v[128:131], v[176:179], v[32:35]
	v_mfma_f32_16x16x32_bf16 v[24:27], v[136:139], v[176:179], v[24:27]
	v_mfma_f32_16x16x32_bf16 v[16:19], v[128:131], v[200:203], v[16:19]
	v_mfma_f32_16x16x32_bf16 v[8:11], v[136:139], v[200:203], v[8:11]
	v_mfma_f32_16x16x32_bf16 v[60:63], v[132:135], v[164:167], v[60:63]
	v_mfma_f32_16x16x32_bf16 v[56:59], v[140:143], v[164:167], v[56:59]
	v_mfma_f32_16x16x32_bf16 v[48:51], v[132:135], v[172:175], v[48:51]
	v_mfma_f32_16x16x32_bf16 v[40:43], v[140:143], v[172:175], v[40:43]
	v_mfma_f32_16x16x32_bf16 v[32:35], v[132:135], v[180:183], v[32:35]
	v_mfma_f32_16x16x32_bf16 v[24:27], v[140:143], v[180:183], v[24:27]
	v_mfma_f32_16x16x32_bf16 v[16:19], v[132:135], v[208:211], v[16:19]
	v_mfma_f32_16x16x32_bf16 v[8:11], v[140:143], v[208:211], v[8:11]
	v_mfma_f32_16x16x32_bf16 v[52:55], v[144:147], v[160:163], v[52:55]
	v_mfma_f32_16x16x32_bf16 v[44:47], v[152:155], v[160:163], v[44:47]
	v_mfma_f32_16x16x32_bf16 v[36:39], v[144:147], v[168:171], v[36:39]
	v_mfma_f32_16x16x32_bf16 v[28:31], v[152:155], v[168:171], v[28:31]
	v_mfma_f32_16x16x32_bf16 v[20:23], v[144:147], v[176:179], v[20:23]
	v_mfma_f32_16x16x32_bf16 v[12:15], v[152:155], v[176:179], v[12:15]
	v_mfma_f32_16x16x32_bf16 v[4:7], v[144:147], v[200:203], v[4:7]
	v_mfma_f32_16x16x32_bf16 v[0:3], v[152:155], v[200:203], v[0:3]
	v_mfma_f32_16x16x32_bf16 v[52:55], v[148:151], v[164:167], v[52:55]
	v_mfma_f32_16x16x32_bf16 v[44:47], v[156:159], v[164:167], v[44:47]
	v_mfma_f32_16x16x32_bf16 v[36:39], v[148:151], v[172:175], v[36:39]
	v_mfma_f32_16x16x32_bf16 v[28:31], v[156:159], v[172:175], v[28:31]
	v_mfma_f32_16x16x32_bf16 v[20:23], v[148:151], v[180:183], v[20:23]
	v_mfma_f32_16x16x32_bf16 v[12:15], v[156:159], v[180:183], v[12:15]
	v_mfma_f32_16x16x32_bf16 v[4:7], v[148:151], v[208:211], v[4:7]
	v_mfma_f32_16x16x32_bf16 v[0:3], v[156:159], v[208:211], v[0:3]
	s_barrier
	s_add_i32 s67, 0, 0x18000
	s_add_i32 s68, 0, 0x1c000
	v_add_u32_e32 v140, s67, v204
	v_add_u32_e32 v156, s68, v204
	ds_read_b128 v[128:131], v140
	ds_read_b128 v[132:135], v140 offset:1024
	ds_read_b128 v[136:139], v140 offset:2048
	ds_read_b128 v[140:143], v140 offset:3072
	ds_read_b128 v[144:147], v156
	ds_read_b128 v[148:151], v156 offset:1024
	ds_read_b128 v[152:155], v156 offset:2048
	ds_read_b128 v[156:159], v156 offset:3072
	s_add_u32 s40, s40, 0x80000
	s_addc_u32 s41, s41, 0
	s_mov_b32 m0, s42
	v_lshl_add_u64 v[220:221], s[40:41], 0, v[190:191]
	ds_read_b128 v[160:163], v207 offset:32768
	ds_read_b128 v[164:167], v207 offset:33792
	ds_read_b128 v[168:171], v207 offset:34816
	ds_read_b128 v[172:175], v207 offset:35840
	ds_read_b128 v[176:179], v207 offset:36864
	ds_read_b128 v[180:183], v207 offset:37888
	ds_read_b128 v[200:203], v207 offset:38912
	ds_read_b128 v[208:211], v207 offset:39936
	global_load_lds_dwordx4 v[220:221], off
	s_mov_b32 m0, s43
	v_lshl_add_u64 v[220:221], s[40:41], 0, v[186:187]
	global_load_lds_dwordx4 v[220:221], off
	s_waitcnt vmcnt(8) lgkmcnt(0)
	s_barrier
	v_mfma_f32_16x16x32_bf16 v[124:127], v[128:131], v[160:163], v[124:127]
	v_mfma_f32_16x16x32_bf16 v[120:123], v[136:139], v[160:163], v[120:123]
	v_mfma_f32_16x16x32_bf16 v[112:115], v[128:131], v[168:171], v[112:115]
	v_mfma_f32_16x16x32_bf16 v[104:107], v[136:139], v[168:171], v[104:107]
	v_mfma_f32_16x16x32_bf16 v[96:99], v[128:131], v[176:179], v[96:99]
	v_mfma_f32_16x16x32_bf16 v[88:91], v[136:139], v[176:179], v[88:91]
	v_mfma_f32_16x16x32_bf16 v[80:83], v[128:131], v[200:203], v[80:83]
	v_mfma_f32_16x16x32_bf16 v[72:75], v[136:139], v[200:203], v[72:75]
	v_mfma_f32_16x16x32_bf16 v[124:127], v[132:135], v[164:167], v[124:127]
	v_mfma_f32_16x16x32_bf16 v[120:123], v[140:143], v[164:167], v[120:123]
	v_mfma_f32_16x16x32_bf16 v[112:115], v[132:135], v[172:175], v[112:115]
	v_mfma_f32_16x16x32_bf16 v[104:107], v[140:143], v[172:175], v[104:107]
	v_mfma_f32_16x16x32_bf16 v[96:99], v[132:135], v[180:183], v[96:99]
	v_mfma_f32_16x16x32_bf16 v[88:91], v[140:143], v[180:183], v[88:91]
	v_mfma_f32_16x16x32_bf16 v[80:83], v[132:135], v[208:211], v[80:83]
	v_mfma_f32_16x16x32_bf16 v[72:75], v[140:143], v[208:211], v[72:75]
	v_mfma_f32_16x16x32_bf16 v[116:119], v[144:147], v[160:163], v[116:119]
	v_mfma_f32_16x16x32_bf16 v[108:111], v[152:155], v[160:163], v[108:111]
	v_mfma_f32_16x16x32_bf16 v[100:103], v[144:147], v[168:171], v[100:103]
	v_mfma_f32_16x16x32_bf16 v[92:95], v[152:155], v[168:171], v[92:95]
	v_mfma_f32_16x16x32_bf16 v[84:87], v[144:147], v[176:179], v[84:87]
	v_mfma_f32_16x16x32_bf16 v[76:79], v[152:155], v[176:179], v[76:79]
	v_mfma_f32_16x16x32_bf16 v[68:71], v[144:147], v[200:203], v[68:71]
	v_mfma_f32_16x16x32_bf16 v[64:67], v[152:155], v[200:203], v[64:67]
	v_mfma_f32_16x16x32_bf16 v[116:119], v[148:151], v[164:167], v[116:119]
	v_mfma_f32_16x16x32_bf16 v[108:111], v[156:159], v[164:167], v[108:111]
	v_mfma_f32_16x16x32_bf16 v[100:103], v[148:151], v[172:175], v[100:103]
	v_mfma_f32_16x16x32_bf16 v[92:95], v[156:159], v[172:175], v[92:95]
	v_mfma_f32_16x16x32_bf16 v[84:87], v[148:151], v[180:183], v[84:87]
	v_mfma_f32_16x16x32_bf16 v[76:79], v[156:159], v[180:183], v[76:79]
	v_mfma_f32_16x16x32_bf16 v[68:71], v[148:151], v[208:211], v[68:71]
	v_mfma_f32_16x16x32_bf16 v[64:67], v[156:159], v[208:211], v[64:67]
	s_barrier
; #define PG8_STAGE(bufoff, gbase, voff) do { _Pragma("unroll") for (int _i = 0; _i < 2; ++_i) \
;         __builtin_amdgcn_global_load_lds((const unsigned*)((const char*)(gbase) + (voff)[_i]), (LAS unsigned*)(lds + (bufoff) + ldsw + _i * 8192), 16, 0, 0); } while (0)
; #define PG8_LDA(dst, b, h) do { _Pragma("unroll") for (int m = 0; m < 4; ++m) _Pragma("unroll") for (int k = 0; k < 2; ++k) dst[m][k] = *(const LAS bf16x8*)(lds + PG8_SA(b, h) + aoff + m * 2048 + k * 1024); } while (0)
; #define PG8_MMA(ai, bj, At, Bt) do { __builtin_amdgcn_s_setprio(1); _Pragma("unroll") for (int m = 0; m < 4; ++m) _Pragma("unroll") for (int n = 0; n < 2; ++n) _Pragma("unroll") for (int k = 0; k < 2; ++k) \
;         acc[ai][bj][m][n] = __builtin_amdgcn_mfma_f32_16x16x32_bf16(Bt[n][k], At[m][k], acc[ai][bj][m][n], 0, 0, 0); __builtin_amdgcn_s_setprio(0); } while (0)
; #define PG8_WAIT_V(n) asm volatile("s_waitcnt vmcnt(" #n ")" ::: "memory")
; #define PG8_WAIT_L(n) asm volatile("s_waitcnt lgkmcnt(" #n ")" ::: "memory")
; #define PG8_BAR __builtin_amdgcn_s_barrier()
; #define PG8_SCHED __builtin_amdgcn_sched_barrier(0)
; template <class Desc, class Epi>
; DI void gemm_phase(LAS unsigned char* lds, const Desc& D, const Epi& E, int wv) {
;     ...
;             PG8_LDA(At, 1, 1); PG8_STAGE(PG8_SB(1, 0), b3, voffB); PG8_STAGE(PG8_SB(1, 1), b3 + hstepB, voffB); PG8_STAGE(PG8_SA(1, 0), a3, voffA);
;             PG8_WAIT_V(8); PG8_WAIT_L(0); PG8_BAR; PG8_MMA(1, 0, At, B0); PG8_MMA(1, 1, At, B1); PG8_BAR; PG8_SCHED;
;         }
;         if (wr == 0) PG8_BAR;
	s_add_i32 s40, s67, s28
	v_lshl_add_u64 v[212:213], v[212:213], 0, s[6:7]
	s_mov_b32 m0, s40
	ds_read_b128 v[160:163], v207 offset:49152
	ds_read_b128 v[164:167], v207 offset:50176
	ds_read_b128 v[168:171], v207 offset:51200
	ds_read_b128 v[172:175], v207 offset:52224
	ds_read_b128 v[176:179], v207 offset:53248
	ds_read_b128 v[180:183], v207 offset:54272
	ds_read_b128 v[200:203], v207 offset:55296
	ds_read_b128 v[208:211], v207 offset:56320
	global_load_lds_dwordx4 v[212:213], off
	s_add_i32 m0, s40, 0x2000
	s_add_u32 s34, s34, 0x80080
	v_lshl_add_u64 v[212:213], v[214:215], 0, s[6:7]
	s_addc_u32 s35, s35, 0
	s_add_i32 s40, s68, s28
	global_load_lds_dwordx4 v[212:213], off
	s_mov_b32 m0, s40
	v_lshl_add_u64 v[212:213], s[34:35], 0, v[188:189]
	global_load_lds_dwordx4 v[212:213], off
	s_add_i32 m0, s40, 0x2000
	v_lshl_add_u64 v[212:213], s[34:35], 0, v[184:185]
	global_load_lds_dwordx4 v[212:213], off
	s_mov_b32 m0, s49
	v_lshl_add_u64 v[212:213], v[216:217], 0, s[6:7]
	global_load_lds_dwordx4 v[212:213], off
	s_mov_b32 m0, s50
	v_lshl_add_u64 v[212:213], v[218:219], 0, s[6:7]
	global_load_lds_dwordx4 v[212:213], off
	s_waitcnt vmcnt(8) lgkmcnt(0)
	s_barrier
	v_mfma_f32_16x16x32_bf16 v[60:63], v[128:131], v[160:163], v[60:63]
	v_mfma_f32_16x16x32_bf16 v[56:59], v[136:139], v[160:163], v[56:59]
	v_mfma_f32_16x16x32_bf16 v[48:51], v[128:131], v[168:171], v[48:51]
	v_mfma_f32_16x16x32_bf16 v[40:43], v[136:139], v[168:171], v[40:43]
	v_mfma_f32_16x16x32_bf16 v[32:35], v[128:131], v[176:179], v[32:35]
	v_mfma_f32_16x16x32_bf16 v[24:27], v[136:139], v[176:179], v[24:27]
	v_mfma_f32_16x16x32_bf16 v[16:19], v[128:131], v[200:203], v[16:19]
	v_mfma_f32_16x16x32_bf16 v[8:11], v[136:139], v[200:203], v[8:11]
	v_mfma_f32_16x16x32_bf16 v[60:63], v[132:135], v[164:167], v[60:63]
	v_mfma_f32_16x16x32_bf16 v[56:59], v[140:143], v[164:167], v[56:59]
	v_mfma_f32_16x16x32_bf16 v[48:51], v[132:135], v[172:175], v[48:51]
	v_mfma_f32_16x16x32_bf16 v[40:43], v[140:143], v[172:175], v[40:43]
	v_mfma_f32_16x16x32_bf16 v[32:35], v[132:135], v[180:183], v[32:35]
	v_mfma_f32_16x16x32_bf16 v[24:27], v[140:143], v[180:183], v[24:27]
	v_mfma_f32_16x16x32_bf16 v[16:19], v[132:135], v[208:211], v[16:19]
	v_mfma_f32_16x16x32_bf16 v[8:11], v[140:143], v[208:211], v[8:11]
	v_mfma_f32_16x16x32_bf16 v[52:55], v[144:147], v[160:163], v[52:55]
	v_mfma_f32_16x16x32_bf16 v[44:47], v[152:155], v[160:163], v[44:47]
	v_mfma_f32_16x16x32_bf16 v[36:39], v[144:147], v[168:171], v[36:39]
	v_mfma_f32_16x16x32_bf16 v[28:31], v[152:155], v[168:171], v[28:31]
	v_mfma_f32_16x16x32_bf16 v[20:23], v[144:147], v[176:179], v[20:23]
	v_mfma_f32_16x16x32_bf16 v[12:15], v[152:155], v[176:179], v[12:15]
	v_mfma_f32_16x16x32_bf16 v[4:7], v[144:147], v[200:203], v[4:7]
	v_mfma_f32_16x16x32_bf16 v[0:3], v[152:155], v[200:203], v[0:3]
	v_mfma_f32_16x16x32_bf16 v[52:55], v[148:151], v[164:167], v[52:55]
	v_mfma_f32_16x16x32_bf16 v[44:47], v[156:159], v[164:167], v[44:47]
	v_mfma_f32_16x16x32_bf16 v[36:39], v[148:151], v[172:175], v[36:39]
	v_mfma_f32_16x16x32_bf16 v[28:31], v[156:159], v[172:175], v[28:31]
	v_mfma_f32_16x16x32_bf16 v[20:23], v[148:151], v[180:183], v[20:23]
	v_mfma_f32_16x16x32_bf16 v[12:15], v[156:159], v[180:183], v[12:15]
	v_mfma_f32_16x16x32_bf16 v[4:7], v[148:151], v[208:211], v[4:7]
	v_mfma_f32_16x16x32_bf16 v[0:3], v[156:159], v[208:211], v[0:3]
	s_barrier
	s_add_i32 s66, s66, 2
	s_add_u32 s24, s24, 0x100
	s_addc_u32 s25, s25, 0
	s_add_u32 s19, s19, 0x100
	s_addc_u32 s21, s21, 0
	s_cmp_gt_u32 s66, 29
	s_cbranch_scc0 .LBB0_2706
	s_and_b64 vcc, exec, s[8:9]
	s_cbranch_vccz .LBB0_2709
	s_barrier
